# GEMM epilogues: packed v_pk_mul/add/fma_f32 split into single-lane ops (bit-identical), on top of v40
# speedup vs baseline: 1.0021x; 1.0021x over previous
;     __device__ __forceinline__ void operator()(const f32x4 (&acc)[2][2][4][2], const Unit& u, int wr, int wc, int fr, int fq, int ui, PG8_LAS unsigned char* lds) const {
;         const int row0 = u.pm * BM + wr * 64 + fr, col0 = u.pn * BM + wc * 32 + 8 * fq;
;         const PG8_LAS float* tab = (const PG8_LAS float*)(lds + RSTD_TAB) + ui * 256 + wr * 64 + fr;
;         const int sec = (u.pn * BM) >> 10;
;         int act = 0; float sc = 1.f;
;         if (mode == 0) act = (sec == 0 || sec == 3) ? 1 : (sec == 1 ? 2 : 0);
;         else if (mode == 1) sc = (sec == 0) ? qscale : 1.f;
;         else act = 3;
;         const bool ksum = (mode == 1) && (sec == 1);
;         f32x4 csum[2][2] = {{(f32x4){0.f, 0.f, 0.f, 0.f}, (f32x4){0.f, 0.f, 0.f, 0.f}}, {(f32x4){0.f, 0.f, 0.f, 0.f}, (f32x4){0.f, 0.f, 0.f, 0.f}}};
; #pragma unroll
;         for (int ai = 0; ai < 2; ++ai) {
;             float rs4[4];
; #pragma unroll
;             for (int m = 0; m < 4; ++m) {
;                 if ((m & 1) == 0) {
;                     if (use_tab) { rs4[m] = tab[ai * HALF + m * 16] * sc; rs4[m + 1] = tab[ai * HALF + (m + 1) * 16] * sc; }
;                     else {
;                         asm volatile("" ::: "memory");
;                         rs4[m] = __builtin_amdgcn_rsqf(ssq_row(ssq, row0 + ai * HALF + m * 16) * (1.0f / 1024.0f) + RMS_EPS) * sc;
;                         rs4[m + 1] = __builtin_amdgcn_rsqf(ssq_row(ssq, row0 + ai * HALF + (m + 1) * 16) * (1.0f / 1024.0f) + RMS_EPS) * sc;
;                     }
;                 }
;                 const int row = row0 + ai * HALF + m * 16;
;                 const float rs = rs4[m];
;                 bf16_t* rowp = O + (size_t)row * ldc + col0;
; #pragma unroll
;                 for (int bj = 0; bj < 2; ++bj) {
;                     f32x4 v[2] = {acc[ai][bj][m][0] * rs, acc[ai][bj][m][1] * rs};
;                     if (ksum) { csum[bj][0] += v[0]; csum[bj][1] += v[1]; }
; #pragma unroll
;                     for (int n = 0; n < 2; ++n) {
;                         f32x4 lbv = (f32x4){0.f, 0.f, 0.f, 0.f};
;                         if (act == 2) lbv = *(const f32x4*)(lb + (col0 - 1024) + bj * HALF + 4 * n);
; #pragma unroll
;                         for (int e = 0; e < 4; ++e) {
;                             float x = v[n][e];
;                             if (act == 1) x = silu_f(x);
.Lepi_id:
	v_lshl_add_u32 v150, s78, 8, v164
	s_lshl_b32 s1, s1, 10
	v_add_u32_e32 v170, s1, v166
	ds_read_b32 v128, v170
	ds_read_b32 v130, v170 offset:64
	ds_read_b32 v144, v170 offset:128
	ds_read_b32 v146, v170 offset:192
	ds_read_b32 v148, v170 offset:512
	ds_read_b32 v156, v170 offset:576
	ds_read_b32 v158, v170 offset:640
	ds_read_b32 v160, v170 offset:704
	s_lshl_b32 s73, s0, 8
	v_or_b32_e32 v172, s73, v167
	v_mov_b32_e32 v173, 0
	v_mad_u64_u32 v[162:163], s[38:39], v150, s96, 0
	s_lshl_b32 s46, s96, 5
	s_mov_b32 s47, 0
	s_lshl_b32 s52, s96, 8
	s_mov_b32 s53, 0
	v_lshl_add_u64 v[162:163], v[162:163], 1, s[14:15]
	v_lshl_add_u64 v[162:163], v[172:173], 1, v[162:163]
	v_lshl_add_u64 v[178:179], v[162:163], 0, s[52:53]
	s_waitcnt lgkmcnt(0)
	v_mul_f32_e32 v128, v169, v128
	v_mul_f32_e32 v130, v169, v130
	v_mul_f32_e32 v144, v169, v144
	v_mul_f32_e32 v146, v169, v146
	v_mul_f32_e32 v148, v169, v148
	v_mul_f32_e32 v156, v169, v156
	v_mul_f32_e32 v158, v169, v158
	v_mul_f32_e32 v160, v169, v160
	v_mul_f32_e32 v124, v124, v128
	v_mul_f32_e32 v125, v125, v128
	v_mul_f32_e32 v126, v126, v128
	v_mul_f32_e32 v127, v127, v128
	v_mul_f32_e32 v120, v120, v128
	v_mul_f32_e32 v121, v121, v128
	v_mul_f32_e32 v122, v122, v128
	v_mul_f32_e32 v123, v123, v128
	v_cvt_pk_bf16_f32 v124, v124, v125
	v_cvt_pk_bf16_f32 v125, v126, v127
	v_cvt_pk_bf16_f32 v126, v120, v121
	v_cvt_pk_bf16_f32 v127, v122, v123
	global_store_dwordx4 v[162:163], v[124:127], off
	v_mul_f32_e32 v116, v116, v128
	v_mul_f32_e32 v117, v117, v128
	v_mul_f32_e32 v118, v118, v128
	v_mul_f32_e32 v119, v119, v128
	v_mul_f32_e32 v112, v112, v128
	v_mul_f32_e32 v113, v113, v128
	v_mul_f32_e32 v114, v114, v128
	v_mul_f32_e32 v115, v115, v128
	v_cvt_pk_bf16_f32 v116, v116, v117
	v_cvt_pk_bf16_f32 v117, v118, v119
	v_cvt_pk_bf16_f32 v118, v112, v113
	v_cvt_pk_bf16_f32 v119, v114, v115
	global_store_dwordx4 v[162:163], v[116:119], off offset:256
	v_lshl_add_u64 v[176:177], v[162:163], 0, s[46:47]
	v_mul_f32_e32 v108, v108, v130
	v_mul_f32_e32 v109, v109, v130
	v_mul_f32_e32 v110, v110, v130
	v_mul_f32_e32 v111, v111, v130
	v_mul_f32_e32 v104, v104, v130
	v_mul_f32_e32 v105, v105, v130
	v_mul_f32_e32 v106, v106, v130
	v_mul_f32_e32 v107, v107, v130
	v_cvt_pk_bf16_f32 v108, v108, v109
	v_cvt_pk_bf16_f32 v109, v110, v111
	v_cvt_pk_bf16_f32 v110, v104, v105
	v_cvt_pk_bf16_f32 v111, v106, v107
	global_store_dwordx4 v[176:177], v[108:111], off
	v_mul_f32_e32 v100, v100, v130
	v_mul_f32_e32 v101, v101, v130
	v_mul_f32_e32 v102, v102, v130
	v_mul_f32_e32 v103, v103, v130
	v_mul_f32_e32 v96, v96, v130
	v_mul_f32_e32 v97, v97, v130
	v_mul_f32_e32 v98, v98, v130
	v_mul_f32_e32 v99, v99, v130
	v_cvt_pk_bf16_f32 v100, v100, v101
	v_cvt_pk_bf16_f32 v101, v102, v103
	v_cvt_pk_bf16_f32 v102, v96, v97
	v_cvt_pk_bf16_f32 v103, v98, v99
	global_store_dwordx4 v[176:177], v[100:103], off offset:256
	s_cmp_eq_u64 s[68:69], 0
	s_cbranch_scc1 .Lal1id_skip
	s_barrier
.Lal1id_skip:
	v_lshl_add_u64 v[162:163], v[176:177], 0, s[46:47]
	v_mul_f32_e32 v92, v92, v144
	v_mul_f32_e32 v93, v93, v144
	v_mul_f32_e32 v94, v94, v144
	v_mul_f32_e32 v95, v95, v144
	v_mul_f32_e32 v88, v88, v144
	v_mul_f32_e32 v89, v89, v144
	v_mul_f32_e32 v90, v90, v144
	v_mul_f32_e32 v91, v91, v144
	v_cvt_pk_bf16_f32 v92, v92, v93
	v_cvt_pk_bf16_f32 v93, v94, v95
	v_cvt_pk_bf16_f32 v94, v88, v89
	v_cvt_pk_bf16_f32 v95, v90, v91
	global_store_dwordx4 v[162:163], v[92:95], off
	v_mul_f32_e32 v84, v84, v144
	v_mul_f32_e32 v85, v85, v144
	v_mul_f32_e32 v86, v86, v144
	v_mul_f32_e32 v87, v87, v144
	v_mul_f32_e32 v80, v80, v144
	v_mul_f32_e32 v81, v81, v144
	v_mul_f32_e32 v82, v82, v144
	v_mul_f32_e32 v83, v83, v144
	v_cvt_pk_bf16_f32 v84, v84, v85
	v_cvt_pk_bf16_f32 v85, v86, v87
	v_cvt_pk_bf16_f32 v86, v80, v81
	v_cvt_pk_bf16_f32 v87, v82, v83
	global_store_dwordx4 v[162:163], v[84:87], off offset:256
	v_lshl_add_u64 v[176:177], v[162:163], 0, s[46:47]
	v_mul_f32_e32 v76, v76, v146
	v_mul_f32_e32 v77, v77, v146
	v_mul_f32_e32 v78, v78, v146
	v_mul_f32_e32 v79, v79, v146
	v_mul_f32_e32 v72, v72, v146
	v_mul_f32_e32 v73, v73, v146
	v_mul_f32_e32 v74, v74, v146
	v_mul_f32_e32 v75, v75, v146
	v_cvt_pk_bf16_f32 v76, v76, v77
	v_cvt_pk_bf16_f32 v77, v78, v79
	v_cvt_pk_bf16_f32 v78, v72, v73
	v_cvt_pk_bf16_f32 v79, v74, v75
	global_store_dwordx4 v[176:177], v[76:79], off
	v_mul_f32_e32 v68, v68, v146
	v_mul_f32_e32 v69, v69, v146
	v_mul_f32_e32 v70, v70, v146
	v_mul_f32_e32 v71, v71, v146
	v_mul_f32_e32 v64, v64, v146
	v_mul_f32_e32 v65, v65, v146
	v_mul_f32_e32 v66, v66, v146
	v_mul_f32_e32 v67, v67, v146
	v_cvt_pk_bf16_f32 v68, v68, v69
	v_cvt_pk_bf16_f32 v69, v70, v71
	v_cvt_pk_bf16_f32 v70, v64, v65
	v_cvt_pk_bf16_f32 v71, v66, v67
	global_store_dwordx4 v[176:177], v[68:71], off offset:256
	v_lshl_add_u64 v[162:163], v[178:179], 0, 0
	v_mul_f32_e32 v60, v60, v148
	v_mul_f32_e32 v61, v61, v148
	v_mul_f32_e32 v62, v62, v148
	v_mul_f32_e32 v63, v63, v148
	v_mul_f32_e32 v56, v56, v148
	v_mul_f32_e32 v57, v57, v148
	v_mul_f32_e32 v58, v58, v148
	v_mul_f32_e32 v59, v59, v148
	v_cvt_pk_bf16_f32 v60, v60, v61
	v_cvt_pk_bf16_f32 v61, v62, v63
	v_cvt_pk_bf16_f32 v62, v56, v57
	v_cvt_pk_bf16_f32 v63, v58, v59
	global_store_dwordx4 v[162:163], v[60:63], off
	v_mul_f32_e32 v52, v52, v148
	v_mul_f32_e32 v53, v53, v148
	v_mul_f32_e32 v54, v54, v148
	v_mul_f32_e32 v55, v55, v148
	v_mul_f32_e32 v48, v48, v148
	v_mul_f32_e32 v49, v49, v148
	v_mul_f32_e32 v50, v50, v148
	v_mul_f32_e32 v51, v51, v148
	v_cvt_pk_bf16_f32 v52, v52, v53
	v_cvt_pk_bf16_f32 v53, v54, v55
	v_cvt_pk_bf16_f32 v54, v48, v49
	v_cvt_pk_bf16_f32 v55, v50, v51
	global_store_dwordx4 v[162:163], v[52:55], off offset:256
; __device__ __forceinline__ unsigned cvt_pk_bf16(float lo, float hi) { unsigned r; asm volatile("v_cvt_pk_bf16_f32 %0, %1, %2" : "=v"(r) : "v"(lo), "v"(hi)); return r; }
; __device__ __forceinline__ float silu_f(float v) { return v * __builtin_amdgcn_rcpf(1.f + __expf(-v)); }
;     __device__ __forceinline__ void operator()(const f32x4 (&acc)[2][2][4][2], const Unit& u, int wr, int wc, int fr, int fq, int ui, PG8_LAS unsigned char* lds) const {
;     ...
;                 const int row = row0 + ai * HALF + m * 16;
;                 const float rs = rs4[m];
;                 bf16_t* rowp = O + (size_t)row * ldc + col0;
; #pragma unroll
;                 for (int bj = 0; bj < 2; ++bj) {
;                     f32x4 v[2] = {acc[ai][bj][m][0] * rs, acc[ai][bj][m][1] * rs};
;                     if (ksum) { csum[bj][0] += v[0]; csum[bj][1] += v[1]; }
; #pragma unroll
;                     for (int n = 0; n < 2; ++n) {
;                         f32x4 lbv = (f32x4){0.f, 0.f, 0.f, 0.f};
;                         if (act == 2) lbv = *(const f32x4*)(lb + (col0 - 1024) + bj * HALF + 4 * n);
; #pragma unroll
;                         for (int e = 0; e < 4; ++e) {
;                             float x = v[n][e];
;                             if (act == 1) x = silu_f(x);
;                             else if (act == 2) { const float l = lbv[e]; x = __logf(l + (1.f - l) * __builtin_amdgcn_rcpf(1.f + __expf(-x))); }
;                             else if (act == 3) { x = fmaxf(x, 0.f); x = x * x; }
;                             v[n][e] = x;
;                         }
;                     }
;                     u32x4 w; w.x = cvt_pk_bf16(v[0][0], v[0][1]); w.y = cvt_pk_bf16(v[0][2], v[0][3]); w.z = cvt_pk_bf16(v[1][0], v[1][1]); w.w = cvt_pk_bf16(v[1][2], v[1][3]);
;                     *(u32x4*)(rowp + bj * HALF) = w;
	v_lshl_add_u64 v[176:177], v[162:163], 0, s[46:47]
	v_mul_f32_e32 v44, v44, v156
	v_mul_f32_e32 v45, v45, v156
	v_mul_f32_e32 v46, v46, v156
	v_mul_f32_e32 v47, v47, v156
	v_mul_f32_e32 v40, v40, v156
	v_mul_f32_e32 v41, v41, v156
	v_mul_f32_e32 v42, v42, v156
	v_mul_f32_e32 v43, v43, v156
	v_cvt_pk_bf16_f32 v44, v44, v45
	v_cvt_pk_bf16_f32 v45, v46, v47
	v_cvt_pk_bf16_f32 v46, v40, v41
	v_cvt_pk_bf16_f32 v47, v42, v43
	global_store_dwordx4 v[176:177], v[44:47], off
	v_mul_f32_e32 v36, v36, v156
	v_mul_f32_e32 v37, v37, v156
	v_mul_f32_e32 v38, v38, v156
	v_mul_f32_e32 v39, v39, v156
	v_mul_f32_e32 v32, v32, v156
	v_mul_f32_e32 v33, v33, v156
	v_mul_f32_e32 v34, v34, v156
	v_mul_f32_e32 v35, v35, v156
	v_cvt_pk_bf16_f32 v36, v36, v37
	v_cvt_pk_bf16_f32 v37, v38, v39
	v_cvt_pk_bf16_f32 v38, v32, v33
	v_cvt_pk_bf16_f32 v39, v34, v35
	global_store_dwordx4 v[176:177], v[36:39], off offset:256
	v_lshl_add_u64 v[162:163], v[176:177], 0, s[46:47]
	v_mul_f32_e32 v28, v28, v158
	v_mul_f32_e32 v29, v29, v158
	v_mul_f32_e32 v30, v30, v158
	v_mul_f32_e32 v31, v31, v158
	v_mul_f32_e32 v24, v24, v158
	v_mul_f32_e32 v25, v25, v158
	v_mul_f32_e32 v26, v26, v158
	v_mul_f32_e32 v27, v27, v158
	v_cvt_pk_bf16_f32 v28, v28, v29
	v_cvt_pk_bf16_f32 v29, v30, v31
	v_cvt_pk_bf16_f32 v30, v24, v25
	v_cvt_pk_bf16_f32 v31, v26, v27
	global_store_dwordx4 v[162:163], v[28:31], off
	v_mul_f32_e32 v20, v20, v158
	v_mul_f32_e32 v21, v21, v158
	v_mul_f32_e32 v22, v22, v158
	v_mul_f32_e32 v23, v23, v158
	v_mul_f32_e32 v16, v16, v158
	v_mul_f32_e32 v17, v17, v158
	v_mul_f32_e32 v18, v18, v158
	v_mul_f32_e32 v19, v19, v158
	v_cvt_pk_bf16_f32 v20, v20, v21
	v_cvt_pk_bf16_f32 v21, v22, v23
	v_cvt_pk_bf16_f32 v22, v16, v17
	v_cvt_pk_bf16_f32 v23, v18, v19
	global_store_dwordx4 v[162:163], v[20:23], off offset:256
	v_lshl_add_u64 v[176:177], v[162:163], 0, s[46:47]
	v_mul_f32_e32 v12, v12, v160
	v_mul_f32_e32 v13, v13, v160
	v_mul_f32_e32 v14, v14, v160
	v_mul_f32_e32 v15, v15, v160
	v_mul_f32_e32 v8, v8, v160
	v_mul_f32_e32 v9, v9, v160
	v_mul_f32_e32 v10, v10, v160
	v_mul_f32_e32 v11, v11, v160
	v_cvt_pk_bf16_f32 v12, v12, v13
	v_cvt_pk_bf16_f32 v13, v14, v15
	v_cvt_pk_bf16_f32 v14, v8, v9
	v_cvt_pk_bf16_f32 v15, v10, v11
	global_store_dwordx4 v[176:177], v[12:15], off
	v_mul_f32_e32 v4, v4, v160
	v_mul_f32_e32 v5, v5, v160
	v_mul_f32_e32 v6, v6, v160
	v_mul_f32_e32 v7, v7, v160
	v_mul_f32_e32 v0, v0, v160
	v_mul_f32_e32 v1, v1, v160
	v_mul_f32_e32 v2, v2, v160
	v_mul_f32_e32 v3, v3, v160
	v_cvt_pk_bf16_f32 v4, v4, v5
	v_cvt_pk_bf16_f32 v5, v6, v7
	v_cvt_pk_bf16_f32 v6, v0, v1
	v_cvt_pk_bf16_f32 v7, v2, v3
	global_store_dwordx4 v[176:177], v[4:7], off offset:256
	s_branch .LBB0_1108
.Lepi_silu:
	v_lshl_add_u32 v150, s78, 8, v164
	s_lshl_b32 s1, s1, 10
	v_add_u32_e32 v170, s1, v166
	ds_read_b32 v128, v170
	ds_read_b32 v130, v170 offset:64
	ds_read_b32 v144, v170 offset:128
	ds_read_b32 v146, v170 offset:192
	ds_read_b32 v148, v170 offset:512
	ds_read_b32 v156, v170 offset:576
	ds_read_b32 v158, v170 offset:640
	ds_read_b32 v160, v170 offset:704
	s_lshl_b32 s73, s0, 8
	v_or_b32_e32 v172, s73, v167
	v_mov_b32_e32 v173, 0
	v_mad_u64_u32 v[162:163], s[38:39], v150, s96, 0
	s_lshl_b32 s46, s96, 5
	s_mov_b32 s47, 0
	s_lshl_b32 s52, s96, 8
	s_mov_b32 s53, 0
	v_lshl_add_u64 v[162:163], v[162:163], 1, s[14:15]
	v_lshl_add_u64 v[162:163], v[172:173], 1, v[162:163]
	v_lshl_add_u64 v[178:179], v[162:163], 0, s[52:53]
	s_waitcnt lgkmcnt(0)
	v_mul_f32_e32 v128, v169, v128
	v_mul_f32_e32 v130, v169, v130
	v_mul_f32_e32 v144, v169, v144
	v_mul_f32_e32 v146, v169, v146
	v_mul_f32_e32 v148, v169, v148
	v_mul_f32_e32 v156, v169, v156
	v_mul_f32_e32 v158, v169, v158
	v_mul_f32_e32 v160, v169, v160
	v_mul_f32_e32 v124, v124, v128
	v_mul_f32_e32 v125, v125, v128
	v_mul_f32_e32 v126, v126, v128
	v_mul_f32_e32 v127, v127, v128
	v_mul_f32_e32 v120, v120, v128
	v_mul_f32_e32 v121, v121, v128
	v_mul_f32_e32 v122, v122, v128
	v_mul_f32_e32 v123, v123, v128
	v_mul_f32_e32 v184, 0xbfb8aa3b, v124
	v_mul_f32_e32 v185, 0xbfb8aa3b, v125
	v_mul_f32_e32 v186, 0xbfb8aa3b, v126
	v_mul_f32_e32 v187, 0xbfb8aa3b, v127
	v_mul_f32_e32 v188, 0xbfb8aa3b, v120
	v_mul_f32_e32 v189, 0xbfb8aa3b, v121
	v_mul_f32_e32 v190, 0xbfb8aa3b, v122
	v_mul_f32_e32 v191, 0xbfb8aa3b, v123
	v_exp_f32_e32 v184, v184
	v_exp_f32_e32 v185, v185
	v_exp_f32_e32 v186, v186
	v_exp_f32_e32 v187, v187
	v_exp_f32_e32 v188, v188
	v_exp_f32_e32 v189, v189
	v_exp_f32_e32 v190, v190
	v_exp_f32_e32 v191, v191
	v_add_f32_e32 v184, 1.0, v184
	v_add_f32_e32 v185, 1.0, v185
	v_add_f32_e32 v186, 1.0, v186
	v_add_f32_e32 v187, 1.0, v187
	v_add_f32_e32 v188, 1.0, v188
	v_add_f32_e32 v189, 1.0, v189
	v_add_f32_e32 v190, 1.0, v190
	v_add_f32_e32 v191, 1.0, v191
	v_rcp_f32_e32 v184, v184
	v_rcp_f32_e32 v185, v185
	v_rcp_f32_e32 v186, v186
	v_rcp_f32_e32 v187, v187
	v_rcp_f32_e32 v188, v188
	v_rcp_f32_e32 v189, v189
	v_rcp_f32_e32 v190, v190
	v_rcp_f32_e32 v191, v191
	v_mul_f32_e32 v124, v124, v184
	v_mul_f32_e32 v125, v125, v185
	v_mul_f32_e32 v126, v126, v186
	v_mul_f32_e32 v127, v127, v187
	v_mul_f32_e32 v120, v120, v188
	v_mul_f32_e32 v121, v121, v189
	v_mul_f32_e32 v122, v122, v190
	v_mul_f32_e32 v123, v123, v191
	v_cvt_pk_bf16_f32 v124, v124, v125
	v_cvt_pk_bf16_f32 v125, v126, v127
	v_cvt_pk_bf16_f32 v126, v120, v121
	v_cvt_pk_bf16_f32 v127, v122, v123
	global_store_dwordx4 v[162:163], v[124:127], off
	v_mul_f32_e32 v116, v116, v128
	v_mul_f32_e32 v117, v117, v128
	v_mul_f32_e32 v118, v118, v128
	v_mul_f32_e32 v119, v119, v128
	v_mul_f32_e32 v112, v112, v128
	v_mul_f32_e32 v113, v113, v128
	v_mul_f32_e32 v114, v114, v128
	v_mul_f32_e32 v115, v115, v128
; __device__ __forceinline__ unsigned cvt_pk_bf16(float lo, float hi) { unsigned r; asm volatile("v_cvt_pk_bf16_f32 %0, %1, %2" : "=v"(r) : "v"(lo), "v"(hi)); return r; }
; __device__ __forceinline__ float silu_f(float v) { return v * __builtin_amdgcn_rcpf(1.f + __expf(-v)); }
;     __device__ __forceinline__ void operator()(const f32x4 (&acc)[2][2][4][2], const Unit& u, int wr, int wc, int fr, int fq, int ui, PG8_LAS unsigned char* lds) const {
;     ...
;                 const int row = row0 + ai * HALF + m * 16;
;                 const float rs = rs4[m];
;                 bf16_t* rowp = O + (size_t)row * ldc + col0;
; #pragma unroll
;                 for (int bj = 0; bj < 2; ++bj) {
;                     f32x4 v[2] = {acc[ai][bj][m][0] * rs, acc[ai][bj][m][1] * rs};
;                     if (ksum) { csum[bj][0] += v[0]; csum[bj][1] += v[1]; }
; #pragma unroll
;                     for (int n = 0; n < 2; ++n) {
;                         f32x4 lbv = (f32x4){0.f, 0.f, 0.f, 0.f};
;                         if (act == 2) lbv = *(const f32x4*)(lb + (col0 - 1024) + bj * HALF + 4 * n);
; #pragma unroll
;                         for (int e = 0; e < 4; ++e) {
;                             float x = v[n][e];
;                             if (act == 1) x = silu_f(x);
;                             else if (act == 2) { const float l = lbv[e]; x = __logf(l + (1.f - l) * __builtin_amdgcn_rcpf(1.f + __expf(-x))); }
;                             else if (act == 3) { x = fmaxf(x, 0.f); x = x * x; }
;                             v[n][e] = x;
;                         }
;                     }
;                     u32x4 w; w.x = cvt_pk_bf16(v[0][0], v[0][1]); w.y = cvt_pk_bf16(v[0][2], v[0][3]); w.z = cvt_pk_bf16(v[1][0], v[1][1]); w.w = cvt_pk_bf16(v[1][2], v[1][3]);
;                     *(u32x4*)(rowp + bj * HALF) = w;
	v_mul_f32_e32 v184, 0xbfb8aa3b, v116
	v_mul_f32_e32 v185, 0xbfb8aa3b, v117
	v_mul_f32_e32 v186, 0xbfb8aa3b, v118
	v_mul_f32_e32 v187, 0xbfb8aa3b, v119
	v_mul_f32_e32 v188, 0xbfb8aa3b, v112
	v_mul_f32_e32 v189, 0xbfb8aa3b, v113
	v_mul_f32_e32 v190, 0xbfb8aa3b, v114
	v_mul_f32_e32 v191, 0xbfb8aa3b, v115
	v_exp_f32_e32 v184, v184
	v_exp_f32_e32 v185, v185
	v_exp_f32_e32 v186, v186
	v_exp_f32_e32 v187, v187
	v_exp_f32_e32 v188, v188
	v_exp_f32_e32 v189, v189
	v_exp_f32_e32 v190, v190
	v_exp_f32_e32 v191, v191
	v_add_f32_e32 v184, 1.0, v184
	v_add_f32_e32 v185, 1.0, v185
	v_add_f32_e32 v186, 1.0, v186
	v_add_f32_e32 v187, 1.0, v187
	v_add_f32_e32 v188, 1.0, v188
	v_add_f32_e32 v189, 1.0, v189
	v_add_f32_e32 v190, 1.0, v190
	v_add_f32_e32 v191, 1.0, v191
	v_rcp_f32_e32 v184, v184
	v_rcp_f32_e32 v185, v185
	v_rcp_f32_e32 v186, v186
	v_rcp_f32_e32 v187, v187
	v_rcp_f32_e32 v188, v188
	v_rcp_f32_e32 v189, v189
	v_rcp_f32_e32 v190, v190
	v_rcp_f32_e32 v191, v191
	v_mul_f32_e32 v116, v116, v184
	v_mul_f32_e32 v117, v117, v185
	v_mul_f32_e32 v118, v118, v186
	v_mul_f32_e32 v119, v119, v187
	v_mul_f32_e32 v112, v112, v188
	v_mul_f32_e32 v113, v113, v189
	v_mul_f32_e32 v114, v114, v190
	v_mul_f32_e32 v115, v115, v191
	v_cvt_pk_bf16_f32 v116, v116, v117
	v_cvt_pk_bf16_f32 v117, v118, v119
	v_cvt_pk_bf16_f32 v118, v112, v113
	v_cvt_pk_bf16_f32 v119, v114, v115
	global_store_dwordx4 v[162:163], v[116:119], off offset:256
	s_cmp_eq_u64 s[68:69], 0
	s_cbranch_scc1 .Lal1si_skip
	s_barrier
.Lal1si_skip:
	v_lshl_add_u64 v[176:177], v[162:163], 0, s[46:47]
	v_mul_f32_e32 v108, v108, v130
	v_mul_f32_e32 v109, v109, v130
	v_mul_f32_e32 v110, v110, v130
	v_mul_f32_e32 v111, v111, v130
	v_mul_f32_e32 v104, v104, v130
	v_mul_f32_e32 v105, v105, v130
	v_mul_f32_e32 v106, v106, v130
	v_mul_f32_e32 v107, v107, v130
	v_mul_f32_e32 v184, 0xbfb8aa3b, v108
	v_mul_f32_e32 v185, 0xbfb8aa3b, v109
	v_mul_f32_e32 v186, 0xbfb8aa3b, v110
	v_mul_f32_e32 v187, 0xbfb8aa3b, v111
	v_mul_f32_e32 v188, 0xbfb8aa3b, v104
	v_mul_f32_e32 v189, 0xbfb8aa3b, v105
	v_mul_f32_e32 v190, 0xbfb8aa3b, v106
	v_mul_f32_e32 v191, 0xbfb8aa3b, v107
	v_exp_f32_e32 v184, v184
	v_exp_f32_e32 v185, v185
	v_exp_f32_e32 v186, v186
	v_exp_f32_e32 v187, v187
	v_exp_f32_e32 v188, v188
	v_exp_f32_e32 v189, v189
	v_exp_f32_e32 v190, v190
	v_exp_f32_e32 v191, v191
	v_add_f32_e32 v184, 1.0, v184
	v_add_f32_e32 v185, 1.0, v185
	v_add_f32_e32 v186, 1.0, v186
	v_add_f32_e32 v187, 1.0, v187
	v_add_f32_e32 v188, 1.0, v188
	v_add_f32_e32 v189, 1.0, v189
	v_add_f32_e32 v190, 1.0, v190
	v_add_f32_e32 v191, 1.0, v191
	v_rcp_f32_e32 v184, v184
	v_rcp_f32_e32 v185, v185
	v_rcp_f32_e32 v186, v186
	v_rcp_f32_e32 v187, v187
	v_rcp_f32_e32 v188, v188
	v_rcp_f32_e32 v189, v189
	v_rcp_f32_e32 v190, v190
	v_rcp_f32_e32 v191, v191
	v_mul_f32_e32 v108, v108, v184
	v_mul_f32_e32 v109, v109, v185
	v_mul_f32_e32 v110, v110, v186
	v_mul_f32_e32 v111, v111, v187
	v_mul_f32_e32 v104, v104, v188
	v_mul_f32_e32 v105, v105, v189
	v_mul_f32_e32 v106, v106, v190
	v_mul_f32_e32 v107, v107, v191
	v_cvt_pk_bf16_f32 v108, v108, v109
	v_cvt_pk_bf16_f32 v109, v110, v111
	v_cvt_pk_bf16_f32 v110, v104, v105
	v_cvt_pk_bf16_f32 v111, v106, v107
	global_store_dwordx4 v[176:177], v[108:111], off
	v_mul_f32_e32 v100, v100, v130
	v_mul_f32_e32 v101, v101, v130
	v_mul_f32_e32 v102, v102, v130
	v_mul_f32_e32 v103, v103, v130
	v_mul_f32_e32 v96, v96, v130
	v_mul_f32_e32 v97, v97, v130
	v_mul_f32_e32 v98, v98, v130
	v_mul_f32_e32 v99, v99, v130
	v_mul_f32_e32 v184, 0xbfb8aa3b, v100
	v_mul_f32_e32 v185, 0xbfb8aa3b, v101
	v_mul_f32_e32 v186, 0xbfb8aa3b, v102
	v_mul_f32_e32 v187, 0xbfb8aa3b, v103
	v_mul_f32_e32 v188, 0xbfb8aa3b, v96
	v_mul_f32_e32 v189, 0xbfb8aa3b, v97
	v_mul_f32_e32 v190, 0xbfb8aa3b, v98
	v_mul_f32_e32 v191, 0xbfb8aa3b, v99
	v_exp_f32_e32 v184, v184
	v_exp_f32_e32 v185, v185
	v_exp_f32_e32 v186, v186
	v_exp_f32_e32 v187, v187
	v_exp_f32_e32 v188, v188
	v_exp_f32_e32 v189, v189
	v_exp_f32_e32 v190, v190
	v_exp_f32_e32 v191, v191
	v_add_f32_e32 v184, 1.0, v184
	v_add_f32_e32 v185, 1.0, v185
	v_add_f32_e32 v186, 1.0, v186
	v_add_f32_e32 v187, 1.0, v187
	v_add_f32_e32 v188, 1.0, v188
	v_add_f32_e32 v189, 1.0, v189
	v_add_f32_e32 v190, 1.0, v190
	v_add_f32_e32 v191, 1.0, v191
	v_rcp_f32_e32 v184, v184
	v_rcp_f32_e32 v185, v185
	v_rcp_f32_e32 v186, v186
	v_rcp_f32_e32 v187, v187
	v_rcp_f32_e32 v188, v188
	v_rcp_f32_e32 v189, v189
	v_rcp_f32_e32 v190, v190
	v_rcp_f32_e32 v191, v191
	v_mul_f32_e32 v100, v100, v184
	v_mul_f32_e32 v101, v101, v185
	v_mul_f32_e32 v102, v102, v186
	v_mul_f32_e32 v103, v103, v187
	v_mul_f32_e32 v96, v96, v188
	v_mul_f32_e32 v97, v97, v189
	v_mul_f32_e32 v98, v98, v190
	v_mul_f32_e32 v99, v99, v191
	v_cvt_pk_bf16_f32 v100, v100, v101
	v_cvt_pk_bf16_f32 v101, v102, v103
	v_cvt_pk_bf16_f32 v102, v96, v97
	v_cvt_pk_bf16_f32 v103, v98, v99
	global_store_dwordx4 v[176:177], v[100:103], off offset:256
	v_lshl_add_u64 v[162:163], v[176:177], 0, s[46:47]
	v_mul_f32_e32 v92, v92, v144
	v_mul_f32_e32 v93, v93, v144
	v_mul_f32_e32 v94, v94, v144
	v_mul_f32_e32 v95, v95, v144
	v_mul_f32_e32 v88, v88, v144
	v_mul_f32_e32 v89, v89, v144
	v_mul_f32_e32 v90, v90, v144
	v_mul_f32_e32 v91, v91, v144
	v_mul_f32_e32 v184, 0xbfb8aa3b, v92
	v_mul_f32_e32 v185, 0xbfb8aa3b, v93
	v_mul_f32_e32 v186, 0xbfb8aa3b, v94
	v_mul_f32_e32 v187, 0xbfb8aa3b, v95
	v_mul_f32_e32 v188, 0xbfb8aa3b, v88
	v_mul_f32_e32 v189, 0xbfb8aa3b, v89
	v_mul_f32_e32 v190, 0xbfb8aa3b, v90
	v_mul_f32_e32 v191, 0xbfb8aa3b, v91
	v_exp_f32_e32 v184, v184
	v_exp_f32_e32 v185, v185
	v_exp_f32_e32 v186, v186
	v_exp_f32_e32 v187, v187
	v_exp_f32_e32 v188, v188
	v_exp_f32_e32 v189, v189
; __device__ __forceinline__ unsigned cvt_pk_bf16(float lo, float hi) { unsigned r; asm volatile("v_cvt_pk_bf16_f32 %0, %1, %2" : "=v"(r) : "v"(lo), "v"(hi)); return r; }
; __device__ __forceinline__ float silu_f(float v) { return v * __builtin_amdgcn_rcpf(1.f + __expf(-v)); }
;     __device__ __forceinline__ void operator()(const f32x4 (&acc)[2][2][4][2], const Unit& u, int wr, int wc, int fr, int fq, int ui, PG8_LAS unsigned char* lds) const {
;     ...
;                 const int row = row0 + ai * HALF + m * 16;
;                 const float rs = rs4[m];
;                 bf16_t* rowp = O + (size_t)row * ldc + col0;
; #pragma unroll
;                 for (int bj = 0; bj < 2; ++bj) {
;                     f32x4 v[2] = {acc[ai][bj][m][0] * rs, acc[ai][bj][m][1] * rs};
;                     if (ksum) { csum[bj][0] += v[0]; csum[bj][1] += v[1]; }
; #pragma unroll
;                     for (int n = 0; n < 2; ++n) {
;                         f32x4 lbv = (f32x4){0.f, 0.f, 0.f, 0.f};
;                         if (act == 2) lbv = *(const f32x4*)(lb + (col0 - 1024) + bj * HALF + 4 * n);
; #pragma unroll
;                         for (int e = 0; e < 4; ++e) {
;                             float x = v[n][e];
;                             if (act == 1) x = silu_f(x);
;                             else if (act == 2) { const float l = lbv[e]; x = __logf(l + (1.f - l) * __builtin_amdgcn_rcpf(1.f + __expf(-x))); }
;                             else if (act == 3) { x = fmaxf(x, 0.f); x = x * x; }
;                             v[n][e] = x;
;                         }
;                     }
;                     u32x4 w; w.x = cvt_pk_bf16(v[0][0], v[0][1]); w.y = cvt_pk_bf16(v[0][2], v[0][3]); w.z = cvt_pk_bf16(v[1][0], v[1][1]); w.w = cvt_pk_bf16(v[1][2], v[1][3]);
;                     *(u32x4*)(rowp + bj * HALF) = w;
	v_exp_f32_e32 v190, v190
	v_exp_f32_e32 v191, v191
	v_add_f32_e32 v184, 1.0, v184
	v_add_f32_e32 v185, 1.0, v185
	v_add_f32_e32 v186, 1.0, v186
	v_add_f32_e32 v187, 1.0, v187
	v_add_f32_e32 v188, 1.0, v188
	v_add_f32_e32 v189, 1.0, v189
	v_add_f32_e32 v190, 1.0, v190
	v_add_f32_e32 v191, 1.0, v191
	v_rcp_f32_e32 v184, v184
	v_rcp_f32_e32 v185, v185
	v_rcp_f32_e32 v186, v186
	v_rcp_f32_e32 v187, v187
	v_rcp_f32_e32 v188, v188
	v_rcp_f32_e32 v189, v189
	v_rcp_f32_e32 v190, v190
	v_rcp_f32_e32 v191, v191
	v_mul_f32_e32 v92, v92, v184
	v_mul_f32_e32 v93, v93, v185
	v_mul_f32_e32 v94, v94, v186
	v_mul_f32_e32 v95, v95, v187
	v_mul_f32_e32 v88, v88, v188
	v_mul_f32_e32 v89, v89, v189
	v_mul_f32_e32 v90, v90, v190
	v_mul_f32_e32 v91, v91, v191
	v_cvt_pk_bf16_f32 v92, v92, v93
	v_cvt_pk_bf16_f32 v93, v94, v95
	v_cvt_pk_bf16_f32 v94, v88, v89
	v_cvt_pk_bf16_f32 v95, v90, v91
	global_store_dwordx4 v[162:163], v[92:95], off
	v_mul_f32_e32 v84, v84, v144
	v_mul_f32_e32 v85, v85, v144
	v_mul_f32_e32 v86, v86, v144
	v_mul_f32_e32 v87, v87, v144
	v_mul_f32_e32 v80, v80, v144
	v_mul_f32_e32 v81, v81, v144
	v_mul_f32_e32 v82, v82, v144
	v_mul_f32_e32 v83, v83, v144
	v_mul_f32_e32 v184, 0xbfb8aa3b, v84
	v_mul_f32_e32 v185, 0xbfb8aa3b, v85
	v_mul_f32_e32 v186, 0xbfb8aa3b, v86
	v_mul_f32_e32 v187, 0xbfb8aa3b, v87
	v_mul_f32_e32 v188, 0xbfb8aa3b, v80
	v_mul_f32_e32 v189, 0xbfb8aa3b, v81
	v_mul_f32_e32 v190, 0xbfb8aa3b, v82
	v_mul_f32_e32 v191, 0xbfb8aa3b, v83
	v_exp_f32_e32 v184, v184
	v_exp_f32_e32 v185, v185
	v_exp_f32_e32 v186, v186
	v_exp_f32_e32 v187, v187
	v_exp_f32_e32 v188, v188
	v_exp_f32_e32 v189, v189
	v_exp_f32_e32 v190, v190
	v_exp_f32_e32 v191, v191
	v_add_f32_e32 v184, 1.0, v184
	v_add_f32_e32 v185, 1.0, v185
	v_add_f32_e32 v186, 1.0, v186
	v_add_f32_e32 v187, 1.0, v187
	v_add_f32_e32 v188, 1.0, v188
	v_add_f32_e32 v189, 1.0, v189
	v_add_f32_e32 v190, 1.0, v190
	v_add_f32_e32 v191, 1.0, v191
	v_rcp_f32_e32 v184, v184
	v_rcp_f32_e32 v185, v185
	v_rcp_f32_e32 v186, v186
	v_rcp_f32_e32 v187, v187
	v_rcp_f32_e32 v188, v188
	v_rcp_f32_e32 v189, v189
	v_rcp_f32_e32 v190, v190
	v_rcp_f32_e32 v191, v191
	v_mul_f32_e32 v84, v84, v184
	v_mul_f32_e32 v85, v85, v185
	v_mul_f32_e32 v86, v86, v186
	v_mul_f32_e32 v87, v87, v187
	v_mul_f32_e32 v80, v80, v188
	v_mul_f32_e32 v81, v81, v189
	v_mul_f32_e32 v82, v82, v190
	v_mul_f32_e32 v83, v83, v191
	v_cvt_pk_bf16_f32 v84, v84, v85
	v_cvt_pk_bf16_f32 v85, v86, v87
	v_cvt_pk_bf16_f32 v86, v80, v81
	v_cvt_pk_bf16_f32 v87, v82, v83
	global_store_dwordx4 v[162:163], v[84:87], off offset:256
	v_lshl_add_u64 v[176:177], v[162:163], 0, s[46:47]
	v_mul_f32_e32 v76, v76, v146
	v_mul_f32_e32 v77, v77, v146
	v_mul_f32_e32 v78, v78, v146
	v_mul_f32_e32 v79, v79, v146
	v_mul_f32_e32 v72, v72, v146
	v_mul_f32_e32 v73, v73, v146
	v_mul_f32_e32 v74, v74, v146
	v_mul_f32_e32 v75, v75, v146
	v_mul_f32_e32 v184, 0xbfb8aa3b, v76
	v_mul_f32_e32 v185, 0xbfb8aa3b, v77
	v_mul_f32_e32 v186, 0xbfb8aa3b, v78
	v_mul_f32_e32 v187, 0xbfb8aa3b, v79
	v_mul_f32_e32 v188, 0xbfb8aa3b, v72
	v_mul_f32_e32 v189, 0xbfb8aa3b, v73
	v_mul_f32_e32 v190, 0xbfb8aa3b, v74
	v_mul_f32_e32 v191, 0xbfb8aa3b, v75
	v_exp_f32_e32 v184, v184
	v_exp_f32_e32 v185, v185
	v_exp_f32_e32 v186, v186
	v_exp_f32_e32 v187, v187
	v_exp_f32_e32 v188, v188
	v_exp_f32_e32 v189, v189
	v_exp_f32_e32 v190, v190
	v_exp_f32_e32 v191, v191
	v_add_f32_e32 v184, 1.0, v184
	v_add_f32_e32 v185, 1.0, v185
	v_add_f32_e32 v186, 1.0, v186
	v_add_f32_e32 v187, 1.0, v187
	v_add_f32_e32 v188, 1.0, v188
	v_add_f32_e32 v189, 1.0, v189
	v_add_f32_e32 v190, 1.0, v190
	v_add_f32_e32 v191, 1.0, v191
	v_rcp_f32_e32 v184, v184
	v_rcp_f32_e32 v185, v185
	v_rcp_f32_e32 v186, v186
	v_rcp_f32_e32 v187, v187
	v_rcp_f32_e32 v188, v188
	v_rcp_f32_e32 v189, v189
	v_rcp_f32_e32 v190, v190
	v_rcp_f32_e32 v191, v191
	v_mul_f32_e32 v76, v76, v184
	v_mul_f32_e32 v77, v77, v185
	v_mul_f32_e32 v78, v78, v186
	v_mul_f32_e32 v79, v79, v187
	v_mul_f32_e32 v72, v72, v188
	v_mul_f32_e32 v73, v73, v189
	v_mul_f32_e32 v74, v74, v190
	v_mul_f32_e32 v75, v75, v191
	v_cvt_pk_bf16_f32 v76, v76, v77
	v_cvt_pk_bf16_f32 v77, v78, v79
	v_cvt_pk_bf16_f32 v78, v72, v73
	v_cvt_pk_bf16_f32 v79, v74, v75
	global_store_dwordx4 v[176:177], v[76:79], off
	v_mul_f32_e32 v68, v68, v146
	v_mul_f32_e32 v69, v69, v146
	v_mul_f32_e32 v70, v70, v146
	v_mul_f32_e32 v71, v71, v146
	v_mul_f32_e32 v64, v64, v146
	v_mul_f32_e32 v65, v65, v146
	v_mul_f32_e32 v66, v66, v146
	v_mul_f32_e32 v67, v67, v146
	v_mul_f32_e32 v184, 0xbfb8aa3b, v68
	v_mul_f32_e32 v185, 0xbfb8aa3b, v69
	v_mul_f32_e32 v186, 0xbfb8aa3b, v70
	v_mul_f32_e32 v187, 0xbfb8aa3b, v71
	v_mul_f32_e32 v188, 0xbfb8aa3b, v64
	v_mul_f32_e32 v189, 0xbfb8aa3b, v65
	v_mul_f32_e32 v190, 0xbfb8aa3b, v66
	v_mul_f32_e32 v191, 0xbfb8aa3b, v67
	v_exp_f32_e32 v184, v184
	v_exp_f32_e32 v185, v185
	v_exp_f32_e32 v186, v186
	v_exp_f32_e32 v187, v187
	v_exp_f32_e32 v188, v188
	v_exp_f32_e32 v189, v189
	v_exp_f32_e32 v190, v190
	v_exp_f32_e32 v191, v191
	v_add_f32_e32 v184, 1.0, v184
	v_add_f32_e32 v185, 1.0, v185
	v_add_f32_e32 v186, 1.0, v186
	v_add_f32_e32 v187, 1.0, v187
	v_add_f32_e32 v188, 1.0, v188
	v_add_f32_e32 v189, 1.0, v189
	v_add_f32_e32 v190, 1.0, v190
	v_add_f32_e32 v191, 1.0, v191
	v_rcp_f32_e32 v184, v184
	v_rcp_f32_e32 v185, v185
	v_rcp_f32_e32 v186, v186
	v_rcp_f32_e32 v187, v187
	v_rcp_f32_e32 v188, v188
	v_rcp_f32_e32 v189, v189
	v_rcp_f32_e32 v190, v190
	v_rcp_f32_e32 v191, v191
	v_mul_f32_e32 v68, v68, v184
	v_mul_f32_e32 v69, v69, v185
	v_mul_f32_e32 v70, v70, v186
	v_mul_f32_e32 v71, v71, v187
	v_mul_f32_e32 v64, v64, v188
	v_mul_f32_e32 v65, v65, v189
	v_mul_f32_e32 v66, v66, v190
; __device__ __forceinline__ unsigned cvt_pk_bf16(float lo, float hi) { unsigned r; asm volatile("v_cvt_pk_bf16_f32 %0, %1, %2" : "=v"(r) : "v"(lo), "v"(hi)); return r; }
; __device__ __forceinline__ float silu_f(float v) { return v * __builtin_amdgcn_rcpf(1.f + __expf(-v)); }
;     __device__ __forceinline__ void operator()(const f32x4 (&acc)[2][2][4][2], const Unit& u, int wr, int wc, int fr, int fq, int ui, PG8_LAS unsigned char* lds) const {
;     ...
;                 const int row = row0 + ai * HALF + m * 16;
;                 const float rs = rs4[m];
;                 bf16_t* rowp = O + (size_t)row * ldc + col0;
; #pragma unroll
;                 for (int bj = 0; bj < 2; ++bj) {
;                     f32x4 v[2] = {acc[ai][bj][m][0] * rs, acc[ai][bj][m][1] * rs};
;                     if (ksum) { csum[bj][0] += v[0]; csum[bj][1] += v[1]; }
; #pragma unroll
;                     for (int n = 0; n < 2; ++n) {
;                         f32x4 lbv = (f32x4){0.f, 0.f, 0.f, 0.f};
;                         if (act == 2) lbv = *(const f32x4*)(lb + (col0 - 1024) + bj * HALF + 4 * n);
; #pragma unroll
;                         for (int e = 0; e < 4; ++e) {
;                             float x = v[n][e];
;                             if (act == 1) x = silu_f(x);
;                             else if (act == 2) { const float l = lbv[e]; x = __logf(l + (1.f - l) * __builtin_amdgcn_rcpf(1.f + __expf(-x))); }
;                             else if (act == 3) { x = fmaxf(x, 0.f); x = x * x; }
;                             v[n][e] = x;
;                         }
;                     }
;                     u32x4 w; w.x = cvt_pk_bf16(v[0][0], v[0][1]); w.y = cvt_pk_bf16(v[0][2], v[0][3]); w.z = cvt_pk_bf16(v[1][0], v[1][1]); w.w = cvt_pk_bf16(v[1][2], v[1][3]);
;                     *(u32x4*)(rowp + bj * HALF) = w;
	v_mul_f32_e32 v67, v67, v191
	v_cvt_pk_bf16_f32 v68, v68, v69
	v_cvt_pk_bf16_f32 v69, v70, v71
	v_cvt_pk_bf16_f32 v70, v64, v65
	v_cvt_pk_bf16_f32 v71, v66, v67
	global_store_dwordx4 v[176:177], v[68:71], off offset:256
	v_lshl_add_u64 v[162:163], v[178:179], 0, 0
	v_mul_f32_e32 v60, v60, v148
	v_mul_f32_e32 v61, v61, v148
	v_mul_f32_e32 v62, v62, v148
	v_mul_f32_e32 v63, v63, v148
	v_mul_f32_e32 v56, v56, v148
	v_mul_f32_e32 v57, v57, v148
	v_mul_f32_e32 v58, v58, v148
	v_mul_f32_e32 v59, v59, v148
	v_mul_f32_e32 v184, 0xbfb8aa3b, v60
	v_mul_f32_e32 v185, 0xbfb8aa3b, v61
	v_mul_f32_e32 v186, 0xbfb8aa3b, v62
	v_mul_f32_e32 v187, 0xbfb8aa3b, v63
	v_mul_f32_e32 v188, 0xbfb8aa3b, v56
	v_mul_f32_e32 v189, 0xbfb8aa3b, v57
	v_mul_f32_e32 v190, 0xbfb8aa3b, v58
	v_mul_f32_e32 v191, 0xbfb8aa3b, v59
	v_exp_f32_e32 v184, v184
	v_exp_f32_e32 v185, v185
	v_exp_f32_e32 v186, v186
	v_exp_f32_e32 v187, v187
	v_exp_f32_e32 v188, v188
	v_exp_f32_e32 v189, v189
	v_exp_f32_e32 v190, v190
	v_exp_f32_e32 v191, v191
	v_add_f32_e32 v184, 1.0, v184
	v_add_f32_e32 v185, 1.0, v185
	v_add_f32_e32 v186, 1.0, v186
	v_add_f32_e32 v187, 1.0, v187
	v_add_f32_e32 v188, 1.0, v188
	v_add_f32_e32 v189, 1.0, v189
	v_add_f32_e32 v190, 1.0, v190
	v_add_f32_e32 v191, 1.0, v191
	v_rcp_f32_e32 v184, v184
	v_rcp_f32_e32 v185, v185
	v_rcp_f32_e32 v186, v186
	v_rcp_f32_e32 v187, v187
	v_rcp_f32_e32 v188, v188
	v_rcp_f32_e32 v189, v189
	v_rcp_f32_e32 v190, v190
	v_rcp_f32_e32 v191, v191
	v_mul_f32_e32 v60, v60, v184
	v_mul_f32_e32 v61, v61, v185
	v_mul_f32_e32 v62, v62, v186
	v_mul_f32_e32 v63, v63, v187
	v_mul_f32_e32 v56, v56, v188
	v_mul_f32_e32 v57, v57, v189
	v_mul_f32_e32 v58, v58, v190
	v_mul_f32_e32 v59, v59, v191
	v_cvt_pk_bf16_f32 v60, v60, v61
	v_cvt_pk_bf16_f32 v61, v62, v63
	v_cvt_pk_bf16_f32 v62, v56, v57
	v_cvt_pk_bf16_f32 v63, v58, v59
	global_store_dwordx4 v[162:163], v[60:63], off
	v_mul_f32_e32 v52, v52, v148
	v_mul_f32_e32 v53, v53, v148
	v_mul_f32_e32 v54, v54, v148
	v_mul_f32_e32 v55, v55, v148
	v_mul_f32_e32 v48, v48, v148
	v_mul_f32_e32 v49, v49, v148
	v_mul_f32_e32 v50, v50, v148
	v_mul_f32_e32 v51, v51, v148
	v_mul_f32_e32 v184, 0xbfb8aa3b, v52
	v_mul_f32_e32 v185, 0xbfb8aa3b, v53
	v_mul_f32_e32 v186, 0xbfb8aa3b, v54
	v_mul_f32_e32 v187, 0xbfb8aa3b, v55
	v_mul_f32_e32 v188, 0xbfb8aa3b, v48
	v_mul_f32_e32 v189, 0xbfb8aa3b, v49
	v_mul_f32_e32 v190, 0xbfb8aa3b, v50
	v_mul_f32_e32 v191, 0xbfb8aa3b, v51
	v_exp_f32_e32 v184, v184
	v_exp_f32_e32 v185, v185
	v_exp_f32_e32 v186, v186
	v_exp_f32_e32 v187, v187
	v_exp_f32_e32 v188, v188
	v_exp_f32_e32 v189, v189
	v_exp_f32_e32 v190, v190
	v_exp_f32_e32 v191, v191
	v_add_f32_e32 v184, 1.0, v184
	v_add_f32_e32 v185, 1.0, v185
	v_add_f32_e32 v186, 1.0, v186
	v_add_f32_e32 v187, 1.0, v187
	v_add_f32_e32 v188, 1.0, v188
	v_add_f32_e32 v189, 1.0, v189
	v_add_f32_e32 v190, 1.0, v190
	v_add_f32_e32 v191, 1.0, v191
	v_rcp_f32_e32 v184, v184
	v_rcp_f32_e32 v185, v185
	v_rcp_f32_e32 v186, v186
	v_rcp_f32_e32 v187, v187
	v_rcp_f32_e32 v188, v188
	v_rcp_f32_e32 v189, v189
	v_rcp_f32_e32 v190, v190
	v_rcp_f32_e32 v191, v191
	v_mul_f32_e32 v52, v52, v184
	v_mul_f32_e32 v53, v53, v185
	v_mul_f32_e32 v54, v54, v186
	v_mul_f32_e32 v55, v55, v187
	v_mul_f32_e32 v48, v48, v188
	v_mul_f32_e32 v49, v49, v189
	v_mul_f32_e32 v50, v50, v190
	v_mul_f32_e32 v51, v51, v191
	v_cvt_pk_bf16_f32 v52, v52, v53
	v_cvt_pk_bf16_f32 v53, v54, v55
	v_cvt_pk_bf16_f32 v54, v48, v49
	v_cvt_pk_bf16_f32 v55, v50, v51
	global_store_dwordx4 v[162:163], v[52:55], off offset:256
	v_lshl_add_u64 v[176:177], v[162:163], 0, s[46:47]
	v_mul_f32_e32 v44, v44, v156
	v_mul_f32_e32 v45, v45, v156
	v_mul_f32_e32 v46, v46, v156
	v_mul_f32_e32 v47, v47, v156
	v_mul_f32_e32 v40, v40, v156
	v_mul_f32_e32 v41, v41, v156
	v_mul_f32_e32 v42, v42, v156
	v_mul_f32_e32 v43, v43, v156
	v_mul_f32_e32 v184, 0xbfb8aa3b, v44
	v_mul_f32_e32 v185, 0xbfb8aa3b, v45
	v_mul_f32_e32 v186, 0xbfb8aa3b, v46
	v_mul_f32_e32 v187, 0xbfb8aa3b, v47
	v_mul_f32_e32 v188, 0xbfb8aa3b, v40
	v_mul_f32_e32 v189, 0xbfb8aa3b, v41
	v_mul_f32_e32 v190, 0xbfb8aa3b, v42
	v_mul_f32_e32 v191, 0xbfb8aa3b, v43
	v_exp_f32_e32 v184, v184
	v_exp_f32_e32 v185, v185
	v_exp_f32_e32 v186, v186
	v_exp_f32_e32 v187, v187
	v_exp_f32_e32 v188, v188
	v_exp_f32_e32 v189, v189
	v_exp_f32_e32 v190, v190
	v_exp_f32_e32 v191, v191
	v_add_f32_e32 v184, 1.0, v184
	v_add_f32_e32 v185, 1.0, v185
	v_add_f32_e32 v186, 1.0, v186
	v_add_f32_e32 v187, 1.0, v187
	v_add_f32_e32 v188, 1.0, v188
	v_add_f32_e32 v189, 1.0, v189
	v_add_f32_e32 v190, 1.0, v190
	v_add_f32_e32 v191, 1.0, v191
	v_rcp_f32_e32 v184, v184
	v_rcp_f32_e32 v185, v185
	v_rcp_f32_e32 v186, v186
	v_rcp_f32_e32 v187, v187
	v_rcp_f32_e32 v188, v188
	v_rcp_f32_e32 v189, v189
	v_rcp_f32_e32 v190, v190
	v_rcp_f32_e32 v191, v191
	v_mul_f32_e32 v44, v44, v184
	v_mul_f32_e32 v45, v45, v185
	v_mul_f32_e32 v46, v46, v186
	v_mul_f32_e32 v47, v47, v187
	v_mul_f32_e32 v40, v40, v188
	v_mul_f32_e32 v41, v41, v189
	v_mul_f32_e32 v42, v42, v190
	v_mul_f32_e32 v43, v43, v191
	v_cvt_pk_bf16_f32 v44, v44, v45
	v_cvt_pk_bf16_f32 v45, v46, v47
	v_cvt_pk_bf16_f32 v46, v40, v41
	v_cvt_pk_bf16_f32 v47, v42, v43
	global_store_dwordx4 v[176:177], v[44:47], off
	v_mul_f32_e32 v36, v36, v156
	v_mul_f32_e32 v37, v37, v156
	v_mul_f32_e32 v38, v38, v156
	v_mul_f32_e32 v39, v39, v156
	v_mul_f32_e32 v32, v32, v156
	v_mul_f32_e32 v33, v33, v156
	v_mul_f32_e32 v34, v34, v156
	v_mul_f32_e32 v35, v35, v156
	v_mul_f32_e32 v184, 0xbfb8aa3b, v36
	v_mul_f32_e32 v185, 0xbfb8aa3b, v37
	v_mul_f32_e32 v186, 0xbfb8aa3b, v38
	v_mul_f32_e32 v187, 0xbfb8aa3b, v39
	v_mul_f32_e32 v188, 0xbfb8aa3b, v32
	v_mul_f32_e32 v189, 0xbfb8aa3b, v33
; __device__ __forceinline__ unsigned cvt_pk_bf16(float lo, float hi) { unsigned r; asm volatile("v_cvt_pk_bf16_f32 %0, %1, %2" : "=v"(r) : "v"(lo), "v"(hi)); return r; }
; __device__ __forceinline__ float silu_f(float v) { return v * __builtin_amdgcn_rcpf(1.f + __expf(-v)); }
;     __device__ __forceinline__ void operator()(const f32x4 (&acc)[2][2][4][2], const Unit& u, int wr, int wc, int fr, int fq, int ui, PG8_LAS unsigned char* lds) const {
;     ...
;                 const int row = row0 + ai * HALF + m * 16;
;                 const float rs = rs4[m];
;                 bf16_t* rowp = O + (size_t)row * ldc + col0;
; #pragma unroll
;                 for (int bj = 0; bj < 2; ++bj) {
;                     f32x4 v[2] = {acc[ai][bj][m][0] * rs, acc[ai][bj][m][1] * rs};
;                     if (ksum) { csum[bj][0] += v[0]; csum[bj][1] += v[1]; }
; #pragma unroll
;                     for (int n = 0; n < 2; ++n) {
;                         f32x4 lbv = (f32x4){0.f, 0.f, 0.f, 0.f};
;                         if (act == 2) lbv = *(const f32x4*)(lb + (col0 - 1024) + bj * HALF + 4 * n);
; #pragma unroll
;                         for (int e = 0; e < 4; ++e) {
;                             float x = v[n][e];
;                             if (act == 1) x = silu_f(x);
;                             else if (act == 2) { const float l = lbv[e]; x = __logf(l + (1.f - l) * __builtin_amdgcn_rcpf(1.f + __expf(-x))); }
;                             else if (act == 3) { x = fmaxf(x, 0.f); x = x * x; }
;                             v[n][e] = x;
;                         }
;                     }
;                     u32x4 w; w.x = cvt_pk_bf16(v[0][0], v[0][1]); w.y = cvt_pk_bf16(v[0][2], v[0][3]); w.z = cvt_pk_bf16(v[1][0], v[1][1]); w.w = cvt_pk_bf16(v[1][2], v[1][3]);
;                     *(u32x4*)(rowp + bj * HALF) = w;
	v_mul_f32_e32 v190, 0xbfb8aa3b, v34
	v_mul_f32_e32 v191, 0xbfb8aa3b, v35
	v_exp_f32_e32 v184, v184
	v_exp_f32_e32 v185, v185
	v_exp_f32_e32 v186, v186
	v_exp_f32_e32 v187, v187
	v_exp_f32_e32 v188, v188
	v_exp_f32_e32 v189, v189
	v_exp_f32_e32 v190, v190
	v_exp_f32_e32 v191, v191
	v_add_f32_e32 v184, 1.0, v184
	v_add_f32_e32 v185, 1.0, v185
	v_add_f32_e32 v186, 1.0, v186
	v_add_f32_e32 v187, 1.0, v187
	v_add_f32_e32 v188, 1.0, v188
	v_add_f32_e32 v189, 1.0, v189
	v_add_f32_e32 v190, 1.0, v190
	v_add_f32_e32 v191, 1.0, v191
	v_rcp_f32_e32 v184, v184
	v_rcp_f32_e32 v185, v185
	v_rcp_f32_e32 v186, v186
	v_rcp_f32_e32 v187, v187
	v_rcp_f32_e32 v188, v188
	v_rcp_f32_e32 v189, v189
	v_rcp_f32_e32 v190, v190
	v_rcp_f32_e32 v191, v191
	v_mul_f32_e32 v36, v36, v184
	v_mul_f32_e32 v37, v37, v185
	v_mul_f32_e32 v38, v38, v186
	v_mul_f32_e32 v39, v39, v187
	v_mul_f32_e32 v32, v32, v188
	v_mul_f32_e32 v33, v33, v189
	v_mul_f32_e32 v34, v34, v190
	v_mul_f32_e32 v35, v35, v191
	v_cvt_pk_bf16_f32 v36, v36, v37
	v_cvt_pk_bf16_f32 v37, v38, v39
	v_cvt_pk_bf16_f32 v38, v32, v33
	v_cvt_pk_bf16_f32 v39, v34, v35
	global_store_dwordx4 v[176:177], v[36:39], off offset:256
	v_lshl_add_u64 v[162:163], v[176:177], 0, s[46:47]
	v_mul_f32_e32 v28, v28, v158
	v_mul_f32_e32 v29, v29, v158
	v_mul_f32_e32 v30, v30, v158
	v_mul_f32_e32 v31, v31, v158
	v_mul_f32_e32 v24, v24, v158
	v_mul_f32_e32 v25, v25, v158
	v_mul_f32_e32 v26, v26, v158
	v_mul_f32_e32 v27, v27, v158
	v_mul_f32_e32 v184, 0xbfb8aa3b, v28
	v_mul_f32_e32 v185, 0xbfb8aa3b, v29
	v_mul_f32_e32 v186, 0xbfb8aa3b, v30
	v_mul_f32_e32 v187, 0xbfb8aa3b, v31
	v_mul_f32_e32 v188, 0xbfb8aa3b, v24
	v_mul_f32_e32 v189, 0xbfb8aa3b, v25
	v_mul_f32_e32 v190, 0xbfb8aa3b, v26
	v_mul_f32_e32 v191, 0xbfb8aa3b, v27
	v_exp_f32_e32 v184, v184
	v_exp_f32_e32 v185, v185
	v_exp_f32_e32 v186, v186
	v_exp_f32_e32 v187, v187
	v_exp_f32_e32 v188, v188
	v_exp_f32_e32 v189, v189
	v_exp_f32_e32 v190, v190
	v_exp_f32_e32 v191, v191
	v_add_f32_e32 v184, 1.0, v184
	v_add_f32_e32 v185, 1.0, v185
	v_add_f32_e32 v186, 1.0, v186
	v_add_f32_e32 v187, 1.0, v187
	v_add_f32_e32 v188, 1.0, v188
	v_add_f32_e32 v189, 1.0, v189
	v_add_f32_e32 v190, 1.0, v190
	v_add_f32_e32 v191, 1.0, v191
	v_rcp_f32_e32 v184, v184
	v_rcp_f32_e32 v185, v185
	v_rcp_f32_e32 v186, v186
	v_rcp_f32_e32 v187, v187
	v_rcp_f32_e32 v188, v188
	v_rcp_f32_e32 v189, v189
	v_rcp_f32_e32 v190, v190
	v_rcp_f32_e32 v191, v191
	v_mul_f32_e32 v28, v28, v184
	v_mul_f32_e32 v29, v29, v185
	v_mul_f32_e32 v30, v30, v186
	v_mul_f32_e32 v31, v31, v187
	v_mul_f32_e32 v24, v24, v188
	v_mul_f32_e32 v25, v25, v189
	v_mul_f32_e32 v26, v26, v190
	v_mul_f32_e32 v27, v27, v191
	v_cvt_pk_bf16_f32 v28, v28, v29
	v_cvt_pk_bf16_f32 v29, v30, v31
	v_cvt_pk_bf16_f32 v30, v24, v25
	v_cvt_pk_bf16_f32 v31, v26, v27
	global_store_dwordx4 v[162:163], v[28:31], off
	v_mul_f32_e32 v20, v20, v158
	v_mul_f32_e32 v21, v21, v158
	v_mul_f32_e32 v22, v22, v158
	v_mul_f32_e32 v23, v23, v158
	v_mul_f32_e32 v16, v16, v158
	v_mul_f32_e32 v17, v17, v158
	v_mul_f32_e32 v18, v18, v158
	v_mul_f32_e32 v19, v19, v158
	v_mul_f32_e32 v184, 0xbfb8aa3b, v20
	v_mul_f32_e32 v185, 0xbfb8aa3b, v21
	v_mul_f32_e32 v186, 0xbfb8aa3b, v22
	v_mul_f32_e32 v187, 0xbfb8aa3b, v23
	v_mul_f32_e32 v188, 0xbfb8aa3b, v16
	v_mul_f32_e32 v189, 0xbfb8aa3b, v17
	v_mul_f32_e32 v190, 0xbfb8aa3b, v18
	v_mul_f32_e32 v191, 0xbfb8aa3b, v19
	v_exp_f32_e32 v184, v184
	v_exp_f32_e32 v185, v185
	v_exp_f32_e32 v186, v186
	v_exp_f32_e32 v187, v187
	v_exp_f32_e32 v188, v188
	v_exp_f32_e32 v189, v189
	v_exp_f32_e32 v190, v190
	v_exp_f32_e32 v191, v191
	v_add_f32_e32 v184, 1.0, v184
	v_add_f32_e32 v185, 1.0, v185
	v_add_f32_e32 v186, 1.0, v186
	v_add_f32_e32 v187, 1.0, v187
	v_add_f32_e32 v188, 1.0, v188
	v_add_f32_e32 v189, 1.0, v189
	v_add_f32_e32 v190, 1.0, v190
	v_add_f32_e32 v191, 1.0, v191
	v_rcp_f32_e32 v184, v184
	v_rcp_f32_e32 v185, v185
	v_rcp_f32_e32 v186, v186
	v_rcp_f32_e32 v187, v187
	v_rcp_f32_e32 v188, v188
	v_rcp_f32_e32 v189, v189
	v_rcp_f32_e32 v190, v190
	v_rcp_f32_e32 v191, v191
	v_mul_f32_e32 v20, v20, v184
	v_mul_f32_e32 v21, v21, v185
	v_mul_f32_e32 v22, v22, v186
	v_mul_f32_e32 v23, v23, v187
	v_mul_f32_e32 v16, v16, v188
	v_mul_f32_e32 v17, v17, v189
	v_mul_f32_e32 v18, v18, v190
	v_mul_f32_e32 v19, v19, v191
	v_cvt_pk_bf16_f32 v20, v20, v21
	v_cvt_pk_bf16_f32 v21, v22, v23
	v_cvt_pk_bf16_f32 v22, v16, v17
	v_cvt_pk_bf16_f32 v23, v18, v19
	global_store_dwordx4 v[162:163], v[20:23], off offset:256
	v_lshl_add_u64 v[176:177], v[162:163], 0, s[46:47]
	v_mul_f32_e32 v12, v12, v160
	v_mul_f32_e32 v13, v13, v160
	v_mul_f32_e32 v14, v14, v160
	v_mul_f32_e32 v15, v15, v160
	v_mul_f32_e32 v8, v8, v160
	v_mul_f32_e32 v9, v9, v160
	v_mul_f32_e32 v10, v10, v160
	v_mul_f32_e32 v11, v11, v160
	v_mul_f32_e32 v184, 0xbfb8aa3b, v12
	v_mul_f32_e32 v185, 0xbfb8aa3b, v13
	v_mul_f32_e32 v186, 0xbfb8aa3b, v14
	v_mul_f32_e32 v187, 0xbfb8aa3b, v15
	v_mul_f32_e32 v188, 0xbfb8aa3b, v8
	v_mul_f32_e32 v189, 0xbfb8aa3b, v9
	v_mul_f32_e32 v190, 0xbfb8aa3b, v10
	v_mul_f32_e32 v191, 0xbfb8aa3b, v11
	v_exp_f32_e32 v184, v184
	v_exp_f32_e32 v185, v185
	v_exp_f32_e32 v186, v186
	v_exp_f32_e32 v187, v187
	v_exp_f32_e32 v188, v188
	v_exp_f32_e32 v189, v189
	v_exp_f32_e32 v190, v190
	v_exp_f32_e32 v191, v191
	v_add_f32_e32 v184, 1.0, v184
	v_add_f32_e32 v185, 1.0, v185
	v_add_f32_e32 v186, 1.0, v186
	v_add_f32_e32 v187, 1.0, v187
	v_add_f32_e32 v188, 1.0, v188
	v_add_f32_e32 v189, 1.0, v189
	v_add_f32_e32 v190, 1.0, v190
	v_add_f32_e32 v191, 1.0, v191
	v_rcp_f32_e32 v184, v184
	v_rcp_f32_e32 v185, v185
	v_rcp_f32_e32 v186, v186
	v_rcp_f32_e32 v187, v187
	v_rcp_f32_e32 v188, v188
; __device__ __forceinline__ unsigned cvt_pk_bf16(float lo, float hi) { unsigned r; asm volatile("v_cvt_pk_bf16_f32 %0, %1, %2" : "=v"(r) : "v"(lo), "v"(hi)); return r; }
; __device__ __forceinline__ float silu_f(float v) { return v * __builtin_amdgcn_rcpf(1.f + __expf(-v)); }
;     __device__ __forceinline__ void operator()(const f32x4 (&acc)[2][2][4][2], const Unit& u, int wr, int wc, int fr, int fq, int ui, PG8_LAS unsigned char* lds) const {
;     ...
;                 const int row = row0 + ai * HALF + m * 16;
;                 const float rs = rs4[m];
;                 bf16_t* rowp = O + (size_t)row * ldc + col0;
; #pragma unroll
;                 for (int bj = 0; bj < 2; ++bj) {
;                     f32x4 v[2] = {acc[ai][bj][m][0] * rs, acc[ai][bj][m][1] * rs};
;                     if (ksum) { csum[bj][0] += v[0]; csum[bj][1] += v[1]; }
; #pragma unroll
;                     for (int n = 0; n < 2; ++n) {
;                         f32x4 lbv = (f32x4){0.f, 0.f, 0.f, 0.f};
;                         if (act == 2) lbv = *(const f32x4*)(lb + (col0 - 1024) + bj * HALF + 4 * n);
; #pragma unroll
;                         for (int e = 0; e < 4; ++e) {
;                             float x = v[n][e];
;                             if (act == 1) x = silu_f(x);
;                             else if (act == 2) { const float l = lbv[e]; x = __logf(l + (1.f - l) * __builtin_amdgcn_rcpf(1.f + __expf(-x))); }
;                             else if (act == 3) { x = fmaxf(x, 0.f); x = x * x; }
;                             v[n][e] = x;
;                         }
;                     }
;                     u32x4 w; w.x = cvt_pk_bf16(v[0][0], v[0][1]); w.y = cvt_pk_bf16(v[0][2], v[0][3]); w.z = cvt_pk_bf16(v[1][0], v[1][1]); w.w = cvt_pk_bf16(v[1][2], v[1][3]);
;                     *(u32x4*)(rowp + bj * HALF) = w;
	v_rcp_f32_e32 v189, v189
	v_rcp_f32_e32 v190, v190
	v_rcp_f32_e32 v191, v191
	v_mul_f32_e32 v12, v12, v184
	v_mul_f32_e32 v13, v13, v185
	v_mul_f32_e32 v14, v14, v186
	v_mul_f32_e32 v15, v15, v187
	v_mul_f32_e32 v8, v8, v188
	v_mul_f32_e32 v9, v9, v189
	v_mul_f32_e32 v10, v10, v190
	v_mul_f32_e32 v11, v11, v191
	v_cvt_pk_bf16_f32 v12, v12, v13
	v_cvt_pk_bf16_f32 v13, v14, v15
	v_cvt_pk_bf16_f32 v14, v8, v9
	v_cvt_pk_bf16_f32 v15, v10, v11
	global_store_dwordx4 v[176:177], v[12:15], off
	v_mul_f32_e32 v4, v4, v160
	v_mul_f32_e32 v5, v5, v160
	v_mul_f32_e32 v6, v6, v160
	v_mul_f32_e32 v7, v7, v160
	v_mul_f32_e32 v0, v0, v160
	v_mul_f32_e32 v1, v1, v160
	v_mul_f32_e32 v2, v2, v160
	v_mul_f32_e32 v3, v3, v160
	v_mul_f32_e32 v184, 0xbfb8aa3b, v4
	v_mul_f32_e32 v185, 0xbfb8aa3b, v5
	v_mul_f32_e32 v186, 0xbfb8aa3b, v6
	v_mul_f32_e32 v187, 0xbfb8aa3b, v7
	v_mul_f32_e32 v188, 0xbfb8aa3b, v0
	v_mul_f32_e32 v189, 0xbfb8aa3b, v1
	v_mul_f32_e32 v190, 0xbfb8aa3b, v2
	v_mul_f32_e32 v191, 0xbfb8aa3b, v3
	v_exp_f32_e32 v184, v184
	v_exp_f32_e32 v185, v185
	v_exp_f32_e32 v186, v186
	v_exp_f32_e32 v187, v187
	v_exp_f32_e32 v188, v188
	v_exp_f32_e32 v189, v189
	v_exp_f32_e32 v190, v190
	v_exp_f32_e32 v191, v191
	v_add_f32_e32 v184, 1.0, v184
	v_add_f32_e32 v185, 1.0, v185
	v_add_f32_e32 v186, 1.0, v186
	v_add_f32_e32 v187, 1.0, v187
	v_add_f32_e32 v188, 1.0, v188
	v_add_f32_e32 v189, 1.0, v189
	v_add_f32_e32 v190, 1.0, v190
	v_add_f32_e32 v191, 1.0, v191
	v_rcp_f32_e32 v184, v184
	v_rcp_f32_e32 v185, v185
	v_rcp_f32_e32 v186, v186
	v_rcp_f32_e32 v187, v187
	v_rcp_f32_e32 v188, v188
	v_rcp_f32_e32 v189, v189
	v_rcp_f32_e32 v190, v190
	v_rcp_f32_e32 v191, v191
	v_mul_f32_e32 v4, v4, v184
	v_mul_f32_e32 v5, v5, v185
	v_mul_f32_e32 v6, v6, v186
	v_mul_f32_e32 v7, v7, v187
	v_mul_f32_e32 v0, v0, v188
	v_mul_f32_e32 v1, v1, v189
	v_mul_f32_e32 v2, v2, v190
	v_mul_f32_e32 v3, v3, v191
	v_cvt_pk_bf16_f32 v4, v4, v5
	v_cvt_pk_bf16_f32 v5, v6, v7
	v_cvt_pk_bf16_f32 v6, v0, v1
	v_cvt_pk_bf16_f32 v7, v2, v3
	global_store_dwordx4 v[176:177], v[4:7], off offset:256
	s_branch .LBB0_1108
.Lepi_logf:
	v_lshl_add_u32 v150, s78, 8, v164
	s_lshl_b32 s1, s1, 10
	v_add_u32_e32 v170, s1, v166
	ds_read_b32 v128, v170
	ds_read_b32 v130, v170 offset:64
	ds_read_b32 v144, v170 offset:128
	ds_read_b32 v146, v170 offset:192
	ds_read_b32 v148, v170 offset:512
	ds_read_b32 v156, v170 offset:576
	ds_read_b32 v158, v170 offset:640
	ds_read_b32 v160, v170 offset:704
	s_lshl_b32 s73, s0, 8
	v_or_b32_e32 v172, s73, v167
	v_mov_b32_e32 v173, 0
	v_mad_u64_u32 v[162:163], s[38:39], v150, s96, 0
	s_lshl_b32 s46, s96, 5
	s_mov_b32 s47, 0
	s_lshl_b32 s52, s96, 8
	s_mov_b32 s53, 0
	v_lshl_add_u64 v[162:163], v[162:163], 1, s[14:15]
	v_lshl_add_u64 v[162:163], v[172:173], 1, v[162:163]
	v_lshl_add_u64 v[178:179], v[162:163], 0, s[52:53]
	s_waitcnt lgkmcnt(0)
	v_mul_f32_e32 v128, v169, v128
	v_mul_f32_e32 v130, v169, v130
	v_mul_f32_e32 v144, v169, v144
	v_mul_f32_e32 v146, v169, v146
	v_mul_f32_e32 v148, v169, v148
	v_mul_f32_e32 v156, v169, v156
	v_mul_f32_e32 v158, v169, v158
	v_mul_f32_e32 v160, v169, v160
	v_lshl_add_u64 v[170:171], v[172:173], 2, s[64:65]
	global_load_dwordx4 v[152:155], v[170:171], off offset:-4096
	global_load_dwordx4 v[180:183], v[170:171], off offset:-4080
	global_load_dwordx4 v[218:221], v[170:171], off offset:-3584
	global_load_dwordx4 v[222:225], v[170:171], off offset:-3568
	s_waitcnt vmcnt(0)
	v_mul_f32_e32 v124, v124, v128
	v_mul_f32_e32 v125, v125, v128
	v_mul_f32_e32 v126, v126, v128
	v_mul_f32_e32 v127, v127, v128
	v_mul_f32_e32 v120, v120, v128
	v_mul_f32_e32 v121, v121, v128
	v_mul_f32_e32 v122, v122, v128
	v_mul_f32_e32 v123, v123, v128
	v_mul_f32_e32 v184, 0xbfb8aa3b, v124
	v_mul_f32_e32 v185, 0xbfb8aa3b, v125
	v_mul_f32_e32 v186, 0xbfb8aa3b, v126
	v_mul_f32_e32 v187, 0xbfb8aa3b, v127
	v_mul_f32_e32 v188, 0xbfb8aa3b, v120
	v_mul_f32_e32 v189, 0xbfb8aa3b, v121
	v_mul_f32_e32 v190, 0xbfb8aa3b, v122
	v_mul_f32_e32 v191, 0xbfb8aa3b, v123
	v_exp_f32_e32 v184, v184
	v_exp_f32_e32 v185, v185
	v_exp_f32_e32 v186, v186
	v_exp_f32_e32 v187, v187
	v_exp_f32_e32 v188, v188
	v_exp_f32_e32 v189, v189
	v_exp_f32_e32 v190, v190
	v_exp_f32_e32 v191, v191
	v_sub_f32_e32 v192, 1.0, v152
	v_sub_f32_e32 v193, 1.0, v153
	v_sub_f32_e32 v194, 1.0, v154
	v_sub_f32_e32 v195, 1.0, v155
	v_sub_f32_e32 v196, 1.0, v180
	v_sub_f32_e32 v197, 1.0, v181
	v_sub_f32_e32 v198, 1.0, v182
	v_sub_f32_e32 v199, 1.0, v183
	v_add_f32_e32 v184, 1.0, v184
	v_add_f32_e32 v185, 1.0, v185
	v_add_f32_e32 v186, 1.0, v186
	v_add_f32_e32 v187, 1.0, v187
	v_add_f32_e32 v188, 1.0, v188
	v_add_f32_e32 v189, 1.0, v189
	v_add_f32_e32 v190, 1.0, v190
	v_add_f32_e32 v191, 1.0, v191
	v_rcp_f32_e32 v184, v184
	v_rcp_f32_e32 v185, v185
	v_rcp_f32_e32 v186, v186
	v_rcp_f32_e32 v187, v187
	v_rcp_f32_e32 v188, v188
	v_rcp_f32_e32 v189, v189
	v_rcp_f32_e32 v190, v190
	v_rcp_f32_e32 v191, v191
	v_fma_f32 v200, v184, v192, v152
	v_fma_f32 v201, v185, v193, v153
	v_fma_f32 v202, v186, v194, v154
	v_fma_f32 v203, v187, v195, v155
	v_fma_f32 v204, v188, v196, v180
	v_fma_f32 v205, v189, v197, v181
	v_fma_f32 v206, v190, v198, v182
	v_fma_f32 v207, v191, v199, v183
	v_cmp_gt_f32_e64 vcc, s35, v200
	v_cmp_gt_f32_e64 s[38:39], s35, v201
	v_cmp_gt_f32_e64 s[48:49], s35, v202
	v_cmp_gt_f32_e64 s[50:51], s35, v203
	v_cndmask_b32_e64 v184, 0, 32, vcc
	v_cndmask_b32_e64 v185, 0, 32, s[38:39]
	v_cndmask_b32_e64 v186, 0, 32, s[48:49]
	v_cndmask_b32_e64 v187, 0, 32, s[50:51]
	v_cndmask_b32_e64 v192, 0, v214, vcc
	v_cndmask_b32_e64 v193, 0, v214, s[38:39]
	v_cndmask_b32_e64 v194, 0, v214, s[48:49]
	v_cndmask_b32_e64 v195, 0, v214, s[50:51]
; __device__ __forceinline__ unsigned cvt_pk_bf16(float lo, float hi) { unsigned r; asm volatile("v_cvt_pk_bf16_f32 %0, %1, %2" : "=v"(r) : "v"(lo), "v"(hi)); return r; }
; __device__ __forceinline__ float silu_f(float v) { return v * __builtin_amdgcn_rcpf(1.f + __expf(-v)); }
;     __device__ __forceinline__ void operator()(const f32x4 (&acc)[2][2][4][2], const Unit& u, int wr, int wc, int fr, int fq, int ui, PG8_LAS unsigned char* lds) const {
;     ...
;                         f32x4 lbv = (f32x4){0.f, 0.f, 0.f, 0.f};
;                         if (act == 2) lbv = *(const f32x4*)(lb + (col0 - 1024) + bj * HALF + 4 * n);
; #pragma unroll
;                         for (int e = 0; e < 4; ++e) {
;                             float x = v[n][e];
;                             if (act == 1) x = silu_f(x);
;                             else if (act == 2) { const float l = lbv[e]; x = __logf(l + (1.f - l) * __builtin_amdgcn_rcpf(1.f + __expf(-x))); }
;                             else if (act == 3) { x = fmaxf(x, 0.f); x = x * x; }
;                             v[n][e] = x;
;                         }
;                     }
;                     u32x4 w; w.x = cvt_pk_bf16(v[0][0], v[0][1]); w.y = cvt_pk_bf16(v[0][2], v[0][3]); w.z = cvt_pk_bf16(v[1][0], v[1][1]); w.w = cvt_pk_bf16(v[1][2], v[1][3]);
;                     *(u32x4*)(rowp + bj * HALF) = w;
	v_cmp_gt_f32_e64 vcc, s35, v204
	v_cmp_gt_f32_e64 s[38:39], s35, v205
	v_cmp_gt_f32_e64 s[48:49], s35, v206
	v_cmp_gt_f32_e64 s[50:51], s35, v207
	v_cndmask_b32_e64 v188, 0, 32, vcc
	v_cndmask_b32_e64 v189, 0, 32, s[38:39]
	v_cndmask_b32_e64 v190, 0, 32, s[48:49]
	v_cndmask_b32_e64 v191, 0, 32, s[50:51]
	v_cndmask_b32_e64 v196, 0, v214, vcc
	v_cndmask_b32_e64 v197, 0, v214, s[38:39]
	v_cndmask_b32_e64 v198, 0, v214, s[48:49]
	v_cndmask_b32_e64 v199, 0, v214, s[50:51]
	v_ldexp_f32 v184, v200, v184
	v_ldexp_f32 v185, v201, v185
	v_ldexp_f32 v186, v202, v186
	v_ldexp_f32 v187, v203, v187
	v_ldexp_f32 v188, v204, v188
	v_ldexp_f32 v189, v205, v189
	v_ldexp_f32 v190, v206, v190
	v_ldexp_f32 v191, v207, v191
	v_log_f32_e32 v184, v184
	v_log_f32_e32 v185, v185
	v_log_f32_e32 v186, v186
	v_log_f32_e32 v187, v187
	v_log_f32_e32 v188, v188
	v_log_f32_e32 v189, v189
	v_log_f32_e32 v190, v190
	v_log_f32_e32 v191, v191
	v_mul_f32_e32 v200, 0x3f317217, v184
	v_mul_f32_e32 v201, 0x3f317217, v185
	v_mul_f32_e32 v202, 0x3f317217, v186
	v_mul_f32_e32 v203, 0x3f317217, v187
	v_mul_f32_e32 v204, 0x3f317217, v188
	v_mul_f32_e32 v205, 0x3f317217, v189
	v_mul_f32_e32 v206, 0x3f317217, v190
	v_mul_f32_e32 v207, 0x3f317217, v191
	v_fma_f32 v200, v184, s13, -v200
	v_fma_f32 v201, v185, s13, -v201
	v_fma_f32 v202, v186, s13, -v202
	v_fma_f32 v203, v187, s13, -v203
	v_fma_f32 v204, v188, s13, -v204
	v_fma_f32 v205, v189, s13, -v205
	v_fma_f32 v206, v190, s13, -v206
	v_fma_f32 v207, v191, s13, -v207
	v_fmac_f32_e32 v200, 0x3377d1cf, v184
	v_fmac_f32_e32 v201, 0x3377d1cf, v185
	v_fmac_f32_e32 v202, 0x3377d1cf, v186
	v_fmac_f32_e32 v203, 0x3377d1cf, v187
	v_fmac_f32_e32 v204, 0x3377d1cf, v188
	v_fmac_f32_e32 v205, 0x3377d1cf, v189
	v_fmac_f32_e32 v206, 0x3377d1cf, v190
	v_fmac_f32_e32 v207, 0x3377d1cf, v191
	v_fmac_f32_e32 v200, 0x3f317217, v184
	v_fmac_f32_e32 v201, 0x3f317217, v185
	v_fmac_f32_e32 v202, 0x3f317217, v186
	v_fmac_f32_e32 v203, 0x3f317217, v187
	v_fmac_f32_e32 v204, 0x3f317217, v188
	v_fmac_f32_e32 v205, 0x3f317217, v189
	v_fmac_f32_e32 v206, 0x3f317217, v190
	v_fmac_f32_e32 v207, 0x3f317217, v191
	v_cmp_lt_f32_e64 vcc, |v184|, s36
	v_cmp_lt_f32_e64 s[38:39], |v185|, s36
	v_cmp_lt_f32_e64 s[48:49], |v186|, s36
	v_cmp_lt_f32_e64 s[50:51], |v187|, s36
	v_cndmask_b32_e64 v184, v184, v200, vcc
	v_cndmask_b32_e64 v185, v185, v201, s[38:39]
	v_cndmask_b32_e64 v186, v186, v202, s[48:49]
	v_cndmask_b32_e64 v187, v187, v203, s[50:51]
	v_cmp_lt_f32_e64 vcc, |v188|, s36
	v_cmp_lt_f32_e64 s[38:39], |v189|, s36
	v_cmp_lt_f32_e64 s[48:49], |v190|, s36
	v_cmp_lt_f32_e64 s[50:51], |v191|, s36
	v_cndmask_b32_e64 v188, v188, v204, vcc
	v_cndmask_b32_e64 v189, v189, v205, s[38:39]
	v_cndmask_b32_e64 v190, v190, v206, s[48:49]
	v_cndmask_b32_e64 v191, v191, v207, s[50:51]
	v_sub_f32_e32 v124, v184, v192
	v_sub_f32_e32 v125, v185, v193
	v_sub_f32_e32 v126, v186, v194
	v_sub_f32_e32 v127, v187, v195
	v_sub_f32_e32 v120, v188, v196
	v_sub_f32_e32 v121, v189, v197
	v_sub_f32_e32 v122, v190, v198
	v_sub_f32_e32 v123, v191, v199
	v_cvt_pk_bf16_f32 v124, v124, v125
	v_cvt_pk_bf16_f32 v125, v126, v127
	v_cvt_pk_bf16_f32 v126, v120, v121
	v_cvt_pk_bf16_f32 v127, v122, v123
	global_store_dwordx4 v[162:163], v[124:127], off
	v_mul_f32_e32 v116, v116, v128
	v_mul_f32_e32 v117, v117, v128
	v_mul_f32_e32 v118, v118, v128
	v_mul_f32_e32 v119, v119, v128
	v_mul_f32_e32 v112, v112, v128
	v_mul_f32_e32 v113, v113, v128
	v_mul_f32_e32 v114, v114, v128
	v_mul_f32_e32 v115, v115, v128
	v_mul_f32_e32 v184, 0xbfb8aa3b, v116
	v_mul_f32_e32 v185, 0xbfb8aa3b, v117
	v_mul_f32_e32 v186, 0xbfb8aa3b, v118
	v_mul_f32_e32 v187, 0xbfb8aa3b, v119
	v_mul_f32_e32 v188, 0xbfb8aa3b, v112
	v_mul_f32_e32 v189, 0xbfb8aa3b, v113
	v_mul_f32_e32 v190, 0xbfb8aa3b, v114
	v_mul_f32_e32 v191, 0xbfb8aa3b, v115
	v_exp_f32_e32 v184, v184
	v_exp_f32_e32 v185, v185
	v_exp_f32_e32 v186, v186
	v_exp_f32_e32 v187, v187
	v_exp_f32_e32 v188, v188
	v_exp_f32_e32 v189, v189
	v_exp_f32_e32 v190, v190
	v_exp_f32_e32 v191, v191
	v_sub_f32_e32 v192, 1.0, v218
	v_sub_f32_e32 v193, 1.0, v219
	v_sub_f32_e32 v194, 1.0, v220
	v_sub_f32_e32 v195, 1.0, v221
	v_sub_f32_e32 v196, 1.0, v222
	v_sub_f32_e32 v197, 1.0, v223
	v_sub_f32_e32 v198, 1.0, v224
	v_sub_f32_e32 v199, 1.0, v225
	v_add_f32_e32 v184, 1.0, v184
	v_add_f32_e32 v185, 1.0, v185
	v_add_f32_e32 v186, 1.0, v186
	v_add_f32_e32 v187, 1.0, v187
	v_add_f32_e32 v188, 1.0, v188
	v_add_f32_e32 v189, 1.0, v189
	v_add_f32_e32 v190, 1.0, v190
	v_add_f32_e32 v191, 1.0, v191
	v_rcp_f32_e32 v184, v184
	v_rcp_f32_e32 v185, v185
	v_rcp_f32_e32 v186, v186
	v_rcp_f32_e32 v187, v187
	v_rcp_f32_e32 v188, v188
	v_rcp_f32_e32 v189, v189
	v_rcp_f32_e32 v190, v190
	v_rcp_f32_e32 v191, v191
	v_fma_f32 v200, v184, v192, v218
	v_fma_f32 v201, v185, v193, v219
	v_fma_f32 v202, v186, v194, v220
	v_fma_f32 v203, v187, v195, v221
	v_fma_f32 v204, v188, v196, v222
	v_fma_f32 v205, v189, v197, v223
	v_fma_f32 v206, v190, v198, v224
	v_fma_f32 v207, v191, v199, v225
	v_cmp_gt_f32_e64 vcc, s35, v200
	v_cmp_gt_f32_e64 s[38:39], s35, v201
	v_cmp_gt_f32_e64 s[48:49], s35, v202
	v_cmp_gt_f32_e64 s[50:51], s35, v203
	v_cndmask_b32_e64 v184, 0, 32, vcc
	v_cndmask_b32_e64 v185, 0, 32, s[38:39]
	v_cndmask_b32_e64 v186, 0, 32, s[48:49]
	v_cndmask_b32_e64 v187, 0, 32, s[50:51]
	v_cndmask_b32_e64 v192, 0, v214, vcc
	v_cndmask_b32_e64 v193, 0, v214, s[38:39]
	v_cndmask_b32_e64 v194, 0, v214, s[48:49]
	v_cndmask_b32_e64 v195, 0, v214, s[50:51]
	v_cmp_gt_f32_e64 vcc, s35, v204
	v_cmp_gt_f32_e64 s[38:39], s35, v205
	v_cmp_gt_f32_e64 s[48:49], s35, v206
	v_cmp_gt_f32_e64 s[50:51], s35, v207
	v_cndmask_b32_e64 v188, 0, 32, vcc
; __device__ __forceinline__ unsigned cvt_pk_bf16(float lo, float hi) { unsigned r; asm volatile("v_cvt_pk_bf16_f32 %0, %1, %2" : "=v"(r) : "v"(lo), "v"(hi)); return r; }
; __device__ __forceinline__ float silu_f(float v) { return v * __builtin_amdgcn_rcpf(1.f + __expf(-v)); }
;     __device__ __forceinline__ void operator()(const f32x4 (&acc)[2][2][4][2], const Unit& u, int wr, int wc, int fr, int fq, int ui, PG8_LAS unsigned char* lds) const {
;     ...
;                         f32x4 lbv = (f32x4){0.f, 0.f, 0.f, 0.f};
;                         if (act == 2) lbv = *(const f32x4*)(lb + (col0 - 1024) + bj * HALF + 4 * n);
; #pragma unroll
;                         for (int e = 0; e < 4; ++e) {
;                             float x = v[n][e];
;                             if (act == 1) x = silu_f(x);
;                             else if (act == 2) { const float l = lbv[e]; x = __logf(l + (1.f - l) * __builtin_amdgcn_rcpf(1.f + __expf(-x))); }
;                             else if (act == 3) { x = fmaxf(x, 0.f); x = x * x; }
;                             v[n][e] = x;
;                         }
;                     }
;                     u32x4 w; w.x = cvt_pk_bf16(v[0][0], v[0][1]); w.y = cvt_pk_bf16(v[0][2], v[0][3]); w.z = cvt_pk_bf16(v[1][0], v[1][1]); w.w = cvt_pk_bf16(v[1][2], v[1][3]);
;                     *(u32x4*)(rowp + bj * HALF) = w;
	v_cndmask_b32_e64 v189, 0, 32, s[38:39]
	v_cndmask_b32_e64 v190, 0, 32, s[48:49]
	v_cndmask_b32_e64 v191, 0, 32, s[50:51]
	v_cndmask_b32_e64 v196, 0, v214, vcc
	v_cndmask_b32_e64 v197, 0, v214, s[38:39]
	v_cndmask_b32_e64 v198, 0, v214, s[48:49]
	v_cndmask_b32_e64 v199, 0, v214, s[50:51]
	v_ldexp_f32 v184, v200, v184
	v_ldexp_f32 v185, v201, v185
	v_ldexp_f32 v186, v202, v186
	v_ldexp_f32 v187, v203, v187
	v_ldexp_f32 v188, v204, v188
	v_ldexp_f32 v189, v205, v189
	v_ldexp_f32 v190, v206, v190
	v_ldexp_f32 v191, v207, v191
	v_log_f32_e32 v184, v184
	v_log_f32_e32 v185, v185
	v_log_f32_e32 v186, v186
	v_log_f32_e32 v187, v187
	v_log_f32_e32 v188, v188
	v_log_f32_e32 v189, v189
	v_log_f32_e32 v190, v190
	v_log_f32_e32 v191, v191
	v_mul_f32_e32 v200, 0x3f317217, v184
	v_mul_f32_e32 v201, 0x3f317217, v185
	v_mul_f32_e32 v202, 0x3f317217, v186
	v_mul_f32_e32 v203, 0x3f317217, v187
	v_mul_f32_e32 v204, 0x3f317217, v188
	v_mul_f32_e32 v205, 0x3f317217, v189
	v_mul_f32_e32 v206, 0x3f317217, v190
	v_mul_f32_e32 v207, 0x3f317217, v191
	v_fma_f32 v200, v184, s13, -v200
	v_fma_f32 v201, v185, s13, -v201
	v_fma_f32 v202, v186, s13, -v202
	v_fma_f32 v203, v187, s13, -v203
	v_fma_f32 v204, v188, s13, -v204
	v_fma_f32 v205, v189, s13, -v205
	v_fma_f32 v206, v190, s13, -v206
	v_fma_f32 v207, v191, s13, -v207
	v_fmac_f32_e32 v200, 0x3377d1cf, v184
	v_fmac_f32_e32 v201, 0x3377d1cf, v185
	v_fmac_f32_e32 v202, 0x3377d1cf, v186
	v_fmac_f32_e32 v203, 0x3377d1cf, v187
	v_fmac_f32_e32 v204, 0x3377d1cf, v188
	v_fmac_f32_e32 v205, 0x3377d1cf, v189
	v_fmac_f32_e32 v206, 0x3377d1cf, v190
	v_fmac_f32_e32 v207, 0x3377d1cf, v191
	v_fmac_f32_e32 v200, 0x3f317217, v184
	v_fmac_f32_e32 v201, 0x3f317217, v185
	v_fmac_f32_e32 v202, 0x3f317217, v186
	v_fmac_f32_e32 v203, 0x3f317217, v187
	v_fmac_f32_e32 v204, 0x3f317217, v188
	v_fmac_f32_e32 v205, 0x3f317217, v189
	v_fmac_f32_e32 v206, 0x3f317217, v190
	v_fmac_f32_e32 v207, 0x3f317217, v191
	v_cmp_lt_f32_e64 vcc, |v184|, s36
	v_cmp_lt_f32_e64 s[38:39], |v185|, s36
	v_cmp_lt_f32_e64 s[48:49], |v186|, s36
	v_cmp_lt_f32_e64 s[50:51], |v187|, s36
	v_cndmask_b32_e64 v184, v184, v200, vcc
	v_cndmask_b32_e64 v185, v185, v201, s[38:39]
	v_cndmask_b32_e64 v186, v186, v202, s[48:49]
	v_cndmask_b32_e64 v187, v187, v203, s[50:51]
	v_cmp_lt_f32_e64 vcc, |v188|, s36
	v_cmp_lt_f32_e64 s[38:39], |v189|, s36
	v_cmp_lt_f32_e64 s[48:49], |v190|, s36
	v_cmp_lt_f32_e64 s[50:51], |v191|, s36
	v_cndmask_b32_e64 v188, v188, v204, vcc
	v_cndmask_b32_e64 v189, v189, v205, s[38:39]
	v_cndmask_b32_e64 v190, v190, v206, s[48:49]
	v_cndmask_b32_e64 v191, v191, v207, s[50:51]
	v_sub_f32_e32 v116, v184, v192
	v_sub_f32_e32 v117, v185, v193
	v_sub_f32_e32 v118, v186, v194
	v_sub_f32_e32 v119, v187, v195
	v_sub_f32_e32 v112, v188, v196
	v_sub_f32_e32 v113, v189, v197
	v_sub_f32_e32 v114, v190, v198
	v_sub_f32_e32 v115, v191, v199
	v_cvt_pk_bf16_f32 v116, v116, v117
	v_cvt_pk_bf16_f32 v117, v118, v119
	v_cvt_pk_bf16_f32 v118, v112, v113
	v_cvt_pk_bf16_f32 v119, v114, v115
	global_store_dwordx4 v[162:163], v[116:119], off offset:256
	s_cmp_eq_u64 s[68:69], 0
	s_cbranch_scc1 .Lal1lo_skip
	s_barrier
.Lal1lo_skip:
	v_lshl_add_u64 v[176:177], v[162:163], 0, s[46:47]
	v_mul_f32_e32 v108, v108, v130
	v_mul_f32_e32 v109, v109, v130
	v_mul_f32_e32 v110, v110, v130
	v_mul_f32_e32 v111, v111, v130
	v_mul_f32_e32 v104, v104, v130
	v_mul_f32_e32 v105, v105, v130
	v_mul_f32_e32 v106, v106, v130
	v_mul_f32_e32 v107, v107, v130
	v_mul_f32_e32 v184, 0xbfb8aa3b, v108
	v_mul_f32_e32 v185, 0xbfb8aa3b, v109
	v_mul_f32_e32 v186, 0xbfb8aa3b, v110
	v_mul_f32_e32 v187, 0xbfb8aa3b, v111
	v_mul_f32_e32 v188, 0xbfb8aa3b, v104
	v_mul_f32_e32 v189, 0xbfb8aa3b, v105
	v_mul_f32_e32 v190, 0xbfb8aa3b, v106
	v_mul_f32_e32 v191, 0xbfb8aa3b, v107
	v_exp_f32_e32 v184, v184
	v_exp_f32_e32 v185, v185
	v_exp_f32_e32 v186, v186
	v_exp_f32_e32 v187, v187
	v_exp_f32_e32 v188, v188
	v_exp_f32_e32 v189, v189
	v_exp_f32_e32 v190, v190
	v_exp_f32_e32 v191, v191
	v_sub_f32_e32 v192, 1.0, v152
	v_sub_f32_e32 v193, 1.0, v153
	v_sub_f32_e32 v194, 1.0, v154
	v_sub_f32_e32 v195, 1.0, v155
	v_sub_f32_e32 v196, 1.0, v180
	v_sub_f32_e32 v197, 1.0, v181
	v_sub_f32_e32 v198, 1.0, v182
	v_sub_f32_e32 v199, 1.0, v183
	v_add_f32_e32 v184, 1.0, v184
	v_add_f32_e32 v185, 1.0, v185
	v_add_f32_e32 v186, 1.0, v186
	v_add_f32_e32 v187, 1.0, v187
	v_add_f32_e32 v188, 1.0, v188
	v_add_f32_e32 v189, 1.0, v189
	v_add_f32_e32 v190, 1.0, v190
	v_add_f32_e32 v191, 1.0, v191
	v_rcp_f32_e32 v184, v184
	v_rcp_f32_e32 v185, v185
	v_rcp_f32_e32 v186, v186
	v_rcp_f32_e32 v187, v187
	v_rcp_f32_e32 v188, v188
	v_rcp_f32_e32 v189, v189
	v_rcp_f32_e32 v190, v190
	v_rcp_f32_e32 v191, v191
	v_fma_f32 v200, v184, v192, v152
	v_fma_f32 v201, v185, v193, v153
	v_fma_f32 v202, v186, v194, v154
	v_fma_f32 v203, v187, v195, v155
	v_fma_f32 v204, v188, v196, v180
	v_fma_f32 v205, v189, v197, v181
	v_fma_f32 v206, v190, v198, v182
	v_fma_f32 v207, v191, v199, v183
	v_cmp_gt_f32_e64 vcc, s35, v200
	v_cmp_gt_f32_e64 s[38:39], s35, v201
	v_cmp_gt_f32_e64 s[48:49], s35, v202
	v_cmp_gt_f32_e64 s[50:51], s35, v203
	v_cndmask_b32_e64 v184, 0, 32, vcc
	v_cndmask_b32_e64 v185, 0, 32, s[38:39]
	v_cndmask_b32_e64 v186, 0, 32, s[48:49]
	v_cndmask_b32_e64 v187, 0, 32, s[50:51]
	v_cndmask_b32_e64 v192, 0, v214, vcc
	v_cndmask_b32_e64 v193, 0, v214, s[38:39]
	v_cndmask_b32_e64 v194, 0, v214, s[48:49]
	v_cndmask_b32_e64 v195, 0, v214, s[50:51]
	v_cmp_gt_f32_e64 vcc, s35, v204
	v_cmp_gt_f32_e64 s[38:39], s35, v205
	v_cmp_gt_f32_e64 s[48:49], s35, v206
	v_cmp_gt_f32_e64 s[50:51], s35, v207
	v_cndmask_b32_e64 v188, 0, 32, vcc
	v_cndmask_b32_e64 v189, 0, 32, s[38:39]
; __device__ __forceinline__ unsigned cvt_pk_bf16(float lo, float hi) { unsigned r; asm volatile("v_cvt_pk_bf16_f32 %0, %1, %2" : "=v"(r) : "v"(lo), "v"(hi)); return r; }
; __device__ __forceinline__ float silu_f(float v) { return v * __builtin_amdgcn_rcpf(1.f + __expf(-v)); }
;     __device__ __forceinline__ void operator()(const f32x4 (&acc)[2][2][4][2], const Unit& u, int wr, int wc, int fr, int fq, int ui, PG8_LAS unsigned char* lds) const {
;     ...
;                         f32x4 lbv = (f32x4){0.f, 0.f, 0.f, 0.f};
;                         if (act == 2) lbv = *(const f32x4*)(lb + (col0 - 1024) + bj * HALF + 4 * n);
; #pragma unroll
;                         for (int e = 0; e < 4; ++e) {
;                             float x = v[n][e];
;                             if (act == 1) x = silu_f(x);
;                             else if (act == 2) { const float l = lbv[e]; x = __logf(l + (1.f - l) * __builtin_amdgcn_rcpf(1.f + __expf(-x))); }
;                             else if (act == 3) { x = fmaxf(x, 0.f); x = x * x; }
;                             v[n][e] = x;
;                         }
;                     }
;                     u32x4 w; w.x = cvt_pk_bf16(v[0][0], v[0][1]); w.y = cvt_pk_bf16(v[0][2], v[0][3]); w.z = cvt_pk_bf16(v[1][0], v[1][1]); w.w = cvt_pk_bf16(v[1][2], v[1][3]);
;                     *(u32x4*)(rowp + bj * HALF) = w;
	v_cndmask_b32_e64 v190, 0, 32, s[48:49]
	v_cndmask_b32_e64 v191, 0, 32, s[50:51]
	v_cndmask_b32_e64 v196, 0, v214, vcc
	v_cndmask_b32_e64 v197, 0, v214, s[38:39]
	v_cndmask_b32_e64 v198, 0, v214, s[48:49]
	v_cndmask_b32_e64 v199, 0, v214, s[50:51]
	v_ldexp_f32 v184, v200, v184
	v_ldexp_f32 v185, v201, v185
	v_ldexp_f32 v186, v202, v186
	v_ldexp_f32 v187, v203, v187
	v_ldexp_f32 v188, v204, v188
	v_ldexp_f32 v189, v205, v189
	v_ldexp_f32 v190, v206, v190
	v_ldexp_f32 v191, v207, v191
	v_log_f32_e32 v184, v184
	v_log_f32_e32 v185, v185
	v_log_f32_e32 v186, v186
	v_log_f32_e32 v187, v187
	v_log_f32_e32 v188, v188
	v_log_f32_e32 v189, v189
	v_log_f32_e32 v190, v190
	v_log_f32_e32 v191, v191
	v_mul_f32_e32 v200, 0x3f317217, v184
	v_mul_f32_e32 v201, 0x3f317217, v185
	v_mul_f32_e32 v202, 0x3f317217, v186
	v_mul_f32_e32 v203, 0x3f317217, v187
	v_mul_f32_e32 v204, 0x3f317217, v188
	v_mul_f32_e32 v205, 0x3f317217, v189
	v_mul_f32_e32 v206, 0x3f317217, v190
	v_mul_f32_e32 v207, 0x3f317217, v191
	v_fma_f32 v200, v184, s13, -v200
	v_fma_f32 v201, v185, s13, -v201
	v_fma_f32 v202, v186, s13, -v202
	v_fma_f32 v203, v187, s13, -v203
	v_fma_f32 v204, v188, s13, -v204
	v_fma_f32 v205, v189, s13, -v205
	v_fma_f32 v206, v190, s13, -v206
	v_fma_f32 v207, v191, s13, -v207
	v_fmac_f32_e32 v200, 0x3377d1cf, v184
	v_fmac_f32_e32 v201, 0x3377d1cf, v185
	v_fmac_f32_e32 v202, 0x3377d1cf, v186
	v_fmac_f32_e32 v203, 0x3377d1cf, v187
	v_fmac_f32_e32 v204, 0x3377d1cf, v188
	v_fmac_f32_e32 v205, 0x3377d1cf, v189
	v_fmac_f32_e32 v206, 0x3377d1cf, v190
	v_fmac_f32_e32 v207, 0x3377d1cf, v191
	v_fmac_f32_e32 v200, 0x3f317217, v184
	v_fmac_f32_e32 v201, 0x3f317217, v185
	v_fmac_f32_e32 v202, 0x3f317217, v186
	v_fmac_f32_e32 v203, 0x3f317217, v187
	v_fmac_f32_e32 v204, 0x3f317217, v188
	v_fmac_f32_e32 v205, 0x3f317217, v189
	v_fmac_f32_e32 v206, 0x3f317217, v190
	v_fmac_f32_e32 v207, 0x3f317217, v191
	v_cmp_lt_f32_e64 vcc, |v184|, s36
	v_cmp_lt_f32_e64 s[38:39], |v185|, s36
	v_cmp_lt_f32_e64 s[48:49], |v186|, s36
	v_cmp_lt_f32_e64 s[50:51], |v187|, s36
	v_cndmask_b32_e64 v184, v184, v200, vcc
	v_cndmask_b32_e64 v185, v185, v201, s[38:39]
	v_cndmask_b32_e64 v186, v186, v202, s[48:49]
	v_cndmask_b32_e64 v187, v187, v203, s[50:51]
	v_cmp_lt_f32_e64 vcc, |v188|, s36
	v_cmp_lt_f32_e64 s[38:39], |v189|, s36
	v_cmp_lt_f32_e64 s[48:49], |v190|, s36
	v_cmp_lt_f32_e64 s[50:51], |v191|, s36
	v_cndmask_b32_e64 v188, v188, v204, vcc
	v_cndmask_b32_e64 v189, v189, v205, s[38:39]
	v_cndmask_b32_e64 v190, v190, v206, s[48:49]
	v_cndmask_b32_e64 v191, v191, v207, s[50:51]
	v_sub_f32_e32 v108, v184, v192
	v_sub_f32_e32 v109, v185, v193
	v_sub_f32_e32 v110, v186, v194
	v_sub_f32_e32 v111, v187, v195
	v_sub_f32_e32 v104, v188, v196
	v_sub_f32_e32 v105, v189, v197
	v_sub_f32_e32 v106, v190, v198
	v_sub_f32_e32 v107, v191, v199
	v_cvt_pk_bf16_f32 v108, v108, v109
	v_cvt_pk_bf16_f32 v109, v110, v111
	v_cvt_pk_bf16_f32 v110, v104, v105
	v_cvt_pk_bf16_f32 v111, v106, v107
	global_store_dwordx4 v[176:177], v[108:111], off
	v_mul_f32_e32 v100, v100, v130
	v_mul_f32_e32 v101, v101, v130
	v_mul_f32_e32 v102, v102, v130
	v_mul_f32_e32 v103, v103, v130
	v_mul_f32_e32 v96, v96, v130
	v_mul_f32_e32 v97, v97, v130
	v_mul_f32_e32 v98, v98, v130
	v_mul_f32_e32 v99, v99, v130
	v_mul_f32_e32 v184, 0xbfb8aa3b, v100
	v_mul_f32_e32 v185, 0xbfb8aa3b, v101
	v_mul_f32_e32 v186, 0xbfb8aa3b, v102
	v_mul_f32_e32 v187, 0xbfb8aa3b, v103
	v_mul_f32_e32 v188, 0xbfb8aa3b, v96
	v_mul_f32_e32 v189, 0xbfb8aa3b, v97
	v_mul_f32_e32 v190, 0xbfb8aa3b, v98
	v_mul_f32_e32 v191, 0xbfb8aa3b, v99
	v_exp_f32_e32 v184, v184
	v_exp_f32_e32 v185, v185
	v_exp_f32_e32 v186, v186
	v_exp_f32_e32 v187, v187
	v_exp_f32_e32 v188, v188
	v_exp_f32_e32 v189, v189
	v_exp_f32_e32 v190, v190
	v_exp_f32_e32 v191, v191
	v_sub_f32_e32 v192, 1.0, v218
	v_sub_f32_e32 v193, 1.0, v219
	v_sub_f32_e32 v194, 1.0, v220
	v_sub_f32_e32 v195, 1.0, v221
	v_sub_f32_e32 v196, 1.0, v222
	v_sub_f32_e32 v197, 1.0, v223
	v_sub_f32_e32 v198, 1.0, v224
	v_sub_f32_e32 v199, 1.0, v225
	v_add_f32_e32 v184, 1.0, v184
	v_add_f32_e32 v185, 1.0, v185
	v_add_f32_e32 v186, 1.0, v186
	v_add_f32_e32 v187, 1.0, v187
	v_add_f32_e32 v188, 1.0, v188
	v_add_f32_e32 v189, 1.0, v189
	v_add_f32_e32 v190, 1.0, v190
	v_add_f32_e32 v191, 1.0, v191
	v_rcp_f32_e32 v184, v184
	v_rcp_f32_e32 v185, v185
	v_rcp_f32_e32 v186, v186
	v_rcp_f32_e32 v187, v187
	v_rcp_f32_e32 v188, v188
	v_rcp_f32_e32 v189, v189
	v_rcp_f32_e32 v190, v190
	v_rcp_f32_e32 v191, v191
	v_fma_f32 v200, v184, v192, v218
	v_fma_f32 v201, v185, v193, v219
	v_fma_f32 v202, v186, v194, v220
	v_fma_f32 v203, v187, v195, v221
	v_fma_f32 v204, v188, v196, v222
	v_fma_f32 v205, v189, v197, v223
	v_fma_f32 v206, v190, v198, v224
	v_fma_f32 v207, v191, v199, v225
	v_cmp_gt_f32_e64 vcc, s35, v200
	v_cmp_gt_f32_e64 s[38:39], s35, v201
	v_cmp_gt_f32_e64 s[48:49], s35, v202
	v_cmp_gt_f32_e64 s[50:51], s35, v203
	v_cndmask_b32_e64 v184, 0, 32, vcc
	v_cndmask_b32_e64 v185, 0, 32, s[38:39]
	v_cndmask_b32_e64 v186, 0, 32, s[48:49]
	v_cndmask_b32_e64 v187, 0, 32, s[50:51]
	v_cndmask_b32_e64 v192, 0, v214, vcc
	v_cndmask_b32_e64 v193, 0, v214, s[38:39]
	v_cndmask_b32_e64 v194, 0, v214, s[48:49]
	v_cndmask_b32_e64 v195, 0, v214, s[50:51]
	v_cmp_gt_f32_e64 vcc, s35, v204
	v_cmp_gt_f32_e64 s[38:39], s35, v205
	v_cmp_gt_f32_e64 s[48:49], s35, v206
	v_cmp_gt_f32_e64 s[50:51], s35, v207
	v_cndmask_b32_e64 v188, 0, 32, vcc
	v_cndmask_b32_e64 v189, 0, 32, s[38:39]
	v_cndmask_b32_e64 v190, 0, 32, s[48:49]
	v_cndmask_b32_e64 v191, 0, 32, s[50:51]
	v_cndmask_b32_e64 v196, 0, v214, vcc
	v_cndmask_b32_e64 v197, 0, v214, s[38:39]
	v_cndmask_b32_e64 v198, 0, v214, s[48:49]
; __device__ __forceinline__ unsigned cvt_pk_bf16(float lo, float hi) { unsigned r; asm volatile("v_cvt_pk_bf16_f32 %0, %1, %2" : "=v"(r) : "v"(lo), "v"(hi)); return r; }
; __device__ __forceinline__ float silu_f(float v) { return v * __builtin_amdgcn_rcpf(1.f + __expf(-v)); }
;     __device__ __forceinline__ void operator()(const f32x4 (&acc)[2][2][4][2], const Unit& u, int wr, int wc, int fr, int fq, int ui, PG8_LAS unsigned char* lds) const {
;     ...
;                         f32x4 lbv = (f32x4){0.f, 0.f, 0.f, 0.f};
;                         if (act == 2) lbv = *(const f32x4*)(lb + (col0 - 1024) + bj * HALF + 4 * n);
; #pragma unroll
;                         for (int e = 0; e < 4; ++e) {
;                             float x = v[n][e];
;                             if (act == 1) x = silu_f(x);
;                             else if (act == 2) { const float l = lbv[e]; x = __logf(l + (1.f - l) * __builtin_amdgcn_rcpf(1.f + __expf(-x))); }
;                             else if (act == 3) { x = fmaxf(x, 0.f); x = x * x; }
;                             v[n][e] = x;
;                         }
;                     }
;                     u32x4 w; w.x = cvt_pk_bf16(v[0][0], v[0][1]); w.y = cvt_pk_bf16(v[0][2], v[0][3]); w.z = cvt_pk_bf16(v[1][0], v[1][1]); w.w = cvt_pk_bf16(v[1][2], v[1][3]);
;                     *(u32x4*)(rowp + bj * HALF) = w;
	v_cndmask_b32_e64 v199, 0, v214, s[50:51]
	v_ldexp_f32 v184, v200, v184
	v_ldexp_f32 v185, v201, v185
	v_ldexp_f32 v186, v202, v186
	v_ldexp_f32 v187, v203, v187
	v_ldexp_f32 v188, v204, v188
	v_ldexp_f32 v189, v205, v189
	v_ldexp_f32 v190, v206, v190
	v_ldexp_f32 v191, v207, v191
	v_log_f32_e32 v184, v184
	v_log_f32_e32 v185, v185
	v_log_f32_e32 v186, v186
	v_log_f32_e32 v187, v187
	v_log_f32_e32 v188, v188
	v_log_f32_e32 v189, v189
	v_log_f32_e32 v190, v190
	v_log_f32_e32 v191, v191
	v_mul_f32_e32 v200, 0x3f317217, v184
	v_mul_f32_e32 v201, 0x3f317217, v185
	v_mul_f32_e32 v202, 0x3f317217, v186
	v_mul_f32_e32 v203, 0x3f317217, v187
	v_mul_f32_e32 v204, 0x3f317217, v188
	v_mul_f32_e32 v205, 0x3f317217, v189
	v_mul_f32_e32 v206, 0x3f317217, v190
	v_mul_f32_e32 v207, 0x3f317217, v191
	v_fma_f32 v200, v184, s13, -v200
	v_fma_f32 v201, v185, s13, -v201
	v_fma_f32 v202, v186, s13, -v202
	v_fma_f32 v203, v187, s13, -v203
	v_fma_f32 v204, v188, s13, -v204
	v_fma_f32 v205, v189, s13, -v205
	v_fma_f32 v206, v190, s13, -v206
	v_fma_f32 v207, v191, s13, -v207
	v_fmac_f32_e32 v200, 0x3377d1cf, v184
	v_fmac_f32_e32 v201, 0x3377d1cf, v185
	v_fmac_f32_e32 v202, 0x3377d1cf, v186
	v_fmac_f32_e32 v203, 0x3377d1cf, v187
	v_fmac_f32_e32 v204, 0x3377d1cf, v188
	v_fmac_f32_e32 v205, 0x3377d1cf, v189
	v_fmac_f32_e32 v206, 0x3377d1cf, v190
	v_fmac_f32_e32 v207, 0x3377d1cf, v191
	v_fmac_f32_e32 v200, 0x3f317217, v184
	v_fmac_f32_e32 v201, 0x3f317217, v185
	v_fmac_f32_e32 v202, 0x3f317217, v186
	v_fmac_f32_e32 v203, 0x3f317217, v187
	v_fmac_f32_e32 v204, 0x3f317217, v188
	v_fmac_f32_e32 v205, 0x3f317217, v189
	v_fmac_f32_e32 v206, 0x3f317217, v190
	v_fmac_f32_e32 v207, 0x3f317217, v191
	v_cmp_lt_f32_e64 vcc, |v184|, s36
	v_cmp_lt_f32_e64 s[38:39], |v185|, s36
	v_cmp_lt_f32_e64 s[48:49], |v186|, s36
	v_cmp_lt_f32_e64 s[50:51], |v187|, s36
	v_cndmask_b32_e64 v184, v184, v200, vcc
	v_cndmask_b32_e64 v185, v185, v201, s[38:39]
	v_cndmask_b32_e64 v186, v186, v202, s[48:49]
	v_cndmask_b32_e64 v187, v187, v203, s[50:51]
	v_cmp_lt_f32_e64 vcc, |v188|, s36
	v_cmp_lt_f32_e64 s[38:39], |v189|, s36
	v_cmp_lt_f32_e64 s[48:49], |v190|, s36
	v_cmp_lt_f32_e64 s[50:51], |v191|, s36
	v_cndmask_b32_e64 v188, v188, v204, vcc
	v_cndmask_b32_e64 v189, v189, v205, s[38:39]
	v_cndmask_b32_e64 v190, v190, v206, s[48:49]
	v_cndmask_b32_e64 v191, v191, v207, s[50:51]
	v_sub_f32_e32 v100, v184, v192
	v_sub_f32_e32 v101, v185, v193
	v_sub_f32_e32 v102, v186, v194
	v_sub_f32_e32 v103, v187, v195
	v_sub_f32_e32 v96, v188, v196
	v_sub_f32_e32 v97, v189, v197
	v_sub_f32_e32 v98, v190, v198
	v_sub_f32_e32 v99, v191, v199
	v_cvt_pk_bf16_f32 v100, v100, v101
	v_cvt_pk_bf16_f32 v101, v102, v103
	v_cvt_pk_bf16_f32 v102, v96, v97
	v_cvt_pk_bf16_f32 v103, v98, v99
	global_store_dwordx4 v[176:177], v[100:103], off offset:256
	v_lshl_add_u64 v[162:163], v[176:177], 0, s[46:47]
	v_mul_f32_e32 v92, v92, v144
	v_mul_f32_e32 v93, v93, v144
	v_mul_f32_e32 v94, v94, v144
	v_mul_f32_e32 v95, v95, v144
	v_mul_f32_e32 v88, v88, v144
	v_mul_f32_e32 v89, v89, v144
	v_mul_f32_e32 v90, v90, v144
	v_mul_f32_e32 v91, v91, v144
	v_mul_f32_e32 v184, 0xbfb8aa3b, v92
	v_mul_f32_e32 v185, 0xbfb8aa3b, v93
	v_mul_f32_e32 v186, 0xbfb8aa3b, v94
	v_mul_f32_e32 v187, 0xbfb8aa3b, v95
	v_mul_f32_e32 v188, 0xbfb8aa3b, v88
	v_mul_f32_e32 v189, 0xbfb8aa3b, v89
	v_mul_f32_e32 v190, 0xbfb8aa3b, v90
	v_mul_f32_e32 v191, 0xbfb8aa3b, v91
	v_exp_f32_e32 v184, v184
	v_exp_f32_e32 v185, v185
	v_exp_f32_e32 v186, v186
	v_exp_f32_e32 v187, v187
	v_exp_f32_e32 v188, v188
	v_exp_f32_e32 v189, v189
	v_exp_f32_e32 v190, v190
	v_exp_f32_e32 v191, v191
	v_sub_f32_e32 v192, 1.0, v152
	v_sub_f32_e32 v193, 1.0, v153
	v_sub_f32_e32 v194, 1.0, v154
	v_sub_f32_e32 v195, 1.0, v155
	v_sub_f32_e32 v196, 1.0, v180
	v_sub_f32_e32 v197, 1.0, v181
	v_sub_f32_e32 v198, 1.0, v182
	v_sub_f32_e32 v199, 1.0, v183
	v_add_f32_e32 v184, 1.0, v184
	v_add_f32_e32 v185, 1.0, v185
	v_add_f32_e32 v186, 1.0, v186
	v_add_f32_e32 v187, 1.0, v187
	v_add_f32_e32 v188, 1.0, v188
	v_add_f32_e32 v189, 1.0, v189
	v_add_f32_e32 v190, 1.0, v190
	v_add_f32_e32 v191, 1.0, v191
	v_rcp_f32_e32 v184, v184
	v_rcp_f32_e32 v185, v185
	v_rcp_f32_e32 v186, v186
	v_rcp_f32_e32 v187, v187
	v_rcp_f32_e32 v188, v188
	v_rcp_f32_e32 v189, v189
	v_rcp_f32_e32 v190, v190
	v_rcp_f32_e32 v191, v191
	v_fma_f32 v200, v184, v192, v152
	v_fma_f32 v201, v185, v193, v153
	v_fma_f32 v202, v186, v194, v154
	v_fma_f32 v203, v187, v195, v155
	v_fma_f32 v204, v188, v196, v180
	v_fma_f32 v205, v189, v197, v181
	v_fma_f32 v206, v190, v198, v182
	v_fma_f32 v207, v191, v199, v183
	v_cmp_gt_f32_e64 vcc, s35, v200
	v_cmp_gt_f32_e64 s[38:39], s35, v201
	v_cmp_gt_f32_e64 s[48:49], s35, v202
	v_cmp_gt_f32_e64 s[50:51], s35, v203
	v_cndmask_b32_e64 v184, 0, 32, vcc
	v_cndmask_b32_e64 v185, 0, 32, s[38:39]
	v_cndmask_b32_e64 v186, 0, 32, s[48:49]
	v_cndmask_b32_e64 v187, 0, 32, s[50:51]
	v_cndmask_b32_e64 v192, 0, v214, vcc
	v_cndmask_b32_e64 v193, 0, v214, s[38:39]
	v_cndmask_b32_e64 v194, 0, v214, s[48:49]
	v_cndmask_b32_e64 v195, 0, v214, s[50:51]
	v_cmp_gt_f32_e64 vcc, s35, v204
	v_cmp_gt_f32_e64 s[38:39], s35, v205
	v_cmp_gt_f32_e64 s[48:49], s35, v206
	v_cmp_gt_f32_e64 s[50:51], s35, v207
	v_cndmask_b32_e64 v188, 0, 32, vcc
	v_cndmask_b32_e64 v189, 0, 32, s[38:39]
	v_cndmask_b32_e64 v190, 0, 32, s[48:49]
	v_cndmask_b32_e64 v191, 0, 32, s[50:51]
	v_cndmask_b32_e64 v196, 0, v214, vcc
	v_cndmask_b32_e64 v197, 0, v214, s[38:39]
	v_cndmask_b32_e64 v198, 0, v214, s[48:49]
	v_cndmask_b32_e64 v199, 0, v214, s[50:51]
	v_ldexp_f32 v184, v200, v184
	v_ldexp_f32 v185, v201, v185
	v_ldexp_f32 v186, v202, v186
	v_ldexp_f32 v187, v203, v187
; __device__ __forceinline__ unsigned cvt_pk_bf16(float lo, float hi) { unsigned r; asm volatile("v_cvt_pk_bf16_f32 %0, %1, %2" : "=v"(r) : "v"(lo), "v"(hi)); return r; }
; __device__ __forceinline__ float silu_f(float v) { return v * __builtin_amdgcn_rcpf(1.f + __expf(-v)); }
;     __device__ __forceinline__ void operator()(const f32x4 (&acc)[2][2][4][2], const Unit& u, int wr, int wc, int fr, int fq, int ui, PG8_LAS unsigned char* lds) const {
;     ...
;                         f32x4 lbv = (f32x4){0.f, 0.f, 0.f, 0.f};
;                         if (act == 2) lbv = *(const f32x4*)(lb + (col0 - 1024) + bj * HALF + 4 * n);
; #pragma unroll
;                         for (int e = 0; e < 4; ++e) {
;                             float x = v[n][e];
;                             if (act == 1) x = silu_f(x);
;                             else if (act == 2) { const float l = lbv[e]; x = __logf(l + (1.f - l) * __builtin_amdgcn_rcpf(1.f + __expf(-x))); }
;                             else if (act == 3) { x = fmaxf(x, 0.f); x = x * x; }
;                             v[n][e] = x;
;                         }
;                     }
;                     u32x4 w; w.x = cvt_pk_bf16(v[0][0], v[0][1]); w.y = cvt_pk_bf16(v[0][2], v[0][3]); w.z = cvt_pk_bf16(v[1][0], v[1][1]); w.w = cvt_pk_bf16(v[1][2], v[1][3]);
;                     *(u32x4*)(rowp + bj * HALF) = w;
	v_ldexp_f32 v188, v204, v188
	v_ldexp_f32 v189, v205, v189
	v_ldexp_f32 v190, v206, v190
	v_ldexp_f32 v191, v207, v191
	v_log_f32_e32 v184, v184
	v_log_f32_e32 v185, v185
	v_log_f32_e32 v186, v186
	v_log_f32_e32 v187, v187
	v_log_f32_e32 v188, v188
	v_log_f32_e32 v189, v189
	v_log_f32_e32 v190, v190
	v_log_f32_e32 v191, v191
	v_mul_f32_e32 v200, 0x3f317217, v184
	v_mul_f32_e32 v201, 0x3f317217, v185
	v_mul_f32_e32 v202, 0x3f317217, v186
	v_mul_f32_e32 v203, 0x3f317217, v187
	v_mul_f32_e32 v204, 0x3f317217, v188
	v_mul_f32_e32 v205, 0x3f317217, v189
	v_mul_f32_e32 v206, 0x3f317217, v190
	v_mul_f32_e32 v207, 0x3f317217, v191
	v_fma_f32 v200, v184, s13, -v200
	v_fma_f32 v201, v185, s13, -v201
	v_fma_f32 v202, v186, s13, -v202
	v_fma_f32 v203, v187, s13, -v203
	v_fma_f32 v204, v188, s13, -v204
	v_fma_f32 v205, v189, s13, -v205
	v_fma_f32 v206, v190, s13, -v206
	v_fma_f32 v207, v191, s13, -v207
	v_fmac_f32_e32 v200, 0x3377d1cf, v184
	v_fmac_f32_e32 v201, 0x3377d1cf, v185
	v_fmac_f32_e32 v202, 0x3377d1cf, v186
	v_fmac_f32_e32 v203, 0x3377d1cf, v187
	v_fmac_f32_e32 v204, 0x3377d1cf, v188
	v_fmac_f32_e32 v205, 0x3377d1cf, v189
	v_fmac_f32_e32 v206, 0x3377d1cf, v190
	v_fmac_f32_e32 v207, 0x3377d1cf, v191
	v_fmac_f32_e32 v200, 0x3f317217, v184
	v_fmac_f32_e32 v201, 0x3f317217, v185
	v_fmac_f32_e32 v202, 0x3f317217, v186
	v_fmac_f32_e32 v203, 0x3f317217, v187
	v_fmac_f32_e32 v204, 0x3f317217, v188
	v_fmac_f32_e32 v205, 0x3f317217, v189
	v_fmac_f32_e32 v206, 0x3f317217, v190
	v_fmac_f32_e32 v207, 0x3f317217, v191
	v_cmp_lt_f32_e64 vcc, |v184|, s36
	v_cmp_lt_f32_e64 s[38:39], |v185|, s36
	v_cmp_lt_f32_e64 s[48:49], |v186|, s36
	v_cmp_lt_f32_e64 s[50:51], |v187|, s36
	v_cndmask_b32_e64 v184, v184, v200, vcc
	v_cndmask_b32_e64 v185, v185, v201, s[38:39]
	v_cndmask_b32_e64 v186, v186, v202, s[48:49]
	v_cndmask_b32_e64 v187, v187, v203, s[50:51]
	v_cmp_lt_f32_e64 vcc, |v188|, s36
	v_cmp_lt_f32_e64 s[38:39], |v189|, s36
	v_cmp_lt_f32_e64 s[48:49], |v190|, s36
	v_cmp_lt_f32_e64 s[50:51], |v191|, s36
	v_cndmask_b32_e64 v188, v188, v204, vcc
	v_cndmask_b32_e64 v189, v189, v205, s[38:39]
	v_cndmask_b32_e64 v190, v190, v206, s[48:49]
	v_cndmask_b32_e64 v191, v191, v207, s[50:51]
	v_sub_f32_e32 v92, v184, v192
	v_sub_f32_e32 v93, v185, v193
	v_sub_f32_e32 v94, v186, v194
	v_sub_f32_e32 v95, v187, v195
	v_sub_f32_e32 v88, v188, v196
	v_sub_f32_e32 v89, v189, v197
	v_sub_f32_e32 v90, v190, v198
	v_sub_f32_e32 v91, v191, v199
	v_cvt_pk_bf16_f32 v92, v92, v93
	v_cvt_pk_bf16_f32 v93, v94, v95
	v_cvt_pk_bf16_f32 v94, v88, v89
	v_cvt_pk_bf16_f32 v95, v90, v91
	global_store_dwordx4 v[162:163], v[92:95], off
	v_mul_f32_e32 v84, v84, v144
	v_mul_f32_e32 v85, v85, v144
	v_mul_f32_e32 v86, v86, v144
	v_mul_f32_e32 v87, v87, v144
	v_mul_f32_e32 v80, v80, v144
	v_mul_f32_e32 v81, v81, v144
	v_mul_f32_e32 v82, v82, v144
	v_mul_f32_e32 v83, v83, v144
	v_mul_f32_e32 v184, 0xbfb8aa3b, v84
	v_mul_f32_e32 v185, 0xbfb8aa3b, v85
	v_mul_f32_e32 v186, 0xbfb8aa3b, v86
	v_mul_f32_e32 v187, 0xbfb8aa3b, v87
	v_mul_f32_e32 v188, 0xbfb8aa3b, v80
	v_mul_f32_e32 v189, 0xbfb8aa3b, v81
	v_mul_f32_e32 v190, 0xbfb8aa3b, v82
	v_mul_f32_e32 v191, 0xbfb8aa3b, v83
	v_exp_f32_e32 v184, v184
	v_exp_f32_e32 v185, v185
	v_exp_f32_e32 v186, v186
	v_exp_f32_e32 v187, v187
	v_exp_f32_e32 v188, v188
	v_exp_f32_e32 v189, v189
	v_exp_f32_e32 v190, v190
	v_exp_f32_e32 v191, v191
	v_sub_f32_e32 v192, 1.0, v218
	v_sub_f32_e32 v193, 1.0, v219
	v_sub_f32_e32 v194, 1.0, v220
	v_sub_f32_e32 v195, 1.0, v221
	v_sub_f32_e32 v196, 1.0, v222
	v_sub_f32_e32 v197, 1.0, v223
	v_sub_f32_e32 v198, 1.0, v224
	v_sub_f32_e32 v199, 1.0, v225
	v_add_f32_e32 v184, 1.0, v184
	v_add_f32_e32 v185, 1.0, v185
	v_add_f32_e32 v186, 1.0, v186
	v_add_f32_e32 v187, 1.0, v187
	v_add_f32_e32 v188, 1.0, v188
	v_add_f32_e32 v189, 1.0, v189
	v_add_f32_e32 v190, 1.0, v190
	v_add_f32_e32 v191, 1.0, v191
	v_rcp_f32_e32 v184, v184
	v_rcp_f32_e32 v185, v185
	v_rcp_f32_e32 v186, v186
	v_rcp_f32_e32 v187, v187
	v_rcp_f32_e32 v188, v188
	v_rcp_f32_e32 v189, v189
	v_rcp_f32_e32 v190, v190
	v_rcp_f32_e32 v191, v191
	v_fma_f32 v200, v184, v192, v218
	v_fma_f32 v201, v185, v193, v219
	v_fma_f32 v202, v186, v194, v220
	v_fma_f32 v203, v187, v195, v221
	v_fma_f32 v204, v188, v196, v222
	v_fma_f32 v205, v189, v197, v223
	v_fma_f32 v206, v190, v198, v224
	v_fma_f32 v207, v191, v199, v225
	v_cmp_gt_f32_e64 vcc, s35, v200
	v_cmp_gt_f32_e64 s[38:39], s35, v201
	v_cmp_gt_f32_e64 s[48:49], s35, v202
	v_cmp_gt_f32_e64 s[50:51], s35, v203
	v_cndmask_b32_e64 v184, 0, 32, vcc
	v_cndmask_b32_e64 v185, 0, 32, s[38:39]
	v_cndmask_b32_e64 v186, 0, 32, s[48:49]
	v_cndmask_b32_e64 v187, 0, 32, s[50:51]
	v_cndmask_b32_e64 v192, 0, v214, vcc
	v_cndmask_b32_e64 v193, 0, v214, s[38:39]
	v_cndmask_b32_e64 v194, 0, v214, s[48:49]
	v_cndmask_b32_e64 v195, 0, v214, s[50:51]
	v_cmp_gt_f32_e64 vcc, s35, v204
	v_cmp_gt_f32_e64 s[38:39], s35, v205
	v_cmp_gt_f32_e64 s[48:49], s35, v206
	v_cmp_gt_f32_e64 s[50:51], s35, v207
	v_cndmask_b32_e64 v188, 0, 32, vcc
	v_cndmask_b32_e64 v189, 0, 32, s[38:39]
	v_cndmask_b32_e64 v190, 0, 32, s[48:49]
	v_cndmask_b32_e64 v191, 0, 32, s[50:51]
	v_cndmask_b32_e64 v196, 0, v214, vcc
	v_cndmask_b32_e64 v197, 0, v214, s[38:39]
	v_cndmask_b32_e64 v198, 0, v214, s[48:49]
	v_cndmask_b32_e64 v199, 0, v214, s[50:51]
	v_ldexp_f32 v184, v200, v184
	v_ldexp_f32 v185, v201, v185
	v_ldexp_f32 v186, v202, v186
	v_ldexp_f32 v187, v203, v187
	v_ldexp_f32 v188, v204, v188
	v_ldexp_f32 v189, v205, v189
	v_ldexp_f32 v190, v206, v190
	v_ldexp_f32 v191, v207, v191
	v_log_f32_e32 v184, v184
	v_log_f32_e32 v185, v185
	v_log_f32_e32 v186, v186
	v_log_f32_e32 v187, v187
; __device__ __forceinline__ unsigned cvt_pk_bf16(float lo, float hi) { unsigned r; asm volatile("v_cvt_pk_bf16_f32 %0, %1, %2" : "=v"(r) : "v"(lo), "v"(hi)); return r; }
; __device__ __forceinline__ float silu_f(float v) { return v * __builtin_amdgcn_rcpf(1.f + __expf(-v)); }
;     __device__ __forceinline__ void operator()(const f32x4 (&acc)[2][2][4][2], const Unit& u, int wr, int wc, int fr, int fq, int ui, PG8_LAS unsigned char* lds) const {
;     ...
;                         f32x4 lbv = (f32x4){0.f, 0.f, 0.f, 0.f};
;                         if (act == 2) lbv = *(const f32x4*)(lb + (col0 - 1024) + bj * HALF + 4 * n);
; #pragma unroll
;                         for (int e = 0; e < 4; ++e) {
;                             float x = v[n][e];
;                             if (act == 1) x = silu_f(x);
;                             else if (act == 2) { const float l = lbv[e]; x = __logf(l + (1.f - l) * __builtin_amdgcn_rcpf(1.f + __expf(-x))); }
;                             else if (act == 3) { x = fmaxf(x, 0.f); x = x * x; }
;                             v[n][e] = x;
;                         }
;                     }
;                     u32x4 w; w.x = cvt_pk_bf16(v[0][0], v[0][1]); w.y = cvt_pk_bf16(v[0][2], v[0][3]); w.z = cvt_pk_bf16(v[1][0], v[1][1]); w.w = cvt_pk_bf16(v[1][2], v[1][3]);
;                     *(u32x4*)(rowp + bj * HALF) = w;
	v_log_f32_e32 v188, v188
	v_log_f32_e32 v189, v189
	v_log_f32_e32 v190, v190
	v_log_f32_e32 v191, v191
	v_mul_f32_e32 v200, 0x3f317217, v184
	v_mul_f32_e32 v201, 0x3f317217, v185
	v_mul_f32_e32 v202, 0x3f317217, v186
	v_mul_f32_e32 v203, 0x3f317217, v187
	v_mul_f32_e32 v204, 0x3f317217, v188
	v_mul_f32_e32 v205, 0x3f317217, v189
	v_mul_f32_e32 v206, 0x3f317217, v190
	v_mul_f32_e32 v207, 0x3f317217, v191
	v_fma_f32 v200, v184, s13, -v200
	v_fma_f32 v201, v185, s13, -v201
	v_fma_f32 v202, v186, s13, -v202
	v_fma_f32 v203, v187, s13, -v203
	v_fma_f32 v204, v188, s13, -v204
	v_fma_f32 v205, v189, s13, -v205
	v_fma_f32 v206, v190, s13, -v206
	v_fma_f32 v207, v191, s13, -v207
	v_fmac_f32_e32 v200, 0x3377d1cf, v184
	v_fmac_f32_e32 v201, 0x3377d1cf, v185
	v_fmac_f32_e32 v202, 0x3377d1cf, v186
	v_fmac_f32_e32 v203, 0x3377d1cf, v187
	v_fmac_f32_e32 v204, 0x3377d1cf, v188
	v_fmac_f32_e32 v205, 0x3377d1cf, v189
	v_fmac_f32_e32 v206, 0x3377d1cf, v190
	v_fmac_f32_e32 v207, 0x3377d1cf, v191
	v_fmac_f32_e32 v200, 0x3f317217, v184
	v_fmac_f32_e32 v201, 0x3f317217, v185
	v_fmac_f32_e32 v202, 0x3f317217, v186
	v_fmac_f32_e32 v203, 0x3f317217, v187
	v_fmac_f32_e32 v204, 0x3f317217, v188
	v_fmac_f32_e32 v205, 0x3f317217, v189
	v_fmac_f32_e32 v206, 0x3f317217, v190
	v_fmac_f32_e32 v207, 0x3f317217, v191
	v_cmp_lt_f32_e64 vcc, |v184|, s36
	v_cmp_lt_f32_e64 s[38:39], |v185|, s36
	v_cmp_lt_f32_e64 s[48:49], |v186|, s36
	v_cmp_lt_f32_e64 s[50:51], |v187|, s36
	v_cndmask_b32_e64 v184, v184, v200, vcc
	v_cndmask_b32_e64 v185, v185, v201, s[38:39]
	v_cndmask_b32_e64 v186, v186, v202, s[48:49]
	v_cndmask_b32_e64 v187, v187, v203, s[50:51]
	v_cmp_lt_f32_e64 vcc, |v188|, s36
	v_cmp_lt_f32_e64 s[38:39], |v189|, s36
	v_cmp_lt_f32_e64 s[48:49], |v190|, s36
	v_cmp_lt_f32_e64 s[50:51], |v191|, s36
	v_cndmask_b32_e64 v188, v188, v204, vcc
	v_cndmask_b32_e64 v189, v189, v205, s[38:39]
	v_cndmask_b32_e64 v190, v190, v206, s[48:49]
	v_cndmask_b32_e64 v191, v191, v207, s[50:51]
	v_sub_f32_e32 v84, v184, v192
	v_sub_f32_e32 v85, v185, v193
	v_sub_f32_e32 v86, v186, v194
	v_sub_f32_e32 v87, v187, v195
	v_sub_f32_e32 v80, v188, v196
	v_sub_f32_e32 v81, v189, v197
	v_sub_f32_e32 v82, v190, v198
	v_sub_f32_e32 v83, v191, v199
	v_cvt_pk_bf16_f32 v84, v84, v85
	v_cvt_pk_bf16_f32 v85, v86, v87
	v_cvt_pk_bf16_f32 v86, v80, v81
	v_cvt_pk_bf16_f32 v87, v82, v83
	global_store_dwordx4 v[162:163], v[84:87], off offset:256
	v_lshl_add_u64 v[176:177], v[162:163], 0, s[46:47]
	v_mul_f32_e32 v76, v76, v146
	v_mul_f32_e32 v77, v77, v146
	v_mul_f32_e32 v78, v78, v146
	v_mul_f32_e32 v79, v79, v146
	v_mul_f32_e32 v72, v72, v146
	v_mul_f32_e32 v73, v73, v146
	v_mul_f32_e32 v74, v74, v146
	v_mul_f32_e32 v75, v75, v146
	v_mul_f32_e32 v184, 0xbfb8aa3b, v76
	v_mul_f32_e32 v185, 0xbfb8aa3b, v77
	v_mul_f32_e32 v186, 0xbfb8aa3b, v78
	v_mul_f32_e32 v187, 0xbfb8aa3b, v79
	v_mul_f32_e32 v188, 0xbfb8aa3b, v72
	v_mul_f32_e32 v189, 0xbfb8aa3b, v73
	v_mul_f32_e32 v190, 0xbfb8aa3b, v74
	v_mul_f32_e32 v191, 0xbfb8aa3b, v75
	v_exp_f32_e32 v184, v184
	v_exp_f32_e32 v185, v185
	v_exp_f32_e32 v186, v186
	v_exp_f32_e32 v187, v187
	v_exp_f32_e32 v188, v188
	v_exp_f32_e32 v189, v189
	v_exp_f32_e32 v190, v190
	v_exp_f32_e32 v191, v191
	v_sub_f32_e32 v192, 1.0, v152
	v_sub_f32_e32 v193, 1.0, v153
	v_sub_f32_e32 v194, 1.0, v154
	v_sub_f32_e32 v195, 1.0, v155
	v_sub_f32_e32 v196, 1.0, v180
	v_sub_f32_e32 v197, 1.0, v181
	v_sub_f32_e32 v198, 1.0, v182
	v_sub_f32_e32 v199, 1.0, v183
	v_add_f32_e32 v184, 1.0, v184
	v_add_f32_e32 v185, 1.0, v185
	v_add_f32_e32 v186, 1.0, v186
	v_add_f32_e32 v187, 1.0, v187
	v_add_f32_e32 v188, 1.0, v188
	v_add_f32_e32 v189, 1.0, v189
	v_add_f32_e32 v190, 1.0, v190
	v_add_f32_e32 v191, 1.0, v191
	v_rcp_f32_e32 v184, v184
	v_rcp_f32_e32 v185, v185
	v_rcp_f32_e32 v186, v186
	v_rcp_f32_e32 v187, v187
	v_rcp_f32_e32 v188, v188
	v_rcp_f32_e32 v189, v189
	v_rcp_f32_e32 v190, v190
	v_rcp_f32_e32 v191, v191
	v_fma_f32 v200, v184, v192, v152
	v_fma_f32 v201, v185, v193, v153
	v_fma_f32 v202, v186, v194, v154
	v_fma_f32 v203, v187, v195, v155
	v_fma_f32 v204, v188, v196, v180
	v_fma_f32 v205, v189, v197, v181
	v_fma_f32 v206, v190, v198, v182
	v_fma_f32 v207, v191, v199, v183
	v_cmp_gt_f32_e64 vcc, s35, v200
	v_cmp_gt_f32_e64 s[38:39], s35, v201
	v_cmp_gt_f32_e64 s[48:49], s35, v202
	v_cmp_gt_f32_e64 s[50:51], s35, v203
	v_cndmask_b32_e64 v184, 0, 32, vcc
	v_cndmask_b32_e64 v185, 0, 32, s[38:39]
	v_cndmask_b32_e64 v186, 0, 32, s[48:49]
	v_cndmask_b32_e64 v187, 0, 32, s[50:51]
	v_cndmask_b32_e64 v192, 0, v214, vcc
	v_cndmask_b32_e64 v193, 0, v214, s[38:39]
	v_cndmask_b32_e64 v194, 0, v214, s[48:49]
	v_cndmask_b32_e64 v195, 0, v214, s[50:51]
	v_cmp_gt_f32_e64 vcc, s35, v204
	v_cmp_gt_f32_e64 s[38:39], s35, v205
	v_cmp_gt_f32_e64 s[48:49], s35, v206
	v_cmp_gt_f32_e64 s[50:51], s35, v207
	v_cndmask_b32_e64 v188, 0, 32, vcc
	v_cndmask_b32_e64 v189, 0, 32, s[38:39]
	v_cndmask_b32_e64 v190, 0, 32, s[48:49]
	v_cndmask_b32_e64 v191, 0, 32, s[50:51]
	v_cndmask_b32_e64 v196, 0, v214, vcc
	v_cndmask_b32_e64 v197, 0, v214, s[38:39]
	v_cndmask_b32_e64 v198, 0, v214, s[48:49]
	v_cndmask_b32_e64 v199, 0, v214, s[50:51]
	v_ldexp_f32 v184, v200, v184
	v_ldexp_f32 v185, v201, v185
	v_ldexp_f32 v186, v202, v186
	v_ldexp_f32 v187, v203, v187
	v_ldexp_f32 v188, v204, v188
	v_ldexp_f32 v189, v205, v189
	v_ldexp_f32 v190, v206, v190
	v_ldexp_f32 v191, v207, v191
	v_log_f32_e32 v184, v184
	v_log_f32_e32 v185, v185
	v_log_f32_e32 v186, v186
	v_log_f32_e32 v187, v187
	v_log_f32_e32 v188, v188
	v_log_f32_e32 v189, v189
	v_log_f32_e32 v190, v190
	v_log_f32_e32 v191, v191
	v_mul_f32_e32 v200, 0x3f317217, v184
	v_mul_f32_e32 v201, 0x3f317217, v185
; __device__ __forceinline__ unsigned cvt_pk_bf16(float lo, float hi) { unsigned r; asm volatile("v_cvt_pk_bf16_f32 %0, %1, %2" : "=v"(r) : "v"(lo), "v"(hi)); return r; }
; __device__ __forceinline__ float silu_f(float v) { return v * __builtin_amdgcn_rcpf(1.f + __expf(-v)); }
;     __device__ __forceinline__ void operator()(const f32x4 (&acc)[2][2][4][2], const Unit& u, int wr, int wc, int fr, int fq, int ui, PG8_LAS unsigned char* lds) const {
;     ...
;                         f32x4 lbv = (f32x4){0.f, 0.f, 0.f, 0.f};
;                         if (act == 2) lbv = *(const f32x4*)(lb + (col0 - 1024) + bj * HALF + 4 * n);
; #pragma unroll
;                         for (int e = 0; e < 4; ++e) {
;                             float x = v[n][e];
;                             if (act == 1) x = silu_f(x);
;                             else if (act == 2) { const float l = lbv[e]; x = __logf(l + (1.f - l) * __builtin_amdgcn_rcpf(1.f + __expf(-x))); }
;                             else if (act == 3) { x = fmaxf(x, 0.f); x = x * x; }
;                             v[n][e] = x;
;                         }
;                     }
;                     u32x4 w; w.x = cvt_pk_bf16(v[0][0], v[0][1]); w.y = cvt_pk_bf16(v[0][2], v[0][3]); w.z = cvt_pk_bf16(v[1][0], v[1][1]); w.w = cvt_pk_bf16(v[1][2], v[1][3]);
;                     *(u32x4*)(rowp + bj * HALF) = w;
	v_mul_f32_e32 v202, 0x3f317217, v186
	v_mul_f32_e32 v203, 0x3f317217, v187
	v_mul_f32_e32 v204, 0x3f317217, v188
	v_mul_f32_e32 v205, 0x3f317217, v189
	v_mul_f32_e32 v206, 0x3f317217, v190
	v_mul_f32_e32 v207, 0x3f317217, v191
	v_fma_f32 v200, v184, s13, -v200
	v_fma_f32 v201, v185, s13, -v201
	v_fma_f32 v202, v186, s13, -v202
	v_fma_f32 v203, v187, s13, -v203
	v_fma_f32 v204, v188, s13, -v204
	v_fma_f32 v205, v189, s13, -v205
	v_fma_f32 v206, v190, s13, -v206
	v_fma_f32 v207, v191, s13, -v207
	v_fmac_f32_e32 v200, 0x3377d1cf, v184
	v_fmac_f32_e32 v201, 0x3377d1cf, v185
	v_fmac_f32_e32 v202, 0x3377d1cf, v186
	v_fmac_f32_e32 v203, 0x3377d1cf, v187
	v_fmac_f32_e32 v204, 0x3377d1cf, v188
	v_fmac_f32_e32 v205, 0x3377d1cf, v189
	v_fmac_f32_e32 v206, 0x3377d1cf, v190
	v_fmac_f32_e32 v207, 0x3377d1cf, v191
	v_fmac_f32_e32 v200, 0x3f317217, v184
	v_fmac_f32_e32 v201, 0x3f317217, v185
	v_fmac_f32_e32 v202, 0x3f317217, v186
	v_fmac_f32_e32 v203, 0x3f317217, v187
	v_fmac_f32_e32 v204, 0x3f317217, v188
	v_fmac_f32_e32 v205, 0x3f317217, v189
	v_fmac_f32_e32 v206, 0x3f317217, v190
	v_fmac_f32_e32 v207, 0x3f317217, v191
	v_cmp_lt_f32_e64 vcc, |v184|, s36
	v_cmp_lt_f32_e64 s[38:39], |v185|, s36
	v_cmp_lt_f32_e64 s[48:49], |v186|, s36
	v_cmp_lt_f32_e64 s[50:51], |v187|, s36
	v_cndmask_b32_e64 v184, v184, v200, vcc
	v_cndmask_b32_e64 v185, v185, v201, s[38:39]
	v_cndmask_b32_e64 v186, v186, v202, s[48:49]
	v_cndmask_b32_e64 v187, v187, v203, s[50:51]
	v_cmp_lt_f32_e64 vcc, |v188|, s36
	v_cmp_lt_f32_e64 s[38:39], |v189|, s36
	v_cmp_lt_f32_e64 s[48:49], |v190|, s36
	v_cmp_lt_f32_e64 s[50:51], |v191|, s36
	v_cndmask_b32_e64 v188, v188, v204, vcc
	v_cndmask_b32_e64 v189, v189, v205, s[38:39]
	v_cndmask_b32_e64 v190, v190, v206, s[48:49]
	v_cndmask_b32_e64 v191, v191, v207, s[50:51]
	v_sub_f32_e32 v76, v184, v192
	v_sub_f32_e32 v77, v185, v193
	v_sub_f32_e32 v78, v186, v194
	v_sub_f32_e32 v79, v187, v195
	v_sub_f32_e32 v72, v188, v196
	v_sub_f32_e32 v73, v189, v197
	v_sub_f32_e32 v74, v190, v198
	v_sub_f32_e32 v75, v191, v199
	v_cvt_pk_bf16_f32 v76, v76, v77
	v_cvt_pk_bf16_f32 v77, v78, v79
	v_cvt_pk_bf16_f32 v78, v72, v73
	v_cvt_pk_bf16_f32 v79, v74, v75
	global_store_dwordx4 v[176:177], v[76:79], off
	v_mul_f32_e32 v68, v68, v146
	v_mul_f32_e32 v69, v69, v146
	v_mul_f32_e32 v70, v70, v146
	v_mul_f32_e32 v71, v71, v146
	v_mul_f32_e32 v64, v64, v146
	v_mul_f32_e32 v65, v65, v146
	v_mul_f32_e32 v66, v66, v146
	v_mul_f32_e32 v67, v67, v146
	v_mul_f32_e32 v184, 0xbfb8aa3b, v68
	v_mul_f32_e32 v185, 0xbfb8aa3b, v69
	v_mul_f32_e32 v186, 0xbfb8aa3b, v70
	v_mul_f32_e32 v187, 0xbfb8aa3b, v71
	v_mul_f32_e32 v188, 0xbfb8aa3b, v64
	v_mul_f32_e32 v189, 0xbfb8aa3b, v65
	v_mul_f32_e32 v190, 0xbfb8aa3b, v66
	v_mul_f32_e32 v191, 0xbfb8aa3b, v67
	v_exp_f32_e32 v184, v184
	v_exp_f32_e32 v185, v185
	v_exp_f32_e32 v186, v186
	v_exp_f32_e32 v187, v187
	v_exp_f32_e32 v188, v188
	v_exp_f32_e32 v189, v189
	v_exp_f32_e32 v190, v190
	v_exp_f32_e32 v191, v191
	v_sub_f32_e32 v192, 1.0, v218
	v_sub_f32_e32 v193, 1.0, v219
	v_sub_f32_e32 v194, 1.0, v220
	v_sub_f32_e32 v195, 1.0, v221
	v_sub_f32_e32 v196, 1.0, v222
	v_sub_f32_e32 v197, 1.0, v223
	v_sub_f32_e32 v198, 1.0, v224
	v_sub_f32_e32 v199, 1.0, v225
	v_add_f32_e32 v184, 1.0, v184
	v_add_f32_e32 v185, 1.0, v185
	v_add_f32_e32 v186, 1.0, v186
	v_add_f32_e32 v187, 1.0, v187
	v_add_f32_e32 v188, 1.0, v188
	v_add_f32_e32 v189, 1.0, v189
	v_add_f32_e32 v190, 1.0, v190
	v_add_f32_e32 v191, 1.0, v191
	v_rcp_f32_e32 v184, v184
	v_rcp_f32_e32 v185, v185
	v_rcp_f32_e32 v186, v186
	v_rcp_f32_e32 v187, v187
	v_rcp_f32_e32 v188, v188
	v_rcp_f32_e32 v189, v189
	v_rcp_f32_e32 v190, v190
	v_rcp_f32_e32 v191, v191
	v_fma_f32 v200, v184, v192, v218
	v_fma_f32 v201, v185, v193, v219
	v_fma_f32 v202, v186, v194, v220
	v_fma_f32 v203, v187, v195, v221
	v_fma_f32 v204, v188, v196, v222
	v_fma_f32 v205, v189, v197, v223
	v_fma_f32 v206, v190, v198, v224
	v_fma_f32 v207, v191, v199, v225
	v_cmp_gt_f32_e64 vcc, s35, v200
	v_cmp_gt_f32_e64 s[38:39], s35, v201
	v_cmp_gt_f32_e64 s[48:49], s35, v202
	v_cmp_gt_f32_e64 s[50:51], s35, v203
	v_cndmask_b32_e64 v184, 0, 32, vcc
	v_cndmask_b32_e64 v185, 0, 32, s[38:39]
	v_cndmask_b32_e64 v186, 0, 32, s[48:49]
	v_cndmask_b32_e64 v187, 0, 32, s[50:51]
	v_cndmask_b32_e64 v192, 0, v214, vcc
	v_cndmask_b32_e64 v193, 0, v214, s[38:39]
	v_cndmask_b32_e64 v194, 0, v214, s[48:49]
	v_cndmask_b32_e64 v195, 0, v214, s[50:51]
	v_cmp_gt_f32_e64 vcc, s35, v204
	v_cmp_gt_f32_e64 s[38:39], s35, v205
	v_cmp_gt_f32_e64 s[48:49], s35, v206
	v_cmp_gt_f32_e64 s[50:51], s35, v207
	v_cndmask_b32_e64 v188, 0, 32, vcc
	v_cndmask_b32_e64 v189, 0, 32, s[38:39]
	v_cndmask_b32_e64 v190, 0, 32, s[48:49]
	v_cndmask_b32_e64 v191, 0, 32, s[50:51]
	v_cndmask_b32_e64 v196, 0, v214, vcc
	v_cndmask_b32_e64 v197, 0, v214, s[38:39]
	v_cndmask_b32_e64 v198, 0, v214, s[48:49]
	v_cndmask_b32_e64 v199, 0, v214, s[50:51]
	v_ldexp_f32 v184, v200, v184
	v_ldexp_f32 v185, v201, v185
	v_ldexp_f32 v186, v202, v186
	v_ldexp_f32 v187, v203, v187
	v_ldexp_f32 v188, v204, v188
	v_ldexp_f32 v189, v205, v189
	v_ldexp_f32 v190, v206, v190
	v_ldexp_f32 v191, v207, v191
	v_log_f32_e32 v184, v184
	v_log_f32_e32 v185, v185
	v_log_f32_e32 v186, v186
	v_log_f32_e32 v187, v187
	v_log_f32_e32 v188, v188
	v_log_f32_e32 v189, v189
	v_log_f32_e32 v190, v190
	v_log_f32_e32 v191, v191
	v_mul_f32_e32 v200, 0x3f317217, v184
	v_mul_f32_e32 v201, 0x3f317217, v185
	v_mul_f32_e32 v202, 0x3f317217, v186
	v_mul_f32_e32 v203, 0x3f317217, v187
	v_mul_f32_e32 v204, 0x3f317217, v188
	v_mul_f32_e32 v205, 0x3f317217, v189
	v_mul_f32_e32 v206, 0x3f317217, v190
	v_mul_f32_e32 v207, 0x3f317217, v191
; __device__ __forceinline__ unsigned cvt_pk_bf16(float lo, float hi) { unsigned r; asm volatile("v_cvt_pk_bf16_f32 %0, %1, %2" : "=v"(r) : "v"(lo), "v"(hi)); return r; }
; __device__ __forceinline__ float silu_f(float v) { return v * __builtin_amdgcn_rcpf(1.f + __expf(-v)); }
;     __device__ __forceinline__ void operator()(const f32x4 (&acc)[2][2][4][2], const Unit& u, int wr, int wc, int fr, int fq, int ui, PG8_LAS unsigned char* lds) const {
;     ...
;                         f32x4 lbv = (f32x4){0.f, 0.f, 0.f, 0.f};
;                         if (act == 2) lbv = *(const f32x4*)(lb + (col0 - 1024) + bj * HALF + 4 * n);
; #pragma unroll
;                         for (int e = 0; e < 4; ++e) {
;                             float x = v[n][e];
;                             if (act == 1) x = silu_f(x);
;                             else if (act == 2) { const float l = lbv[e]; x = __logf(l + (1.f - l) * __builtin_amdgcn_rcpf(1.f + __expf(-x))); }
;                             else if (act == 3) { x = fmaxf(x, 0.f); x = x * x; }
;                             v[n][e] = x;
;                         }
;                     }
;                     u32x4 w; w.x = cvt_pk_bf16(v[0][0], v[0][1]); w.y = cvt_pk_bf16(v[0][2], v[0][3]); w.z = cvt_pk_bf16(v[1][0], v[1][1]); w.w = cvt_pk_bf16(v[1][2], v[1][3]);
;                     *(u32x4*)(rowp + bj * HALF) = w;
	v_fma_f32 v200, v184, s13, -v200
	v_fma_f32 v201, v185, s13, -v201
	v_fma_f32 v202, v186, s13, -v202
	v_fma_f32 v203, v187, s13, -v203
	v_fma_f32 v204, v188, s13, -v204
	v_fma_f32 v205, v189, s13, -v205
	v_fma_f32 v206, v190, s13, -v206
	v_fma_f32 v207, v191, s13, -v207
	v_fmac_f32_e32 v200, 0x3377d1cf, v184
	v_fmac_f32_e32 v201, 0x3377d1cf, v185
	v_fmac_f32_e32 v202, 0x3377d1cf, v186
	v_fmac_f32_e32 v203, 0x3377d1cf, v187
	v_fmac_f32_e32 v204, 0x3377d1cf, v188
	v_fmac_f32_e32 v205, 0x3377d1cf, v189
	v_fmac_f32_e32 v206, 0x3377d1cf, v190
	v_fmac_f32_e32 v207, 0x3377d1cf, v191
	v_fmac_f32_e32 v200, 0x3f317217, v184
	v_fmac_f32_e32 v201, 0x3f317217, v185
	v_fmac_f32_e32 v202, 0x3f317217, v186
	v_fmac_f32_e32 v203, 0x3f317217, v187
	v_fmac_f32_e32 v204, 0x3f317217, v188
	v_fmac_f32_e32 v205, 0x3f317217, v189
	v_fmac_f32_e32 v206, 0x3f317217, v190
	v_fmac_f32_e32 v207, 0x3f317217, v191
	v_cmp_lt_f32_e64 vcc, |v184|, s36
	v_cmp_lt_f32_e64 s[38:39], |v185|, s36
	v_cmp_lt_f32_e64 s[48:49], |v186|, s36
	v_cmp_lt_f32_e64 s[50:51], |v187|, s36
	v_cndmask_b32_e64 v184, v184, v200, vcc
	v_cndmask_b32_e64 v185, v185, v201, s[38:39]
	v_cndmask_b32_e64 v186, v186, v202, s[48:49]
	v_cndmask_b32_e64 v187, v187, v203, s[50:51]
	v_cmp_lt_f32_e64 vcc, |v188|, s36
	v_cmp_lt_f32_e64 s[38:39], |v189|, s36
	v_cmp_lt_f32_e64 s[48:49], |v190|, s36
	v_cmp_lt_f32_e64 s[50:51], |v191|, s36
	v_cndmask_b32_e64 v188, v188, v204, vcc
	v_cndmask_b32_e64 v189, v189, v205, s[38:39]
	v_cndmask_b32_e64 v190, v190, v206, s[48:49]
	v_cndmask_b32_e64 v191, v191, v207, s[50:51]
	v_sub_f32_e32 v68, v184, v192
	v_sub_f32_e32 v69, v185, v193
	v_sub_f32_e32 v70, v186, v194
	v_sub_f32_e32 v71, v187, v195
	v_sub_f32_e32 v64, v188, v196
	v_sub_f32_e32 v65, v189, v197
	v_sub_f32_e32 v66, v190, v198
	v_sub_f32_e32 v67, v191, v199
	v_cvt_pk_bf16_f32 v68, v68, v69
	v_cvt_pk_bf16_f32 v69, v70, v71
	v_cvt_pk_bf16_f32 v70, v64, v65
	v_cvt_pk_bf16_f32 v71, v66, v67
	global_store_dwordx4 v[176:177], v[68:71], off offset:256
	v_lshl_add_u64 v[162:163], v[178:179], 0, 0
	v_mul_f32_e32 v60, v60, v148
	v_mul_f32_e32 v61, v61, v148
	v_mul_f32_e32 v62, v62, v148
	v_mul_f32_e32 v63, v63, v148
	v_mul_f32_e32 v56, v56, v148
	v_mul_f32_e32 v57, v57, v148
	v_mul_f32_e32 v58, v58, v148
	v_mul_f32_e32 v59, v59, v148
	v_mul_f32_e32 v184, 0xbfb8aa3b, v60
	v_mul_f32_e32 v185, 0xbfb8aa3b, v61
	v_mul_f32_e32 v186, 0xbfb8aa3b, v62
	v_mul_f32_e32 v187, 0xbfb8aa3b, v63
	v_mul_f32_e32 v188, 0xbfb8aa3b, v56
	v_mul_f32_e32 v189, 0xbfb8aa3b, v57
	v_mul_f32_e32 v190, 0xbfb8aa3b, v58
	v_mul_f32_e32 v191, 0xbfb8aa3b, v59
	v_exp_f32_e32 v184, v184
	v_exp_f32_e32 v185, v185
	v_exp_f32_e32 v186, v186
	v_exp_f32_e32 v187, v187
	v_exp_f32_e32 v188, v188
	v_exp_f32_e32 v189, v189
	v_exp_f32_e32 v190, v190
	v_exp_f32_e32 v191, v191
	v_sub_f32_e32 v192, 1.0, v152
	v_sub_f32_e32 v193, 1.0, v153
	v_sub_f32_e32 v194, 1.0, v154
	v_sub_f32_e32 v195, 1.0, v155
	v_sub_f32_e32 v196, 1.0, v180
	v_sub_f32_e32 v197, 1.0, v181
	v_sub_f32_e32 v198, 1.0, v182
	v_sub_f32_e32 v199, 1.0, v183
	v_add_f32_e32 v184, 1.0, v184
	v_add_f32_e32 v185, 1.0, v185
	v_add_f32_e32 v186, 1.0, v186
	v_add_f32_e32 v187, 1.0, v187
	v_add_f32_e32 v188, 1.0, v188
	v_add_f32_e32 v189, 1.0, v189
	v_add_f32_e32 v190, 1.0, v190
	v_add_f32_e32 v191, 1.0, v191
	v_rcp_f32_e32 v184, v184
	v_rcp_f32_e32 v185, v185
	v_rcp_f32_e32 v186, v186
	v_rcp_f32_e32 v187, v187
	v_rcp_f32_e32 v188, v188
	v_rcp_f32_e32 v189, v189
	v_rcp_f32_e32 v190, v190
	v_rcp_f32_e32 v191, v191
	v_fma_f32 v200, v184, v192, v152
	v_fma_f32 v201, v185, v193, v153
	v_fma_f32 v202, v186, v194, v154
	v_fma_f32 v203, v187, v195, v155
	v_fma_f32 v204, v188, v196, v180
	v_fma_f32 v205, v189, v197, v181
	v_fma_f32 v206, v190, v198, v182
	v_fma_f32 v207, v191, v199, v183
	v_cmp_gt_f32_e64 vcc, s35, v200
	v_cmp_gt_f32_e64 s[38:39], s35, v201
	v_cmp_gt_f32_e64 s[48:49], s35, v202
	v_cmp_gt_f32_e64 s[50:51], s35, v203
	v_cndmask_b32_e64 v184, 0, 32, vcc
	v_cndmask_b32_e64 v185, 0, 32, s[38:39]
	v_cndmask_b32_e64 v186, 0, 32, s[48:49]
	v_cndmask_b32_e64 v187, 0, 32, s[50:51]
	v_cndmask_b32_e64 v192, 0, v214, vcc
	v_cndmask_b32_e64 v193, 0, v214, s[38:39]
	v_cndmask_b32_e64 v194, 0, v214, s[48:49]
	v_cndmask_b32_e64 v195, 0, v214, s[50:51]
	v_cmp_gt_f32_e64 vcc, s35, v204
	v_cmp_gt_f32_e64 s[38:39], s35, v205
	v_cmp_gt_f32_e64 s[48:49], s35, v206
	v_cmp_gt_f32_e64 s[50:51], s35, v207
	v_cndmask_b32_e64 v188, 0, 32, vcc
	v_cndmask_b32_e64 v189, 0, 32, s[38:39]
	v_cndmask_b32_e64 v190, 0, 32, s[48:49]
	v_cndmask_b32_e64 v191, 0, 32, s[50:51]
	v_cndmask_b32_e64 v196, 0, v214, vcc
	v_cndmask_b32_e64 v197, 0, v214, s[38:39]
	v_cndmask_b32_e64 v198, 0, v214, s[48:49]
	v_cndmask_b32_e64 v199, 0, v214, s[50:51]
	v_ldexp_f32 v184, v200, v184
	v_ldexp_f32 v185, v201, v185
	v_ldexp_f32 v186, v202, v186
	v_ldexp_f32 v187, v203, v187
	v_ldexp_f32 v188, v204, v188
	v_ldexp_f32 v189, v205, v189
	v_ldexp_f32 v190, v206, v190
	v_ldexp_f32 v191, v207, v191
	v_log_f32_e32 v184, v184
	v_log_f32_e32 v185, v185
	v_log_f32_e32 v186, v186
	v_log_f32_e32 v187, v187
	v_log_f32_e32 v188, v188
	v_log_f32_e32 v189, v189
	v_log_f32_e32 v190, v190
	v_log_f32_e32 v191, v191
	v_mul_f32_e32 v200, 0x3f317217, v184
	v_mul_f32_e32 v201, 0x3f317217, v185
	v_mul_f32_e32 v202, 0x3f317217, v186
	v_mul_f32_e32 v203, 0x3f317217, v187
	v_mul_f32_e32 v204, 0x3f317217, v188
	v_mul_f32_e32 v205, 0x3f317217, v189
	v_mul_f32_e32 v206, 0x3f317217, v190
	v_mul_f32_e32 v207, 0x3f317217, v191
	v_fma_f32 v200, v184, s13, -v200
	v_fma_f32 v201, v185, s13, -v201
	v_fma_f32 v202, v186, s13, -v202
	v_fma_f32 v203, v187, s13, -v203
	v_fma_f32 v204, v188, s13, -v204
; __device__ __forceinline__ unsigned cvt_pk_bf16(float lo, float hi) { unsigned r; asm volatile("v_cvt_pk_bf16_f32 %0, %1, %2" : "=v"(r) : "v"(lo), "v"(hi)); return r; }
; __device__ __forceinline__ float silu_f(float v) { return v * __builtin_amdgcn_rcpf(1.f + __expf(-v)); }
;     __device__ __forceinline__ void operator()(const f32x4 (&acc)[2][2][4][2], const Unit& u, int wr, int wc, int fr, int fq, int ui, PG8_LAS unsigned char* lds) const {
;     ...
;                         f32x4 lbv = (f32x4){0.f, 0.f, 0.f, 0.f};
;                         if (act == 2) lbv = *(const f32x4*)(lb + (col0 - 1024) + bj * HALF + 4 * n);
; #pragma unroll
;                         for (int e = 0; e < 4; ++e) {
;                             float x = v[n][e];
;                             if (act == 1) x = silu_f(x);
;                             else if (act == 2) { const float l = lbv[e]; x = __logf(l + (1.f - l) * __builtin_amdgcn_rcpf(1.f + __expf(-x))); }
;                             else if (act == 3) { x = fmaxf(x, 0.f); x = x * x; }
;                             v[n][e] = x;
;                         }
;                     }
;                     u32x4 w; w.x = cvt_pk_bf16(v[0][0], v[0][1]); w.y = cvt_pk_bf16(v[0][2], v[0][3]); w.z = cvt_pk_bf16(v[1][0], v[1][1]); w.w = cvt_pk_bf16(v[1][2], v[1][3]);
;                     *(u32x4*)(rowp + bj * HALF) = w;
	v_fma_f32 v205, v189, s13, -v205
	v_fma_f32 v206, v190, s13, -v206
	v_fma_f32 v207, v191, s13, -v207
	v_fmac_f32_e32 v200, 0x3377d1cf, v184
	v_fmac_f32_e32 v201, 0x3377d1cf, v185
	v_fmac_f32_e32 v202, 0x3377d1cf, v186
	v_fmac_f32_e32 v203, 0x3377d1cf, v187
	v_fmac_f32_e32 v204, 0x3377d1cf, v188
	v_fmac_f32_e32 v205, 0x3377d1cf, v189
	v_fmac_f32_e32 v206, 0x3377d1cf, v190
	v_fmac_f32_e32 v207, 0x3377d1cf, v191
	v_fmac_f32_e32 v200, 0x3f317217, v184
	v_fmac_f32_e32 v201, 0x3f317217, v185
	v_fmac_f32_e32 v202, 0x3f317217, v186
	v_fmac_f32_e32 v203, 0x3f317217, v187
	v_fmac_f32_e32 v204, 0x3f317217, v188
	v_fmac_f32_e32 v205, 0x3f317217, v189
	v_fmac_f32_e32 v206, 0x3f317217, v190
	v_fmac_f32_e32 v207, 0x3f317217, v191
	v_cmp_lt_f32_e64 vcc, |v184|, s36
	v_cmp_lt_f32_e64 s[38:39], |v185|, s36
	v_cmp_lt_f32_e64 s[48:49], |v186|, s36
	v_cmp_lt_f32_e64 s[50:51], |v187|, s36
	v_cndmask_b32_e64 v184, v184, v200, vcc
	v_cndmask_b32_e64 v185, v185, v201, s[38:39]
	v_cndmask_b32_e64 v186, v186, v202, s[48:49]
	v_cndmask_b32_e64 v187, v187, v203, s[50:51]
	v_cmp_lt_f32_e64 vcc, |v188|, s36
	v_cmp_lt_f32_e64 s[38:39], |v189|, s36
	v_cmp_lt_f32_e64 s[48:49], |v190|, s36
	v_cmp_lt_f32_e64 s[50:51], |v191|, s36
	v_cndmask_b32_e64 v188, v188, v204, vcc
	v_cndmask_b32_e64 v189, v189, v205, s[38:39]
	v_cndmask_b32_e64 v190, v190, v206, s[48:49]
	v_cndmask_b32_e64 v191, v191, v207, s[50:51]
	v_sub_f32_e32 v60, v184, v192
	v_sub_f32_e32 v61, v185, v193
	v_sub_f32_e32 v62, v186, v194
	v_sub_f32_e32 v63, v187, v195
	v_sub_f32_e32 v56, v188, v196
	v_sub_f32_e32 v57, v189, v197
	v_sub_f32_e32 v58, v190, v198
	v_sub_f32_e32 v59, v191, v199
	v_cvt_pk_bf16_f32 v60, v60, v61
	v_cvt_pk_bf16_f32 v61, v62, v63
	v_cvt_pk_bf16_f32 v62, v56, v57
	v_cvt_pk_bf16_f32 v63, v58, v59
	global_store_dwordx4 v[162:163], v[60:63], off
	v_mul_f32_e32 v52, v52, v148
	v_mul_f32_e32 v53, v53, v148
	v_mul_f32_e32 v54, v54, v148
	v_mul_f32_e32 v55, v55, v148
	v_mul_f32_e32 v48, v48, v148
	v_mul_f32_e32 v49, v49, v148
	v_mul_f32_e32 v50, v50, v148
	v_mul_f32_e32 v51, v51, v148
	v_mul_f32_e32 v184, 0xbfb8aa3b, v52
	v_mul_f32_e32 v185, 0xbfb8aa3b, v53
	v_mul_f32_e32 v186, 0xbfb8aa3b, v54
	v_mul_f32_e32 v187, 0xbfb8aa3b, v55
	v_mul_f32_e32 v188, 0xbfb8aa3b, v48
	v_mul_f32_e32 v189, 0xbfb8aa3b, v49
	v_mul_f32_e32 v190, 0xbfb8aa3b, v50
	v_mul_f32_e32 v191, 0xbfb8aa3b, v51
	v_exp_f32_e32 v184, v184
	v_exp_f32_e32 v185, v185
	v_exp_f32_e32 v186, v186
	v_exp_f32_e32 v187, v187
	v_exp_f32_e32 v188, v188
	v_exp_f32_e32 v189, v189
	v_exp_f32_e32 v190, v190
	v_exp_f32_e32 v191, v191
	v_sub_f32_e32 v192, 1.0, v218
	v_sub_f32_e32 v193, 1.0, v219
	v_sub_f32_e32 v194, 1.0, v220
	v_sub_f32_e32 v195, 1.0, v221
	v_sub_f32_e32 v196, 1.0, v222
	v_sub_f32_e32 v197, 1.0, v223
	v_sub_f32_e32 v198, 1.0, v224
	v_sub_f32_e32 v199, 1.0, v225
	v_add_f32_e32 v184, 1.0, v184
	v_add_f32_e32 v185, 1.0, v185
	v_add_f32_e32 v186, 1.0, v186
	v_add_f32_e32 v187, 1.0, v187
	v_add_f32_e32 v188, 1.0, v188
	v_add_f32_e32 v189, 1.0, v189
	v_add_f32_e32 v190, 1.0, v190
	v_add_f32_e32 v191, 1.0, v191
	v_rcp_f32_e32 v184, v184
	v_rcp_f32_e32 v185, v185
	v_rcp_f32_e32 v186, v186
	v_rcp_f32_e32 v187, v187
	v_rcp_f32_e32 v188, v188
	v_rcp_f32_e32 v189, v189
	v_rcp_f32_e32 v190, v190
	v_rcp_f32_e32 v191, v191
	v_fma_f32 v200, v184, v192, v218
	v_fma_f32 v201, v185, v193, v219
	v_fma_f32 v202, v186, v194, v220
	v_fma_f32 v203, v187, v195, v221
	v_fma_f32 v204, v188, v196, v222
	v_fma_f32 v205, v189, v197, v223
	v_fma_f32 v206, v190, v198, v224
	v_fma_f32 v207, v191, v199, v225
	v_cmp_gt_f32_e64 vcc, s35, v200
	v_cmp_gt_f32_e64 s[38:39], s35, v201
	v_cmp_gt_f32_e64 s[48:49], s35, v202
	v_cmp_gt_f32_e64 s[50:51], s35, v203
	v_cndmask_b32_e64 v184, 0, 32, vcc
	v_cndmask_b32_e64 v185, 0, 32, s[38:39]
	v_cndmask_b32_e64 v186, 0, 32, s[48:49]
	v_cndmask_b32_e64 v187, 0, 32, s[50:51]
	v_cndmask_b32_e64 v192, 0, v214, vcc
	v_cndmask_b32_e64 v193, 0, v214, s[38:39]
	v_cndmask_b32_e64 v194, 0, v214, s[48:49]
	v_cndmask_b32_e64 v195, 0, v214, s[50:51]
	v_cmp_gt_f32_e64 vcc, s35, v204
	v_cmp_gt_f32_e64 s[38:39], s35, v205
	v_cmp_gt_f32_e64 s[48:49], s35, v206
	v_cmp_gt_f32_e64 s[50:51], s35, v207
	v_cndmask_b32_e64 v188, 0, 32, vcc
	v_cndmask_b32_e64 v189, 0, 32, s[38:39]
	v_cndmask_b32_e64 v190, 0, 32, s[48:49]
	v_cndmask_b32_e64 v191, 0, 32, s[50:51]
	v_cndmask_b32_e64 v196, 0, v214, vcc
	v_cndmask_b32_e64 v197, 0, v214, s[38:39]
	v_cndmask_b32_e64 v198, 0, v214, s[48:49]
	v_cndmask_b32_e64 v199, 0, v214, s[50:51]
	v_ldexp_f32 v184, v200, v184
	v_ldexp_f32 v185, v201, v185
	v_ldexp_f32 v186, v202, v186
	v_ldexp_f32 v187, v203, v187
	v_ldexp_f32 v188, v204, v188
	v_ldexp_f32 v189, v205, v189
	v_ldexp_f32 v190, v206, v190
	v_ldexp_f32 v191, v207, v191
	v_log_f32_e32 v184, v184
	v_log_f32_e32 v185, v185
	v_log_f32_e32 v186, v186
	v_log_f32_e32 v187, v187
	v_log_f32_e32 v188, v188
	v_log_f32_e32 v189, v189
	v_log_f32_e32 v190, v190
	v_log_f32_e32 v191, v191
	v_mul_f32_e32 v200, 0x3f317217, v184
	v_mul_f32_e32 v201, 0x3f317217, v185
	v_mul_f32_e32 v202, 0x3f317217, v186
	v_mul_f32_e32 v203, 0x3f317217, v187
	v_mul_f32_e32 v204, 0x3f317217, v188
	v_mul_f32_e32 v205, 0x3f317217, v189
	v_mul_f32_e32 v206, 0x3f317217, v190
	v_mul_f32_e32 v207, 0x3f317217, v191
	v_fma_f32 v200, v184, s13, -v200
	v_fma_f32 v201, v185, s13, -v201
	v_fma_f32 v202, v186, s13, -v202
	v_fma_f32 v203, v187, s13, -v203
	v_fma_f32 v204, v188, s13, -v204
	v_fma_f32 v205, v189, s13, -v205
	v_fma_f32 v206, v190, s13, -v206
	v_fma_f32 v207, v191, s13, -v207
	v_fmac_f32_e32 v200, 0x3377d1cf, v184
	v_fmac_f32_e32 v201, 0x3377d1cf, v185
	v_fmac_f32_e32 v202, 0x3377d1cf, v186
; __device__ __forceinline__ unsigned cvt_pk_bf16(float lo, float hi) { unsigned r; asm volatile("v_cvt_pk_bf16_f32 %0, %1, %2" : "=v"(r) : "v"(lo), "v"(hi)); return r; }
; __device__ __forceinline__ float silu_f(float v) { return v * __builtin_amdgcn_rcpf(1.f + __expf(-v)); }
;     __device__ __forceinline__ void operator()(const f32x4 (&acc)[2][2][4][2], const Unit& u, int wr, int wc, int fr, int fq, int ui, PG8_LAS unsigned char* lds) const {
;     ...
;                     f32x4 v[2] = {acc[ai][bj][m][0] * rs, acc[ai][bj][m][1] * rs};
;                     if (ksum) { csum[bj][0] += v[0]; csum[bj][1] += v[1]; }
; #pragma unroll
;                     for (int n = 0; n < 2; ++n) {
;                         f32x4 lbv = (f32x4){0.f, 0.f, 0.f, 0.f};
;                         if (act == 2) lbv = *(const f32x4*)(lb + (col0 - 1024) + bj * HALF + 4 * n);
; #pragma unroll
;                         for (int e = 0; e < 4; ++e) {
;                             float x = v[n][e];
;                             if (act == 1) x = silu_f(x);
;                             else if (act == 2) { const float l = lbv[e]; x = __logf(l + (1.f - l) * __builtin_amdgcn_rcpf(1.f + __expf(-x))); }
;                             else if (act == 3) { x = fmaxf(x, 0.f); x = x * x; }
;                             v[n][e] = x;
;                         }
;                     }
;                     u32x4 w; w.x = cvt_pk_bf16(v[0][0], v[0][1]); w.y = cvt_pk_bf16(v[0][2], v[0][3]); w.z = cvt_pk_bf16(v[1][0], v[1][1]); w.w = cvt_pk_bf16(v[1][2], v[1][3]);
;                     *(u32x4*)(rowp + bj * HALF) = w;
	v_fmac_f32_e32 v203, 0x3377d1cf, v187
	v_fmac_f32_e32 v204, 0x3377d1cf, v188
	v_fmac_f32_e32 v205, 0x3377d1cf, v189
	v_fmac_f32_e32 v206, 0x3377d1cf, v190
	v_fmac_f32_e32 v207, 0x3377d1cf, v191
	v_fmac_f32_e32 v200, 0x3f317217, v184
	v_fmac_f32_e32 v201, 0x3f317217, v185
	v_fmac_f32_e32 v202, 0x3f317217, v186
	v_fmac_f32_e32 v203, 0x3f317217, v187
	v_fmac_f32_e32 v204, 0x3f317217, v188
	v_fmac_f32_e32 v205, 0x3f317217, v189
	v_fmac_f32_e32 v206, 0x3f317217, v190
	v_fmac_f32_e32 v207, 0x3f317217, v191
	v_cmp_lt_f32_e64 vcc, |v184|, s36
	v_cmp_lt_f32_e64 s[38:39], |v185|, s36
	v_cmp_lt_f32_e64 s[48:49], |v186|, s36
	v_cmp_lt_f32_e64 s[50:51], |v187|, s36
	v_cndmask_b32_e64 v184, v184, v200, vcc
	v_cndmask_b32_e64 v185, v185, v201, s[38:39]
	v_cndmask_b32_e64 v186, v186, v202, s[48:49]
	v_cndmask_b32_e64 v187, v187, v203, s[50:51]
	v_cmp_lt_f32_e64 vcc, |v188|, s36
	v_cmp_lt_f32_e64 s[38:39], |v189|, s36
	v_cmp_lt_f32_e64 s[48:49], |v190|, s36
	v_cmp_lt_f32_e64 s[50:51], |v191|, s36
	v_cndmask_b32_e64 v188, v188, v204, vcc
	v_cndmask_b32_e64 v189, v189, v205, s[38:39]
	v_cndmask_b32_e64 v190, v190, v206, s[48:49]
	v_cndmask_b32_e64 v191, v191, v207, s[50:51]
	v_sub_f32_e32 v52, v184, v192
	v_sub_f32_e32 v53, v185, v193
	v_sub_f32_e32 v54, v186, v194
	v_sub_f32_e32 v55, v187, v195
	v_sub_f32_e32 v48, v188, v196
	v_sub_f32_e32 v49, v189, v197
	v_sub_f32_e32 v50, v190, v198
	v_sub_f32_e32 v51, v191, v199
	v_cvt_pk_bf16_f32 v52, v52, v53
	v_cvt_pk_bf16_f32 v53, v54, v55
	v_cvt_pk_bf16_f32 v54, v48, v49
	v_cvt_pk_bf16_f32 v55, v50, v51
	global_store_dwordx4 v[162:163], v[52:55], off offset:256
	v_lshl_add_u64 v[176:177], v[162:163], 0, s[46:47]
	v_mul_f32_e32 v44, v44, v156
	v_mul_f32_e32 v45, v45, v156
	v_mul_f32_e32 v46, v46, v156
	v_mul_f32_e32 v47, v47, v156
	v_mul_f32_e32 v40, v40, v156
	v_mul_f32_e32 v41, v41, v156
	v_mul_f32_e32 v42, v42, v156
	v_mul_f32_e32 v43, v43, v156
	v_mul_f32_e32 v184, 0xbfb8aa3b, v44
	v_mul_f32_e32 v185, 0xbfb8aa3b, v45
	v_mul_f32_e32 v186, 0xbfb8aa3b, v46
	v_mul_f32_e32 v187, 0xbfb8aa3b, v47
	v_mul_f32_e32 v188, 0xbfb8aa3b, v40
	v_mul_f32_e32 v189, 0xbfb8aa3b, v41
	v_mul_f32_e32 v190, 0xbfb8aa3b, v42
	v_mul_f32_e32 v191, 0xbfb8aa3b, v43
	v_exp_f32_e32 v184, v184
	v_exp_f32_e32 v185, v185
	v_exp_f32_e32 v186, v186
	v_exp_f32_e32 v187, v187
	v_exp_f32_e32 v188, v188
	v_exp_f32_e32 v189, v189
	v_exp_f32_e32 v190, v190
	v_exp_f32_e32 v191, v191
	v_sub_f32_e32 v192, 1.0, v152
	v_sub_f32_e32 v193, 1.0, v153
	v_sub_f32_e32 v194, 1.0, v154
	v_sub_f32_e32 v195, 1.0, v155
	v_sub_f32_e32 v196, 1.0, v180
	v_sub_f32_e32 v197, 1.0, v181
	v_sub_f32_e32 v198, 1.0, v182
	v_sub_f32_e32 v199, 1.0, v183
	v_add_f32_e32 v184, 1.0, v184
	v_add_f32_e32 v185, 1.0, v185
	v_add_f32_e32 v186, 1.0, v186
	v_add_f32_e32 v187, 1.0, v187
	v_add_f32_e32 v188, 1.0, v188
	v_add_f32_e32 v189, 1.0, v189
	v_add_f32_e32 v190, 1.0, v190
	v_add_f32_e32 v191, 1.0, v191
	v_rcp_f32_e32 v184, v184
	v_rcp_f32_e32 v185, v185
	v_rcp_f32_e32 v186, v186
	v_rcp_f32_e32 v187, v187
	v_rcp_f32_e32 v188, v188
	v_rcp_f32_e32 v189, v189
	v_rcp_f32_e32 v190, v190
	v_rcp_f32_e32 v191, v191
	v_fma_f32 v200, v184, v192, v152
	v_fma_f32 v201, v185, v193, v153
	v_fma_f32 v202, v186, v194, v154
	v_fma_f32 v203, v187, v195, v155
	v_fma_f32 v204, v188, v196, v180
	v_fma_f32 v205, v189, v197, v181
	v_fma_f32 v206, v190, v198, v182
	v_fma_f32 v207, v191, v199, v183
	v_cmp_gt_f32_e64 vcc, s35, v200
	v_cmp_gt_f32_e64 s[38:39], s35, v201
	v_cmp_gt_f32_e64 s[48:49], s35, v202
	v_cmp_gt_f32_e64 s[50:51], s35, v203
	v_cndmask_b32_e64 v184, 0, 32, vcc
	v_cndmask_b32_e64 v185, 0, 32, s[38:39]
	v_cndmask_b32_e64 v186, 0, 32, s[48:49]
	v_cndmask_b32_e64 v187, 0, 32, s[50:51]
	v_cndmask_b32_e64 v192, 0, v214, vcc
	v_cndmask_b32_e64 v193, 0, v214, s[38:39]
	v_cndmask_b32_e64 v194, 0, v214, s[48:49]
	v_cndmask_b32_e64 v195, 0, v214, s[50:51]
	v_cmp_gt_f32_e64 vcc, s35, v204
	v_cmp_gt_f32_e64 s[38:39], s35, v205
	v_cmp_gt_f32_e64 s[48:49], s35, v206
	v_cmp_gt_f32_e64 s[50:51], s35, v207
	v_cndmask_b32_e64 v188, 0, 32, vcc
	v_cndmask_b32_e64 v189, 0, 32, s[38:39]
	v_cndmask_b32_e64 v190, 0, 32, s[48:49]
	v_cndmask_b32_e64 v191, 0, 32, s[50:51]
	v_cndmask_b32_e64 v196, 0, v214, vcc
	v_cndmask_b32_e64 v197, 0, v214, s[38:39]
	v_cndmask_b32_e64 v198, 0, v214, s[48:49]
	v_cndmask_b32_e64 v199, 0, v214, s[50:51]
	v_ldexp_f32 v184, v200, v184
	v_ldexp_f32 v185, v201, v185
	v_ldexp_f32 v186, v202, v186
	v_ldexp_f32 v187, v203, v187
	v_ldexp_f32 v188, v204, v188
	v_ldexp_f32 v189, v205, v189
	v_ldexp_f32 v190, v206, v190
	v_ldexp_f32 v191, v207, v191
	v_log_f32_e32 v184, v184
	v_log_f32_e32 v185, v185
	v_log_f32_e32 v186, v186
	v_log_f32_e32 v187, v187
	v_log_f32_e32 v188, v188
	v_log_f32_e32 v189, v189
	v_log_f32_e32 v190, v190
	v_log_f32_e32 v191, v191
	v_mul_f32_e32 v200, 0x3f317217, v184
	v_mul_f32_e32 v201, 0x3f317217, v185
	v_mul_f32_e32 v202, 0x3f317217, v186
	v_mul_f32_e32 v203, 0x3f317217, v187
	v_mul_f32_e32 v204, 0x3f317217, v188
	v_mul_f32_e32 v205, 0x3f317217, v189
	v_mul_f32_e32 v206, 0x3f317217, v190
	v_mul_f32_e32 v207, 0x3f317217, v191
	v_fma_f32 v200, v184, s13, -v200
	v_fma_f32 v201, v185, s13, -v201
	v_fma_f32 v202, v186, s13, -v202
	v_fma_f32 v203, v187, s13, -v203
	v_fma_f32 v204, v188, s13, -v204
	v_fma_f32 v205, v189, s13, -v205
	v_fma_f32 v206, v190, s13, -v206
	v_fma_f32 v207, v191, s13, -v207
	v_fmac_f32_e32 v200, 0x3377d1cf, v184
	v_fmac_f32_e32 v201, 0x3377d1cf, v185
	v_fmac_f32_e32 v202, 0x3377d1cf, v186
	v_fmac_f32_e32 v203, 0x3377d1cf, v187
	v_fmac_f32_e32 v204, 0x3377d1cf, v188
	v_fmac_f32_e32 v205, 0x3377d1cf, v189
	v_fmac_f32_e32 v206, 0x3377d1cf, v190
; __device__ __forceinline__ unsigned cvt_pk_bf16(float lo, float hi) { unsigned r; asm volatile("v_cvt_pk_bf16_f32 %0, %1, %2" : "=v"(r) : "v"(lo), "v"(hi)); return r; }
; __device__ __forceinline__ float silu_f(float v) { return v * __builtin_amdgcn_rcpf(1.f + __expf(-v)); }
;     __device__ __forceinline__ void operator()(const f32x4 (&acc)[2][2][4][2], const Unit& u, int wr, int wc, int fr, int fq, int ui, PG8_LAS unsigned char* lds) const {
;     ...
;                     f32x4 v[2] = {acc[ai][bj][m][0] * rs, acc[ai][bj][m][1] * rs};
;                     if (ksum) { csum[bj][0] += v[0]; csum[bj][1] += v[1]; }
; #pragma unroll
;                     for (int n = 0; n < 2; ++n) {
;                         f32x4 lbv = (f32x4){0.f, 0.f, 0.f, 0.f};
;                         if (act == 2) lbv = *(const f32x4*)(lb + (col0 - 1024) + bj * HALF + 4 * n);
; #pragma unroll
;                         for (int e = 0; e < 4; ++e) {
;                             float x = v[n][e];
;                             if (act == 1) x = silu_f(x);
;                             else if (act == 2) { const float l = lbv[e]; x = __logf(l + (1.f - l) * __builtin_amdgcn_rcpf(1.f + __expf(-x))); }
;                             else if (act == 3) { x = fmaxf(x, 0.f); x = x * x; }
;                             v[n][e] = x;
;                         }
;                     }
;                     u32x4 w; w.x = cvt_pk_bf16(v[0][0], v[0][1]); w.y = cvt_pk_bf16(v[0][2], v[0][3]); w.z = cvt_pk_bf16(v[1][0], v[1][1]); w.w = cvt_pk_bf16(v[1][2], v[1][3]);
;                     *(u32x4*)(rowp + bj * HALF) = w;
	v_fmac_f32_e32 v207, 0x3377d1cf, v191
	v_fmac_f32_e32 v200, 0x3f317217, v184
	v_fmac_f32_e32 v201, 0x3f317217, v185
	v_fmac_f32_e32 v202, 0x3f317217, v186
	v_fmac_f32_e32 v203, 0x3f317217, v187
	v_fmac_f32_e32 v204, 0x3f317217, v188
	v_fmac_f32_e32 v205, 0x3f317217, v189
	v_fmac_f32_e32 v206, 0x3f317217, v190
	v_fmac_f32_e32 v207, 0x3f317217, v191
	v_cmp_lt_f32_e64 vcc, |v184|, s36
	v_cmp_lt_f32_e64 s[38:39], |v185|, s36
	v_cmp_lt_f32_e64 s[48:49], |v186|, s36
	v_cmp_lt_f32_e64 s[50:51], |v187|, s36
	v_cndmask_b32_e64 v184, v184, v200, vcc
	v_cndmask_b32_e64 v185, v185, v201, s[38:39]
	v_cndmask_b32_e64 v186, v186, v202, s[48:49]
	v_cndmask_b32_e64 v187, v187, v203, s[50:51]
	v_cmp_lt_f32_e64 vcc, |v188|, s36
	v_cmp_lt_f32_e64 s[38:39], |v189|, s36
	v_cmp_lt_f32_e64 s[48:49], |v190|, s36
	v_cmp_lt_f32_e64 s[50:51], |v191|, s36
	v_cndmask_b32_e64 v188, v188, v204, vcc
	v_cndmask_b32_e64 v189, v189, v205, s[38:39]
	v_cndmask_b32_e64 v190, v190, v206, s[48:49]
	v_cndmask_b32_e64 v191, v191, v207, s[50:51]
	v_sub_f32_e32 v44, v184, v192
	v_sub_f32_e32 v45, v185, v193
	v_sub_f32_e32 v46, v186, v194
	v_sub_f32_e32 v47, v187, v195
	v_sub_f32_e32 v40, v188, v196
	v_sub_f32_e32 v41, v189, v197
	v_sub_f32_e32 v42, v190, v198
	v_sub_f32_e32 v43, v191, v199
	v_cvt_pk_bf16_f32 v44, v44, v45
	v_cvt_pk_bf16_f32 v45, v46, v47
	v_cvt_pk_bf16_f32 v46, v40, v41
	v_cvt_pk_bf16_f32 v47, v42, v43
	global_store_dwordx4 v[176:177], v[44:47], off
	v_mul_f32_e32 v36, v36, v156
	v_mul_f32_e32 v37, v37, v156
	v_mul_f32_e32 v38, v38, v156
	v_mul_f32_e32 v39, v39, v156
	v_mul_f32_e32 v32, v32, v156
	v_mul_f32_e32 v33, v33, v156
	v_mul_f32_e32 v34, v34, v156
	v_mul_f32_e32 v35, v35, v156
	v_mul_f32_e32 v184, 0xbfb8aa3b, v36
	v_mul_f32_e32 v185, 0xbfb8aa3b, v37
	v_mul_f32_e32 v186, 0xbfb8aa3b, v38
	v_mul_f32_e32 v187, 0xbfb8aa3b, v39
	v_mul_f32_e32 v188, 0xbfb8aa3b, v32
	v_mul_f32_e32 v189, 0xbfb8aa3b, v33
	v_mul_f32_e32 v190, 0xbfb8aa3b, v34
	v_mul_f32_e32 v191, 0xbfb8aa3b, v35
	v_exp_f32_e32 v184, v184
	v_exp_f32_e32 v185, v185
	v_exp_f32_e32 v186, v186
	v_exp_f32_e32 v187, v187
	v_exp_f32_e32 v188, v188
	v_exp_f32_e32 v189, v189
	v_exp_f32_e32 v190, v190
	v_exp_f32_e32 v191, v191
	v_sub_f32_e32 v192, 1.0, v218
	v_sub_f32_e32 v193, 1.0, v219
	v_sub_f32_e32 v194, 1.0, v220
	v_sub_f32_e32 v195, 1.0, v221
	v_sub_f32_e32 v196, 1.0, v222
	v_sub_f32_e32 v197, 1.0, v223
	v_sub_f32_e32 v198, 1.0, v224
	v_sub_f32_e32 v199, 1.0, v225
	v_add_f32_e32 v184, 1.0, v184
	v_add_f32_e32 v185, 1.0, v185
	v_add_f32_e32 v186, 1.0, v186
	v_add_f32_e32 v187, 1.0, v187
	v_add_f32_e32 v188, 1.0, v188
	v_add_f32_e32 v189, 1.0, v189
	v_add_f32_e32 v190, 1.0, v190
	v_add_f32_e32 v191, 1.0, v191
	v_rcp_f32_e32 v184, v184
	v_rcp_f32_e32 v185, v185
	v_rcp_f32_e32 v186, v186
	v_rcp_f32_e32 v187, v187
	v_rcp_f32_e32 v188, v188
	v_rcp_f32_e32 v189, v189
	v_rcp_f32_e32 v190, v190
	v_rcp_f32_e32 v191, v191
	v_fma_f32 v200, v184, v192, v218
	v_fma_f32 v201, v185, v193, v219
	v_fma_f32 v202, v186, v194, v220
	v_fma_f32 v203, v187, v195, v221
	v_fma_f32 v204, v188, v196, v222
	v_fma_f32 v205, v189, v197, v223
	v_fma_f32 v206, v190, v198, v224
	v_fma_f32 v207, v191, v199, v225
	v_cmp_gt_f32_e64 vcc, s35, v200
	v_cmp_gt_f32_e64 s[38:39], s35, v201
	v_cmp_gt_f32_e64 s[48:49], s35, v202
	v_cmp_gt_f32_e64 s[50:51], s35, v203
	v_cndmask_b32_e64 v184, 0, 32, vcc
	v_cndmask_b32_e64 v185, 0, 32, s[38:39]
	v_cndmask_b32_e64 v186, 0, 32, s[48:49]
	v_cndmask_b32_e64 v187, 0, 32, s[50:51]
	v_cndmask_b32_e64 v192, 0, v214, vcc
	v_cndmask_b32_e64 v193, 0, v214, s[38:39]
	v_cndmask_b32_e64 v194, 0, v214, s[48:49]
	v_cndmask_b32_e64 v195, 0, v214, s[50:51]
	v_cmp_gt_f32_e64 vcc, s35, v204
	v_cmp_gt_f32_e64 s[38:39], s35, v205
	v_cmp_gt_f32_e64 s[48:49], s35, v206
	v_cmp_gt_f32_e64 s[50:51], s35, v207
	v_cndmask_b32_e64 v188, 0, 32, vcc
	v_cndmask_b32_e64 v189, 0, 32, s[38:39]
	v_cndmask_b32_e64 v190, 0, 32, s[48:49]
	v_cndmask_b32_e64 v191, 0, 32, s[50:51]
	v_cndmask_b32_e64 v196, 0, v214, vcc
	v_cndmask_b32_e64 v197, 0, v214, s[38:39]
	v_cndmask_b32_e64 v198, 0, v214, s[48:49]
	v_cndmask_b32_e64 v199, 0, v214, s[50:51]
	v_ldexp_f32 v184, v200, v184
	v_ldexp_f32 v185, v201, v185
	v_ldexp_f32 v186, v202, v186
	v_ldexp_f32 v187, v203, v187
	v_ldexp_f32 v188, v204, v188
	v_ldexp_f32 v189, v205, v189
	v_ldexp_f32 v190, v206, v190
	v_ldexp_f32 v191, v207, v191
	v_log_f32_e32 v184, v184
	v_log_f32_e32 v185, v185
	v_log_f32_e32 v186, v186
	v_log_f32_e32 v187, v187
	v_log_f32_e32 v188, v188
	v_log_f32_e32 v189, v189
	v_log_f32_e32 v190, v190
	v_log_f32_e32 v191, v191
	v_mul_f32_e32 v200, 0x3f317217, v184
	v_mul_f32_e32 v201, 0x3f317217, v185
	v_mul_f32_e32 v202, 0x3f317217, v186
	v_mul_f32_e32 v203, 0x3f317217, v187
	v_mul_f32_e32 v204, 0x3f317217, v188
	v_mul_f32_e32 v205, 0x3f317217, v189
	v_mul_f32_e32 v206, 0x3f317217, v190
	v_mul_f32_e32 v207, 0x3f317217, v191
	v_fma_f32 v200, v184, s13, -v200
	v_fma_f32 v201, v185, s13, -v201
	v_fma_f32 v202, v186, s13, -v202
	v_fma_f32 v203, v187, s13, -v203
	v_fma_f32 v204, v188, s13, -v204
	v_fma_f32 v205, v189, s13, -v205
	v_fma_f32 v206, v190, s13, -v206
	v_fma_f32 v207, v191, s13, -v207
	v_fmac_f32_e32 v200, 0x3377d1cf, v184
	v_fmac_f32_e32 v201, 0x3377d1cf, v185
	v_fmac_f32_e32 v202, 0x3377d1cf, v186
	v_fmac_f32_e32 v203, 0x3377d1cf, v187
	v_fmac_f32_e32 v204, 0x3377d1cf, v188
	v_fmac_f32_e32 v205, 0x3377d1cf, v189
	v_fmac_f32_e32 v206, 0x3377d1cf, v190
	v_fmac_f32_e32 v207, 0x3377d1cf, v191
	v_fmac_f32_e32 v200, 0x3f317217, v184
	v_fmac_f32_e32 v201, 0x3f317217, v185
	v_fmac_f32_e32 v202, 0x3f317217, v186
	v_fmac_f32_e32 v203, 0x3f317217, v187
	v_fmac_f32_e32 v204, 0x3f317217, v188
; __device__ __forceinline__ unsigned cvt_pk_bf16(float lo, float hi) { unsigned r; asm volatile("v_cvt_pk_bf16_f32 %0, %1, %2" : "=v"(r) : "v"(lo), "v"(hi)); return r; }
; __device__ __forceinline__ float silu_f(float v) { return v * __builtin_amdgcn_rcpf(1.f + __expf(-v)); }
;     __device__ __forceinline__ void operator()(const f32x4 (&acc)[2][2][4][2], const Unit& u, int wr, int wc, int fr, int fq, int ui, PG8_LAS unsigned char* lds) const {
;     ...
;                     f32x4 v[2] = {acc[ai][bj][m][0] * rs, acc[ai][bj][m][1] * rs};
;                     if (ksum) { csum[bj][0] += v[0]; csum[bj][1] += v[1]; }
; #pragma unroll
;                     for (int n = 0; n < 2; ++n) {
;                         f32x4 lbv = (f32x4){0.f, 0.f, 0.f, 0.f};
;                         if (act == 2) lbv = *(const f32x4*)(lb + (col0 - 1024) + bj * HALF + 4 * n);
; #pragma unroll
;                         for (int e = 0; e < 4; ++e) {
;                             float x = v[n][e];
;                             if (act == 1) x = silu_f(x);
;                             else if (act == 2) { const float l = lbv[e]; x = __logf(l + (1.f - l) * __builtin_amdgcn_rcpf(1.f + __expf(-x))); }
;                             else if (act == 3) { x = fmaxf(x, 0.f); x = x * x; }
;                             v[n][e] = x;
;                         }
;                     }
;                     u32x4 w; w.x = cvt_pk_bf16(v[0][0], v[0][1]); w.y = cvt_pk_bf16(v[0][2], v[0][3]); w.z = cvt_pk_bf16(v[1][0], v[1][1]); w.w = cvt_pk_bf16(v[1][2], v[1][3]);
;                     *(u32x4*)(rowp + bj * HALF) = w;
	v_fmac_f32_e32 v205, 0x3f317217, v189
	v_fmac_f32_e32 v206, 0x3f317217, v190
	v_fmac_f32_e32 v207, 0x3f317217, v191
	v_cmp_lt_f32_e64 vcc, |v184|, s36
	v_cmp_lt_f32_e64 s[38:39], |v185|, s36
	v_cmp_lt_f32_e64 s[48:49], |v186|, s36
	v_cmp_lt_f32_e64 s[50:51], |v187|, s36
	v_cndmask_b32_e64 v184, v184, v200, vcc
	v_cndmask_b32_e64 v185, v185, v201, s[38:39]
	v_cndmask_b32_e64 v186, v186, v202, s[48:49]
	v_cndmask_b32_e64 v187, v187, v203, s[50:51]
	v_cmp_lt_f32_e64 vcc, |v188|, s36
	v_cmp_lt_f32_e64 s[38:39], |v189|, s36
	v_cmp_lt_f32_e64 s[48:49], |v190|, s36
	v_cmp_lt_f32_e64 s[50:51], |v191|, s36
	v_cndmask_b32_e64 v188, v188, v204, vcc
	v_cndmask_b32_e64 v189, v189, v205, s[38:39]
	v_cndmask_b32_e64 v190, v190, v206, s[48:49]
	v_cndmask_b32_e64 v191, v191, v207, s[50:51]
	v_sub_f32_e32 v36, v184, v192
	v_sub_f32_e32 v37, v185, v193
	v_sub_f32_e32 v38, v186, v194
	v_sub_f32_e32 v39, v187, v195
	v_sub_f32_e32 v32, v188, v196
	v_sub_f32_e32 v33, v189, v197
	v_sub_f32_e32 v34, v190, v198
	v_sub_f32_e32 v35, v191, v199
	v_cvt_pk_bf16_f32 v36, v36, v37
	v_cvt_pk_bf16_f32 v37, v38, v39
	v_cvt_pk_bf16_f32 v38, v32, v33
	v_cvt_pk_bf16_f32 v39, v34, v35
	global_store_dwordx4 v[176:177], v[36:39], off offset:256
	v_lshl_add_u64 v[162:163], v[176:177], 0, s[46:47]
	v_mul_f32_e32 v28, v28, v158
	v_mul_f32_e32 v29, v29, v158
	v_mul_f32_e32 v30, v30, v158
	v_mul_f32_e32 v31, v31, v158
	v_mul_f32_e32 v24, v24, v158
	v_mul_f32_e32 v25, v25, v158
	v_mul_f32_e32 v26, v26, v158
	v_mul_f32_e32 v27, v27, v158
	v_mul_f32_e32 v184, 0xbfb8aa3b, v28
	v_mul_f32_e32 v185, 0xbfb8aa3b, v29
	v_mul_f32_e32 v186, 0xbfb8aa3b, v30
	v_mul_f32_e32 v187, 0xbfb8aa3b, v31
	v_mul_f32_e32 v188, 0xbfb8aa3b, v24
	v_mul_f32_e32 v189, 0xbfb8aa3b, v25
	v_mul_f32_e32 v190, 0xbfb8aa3b, v26
	v_mul_f32_e32 v191, 0xbfb8aa3b, v27
	v_exp_f32_e32 v184, v184
	v_exp_f32_e32 v185, v185
	v_exp_f32_e32 v186, v186
	v_exp_f32_e32 v187, v187
	v_exp_f32_e32 v188, v188
	v_exp_f32_e32 v189, v189
	v_exp_f32_e32 v190, v190
	v_exp_f32_e32 v191, v191
	v_sub_f32_e32 v192, 1.0, v152
	v_sub_f32_e32 v193, 1.0, v153
	v_sub_f32_e32 v194, 1.0, v154
	v_sub_f32_e32 v195, 1.0, v155
	v_sub_f32_e32 v196, 1.0, v180
	v_sub_f32_e32 v197, 1.0, v181
	v_sub_f32_e32 v198, 1.0, v182
	v_sub_f32_e32 v199, 1.0, v183
	v_add_f32_e32 v184, 1.0, v184
	v_add_f32_e32 v185, 1.0, v185
	v_add_f32_e32 v186, 1.0, v186
	v_add_f32_e32 v187, 1.0, v187
	v_add_f32_e32 v188, 1.0, v188
	v_add_f32_e32 v189, 1.0, v189
	v_add_f32_e32 v190, 1.0, v190
	v_add_f32_e32 v191, 1.0, v191
	v_rcp_f32_e32 v184, v184
	v_rcp_f32_e32 v185, v185
	v_rcp_f32_e32 v186, v186
	v_rcp_f32_e32 v187, v187
	v_rcp_f32_e32 v188, v188
	v_rcp_f32_e32 v189, v189
	v_rcp_f32_e32 v190, v190
	v_rcp_f32_e32 v191, v191
	v_fma_f32 v200, v184, v192, v152
	v_fma_f32 v201, v185, v193, v153
	v_fma_f32 v202, v186, v194, v154
	v_fma_f32 v203, v187, v195, v155
	v_fma_f32 v204, v188, v196, v180
	v_fma_f32 v205, v189, v197, v181
	v_fma_f32 v206, v190, v198, v182
	v_fma_f32 v207, v191, v199, v183
	v_cmp_gt_f32_e64 vcc, s35, v200
	v_cmp_gt_f32_e64 s[38:39], s35, v201
	v_cmp_gt_f32_e64 s[48:49], s35, v202
	v_cmp_gt_f32_e64 s[50:51], s35, v203
	v_cndmask_b32_e64 v184, 0, 32, vcc
	v_cndmask_b32_e64 v185, 0, 32, s[38:39]
	v_cndmask_b32_e64 v186, 0, 32, s[48:49]
	v_cndmask_b32_e64 v187, 0, 32, s[50:51]
	v_cndmask_b32_e64 v192, 0, v214, vcc
	v_cndmask_b32_e64 v193, 0, v214, s[38:39]
	v_cndmask_b32_e64 v194, 0, v214, s[48:49]
	v_cndmask_b32_e64 v195, 0, v214, s[50:51]
	v_cmp_gt_f32_e64 vcc, s35, v204
	v_cmp_gt_f32_e64 s[38:39], s35, v205
	v_cmp_gt_f32_e64 s[48:49], s35, v206
	v_cmp_gt_f32_e64 s[50:51], s35, v207
	v_cndmask_b32_e64 v188, 0, 32, vcc
	v_cndmask_b32_e64 v189, 0, 32, s[38:39]
	v_cndmask_b32_e64 v190, 0, 32, s[48:49]
	v_cndmask_b32_e64 v191, 0, 32, s[50:51]
	v_cndmask_b32_e64 v196, 0, v214, vcc
	v_cndmask_b32_e64 v197, 0, v214, s[38:39]
	v_cndmask_b32_e64 v198, 0, v214, s[48:49]
	v_cndmask_b32_e64 v199, 0, v214, s[50:51]
	v_ldexp_f32 v184, v200, v184
	v_ldexp_f32 v185, v201, v185
	v_ldexp_f32 v186, v202, v186
	v_ldexp_f32 v187, v203, v187
	v_ldexp_f32 v188, v204, v188
	v_ldexp_f32 v189, v205, v189
	v_ldexp_f32 v190, v206, v190
	v_ldexp_f32 v191, v207, v191
	v_log_f32_e32 v184, v184
	v_log_f32_e32 v185, v185
	v_log_f32_e32 v186, v186
	v_log_f32_e32 v187, v187
	v_log_f32_e32 v188, v188
	v_log_f32_e32 v189, v189
	v_log_f32_e32 v190, v190
	v_log_f32_e32 v191, v191
	v_mul_f32_e32 v200, 0x3f317217, v184
	v_mul_f32_e32 v201, 0x3f317217, v185
	v_mul_f32_e32 v202, 0x3f317217, v186
	v_mul_f32_e32 v203, 0x3f317217, v187
	v_mul_f32_e32 v204, 0x3f317217, v188
	v_mul_f32_e32 v205, 0x3f317217, v189
	v_mul_f32_e32 v206, 0x3f317217, v190
	v_mul_f32_e32 v207, 0x3f317217, v191
	v_fma_f32 v200, v184, s13, -v200
	v_fma_f32 v201, v185, s13, -v201
	v_fma_f32 v202, v186, s13, -v202
	v_fma_f32 v203, v187, s13, -v203
	v_fma_f32 v204, v188, s13, -v204
	v_fma_f32 v205, v189, s13, -v205
	v_fma_f32 v206, v190, s13, -v206
	v_fma_f32 v207, v191, s13, -v207
	v_fmac_f32_e32 v200, 0x3377d1cf, v184
	v_fmac_f32_e32 v201, 0x3377d1cf, v185
	v_fmac_f32_e32 v202, 0x3377d1cf, v186
	v_fmac_f32_e32 v203, 0x3377d1cf, v187
	v_fmac_f32_e32 v204, 0x3377d1cf, v188
	v_fmac_f32_e32 v205, 0x3377d1cf, v189
	v_fmac_f32_e32 v206, 0x3377d1cf, v190
	v_fmac_f32_e32 v207, 0x3377d1cf, v191
	v_fmac_f32_e32 v200, 0x3f317217, v184
	v_fmac_f32_e32 v201, 0x3f317217, v185
	v_fmac_f32_e32 v202, 0x3f317217, v186
	v_fmac_f32_e32 v203, 0x3f317217, v187
	v_fmac_f32_e32 v204, 0x3f317217, v188
	v_fmac_f32_e32 v205, 0x3f317217, v189
	v_fmac_f32_e32 v206, 0x3f317217, v190
	v_fmac_f32_e32 v207, 0x3f317217, v191
	v_cmp_lt_f32_e64 vcc, |v184|, s36
; __device__ __forceinline__ unsigned cvt_pk_bf16(float lo, float hi) { unsigned r; asm volatile("v_cvt_pk_bf16_f32 %0, %1, %2" : "=v"(r) : "v"(lo), "v"(hi)); return r; }
; __device__ __forceinline__ float silu_f(float v) { return v * __builtin_amdgcn_rcpf(1.f + __expf(-v)); }
;     __device__ __forceinline__ void operator()(const f32x4 (&acc)[2][2][4][2], const Unit& u, int wr, int wc, int fr, int fq, int ui, PG8_LAS unsigned char* lds) const {
;     ...
;                     f32x4 v[2] = {acc[ai][bj][m][0] * rs, acc[ai][bj][m][1] * rs};
;                     if (ksum) { csum[bj][0] += v[0]; csum[bj][1] += v[1]; }
; #pragma unroll
;                     for (int n = 0; n < 2; ++n) {
;                         f32x4 lbv = (f32x4){0.f, 0.f, 0.f, 0.f};
;                         if (act == 2) lbv = *(const f32x4*)(lb + (col0 - 1024) + bj * HALF + 4 * n);
; #pragma unroll
;                         for (int e = 0; e < 4; ++e) {
;                             float x = v[n][e];
;                             if (act == 1) x = silu_f(x);
;                             else if (act == 2) { const float l = lbv[e]; x = __logf(l + (1.f - l) * __builtin_amdgcn_rcpf(1.f + __expf(-x))); }
;                             else if (act == 3) { x = fmaxf(x, 0.f); x = x * x; }
;                             v[n][e] = x;
;                         }
;                     }
;                     u32x4 w; w.x = cvt_pk_bf16(v[0][0], v[0][1]); w.y = cvt_pk_bf16(v[0][2], v[0][3]); w.z = cvt_pk_bf16(v[1][0], v[1][1]); w.w = cvt_pk_bf16(v[1][2], v[1][3]);
;                     *(u32x4*)(rowp + bj * HALF) = w;
	v_cmp_lt_f32_e64 s[38:39], |v185|, s36
	v_cmp_lt_f32_e64 s[48:49], |v186|, s36
	v_cmp_lt_f32_e64 s[50:51], |v187|, s36
	v_cndmask_b32_e64 v184, v184, v200, vcc
	v_cndmask_b32_e64 v185, v185, v201, s[38:39]
	v_cndmask_b32_e64 v186, v186, v202, s[48:49]
	v_cndmask_b32_e64 v187, v187, v203, s[50:51]
	v_cmp_lt_f32_e64 vcc, |v188|, s36
	v_cmp_lt_f32_e64 s[38:39], |v189|, s36
	v_cmp_lt_f32_e64 s[48:49], |v190|, s36
	v_cmp_lt_f32_e64 s[50:51], |v191|, s36
	v_cndmask_b32_e64 v188, v188, v204, vcc
	v_cndmask_b32_e64 v189, v189, v205, s[38:39]
	v_cndmask_b32_e64 v190, v190, v206, s[48:49]
	v_cndmask_b32_e64 v191, v191, v207, s[50:51]
	v_sub_f32_e32 v28, v184, v192
	v_sub_f32_e32 v29, v185, v193
	v_sub_f32_e32 v30, v186, v194
	v_sub_f32_e32 v31, v187, v195
	v_sub_f32_e32 v24, v188, v196
	v_sub_f32_e32 v25, v189, v197
	v_sub_f32_e32 v26, v190, v198
	v_sub_f32_e32 v27, v191, v199
	v_cvt_pk_bf16_f32 v28, v28, v29
	v_cvt_pk_bf16_f32 v29, v30, v31
	v_cvt_pk_bf16_f32 v30, v24, v25
	v_cvt_pk_bf16_f32 v31, v26, v27
	global_store_dwordx4 v[162:163], v[28:31], off
	v_mul_f32_e32 v20, v20, v158
	v_mul_f32_e32 v21, v21, v158
	v_mul_f32_e32 v22, v22, v158
	v_mul_f32_e32 v23, v23, v158
	v_mul_f32_e32 v16, v16, v158
	v_mul_f32_e32 v17, v17, v158
	v_mul_f32_e32 v18, v18, v158
	v_mul_f32_e32 v19, v19, v158
	v_mul_f32_e32 v184, 0xbfb8aa3b, v20
	v_mul_f32_e32 v185, 0xbfb8aa3b, v21
	v_mul_f32_e32 v186, 0xbfb8aa3b, v22
	v_mul_f32_e32 v187, 0xbfb8aa3b, v23
	v_mul_f32_e32 v188, 0xbfb8aa3b, v16
	v_mul_f32_e32 v189, 0xbfb8aa3b, v17
	v_mul_f32_e32 v190, 0xbfb8aa3b, v18
	v_mul_f32_e32 v191, 0xbfb8aa3b, v19
	v_exp_f32_e32 v184, v184
	v_exp_f32_e32 v185, v185
	v_exp_f32_e32 v186, v186
	v_exp_f32_e32 v187, v187
	v_exp_f32_e32 v188, v188
	v_exp_f32_e32 v189, v189
	v_exp_f32_e32 v190, v190
	v_exp_f32_e32 v191, v191
	v_sub_f32_e32 v192, 1.0, v218
	v_sub_f32_e32 v193, 1.0, v219
	v_sub_f32_e32 v194, 1.0, v220
	v_sub_f32_e32 v195, 1.0, v221
	v_sub_f32_e32 v196, 1.0, v222
	v_sub_f32_e32 v197, 1.0, v223
	v_sub_f32_e32 v198, 1.0, v224
	v_sub_f32_e32 v199, 1.0, v225
	v_add_f32_e32 v184, 1.0, v184
	v_add_f32_e32 v185, 1.0, v185
	v_add_f32_e32 v186, 1.0, v186
	v_add_f32_e32 v187, 1.0, v187
	v_add_f32_e32 v188, 1.0, v188
	v_add_f32_e32 v189, 1.0, v189
	v_add_f32_e32 v190, 1.0, v190
	v_add_f32_e32 v191, 1.0, v191
	v_rcp_f32_e32 v184, v184
	v_rcp_f32_e32 v185, v185
	v_rcp_f32_e32 v186, v186
	v_rcp_f32_e32 v187, v187
	v_rcp_f32_e32 v188, v188
	v_rcp_f32_e32 v189, v189
	v_rcp_f32_e32 v190, v190
	v_rcp_f32_e32 v191, v191
	v_fma_f32 v200, v184, v192, v218
	v_fma_f32 v201, v185, v193, v219
	v_fma_f32 v202, v186, v194, v220
	v_fma_f32 v203, v187, v195, v221
	v_fma_f32 v204, v188, v196, v222
	v_fma_f32 v205, v189, v197, v223
	v_fma_f32 v206, v190, v198, v224
	v_fma_f32 v207, v191, v199, v225
	v_cmp_gt_f32_e64 vcc, s35, v200
	v_cmp_gt_f32_e64 s[38:39], s35, v201
	v_cmp_gt_f32_e64 s[48:49], s35, v202
	v_cmp_gt_f32_e64 s[50:51], s35, v203
	v_cndmask_b32_e64 v184, 0, 32, vcc
	v_cndmask_b32_e64 v185, 0, 32, s[38:39]
	v_cndmask_b32_e64 v186, 0, 32, s[48:49]
	v_cndmask_b32_e64 v187, 0, 32, s[50:51]
	v_cndmask_b32_e64 v192, 0, v214, vcc
	v_cndmask_b32_e64 v193, 0, v214, s[38:39]
	v_cndmask_b32_e64 v194, 0, v214, s[48:49]
	v_cndmask_b32_e64 v195, 0, v214, s[50:51]
	v_cmp_gt_f32_e64 vcc, s35, v204
	v_cmp_gt_f32_e64 s[38:39], s35, v205
	v_cmp_gt_f32_e64 s[48:49], s35, v206
	v_cmp_gt_f32_e64 s[50:51], s35, v207
	v_cndmask_b32_e64 v188, 0, 32, vcc
	v_cndmask_b32_e64 v189, 0, 32, s[38:39]
	v_cndmask_b32_e64 v190, 0, 32, s[48:49]
	v_cndmask_b32_e64 v191, 0, 32, s[50:51]
	v_cndmask_b32_e64 v196, 0, v214, vcc
	v_cndmask_b32_e64 v197, 0, v214, s[38:39]
	v_cndmask_b32_e64 v198, 0, v214, s[48:49]
	v_cndmask_b32_e64 v199, 0, v214, s[50:51]
	v_ldexp_f32 v184, v200, v184
	v_ldexp_f32 v185, v201, v185
	v_ldexp_f32 v186, v202, v186
	v_ldexp_f32 v187, v203, v187
	v_ldexp_f32 v188, v204, v188
	v_ldexp_f32 v189, v205, v189
	v_ldexp_f32 v190, v206, v190
	v_ldexp_f32 v191, v207, v191
	v_log_f32_e32 v184, v184
	v_log_f32_e32 v185, v185
	v_log_f32_e32 v186, v186
	v_log_f32_e32 v187, v187
	v_log_f32_e32 v188, v188
	v_log_f32_e32 v189, v189
	v_log_f32_e32 v190, v190
	v_log_f32_e32 v191, v191
	v_mul_f32_e32 v200, 0x3f317217, v184
	v_mul_f32_e32 v201, 0x3f317217, v185
	v_mul_f32_e32 v202, 0x3f317217, v186
	v_mul_f32_e32 v203, 0x3f317217, v187
	v_mul_f32_e32 v204, 0x3f317217, v188
	v_mul_f32_e32 v205, 0x3f317217, v189
	v_mul_f32_e32 v206, 0x3f317217, v190
	v_mul_f32_e32 v207, 0x3f317217, v191
	v_fma_f32 v200, v184, s13, -v200
	v_fma_f32 v201, v185, s13, -v201
	v_fma_f32 v202, v186, s13, -v202
	v_fma_f32 v203, v187, s13, -v203
	v_fma_f32 v204, v188, s13, -v204
	v_fma_f32 v205, v189, s13, -v205
	v_fma_f32 v206, v190, s13, -v206
	v_fma_f32 v207, v191, s13, -v207
	v_fmac_f32_e32 v200, 0x3377d1cf, v184
	v_fmac_f32_e32 v201, 0x3377d1cf, v185
	v_fmac_f32_e32 v202, 0x3377d1cf, v186
	v_fmac_f32_e32 v203, 0x3377d1cf, v187
	v_fmac_f32_e32 v204, 0x3377d1cf, v188
	v_fmac_f32_e32 v205, 0x3377d1cf, v189
	v_fmac_f32_e32 v206, 0x3377d1cf, v190
	v_fmac_f32_e32 v207, 0x3377d1cf, v191
	v_fmac_f32_e32 v200, 0x3f317217, v184
	v_fmac_f32_e32 v201, 0x3f317217, v185
	v_fmac_f32_e32 v202, 0x3f317217, v186
	v_fmac_f32_e32 v203, 0x3f317217, v187
	v_fmac_f32_e32 v204, 0x3f317217, v188
	v_fmac_f32_e32 v205, 0x3f317217, v189
	v_fmac_f32_e32 v206, 0x3f317217, v190
	v_fmac_f32_e32 v207, 0x3f317217, v191
	v_cmp_lt_f32_e64 vcc, |v184|, s36
	v_cmp_lt_f32_e64 s[38:39], |v185|, s36
	v_cmp_lt_f32_e64 s[48:49], |v186|, s36
	v_cmp_lt_f32_e64 s[50:51], |v187|, s36
	v_cndmask_b32_e64 v184, v184, v200, vcc
	v_cndmask_b32_e64 v185, v185, v201, s[38:39]
; __device__ __forceinline__ unsigned cvt_pk_bf16(float lo, float hi) { unsigned r; asm volatile("v_cvt_pk_bf16_f32 %0, %1, %2" : "=v"(r) : "v"(lo), "v"(hi)); return r; }
; __device__ __forceinline__ float silu_f(float v) { return v * __builtin_amdgcn_rcpf(1.f + __expf(-v)); }
;     __device__ __forceinline__ void operator()(const f32x4 (&acc)[2][2][4][2], const Unit& u, int wr, int wc, int fr, int fq, int ui, PG8_LAS unsigned char* lds) const {
;     ...
;                     f32x4 v[2] = {acc[ai][bj][m][0] * rs, acc[ai][bj][m][1] * rs};
;                     if (ksum) { csum[bj][0] += v[0]; csum[bj][1] += v[1]; }
; #pragma unroll
;                     for (int n = 0; n < 2; ++n) {
;                         f32x4 lbv = (f32x4){0.f, 0.f, 0.f, 0.f};
;                         if (act == 2) lbv = *(const f32x4*)(lb + (col0 - 1024) + bj * HALF + 4 * n);
; #pragma unroll
;                         for (int e = 0; e < 4; ++e) {
;                             float x = v[n][e];
;                             if (act == 1) x = silu_f(x);
;                             else if (act == 2) { const float l = lbv[e]; x = __logf(l + (1.f - l) * __builtin_amdgcn_rcpf(1.f + __expf(-x))); }
;                             else if (act == 3) { x = fmaxf(x, 0.f); x = x * x; }
;                             v[n][e] = x;
;                         }
;                     }
;                     u32x4 w; w.x = cvt_pk_bf16(v[0][0], v[0][1]); w.y = cvt_pk_bf16(v[0][2], v[0][3]); w.z = cvt_pk_bf16(v[1][0], v[1][1]); w.w = cvt_pk_bf16(v[1][2], v[1][3]);
;                     *(u32x4*)(rowp + bj * HALF) = w;
	v_cndmask_b32_e64 v186, v186, v202, s[48:49]
	v_cndmask_b32_e64 v187, v187, v203, s[50:51]
	v_cmp_lt_f32_e64 vcc, |v188|, s36
	v_cmp_lt_f32_e64 s[38:39], |v189|, s36
	v_cmp_lt_f32_e64 s[48:49], |v190|, s36
	v_cmp_lt_f32_e64 s[50:51], |v191|, s36
	v_cndmask_b32_e64 v188, v188, v204, vcc
	v_cndmask_b32_e64 v189, v189, v205, s[38:39]
	v_cndmask_b32_e64 v190, v190, v206, s[48:49]
	v_cndmask_b32_e64 v191, v191, v207, s[50:51]
	v_sub_f32_e32 v20, v184, v192
	v_sub_f32_e32 v21, v185, v193
	v_sub_f32_e32 v22, v186, v194
	v_sub_f32_e32 v23, v187, v195
	v_sub_f32_e32 v16, v188, v196
	v_sub_f32_e32 v17, v189, v197
	v_sub_f32_e32 v18, v190, v198
	v_sub_f32_e32 v19, v191, v199
	v_cvt_pk_bf16_f32 v20, v20, v21
	v_cvt_pk_bf16_f32 v21, v22, v23
	v_cvt_pk_bf16_f32 v22, v16, v17
	v_cvt_pk_bf16_f32 v23, v18, v19
	global_store_dwordx4 v[162:163], v[20:23], off offset:256
	v_lshl_add_u64 v[176:177], v[162:163], 0, s[46:47]
	v_mul_f32_e32 v12, v12, v160
	v_mul_f32_e32 v13, v13, v160
	v_mul_f32_e32 v14, v14, v160
	v_mul_f32_e32 v15, v15, v160
	v_mul_f32_e32 v8, v8, v160
	v_mul_f32_e32 v9, v9, v160
	v_mul_f32_e32 v10, v10, v160
	v_mul_f32_e32 v11, v11, v160
	v_mul_f32_e32 v184, 0xbfb8aa3b, v12
	v_mul_f32_e32 v185, 0xbfb8aa3b, v13
	v_mul_f32_e32 v186, 0xbfb8aa3b, v14
	v_mul_f32_e32 v187, 0xbfb8aa3b, v15
	v_mul_f32_e32 v188, 0xbfb8aa3b, v8
	v_mul_f32_e32 v189, 0xbfb8aa3b, v9
	v_mul_f32_e32 v190, 0xbfb8aa3b, v10
	v_mul_f32_e32 v191, 0xbfb8aa3b, v11
	v_exp_f32_e32 v184, v184
	v_exp_f32_e32 v185, v185
	v_exp_f32_e32 v186, v186
	v_exp_f32_e32 v187, v187
	v_exp_f32_e32 v188, v188
	v_exp_f32_e32 v189, v189
	v_exp_f32_e32 v190, v190
	v_exp_f32_e32 v191, v191
	v_sub_f32_e32 v192, 1.0, v152
	v_sub_f32_e32 v193, 1.0, v153
	v_sub_f32_e32 v194, 1.0, v154
	v_sub_f32_e32 v195, 1.0, v155
	v_sub_f32_e32 v196, 1.0, v180
	v_sub_f32_e32 v197, 1.0, v181
	v_sub_f32_e32 v198, 1.0, v182
	v_sub_f32_e32 v199, 1.0, v183
	v_add_f32_e32 v184, 1.0, v184
	v_add_f32_e32 v185, 1.0, v185
	v_add_f32_e32 v186, 1.0, v186
	v_add_f32_e32 v187, 1.0, v187
	v_add_f32_e32 v188, 1.0, v188
	v_add_f32_e32 v189, 1.0, v189
	v_add_f32_e32 v190, 1.0, v190
	v_add_f32_e32 v191, 1.0, v191
	v_rcp_f32_e32 v184, v184
	v_rcp_f32_e32 v185, v185
	v_rcp_f32_e32 v186, v186
	v_rcp_f32_e32 v187, v187
	v_rcp_f32_e32 v188, v188
	v_rcp_f32_e32 v189, v189
	v_rcp_f32_e32 v190, v190
	v_rcp_f32_e32 v191, v191
	v_fma_f32 v200, v184, v192, v152
	v_fma_f32 v201, v185, v193, v153
	v_fma_f32 v202, v186, v194, v154
	v_fma_f32 v203, v187, v195, v155
	v_fma_f32 v204, v188, v196, v180
	v_fma_f32 v205, v189, v197, v181
	v_fma_f32 v206, v190, v198, v182
	v_fma_f32 v207, v191, v199, v183
	v_cmp_gt_f32_e64 vcc, s35, v200
	v_cmp_gt_f32_e64 s[38:39], s35, v201
	v_cmp_gt_f32_e64 s[48:49], s35, v202
	v_cmp_gt_f32_e64 s[50:51], s35, v203
	v_cndmask_b32_e64 v184, 0, 32, vcc
	v_cndmask_b32_e64 v185, 0, 32, s[38:39]
	v_cndmask_b32_e64 v186, 0, 32, s[48:49]
	v_cndmask_b32_e64 v187, 0, 32, s[50:51]
	v_cndmask_b32_e64 v192, 0, v214, vcc
	v_cndmask_b32_e64 v193, 0, v214, s[38:39]
	v_cndmask_b32_e64 v194, 0, v214, s[48:49]
	v_cndmask_b32_e64 v195, 0, v214, s[50:51]
	v_cmp_gt_f32_e64 vcc, s35, v204
	v_cmp_gt_f32_e64 s[38:39], s35, v205
	v_cmp_gt_f32_e64 s[48:49], s35, v206
	v_cmp_gt_f32_e64 s[50:51], s35, v207
	v_cndmask_b32_e64 v188, 0, 32, vcc
	v_cndmask_b32_e64 v189, 0, 32, s[38:39]
	v_cndmask_b32_e64 v190, 0, 32, s[48:49]
	v_cndmask_b32_e64 v191, 0, 32, s[50:51]
	v_cndmask_b32_e64 v196, 0, v214, vcc
	v_cndmask_b32_e64 v197, 0, v214, s[38:39]
	v_cndmask_b32_e64 v198, 0, v214, s[48:49]
	v_cndmask_b32_e64 v199, 0, v214, s[50:51]
	v_ldexp_f32 v184, v200, v184
	v_ldexp_f32 v185, v201, v185
	v_ldexp_f32 v186, v202, v186
	v_ldexp_f32 v187, v203, v187
	v_ldexp_f32 v188, v204, v188
	v_ldexp_f32 v189, v205, v189
	v_ldexp_f32 v190, v206, v190
	v_ldexp_f32 v191, v207, v191
	v_log_f32_e32 v184, v184
	v_log_f32_e32 v185, v185
	v_log_f32_e32 v186, v186
	v_log_f32_e32 v187, v187
	v_log_f32_e32 v188, v188
	v_log_f32_e32 v189, v189
	v_log_f32_e32 v190, v190
	v_log_f32_e32 v191, v191
	v_mul_f32_e32 v200, 0x3f317217, v184
	v_mul_f32_e32 v201, 0x3f317217, v185
	v_mul_f32_e32 v202, 0x3f317217, v186
	v_mul_f32_e32 v203, 0x3f317217, v187
	v_mul_f32_e32 v204, 0x3f317217, v188
	v_mul_f32_e32 v205, 0x3f317217, v189
	v_mul_f32_e32 v206, 0x3f317217, v190
	v_mul_f32_e32 v207, 0x3f317217, v191
	v_fma_f32 v200, v184, s13, -v200
	v_fma_f32 v201, v185, s13, -v201
	v_fma_f32 v202, v186, s13, -v202
	v_fma_f32 v203, v187, s13, -v203
	v_fma_f32 v204, v188, s13, -v204
	v_fma_f32 v205, v189, s13, -v205
	v_fma_f32 v206, v190, s13, -v206
	v_fma_f32 v207, v191, s13, -v207
	v_fmac_f32_e32 v200, 0x3377d1cf, v184
	v_fmac_f32_e32 v201, 0x3377d1cf, v185
	v_fmac_f32_e32 v202, 0x3377d1cf, v186
	v_fmac_f32_e32 v203, 0x3377d1cf, v187
	v_fmac_f32_e32 v204, 0x3377d1cf, v188
	v_fmac_f32_e32 v205, 0x3377d1cf, v189
	v_fmac_f32_e32 v206, 0x3377d1cf, v190
	v_fmac_f32_e32 v207, 0x3377d1cf, v191
	v_fmac_f32_e32 v200, 0x3f317217, v184
	v_fmac_f32_e32 v201, 0x3f317217, v185
	v_fmac_f32_e32 v202, 0x3f317217, v186
	v_fmac_f32_e32 v203, 0x3f317217, v187
	v_fmac_f32_e32 v204, 0x3f317217, v188
	v_fmac_f32_e32 v205, 0x3f317217, v189
	v_fmac_f32_e32 v206, 0x3f317217, v190
	v_fmac_f32_e32 v207, 0x3f317217, v191
	v_cmp_lt_f32_e64 vcc, |v184|, s36
	v_cmp_lt_f32_e64 s[38:39], |v185|, s36
	v_cmp_lt_f32_e64 s[48:49], |v186|, s36
	v_cmp_lt_f32_e64 s[50:51], |v187|, s36
	v_cndmask_b32_e64 v184, v184, v200, vcc
	v_cndmask_b32_e64 v185, v185, v201, s[38:39]
	v_cndmask_b32_e64 v186, v186, v202, s[48:49]
	v_cndmask_b32_e64 v187, v187, v203, s[50:51]
	v_cmp_lt_f32_e64 vcc, |v188|, s36
	v_cmp_lt_f32_e64 s[38:39], |v189|, s36
; __device__ __forceinline__ unsigned cvt_pk_bf16(float lo, float hi) { unsigned r; asm volatile("v_cvt_pk_bf16_f32 %0, %1, %2" : "=v"(r) : "v"(lo), "v"(hi)); return r; }
; __device__ __forceinline__ float silu_f(float v) { return v * __builtin_amdgcn_rcpf(1.f + __expf(-v)); }
;     __device__ __forceinline__ void operator()(const f32x4 (&acc)[2][2][4][2], const Unit& u, int wr, int wc, int fr, int fq, int ui, PG8_LAS unsigned char* lds) const {
;     ...
;                     f32x4 v[2] = {acc[ai][bj][m][0] * rs, acc[ai][bj][m][1] * rs};
;                     if (ksum) { csum[bj][0] += v[0]; csum[bj][1] += v[1]; }
; #pragma unroll
;                     for (int n = 0; n < 2; ++n) {
;                         f32x4 lbv = (f32x4){0.f, 0.f, 0.f, 0.f};
;                         if (act == 2) lbv = *(const f32x4*)(lb + (col0 - 1024) + bj * HALF + 4 * n);
; #pragma unroll
;                         for (int e = 0; e < 4; ++e) {
;                             float x = v[n][e];
;                             if (act == 1) x = silu_f(x);
;                             else if (act == 2) { const float l = lbv[e]; x = __logf(l + (1.f - l) * __builtin_amdgcn_rcpf(1.f + __expf(-x))); }
;                             else if (act == 3) { x = fmaxf(x, 0.f); x = x * x; }
;                             v[n][e] = x;
;                         }
;                     }
;                     u32x4 w; w.x = cvt_pk_bf16(v[0][0], v[0][1]); w.y = cvt_pk_bf16(v[0][2], v[0][3]); w.z = cvt_pk_bf16(v[1][0], v[1][1]); w.w = cvt_pk_bf16(v[1][2], v[1][3]);
;                     *(u32x4*)(rowp + bj * HALF) = w;
	v_cmp_lt_f32_e64 s[48:49], |v190|, s36
	v_cmp_lt_f32_e64 s[50:51], |v191|, s36
	v_cndmask_b32_e64 v188, v188, v204, vcc
	v_cndmask_b32_e64 v189, v189, v205, s[38:39]
	v_cndmask_b32_e64 v190, v190, v206, s[48:49]
	v_cndmask_b32_e64 v191, v191, v207, s[50:51]
	v_sub_f32_e32 v12, v184, v192
	v_sub_f32_e32 v13, v185, v193
	v_sub_f32_e32 v14, v186, v194
	v_sub_f32_e32 v15, v187, v195
	v_sub_f32_e32 v8, v188, v196
	v_sub_f32_e32 v9, v189, v197
	v_sub_f32_e32 v10, v190, v198
	v_sub_f32_e32 v11, v191, v199
	v_cvt_pk_bf16_f32 v12, v12, v13
	v_cvt_pk_bf16_f32 v13, v14, v15
	v_cvt_pk_bf16_f32 v14, v8, v9
	v_cvt_pk_bf16_f32 v15, v10, v11
	global_store_dwordx4 v[176:177], v[12:15], off
	v_mul_f32_e32 v4, v4, v160
	v_mul_f32_e32 v5, v5, v160
	v_mul_f32_e32 v6, v6, v160
	v_mul_f32_e32 v7, v7, v160
	v_mul_f32_e32 v0, v0, v160
	v_mul_f32_e32 v1, v1, v160
	v_mul_f32_e32 v2, v2, v160
	v_mul_f32_e32 v3, v3, v160
	v_mul_f32_e32 v184, 0xbfb8aa3b, v4
	v_mul_f32_e32 v185, 0xbfb8aa3b, v5
	v_mul_f32_e32 v186, 0xbfb8aa3b, v6
	v_mul_f32_e32 v187, 0xbfb8aa3b, v7
	v_mul_f32_e32 v188, 0xbfb8aa3b, v0
	v_mul_f32_e32 v189, 0xbfb8aa3b, v1
	v_mul_f32_e32 v190, 0xbfb8aa3b, v2
	v_mul_f32_e32 v191, 0xbfb8aa3b, v3
	v_exp_f32_e32 v184, v184
	v_exp_f32_e32 v185, v185
	v_exp_f32_e32 v186, v186
	v_exp_f32_e32 v187, v187
	v_exp_f32_e32 v188, v188
	v_exp_f32_e32 v189, v189
	v_exp_f32_e32 v190, v190
	v_exp_f32_e32 v191, v191
	v_sub_f32_e32 v192, 1.0, v218
	v_sub_f32_e32 v193, 1.0, v219
	v_sub_f32_e32 v194, 1.0, v220
	v_sub_f32_e32 v195, 1.0, v221
	v_sub_f32_e32 v196, 1.0, v222
	v_sub_f32_e32 v197, 1.0, v223
	v_sub_f32_e32 v198, 1.0, v224
	v_sub_f32_e32 v199, 1.0, v225
	v_add_f32_e32 v184, 1.0, v184
	v_add_f32_e32 v185, 1.0, v185
	v_add_f32_e32 v186, 1.0, v186
	v_add_f32_e32 v187, 1.0, v187
	v_add_f32_e32 v188, 1.0, v188
	v_add_f32_e32 v189, 1.0, v189
	v_add_f32_e32 v190, 1.0, v190
	v_add_f32_e32 v191, 1.0, v191
	v_rcp_f32_e32 v184, v184
	v_rcp_f32_e32 v185, v185
	v_rcp_f32_e32 v186, v186
	v_rcp_f32_e32 v187, v187
	v_rcp_f32_e32 v188, v188
	v_rcp_f32_e32 v189, v189
	v_rcp_f32_e32 v190, v190
	v_rcp_f32_e32 v191, v191
	v_fma_f32 v200, v184, v192, v218
	v_fma_f32 v201, v185, v193, v219
	v_fma_f32 v202, v186, v194, v220
	v_fma_f32 v203, v187, v195, v221
	v_fma_f32 v204, v188, v196, v222
	v_fma_f32 v205, v189, v197, v223
	v_fma_f32 v206, v190, v198, v224
	v_fma_f32 v207, v191, v199, v225
	v_cmp_gt_f32_e64 vcc, s35, v200
	v_cmp_gt_f32_e64 s[38:39], s35, v201
	v_cmp_gt_f32_e64 s[48:49], s35, v202
	v_cmp_gt_f32_e64 s[50:51], s35, v203
	v_cndmask_b32_e64 v184, 0, 32, vcc
	v_cndmask_b32_e64 v185, 0, 32, s[38:39]
	v_cndmask_b32_e64 v186, 0, 32, s[48:49]
	v_cndmask_b32_e64 v187, 0, 32, s[50:51]
	v_cndmask_b32_e64 v192, 0, v214, vcc
	v_cndmask_b32_e64 v193, 0, v214, s[38:39]
	v_cndmask_b32_e64 v194, 0, v214, s[48:49]
	v_cndmask_b32_e64 v195, 0, v214, s[50:51]
	v_cmp_gt_f32_e64 vcc, s35, v204
	v_cmp_gt_f32_e64 s[38:39], s35, v205
	v_cmp_gt_f32_e64 s[48:49], s35, v206
	v_cmp_gt_f32_e64 s[50:51], s35, v207
	v_cndmask_b32_e64 v188, 0, 32, vcc
	v_cndmask_b32_e64 v189, 0, 32, s[38:39]
	v_cndmask_b32_e64 v190, 0, 32, s[48:49]
	v_cndmask_b32_e64 v191, 0, 32, s[50:51]
	v_cndmask_b32_e64 v196, 0, v214, vcc
	v_cndmask_b32_e64 v197, 0, v214, s[38:39]
	v_cndmask_b32_e64 v198, 0, v214, s[48:49]
	v_cndmask_b32_e64 v199, 0, v214, s[50:51]
	v_ldexp_f32 v184, v200, v184
	v_ldexp_f32 v185, v201, v185
	v_ldexp_f32 v186, v202, v186
	v_ldexp_f32 v187, v203, v187
	v_ldexp_f32 v188, v204, v188
	v_ldexp_f32 v189, v205, v189
	v_ldexp_f32 v190, v206, v190
	v_ldexp_f32 v191, v207, v191
	v_log_f32_e32 v184, v184
	v_log_f32_e32 v185, v185
	v_log_f32_e32 v186, v186
	v_log_f32_e32 v187, v187
	v_log_f32_e32 v188, v188
	v_log_f32_e32 v189, v189
	v_log_f32_e32 v190, v190
	v_log_f32_e32 v191, v191
	v_mul_f32_e32 v200, 0x3f317217, v184
	v_mul_f32_e32 v201, 0x3f317217, v185
	v_mul_f32_e32 v202, 0x3f317217, v186
	v_mul_f32_e32 v203, 0x3f317217, v187
	v_mul_f32_e32 v204, 0x3f317217, v188
	v_mul_f32_e32 v205, 0x3f317217, v189
	v_mul_f32_e32 v206, 0x3f317217, v190
	v_mul_f32_e32 v207, 0x3f317217, v191
	v_fma_f32 v200, v184, s13, -v200
	v_fma_f32 v201, v185, s13, -v201
	v_fma_f32 v202, v186, s13, -v202
	v_fma_f32 v203, v187, s13, -v203
	v_fma_f32 v204, v188, s13, -v204
	v_fma_f32 v205, v189, s13, -v205
	v_fma_f32 v206, v190, s13, -v206
	v_fma_f32 v207, v191, s13, -v207
	v_fmac_f32_e32 v200, 0x3377d1cf, v184
	v_fmac_f32_e32 v201, 0x3377d1cf, v185
	v_fmac_f32_e32 v202, 0x3377d1cf, v186
	v_fmac_f32_e32 v203, 0x3377d1cf, v187
	v_fmac_f32_e32 v204, 0x3377d1cf, v188
	v_fmac_f32_e32 v205, 0x3377d1cf, v189
	v_fmac_f32_e32 v206, 0x3377d1cf, v190
	v_fmac_f32_e32 v207, 0x3377d1cf, v191
	v_fmac_f32_e32 v200, 0x3f317217, v184
	v_fmac_f32_e32 v201, 0x3f317217, v185
	v_fmac_f32_e32 v202, 0x3f317217, v186
	v_fmac_f32_e32 v203, 0x3f317217, v187
	v_fmac_f32_e32 v204, 0x3f317217, v188
	v_fmac_f32_e32 v205, 0x3f317217, v189
	v_fmac_f32_e32 v206, 0x3f317217, v190
	v_fmac_f32_e32 v207, 0x3f317217, v191
	v_cmp_lt_f32_e64 vcc, |v184|, s36
	v_cmp_lt_f32_e64 s[38:39], |v185|, s36
	v_cmp_lt_f32_e64 s[48:49], |v186|, s36
	v_cmp_lt_f32_e64 s[50:51], |v187|, s36
	v_cndmask_b32_e64 v184, v184, v200, vcc
	v_cndmask_b32_e64 v185, v185, v201, s[38:39]
	v_cndmask_b32_e64 v186, v186, v202, s[48:49]
	v_cndmask_b32_e64 v187, v187, v203, s[50:51]
	v_cmp_lt_f32_e64 vcc, |v188|, s36
	v_cmp_lt_f32_e64 s[38:39], |v189|, s36
	v_cmp_lt_f32_e64 s[48:49], |v190|, s36
	v_cmp_lt_f32_e64 s[50:51], |v191|, s36
	v_cndmask_b32_e64 v188, v188, v204, vcc
	v_cndmask_b32_e64 v189, v189, v205, s[38:39]
	v_cndmask_b32_e64 v190, v190, v206, s[48:49]
	v_cndmask_b32_e64 v191, v191, v207, s[50:51]
	v_sub_f32_e32 v4, v184, v192
	v_sub_f32_e32 v5, v185, v193
	v_sub_f32_e32 v6, v186, v194
	v_sub_f32_e32 v7, v187, v195
	v_sub_f32_e32 v0, v188, v196
	v_sub_f32_e32 v1, v189, v197
	v_sub_f32_e32 v2, v190, v198
	v_sub_f32_e32 v3, v191, v199
	v_cvt_pk_bf16_f32 v4, v4, v5
	v_cvt_pk_bf16_f32 v5, v6, v7
	v_cvt_pk_bf16_f32 v6, v0, v1
	v_cvt_pk_bf16_f32 v7, v2, v3
	global_store_dwordx4 v[176:177], v[4:7], off offset:256
	s_branch .LBB0_1108

; __device__ __forceinline__ float ssq_row(const float* part, int row) {
;     const f32x4* p = (const f32x4*)(part + (size_t)row * 16);
;     const f32x4 a = p[0], b = p[1], c = p[2], d = p[3];
;     return (((a[0] + a[1]) + (a[2] + a[3])) + ((b[0] + b[1]) + (b[2] + b[3]))) + (((c[0] + c[1]) + (c[2] + c[3])) + ((d[0] + d[1]) + (d[2] + d[3])));
; }
;     __device__ __forceinline__ void operator()(const f32x4 (&acc)[2][2][4][2], const Unit& u, int wr, int wc, int fr, int fq, int ui, PG8_LAS unsigned char* lds) const {
;     ...
;                     if (use_tab) { rs4[m] = tab[ai * HALF + m * 16] * sc; rs4[m + 1] = tab[ai * HALF + (m + 1) * 16] * sc; }
;                     else {
;                         asm volatile("" ::: "memory");
;                         rs4[m] = __builtin_amdgcn_rsqf(ssq_row(ssq, row0 + ai * HALF + m * 16) * (1.0f / 1024.0f) + RMS_EPS) * sc;
;                         rs4[m + 1] = __builtin_amdgcn_rsqf(ssq_row(ssq, row0 + ai * HALF + (m + 1) * 16) * (1.0f / 1024.0f) + RMS_EPS) * sc;
.LBB0_228:
	s_andn2_b64 vcc, exec, s[38:39]
	v_or_b32_e32 v154, 16, v150
	s_cbranch_vccnz .LBB0_230
	v_lshlrev_b64 v[128:129], 6, v[150:151]
	v_lshl_add_u64 v[148:149], s[24:25], 0, v[128:129]
	global_load_dwordx4 v[128:131], v[148:149], off offset:16
	global_load_dwordx4 v[144:147], v[148:149], off offset:48
	global_load_dwordx4 v[156:159], v[148:149], off
	global_load_dwordx4 v[160:163], v[148:149], off offset:32
	v_ashrrev_i32_e32 v155, 31, v154
	s_waitcnt vmcnt(0)
	v_mov_b32_e32 v148, v156
	v_mov_b32_e32 v149, v160
	v_mov_b32_e32 v160, v157
	v_mov_b32_e32 v152, v158
	v_mov_b32_e32 v153, v162
	v_mov_b32_e32 v162, v159
	v_add_f32_e32 v148, v148, v160
	v_add_f32_e32 v149, v149, v161
	v_add_f32_e32 v152, v152, v162
	v_add_f32_e32 v153, v153, v163
	s_nop 0
	v_add_f32_e32 v148, v148, v152
	v_add_f32_e32 v149, v149, v153
	v_mov_b32_e32 v152, v128
	v_mov_b32_e32 v153, v144
	v_mov_b32_e32 v144, v129
	v_add_f32_e32 v128, v152, v144
	v_add_f32_e32 v129, v153, v145
	v_mov_b32_e32 v144, v130
	v_mov_b32_e32 v145, v146
	v_mov_b32_e32 v146, v131
	v_add_f32_e32 v130, v144, v146
	v_add_f32_e32 v131, v145, v147
	s_nop 0
	v_add_f32_e32 v128, v128, v130
	v_add_f32_e32 v129, v129, v131
	s_nop 0
	v_add_f32_e32 v128, v148, v128
	v_add_f32_e32 v129, v149, v129
	s_nop 0
	v_add_f32_e32 v128, v128, v129
	v_fmamk_f32 v128, v128, 0x3a800000, v211
	v_rsq_f32_e32 v128, v128
	s_nop 0
	v_mul_f32_e32 v156, v169, v128
	v_lshlrev_b64 v[128:129], 6, v[154:155]
	v_lshl_add_u64 v[148:149], s[24:25], 0, v[128:129]
	global_load_dwordx4 v[128:131], v[148:149], off offset:16
	global_load_dwordx4 v[144:147], v[148:149], off offset:48
	global_load_dwordx4 v[158:161], v[148:149], off
	global_load_dwordx4 v[180:183], v[148:149], off offset:32
	s_waitcnt vmcnt(1)
	v_mov_b32_e32 v148, v158
	s_waitcnt vmcnt(0)
	v_mov_b32_e32 v149, v180
	v_mov_b32_e32 v180, v159
	v_mov_b32_e32 v152, v160
	v_mov_b32_e32 v153, v182
	v_mov_b32_e32 v182, v161
	v_add_f32_e32 v148, v148, v180
	v_add_f32_e32 v149, v149, v181
	v_add_f32_e32 v152, v152, v182
	v_add_f32_e32 v153, v153, v183
	s_nop 0
	v_add_f32_e32 v148, v148, v152
	v_add_f32_e32 v149, v149, v153
	v_mov_b32_e32 v152, v128
	v_mov_b32_e32 v153, v144
	v_mov_b32_e32 v144, v129
	v_add_f32_e32 v128, v152, v144
	v_add_f32_e32 v129, v153, v145
	v_mov_b32_e32 v144, v130
	v_mov_b32_e32 v145, v146
	v_mov_b32_e32 v146, v131
	v_add_f32_e32 v130, v144, v146
	v_add_f32_e32 v131, v145, v147
	s_nop 0
	v_add_f32_e32 v128, v128, v130
	v_add_f32_e32 v129, v129, v131
	s_nop 0
	v_add_f32_e32 v128, v148, v128
	v_add_f32_e32 v129, v149, v129
	s_nop 0
	v_add_f32_e32 v128, v128, v129
	v_fmamk_f32 v128, v128, 0x3a800000, v211
	v_rsq_f32_e32 v155, v128

; __device__ __forceinline__ float silu_f(float v) { return v * __builtin_amdgcn_rcpf(1.f + __expf(-v)); }
;     __device__ __forceinline__ void operator()(const f32x4 (&acc)[2][2][4][2], const Unit& u, int wr, int wc, int fr, int fq, int ui, PG8_LAS unsigned char* lds) const {
;     ...
;                     f32x4 v[2] = {acc[ai][bj][m][0] * rs, acc[ai][bj][m][1] * rs};
;                     if (ksum) { csum[bj][0] += v[0]; csum[bj][1] += v[1]; }
; #pragma unroll
;                     for (int n = 0; n < 2; ++n) {
;                         f32x4 lbv = (f32x4){0.f, 0.f, 0.f, 0.f};
;                         if (act == 2) lbv = *(const f32x4*)(lb + (col0 - 1024) + bj * HALF + 4 * n);
; #pragma unroll
;                         for (int e = 0; e < 4; ++e) {
;                             float x = v[n][e];
;                             if (act == 1) x = silu_f(x);
;                             else if (act == 2) { const float l = lbv[e]; x = __logf(l + (1.f - l) * __builtin_amdgcn_rcpf(1.f + __expf(-x))); }
.LBB0_232:
	s_cmp_lg_u32 s48, 1
	v_mul_f32_e32 v148, v124, v156
	v_mul_f32_e32 v149, v125, v156
	s_cselect_b64 s[0:1], -1, 0
	v_cndmask_b32_e64 v124, 0, 1, s[38:39]
	s_mov_b64 s[48:49], -1
	s_and_b64 vcc, exec, s[0:1]
	v_cmp_ne_u32_e64 s[46:47], 1, v124
	s_cbranch_vccz .LBB0_236
	s_and_b64 vcc, exec, s[46:47]
	v_mov_b32_e32 v160, v148
	s_cbranch_vccnz .LBB0_235
	v_mul_f32_e32 v124, 0xbfb8aa3b, v148
	v_exp_f32_e32 v124, v124
	s_waitcnt vmcnt(0)
	v_sub_f32_e32 v125, 1.0, v128
	v_add_f32_e32 v124, 1.0, v124
	v_rcp_f32_e32 v124, v124
	s_nop 0
	v_fmac_f32_e32 v128, v124, v125
	v_cmp_gt_f32_e32 vcc, s35, v128
	s_nop 1
	v_cndmask_b32_e64 v124, 0, 32, vcc
	v_ldexp_f32 v124, v128, v124
	v_log_f32_e32 v124, v124
	s_nop 0
	v_mul_f32_e32 v125, 0x3f317217, v124
	v_fma_f32 v125, v124, s13, -v125
	v_fmac_f32_e32 v125, 0x3377d1cf, v124
	v_fmac_f32_e32 v125, 0x3f317217, v124
	v_cmp_lt_f32_e64 s[48:49], |v124|, s36
	s_nop 1
	v_cndmask_b32_e64 v124, v124, v125, s[48:49]
	v_cndmask_b32_e32 v125, 0, v214, vcc
	v_sub_f32_e32 v160, v124, v125

; __device__ __forceinline__ float silu_f(float v) { return v * __builtin_amdgcn_rcpf(1.f + __expf(-v)); }
;     __device__ __forceinline__ void operator()(const f32x4 (&acc)[2][2][4][2], const Unit& u, int wr, int wc, int fr, int fq, int ui, PG8_LAS unsigned char* lds) const {
;     ...
;                     f32x4 v[2] = {acc[ai][bj][m][0] * rs, acc[ai][bj][m][1] * rs};
;                     if (ksum) { csum[bj][0] += v[0]; csum[bj][1] += v[1]; }
; #pragma unroll
;                     for (int n = 0; n < 2; ++n) {
;                         f32x4 lbv = (f32x4){0.f, 0.f, 0.f, 0.f};
;                         if (act == 2) lbv = *(const f32x4*)(lb + (col0 - 1024) + bj * HALF + 4 * n);
; #pragma unroll
;                         for (int e = 0; e < 4; ++e) {
;                             float x = v[n][e];
;                             if (act == 1) x = silu_f(x);
;                             else if (act == 2) { const float l = lbv[e]; x = __logf(l + (1.f - l) * __builtin_amdgcn_rcpf(1.f + __expf(-x))); }
.LBB0_238:
	v_cndmask_b32_e64 v124, 0, 1, s[0:1]
	v_mul_f32_e32 v146, v126, v156
	v_mul_f32_e32 v147, v127, v156
	v_cmp_ne_u32_e64 s[48:49], 1, v124
	s_andn2_b64 vcc, exec, s[0:1]
	s_mov_b64 s[0:1], -1
	s_cbranch_vccnz .LBB0_250
	s_and_b64 vcc, exec, s[46:47]
	v_mov_b32_e32 v161, v149
	s_cbranch_vccnz .LBB0_241
	v_mul_f32_e32 v124, 0xbfb8aa3b, v149
	v_exp_f32_e32 v124, v124
	s_waitcnt vmcnt(0)
	v_sub_f32_e32 v125, 1.0, v129
	v_add_f32_e32 v124, 1.0, v124
	v_rcp_f32_e32 v124, v124
	s_nop 0
	v_fmac_f32_e32 v129, v124, v125
	v_cmp_gt_f32_e32 vcc, s35, v129
	s_nop 1
	v_cndmask_b32_e64 v124, 0, 32, vcc
	v_ldexp_f32 v124, v129, v124
	v_log_f32_e32 v124, v124
	s_nop 0
	v_mul_f32_e32 v125, 0x3f317217, v124
	v_fma_f32 v125, v124, s13, -v125
	v_fmac_f32_e32 v125, 0x3377d1cf, v124
	v_fmac_f32_e32 v125, 0x3f317217, v124
	v_cmp_lt_f32_e64 s[52:53], |v124|, s36
	s_nop 1
	v_cndmask_b32_e64 v124, v124, v125, s[52:53]
	v_cndmask_b32_e32 v125, 0, v214, vcc
	v_sub_f32_e32 v161, v124, v125

; __device__ __forceinline__ float silu_f(float v) { return v * __builtin_amdgcn_rcpf(1.f + __expf(-v)); }
;     __device__ __forceinline__ void operator()(const f32x4 (&acc)[2][2][4][2], const Unit& u, int wr, int wc, int fr, int fq, int ui, PG8_LAS unsigned char* lds) const {
;     ...
;                     f32x4 v[2] = {acc[ai][bj][m][0] * rs, acc[ai][bj][m][1] * rs};
;                     if (ksum) { csum[bj][0] += v[0]; csum[bj][1] += v[1]; }
; #pragma unroll
;                     for (int n = 0; n < 2; ++n) {
;                         f32x4 lbv = (f32x4){0.f, 0.f, 0.f, 0.f};
;                         if (act == 2) lbv = *(const f32x4*)(lb + (col0 - 1024) + bj * HALF + 4 * n);
; #pragma unroll
;                         for (int e = 0; e < 4; ++e) {
;                             float x = v[n][e];
;                             if (act == 1) x = silu_f(x);
;                             else if (act == 2) { const float l = lbv[e]; x = __logf(l + (1.f - l) * __builtin_amdgcn_rcpf(1.f + __expf(-x))); }
.LBB0_258:
	v_mov_b32_e32 v157, v156
	s_waitcnt vmcnt(0)
	v_mul_f32_e32 v128, v120, v156
	v_mul_f32_e32 v129, v121, v157
	s_and_b64 vcc, exec, s[48:49]
	s_mov_b64 s[0:1], -1
	s_cbranch_vccnz .LBB0_262
	s_and_b64 vcc, exec, s[46:47]
	v_mov_b32_e32 v120, v128
	s_cbranch_vccnz .LBB0_261
	v_mul_f32_e32 v120, 0xbfb8aa3b, v128
	v_exp_f32_e32 v120, v120
	v_sub_f32_e32 v121, 1.0, v124
	v_add_f32_e32 v120, 1.0, v120
	v_rcp_f32_e32 v120, v120
	s_nop 0
	v_fmac_f32_e32 v124, v120, v121
	v_cmp_gt_f32_e32 vcc, s35, v124
	s_nop 1
	v_cndmask_b32_e64 v120, 0, 32, vcc
	v_ldexp_f32 v120, v124, v120
	v_log_f32_e32 v120, v120
	s_nop 0
	v_mul_f32_e32 v121, 0x3f317217, v120
	v_fma_f32 v121, v120, s13, -v121
	v_fmac_f32_e32 v121, 0x3377d1cf, v120
	v_fmac_f32_e32 v121, 0x3f317217, v120
	v_cmp_lt_f32_e64 s[52:53], |v120|, s36
	s_nop 1
	v_cndmask_b32_e64 v120, v120, v121, s[52:53]
	v_cndmask_b32_e32 v121, 0, v214, vcc
	v_sub_f32_e32 v120, v120, v121

; __device__ __forceinline__ float silu_f(float v) { return v * __builtin_amdgcn_rcpf(1.f + __expf(-v)); }
;     __device__ __forceinline__ void operator()(const f32x4 (&acc)[2][2][4][2], const Unit& u, int wr, int wc, int fr, int fq, int ui, PG8_LAS unsigned char* lds) const {
;     ...
;                     f32x4 v[2] = {acc[ai][bj][m][0] * rs, acc[ai][bj][m][1] * rs};
;                     if (ksum) { csum[bj][0] += v[0]; csum[bj][1] += v[1]; }
; #pragma unroll
;                     for (int n = 0; n < 2; ++n) {
;                         f32x4 lbv = (f32x4){0.f, 0.f, 0.f, 0.f};
;                         if (act == 2) lbv = *(const f32x4*)(lb + (col0 - 1024) + bj * HALF + 4 * n);
; #pragma unroll
;                         for (int e = 0; e < 4; ++e) {
;                             float x = v[n][e];
;                             if (act == 1) x = silu_f(x);
;                             else if (act == 2) { const float l = lbv[e]; x = __logf(l + (1.f - l) * __builtin_amdgcn_rcpf(1.f + __expf(-x))); }
.LBB0_264:
	v_mov_b32_e32 v130, v156
	v_mov_b32_e32 v131, v156
	v_mul_f32_e32 v130, v122, v130
	v_mul_f32_e32 v131, v123, v131
	s_and_b64 vcc, exec, s[48:49]
	s_mov_b64 s[0:1], -1
	s_cbranch_vccnz .LBB0_276
	s_and_b64 vcc, exec, s[46:47]
	v_mov_b32_e32 v121, v129
	s_cbranch_vccnz .LBB0_267
	v_mul_f32_e32 v121, 0xbfb8aa3b, v129
	v_exp_f32_e32 v121, v121
	v_sub_f32_e32 v122, 1.0, v125
	v_add_f32_e32 v121, 1.0, v121
	v_rcp_f32_e32 v121, v121
	s_nop 0
	v_fmac_f32_e32 v125, v121, v122
	v_cmp_gt_f32_e32 vcc, s35, v125
	s_nop 1
	v_cndmask_b32_e64 v121, 0, 32, vcc
	v_ldexp_f32 v121, v125, v121
	v_log_f32_e32 v121, v121
	s_nop 0
	v_mul_f32_e32 v122, 0x3f317217, v121
	v_fma_f32 v122, v121, s13, -v122
	v_fmac_f32_e32 v122, 0x3377d1cf, v121
	v_fmac_f32_e32 v122, 0x3f317217, v121
	v_cmp_lt_f32_e64 s[52:53], |v121|, s36
	s_nop 1
	v_cndmask_b32_e64 v121, v121, v122, s[52:53]
	v_cndmask_b32_e32 v122, 0, v214, vcc
	v_sub_f32_e32 v121, v121, v122

; __device__ __forceinline__ float silu_f(float v) { return v * __builtin_amdgcn_rcpf(1.f + __expf(-v)); }
;     __device__ __forceinline__ void operator()(const f32x4 (&acc)[2][2][4][2], const Unit& u, int wr, int wc, int fr, int fq, int ui, PG8_LAS unsigned char* lds) const {
;     ...
;                     f32x4 v[2] = {acc[ai][bj][m][0] * rs, acc[ai][bj][m][1] * rs};
;                     if (ksum) { csum[bj][0] += v[0]; csum[bj][1] += v[1]; }
; #pragma unroll
;                     for (int n = 0; n < 2; ++n) {
;                         f32x4 lbv = (f32x4){0.f, 0.f, 0.f, 0.f};
;                         if (act == 2) lbv = *(const f32x4*)(lb + (col0 - 1024) + bj * HALF + 4 * n);
; #pragma unroll
;                         for (int e = 0; e < 4; ++e) {
;                             float x = v[n][e];
;                             if (act == 1) x = silu_f(x);
;                             else if (act == 2) { const float l = lbv[e]; x = __logf(l + (1.f - l) * __builtin_amdgcn_rcpf(1.f + __expf(-x))); }
.LBB0_284:
	s_nop 0
	v_mul_f32_e32 v126, v116, v156
	v_mul_f32_e32 v127, v117, v157
	s_and_b64 vcc, exec, s[48:49]
	s_mov_b64 s[0:1], -1
	s_cbranch_vccnz .LBB0_288
	s_and_b64 vcc, exec, s[46:47]
	v_mov_b32_e32 v160, v126
	s_cbranch_vccnz .LBB0_287
	v_mul_f32_e32 v116, 0xbfb8aa3b, v126
	v_exp_f32_e32 v116, v116
	s_waitcnt vmcnt(0)
	v_sub_f32_e32 v117, 1.0, v120
	v_add_f32_e32 v116, 1.0, v116
	v_rcp_f32_e32 v116, v116
	s_nop 0
	v_fmac_f32_e32 v120, v116, v117
	v_cmp_gt_f32_e32 vcc, s35, v120
	s_nop 1
	v_cndmask_b32_e64 v116, 0, 32, vcc
	v_ldexp_f32 v116, v120, v116
	v_log_f32_e32 v116, v116
	s_nop 0
	v_mul_f32_e32 v117, 0x3f317217, v116
	v_fma_f32 v117, v116, s13, -v117
	v_fmac_f32_e32 v117, 0x3377d1cf, v116
	v_fmac_f32_e32 v117, 0x3f317217, v116
	v_cmp_lt_f32_e64 s[52:53], |v116|, s36
	s_nop 1
	v_cndmask_b32_e64 v116, v116, v117, s[52:53]
	v_cndmask_b32_e32 v117, 0, v214, vcc
	v_sub_f32_e32 v160, v116, v117

; __device__ __forceinline__ float silu_f(float v) { return v * __builtin_amdgcn_rcpf(1.f + __expf(-v)); }
;     __device__ __forceinline__ void operator()(const f32x4 (&acc)[2][2][4][2], const Unit& u, int wr, int wc, int fr, int fq, int ui, PG8_LAS unsigned char* lds) const {
;     ...
;                     f32x4 v[2] = {acc[ai][bj][m][0] * rs, acc[ai][bj][m][1] * rs};
;                     if (ksum) { csum[bj][0] += v[0]; csum[bj][1] += v[1]; }
; #pragma unroll
;                     for (int n = 0; n < 2; ++n) {
;                         f32x4 lbv = (f32x4){0.f, 0.f, 0.f, 0.f};
;                         if (act == 2) lbv = *(const f32x4*)(lb + (col0 - 1024) + bj * HALF + 4 * n);
; #pragma unroll
;                         for (int e = 0; e < 4; ++e) {
;                             float x = v[n][e];
;                             if (act == 1) x = silu_f(x);
;                             else if (act == 2) { const float l = lbv[e]; x = __logf(l + (1.f - l) * __builtin_amdgcn_rcpf(1.f + __expf(-x))); }
.LBB0_290:
	v_mov_b32_e32 v116, v156
	v_mov_b32_e32 v117, v156
	v_mul_f32_e32 v124, v118, v116
	v_mul_f32_e32 v125, v119, v117
	s_and_b64 vcc, exec, s[48:49]
	s_mov_b64 s[0:1], -1
	s_cbranch_vccnz .LBB0_302
	s_and_b64 vcc, exec, s[46:47]
	v_mov_b32_e32 v161, v127
	s_cbranch_vccnz .LBB0_293
	v_mul_f32_e32 v116, 0xbfb8aa3b, v127
	v_exp_f32_e32 v116, v116
	s_waitcnt vmcnt(0)
	v_sub_f32_e32 v117, 1.0, v121
	v_add_f32_e32 v116, 1.0, v116
	v_rcp_f32_e32 v116, v116
	s_nop 0
	v_fmac_f32_e32 v121, v116, v117
	v_cmp_gt_f32_e32 vcc, s35, v121
	s_nop 1
	v_cndmask_b32_e64 v116, 0, 32, vcc
	v_ldexp_f32 v116, v121, v116
	v_log_f32_e32 v116, v116
	s_nop 0
	v_mul_f32_e32 v117, 0x3f317217, v116
	v_fma_f32 v117, v116, s13, -v117
	v_fmac_f32_e32 v117, 0x3377d1cf, v116
	v_fmac_f32_e32 v117, 0x3f317217, v116
	v_cmp_lt_f32_e64 s[52:53], |v116|, s36
	s_nop 1
	v_cndmask_b32_e64 v116, v116, v117, s[52:53]
	v_cndmask_b32_e32 v117, 0, v214, vcc
	v_sub_f32_e32 v161, v116, v117

; __device__ __forceinline__ float silu_f(float v) { return v * __builtin_amdgcn_rcpf(1.f + __expf(-v)); }
;     __device__ __forceinline__ void operator()(const f32x4 (&acc)[2][2][4][2], const Unit& u, int wr, int wc, int fr, int fq, int ui, PG8_LAS unsigned char* lds) const {
;     ...
;                     f32x4 v[2] = {acc[ai][bj][m][0] * rs, acc[ai][bj][m][1] * rs};
;                     if (ksum) { csum[bj][0] += v[0]; csum[bj][1] += v[1]; }
; #pragma unroll
;                     for (int n = 0; n < 2; ++n) {
;                         f32x4 lbv = (f32x4){0.f, 0.f, 0.f, 0.f};
;                         if (act == 2) lbv = *(const f32x4*)(lb + (col0 - 1024) + bj * HALF + 4 * n);
; #pragma unroll
;                         for (int e = 0; e < 4; ++e) {
;                             float x = v[n][e];
;                             if (act == 1) x = silu_f(x);
;                             else if (act == 2) { const float l = lbv[e]; x = __logf(l + (1.f - l) * __builtin_amdgcn_rcpf(1.f + __expf(-x))); }
.LBB0_310:
	s_waitcnt vmcnt(0)
	v_mul_f32_e32 v120, v112, v156
	v_mul_f32_e32 v121, v113, v157
	s_and_b64 vcc, exec, s[48:49]
	s_mov_b64 s[0:1], -1
	s_cbranch_vccnz .LBB0_314
	s_and_b64 vcc, exec, s[46:47]
	v_mov_b32_e32 v112, v120
	s_cbranch_vccnz .LBB0_313
	v_mul_f32_e32 v112, 0xbfb8aa3b, v120
	v_exp_f32_e32 v112, v112
	v_sub_f32_e32 v113, 1.0, v116
	v_add_f32_e32 v112, 1.0, v112
	v_rcp_f32_e32 v112, v112
	s_nop 0
	v_fmac_f32_e32 v116, v112, v113
	v_cmp_gt_f32_e32 vcc, s35, v116
	s_nop 1
	v_cndmask_b32_e64 v112, 0, 32, vcc
	v_ldexp_f32 v112, v116, v112
	v_log_f32_e32 v112, v112
	s_nop 0
	v_mul_f32_e32 v113, 0x3f317217, v112
	v_fma_f32 v113, v112, s13, -v113
	v_fmac_f32_e32 v113, 0x3377d1cf, v112
	v_fmac_f32_e32 v113, 0x3f317217, v112
	v_cmp_lt_f32_e64 s[52:53], |v112|, s36
	s_nop 1
	v_cndmask_b32_e64 v112, v112, v113, s[52:53]
	v_cndmask_b32_e32 v113, 0, v214, vcc
	v_sub_f32_e32 v112, v112, v113

; __device__ __forceinline__ float silu_f(float v) { return v * __builtin_amdgcn_rcpf(1.f + __expf(-v)); }
;     __device__ __forceinline__ void operator()(const f32x4 (&acc)[2][2][4][2], const Unit& u, int wr, int wc, int fr, int fq, int ui, PG8_LAS unsigned char* lds) const {
;     ...
;                     f32x4 v[2] = {acc[ai][bj][m][0] * rs, acc[ai][bj][m][1] * rs};
;                     if (ksum) { csum[bj][0] += v[0]; csum[bj][1] += v[1]; }
; #pragma unroll
;                     for (int n = 0; n < 2; ++n) {
;                         f32x4 lbv = (f32x4){0.f, 0.f, 0.f, 0.f};
;                         if (act == 2) lbv = *(const f32x4*)(lb + (col0 - 1024) + bj * HALF + 4 * n);
; #pragma unroll
;                         for (int e = 0; e < 4; ++e) {
;                             float x = v[n][e];
;                             if (act == 1) x = silu_f(x);
;                             else if (act == 2) { const float l = lbv[e]; x = __logf(l + (1.f - l) * __builtin_amdgcn_rcpf(1.f + __expf(-x))); }
.LBB0_316:
	v_mov_b32_e32 v157, v156
	v_mul_f32_e32 v122, v114, v156
	v_mul_f32_e32 v123, v115, v157
	s_and_b64 vcc, exec, s[48:49]
	s_mov_b64 s[0:1], -1
	s_cbranch_vccnz .LBB0_328
	s_and_b64 vcc, exec, s[46:47]
	v_mov_b32_e32 v113, v121
	s_cbranch_vccnz .LBB0_319
	v_mul_f32_e32 v113, 0xbfb8aa3b, v121
	v_exp_f32_e32 v113, v113
	v_sub_f32_e32 v114, 1.0, v117
	v_add_f32_e32 v113, 1.0, v113
	v_rcp_f32_e32 v113, v113
	s_nop 0
	v_fmac_f32_e32 v117, v113, v114
	v_cmp_gt_f32_e32 vcc, s35, v117
	s_nop 1
	v_cndmask_b32_e64 v113, 0, 32, vcc
	v_ldexp_f32 v113, v117, v113
	v_log_f32_e32 v113, v113
	s_nop 0
	v_mul_f32_e32 v114, 0x3f317217, v113
	v_fma_f32 v114, v113, s13, -v114
	v_fmac_f32_e32 v114, 0x3377d1cf, v113
	v_fmac_f32_e32 v114, 0x3f317217, v113
	v_cmp_lt_f32_e64 s[52:53], |v113|, s36
	s_nop 1
	v_cndmask_b32_e64 v113, v113, v114, s[52:53]
	v_cndmask_b32_e32 v114, 0, v214, vcc
	v_sub_f32_e32 v113, v113, v114

; __device__ __forceinline__ float silu_f(float v) { return v * __builtin_amdgcn_rcpf(1.f + __expf(-v)); }
;     __device__ __forceinline__ void operator()(const f32x4 (&acc)[2][2][4][2], const Unit& u, int wr, int wc, int fr, int fq, int ui, PG8_LAS unsigned char* lds) const {
;     ...
;                         rs4[m] = __builtin_amdgcn_rsqf(ssq_row(ssq, row0 + ai * HALF + m * 16) * (1.0f / 1024.0f) + RMS_EPS) * sc;
;                         rs4[m + 1] = __builtin_amdgcn_rsqf(ssq_row(ssq, row0 + ai * HALF + (m + 1) * 16) * (1.0f / 1024.0f) + RMS_EPS) * sc;
;                     }
;                 }
;                 const int row = row0 + ai * HALF + m * 16;
;                 const float rs = rs4[m];
;                 bf16_t* rowp = O + (size_t)row * ldc + col0;
; #pragma unroll
;                 for (int bj = 0; bj < 2; ++bj) {
;                     f32x4 v[2] = {acc[ai][bj][m][0] * rs, acc[ai][bj][m][1] * rs};
;                     if (ksum) { csum[bj][0] += v[0]; csum[bj][1] += v[1]; }
; #pragma unroll
;                     for (int n = 0; n < 2; ++n) {
;                         f32x4 lbv = (f32x4){0.f, 0.f, 0.f, 0.f};
;                         if (act == 2) lbv = *(const f32x4*)(lb + (col0 - 1024) + bj * HALF + 4 * n);
; #pragma unroll
;                         for (int e = 0; e < 4; ++e) {
;                             float x = v[n][e];
;                             if (act == 1) x = silu_f(x);
;                             else if (act == 2) { const float l = lbv[e]; x = __logf(l + (1.f - l) * __builtin_amdgcn_rcpf(1.f + __expf(-x))); }
.LBB0_336:
	v_mul_f32_e32 v156, v169, v155
	v_mul_f32_e32 v118, v108, v156
	v_mul_f32_e32 v119, v109, v156
	s_and_b64 vcc, exec, s[48:49]
	s_mov_b64 s[0:1], -1
	s_cbranch_vccnz .LBB0_340
	s_and_b64 vcc, exec, s[46:47]
	v_mov_b32_e32 v155, v118
	s_cbranch_vccnz .LBB0_339
	v_mul_f32_e32 v108, 0xbfb8aa3b, v118
	v_exp_f32_e32 v108, v108
	s_waitcnt vmcnt(0)
	v_sub_f32_e32 v109, 1.0, v112
	v_add_f32_e32 v108, 1.0, v108
	v_rcp_f32_e32 v108, v108
	s_nop 0
	v_fmac_f32_e32 v112, v108, v109
	v_cmp_gt_f32_e32 vcc, s35, v112
	s_nop 1
	v_cndmask_b32_e64 v108, 0, 32, vcc
	v_ldexp_f32 v108, v112, v108
	v_log_f32_e32 v108, v108
	s_nop 0
	v_mul_f32_e32 v109, 0x3f317217, v108
	v_fma_f32 v109, v108, s13, -v109
	v_fmac_f32_e32 v109, 0x3377d1cf, v108
	v_fmac_f32_e32 v109, 0x3f317217, v108
	v_cmp_lt_f32_e64 s[52:53], |v108|, s36
	s_nop 1
	v_cndmask_b32_e64 v108, v108, v109, s[52:53]
	v_cndmask_b32_e32 v109, 0, v214, vcc
	v_sub_f32_e32 v155, v108, v109

; __device__ __forceinline__ float silu_f(float v) { return v * __builtin_amdgcn_rcpf(1.f + __expf(-v)); }
;     __device__ __forceinline__ void operator()(const f32x4 (&acc)[2][2][4][2], const Unit& u, int wr, int wc, int fr, int fq, int ui, PG8_LAS unsigned char* lds) const {
;     ...
;                     f32x4 v[2] = {acc[ai][bj][m][0] * rs, acc[ai][bj][m][1] * rs};
;                     if (ksum) { csum[bj][0] += v[0]; csum[bj][1] += v[1]; }
; #pragma unroll
;                     for (int n = 0; n < 2; ++n) {
;                         f32x4 lbv = (f32x4){0.f, 0.f, 0.f, 0.f};
;                         if (act == 2) lbv = *(const f32x4*)(lb + (col0 - 1024) + bj * HALF + 4 * n);
; #pragma unroll
;                         for (int e = 0; e < 4; ++e) {
;                             float x = v[n][e];
;                             if (act == 1) x = silu_f(x);
;                             else if (act == 2) { const float l = lbv[e]; x = __logf(l + (1.f - l) * __builtin_amdgcn_rcpf(1.f + __expf(-x))); }
.LBB0_342:
	v_mul_f32_e32 v116, v110, v156
	v_mul_f32_e32 v117, v111, v156
	s_and_b64 vcc, exec, s[48:49]
	s_mov_b64 s[0:1], -1
	s_cbranch_vccnz .LBB0_354
	s_and_b64 vcc, exec, s[46:47]
	v_mov_b32_e32 v160, v119
	s_cbranch_vccnz .LBB0_345
	v_mul_f32_e32 v108, 0xbfb8aa3b, v119
	v_exp_f32_e32 v108, v108
	s_waitcnt vmcnt(0)
	v_sub_f32_e32 v109, 1.0, v113
	v_add_f32_e32 v108, 1.0, v108
	v_rcp_f32_e32 v108, v108
	s_nop 0
	v_fmac_f32_e32 v113, v108, v109
	v_cmp_gt_f32_e32 vcc, s35, v113
	s_nop 1
	v_cndmask_b32_e64 v108, 0, 32, vcc
	v_ldexp_f32 v108, v113, v108
	v_log_f32_e32 v108, v108
	s_nop 0
	v_mul_f32_e32 v109, 0x3f317217, v108
	v_fma_f32 v109, v108, s13, -v109
	v_fmac_f32_e32 v109, 0x3377d1cf, v108
	v_fmac_f32_e32 v109, 0x3f317217, v108
	v_cmp_lt_f32_e64 s[52:53], |v108|, s36
	s_nop 1
	v_cndmask_b32_e64 v108, v108, v109, s[52:53]
	v_cndmask_b32_e32 v109, 0, v214, vcc
	v_sub_f32_e32 v160, v108, v109

; __device__ __forceinline__ float silu_f(float v) { return v * __builtin_amdgcn_rcpf(1.f + __expf(-v)); }
;     __device__ __forceinline__ void operator()(const f32x4 (&acc)[2][2][4][2], const Unit& u, int wr, int wc, int fr, int fq, int ui, PG8_LAS unsigned char* lds) const {
;     ...
;                     f32x4 v[2] = {acc[ai][bj][m][0] * rs, acc[ai][bj][m][1] * rs};
;                     if (ksum) { csum[bj][0] += v[0]; csum[bj][1] += v[1]; }
; #pragma unroll
;                     for (int n = 0; n < 2; ++n) {
;                         f32x4 lbv = (f32x4){0.f, 0.f, 0.f, 0.f};
;                         if (act == 2) lbv = *(const f32x4*)(lb + (col0 - 1024) + bj * HALF + 4 * n);
; #pragma unroll
;                         for (int e = 0; e < 4; ++e) {
;                             float x = v[n][e];
;                             if (act == 1) x = silu_f(x);
;                             else if (act == 2) { const float l = lbv[e]; x = __logf(l + (1.f - l) * __builtin_amdgcn_rcpf(1.f + __expf(-x))); }
.LBB0_362:
	v_mov_b32_e32 v157, v156
	s_waitcnt vmcnt(0)
	v_mul_f32_e32 v112, v104, v156
	v_mul_f32_e32 v113, v105, v157
	s_and_b64 vcc, exec, s[48:49]
	s_mov_b64 s[0:1], -1
	s_cbranch_vccnz .LBB0_366
	s_and_b64 vcc, exec, s[46:47]
	v_mov_b32_e32 v104, v112
	s_cbranch_vccnz .LBB0_365
	v_mul_f32_e32 v104, 0xbfb8aa3b, v112
	v_exp_f32_e32 v104, v104
	v_sub_f32_e32 v105, 1.0, v108
	v_add_f32_e32 v104, 1.0, v104
	v_rcp_f32_e32 v104, v104
	s_nop 0
	v_fmac_f32_e32 v108, v104, v105
	v_cmp_gt_f32_e32 vcc, s35, v108
	s_nop 1
	v_cndmask_b32_e64 v104, 0, 32, vcc
	v_ldexp_f32 v104, v108, v104
	v_log_f32_e32 v104, v104
	s_nop 0
	v_mul_f32_e32 v105, 0x3f317217, v104
	v_fma_f32 v105, v104, s13, -v105
	v_fmac_f32_e32 v105, 0x3377d1cf, v104
	v_fmac_f32_e32 v105, 0x3f317217, v104
	v_cmp_lt_f32_e64 s[52:53], |v104|, s36
	s_nop 1
	v_cndmask_b32_e64 v104, v104, v105, s[52:53]
	v_cndmask_b32_e32 v105, 0, v214, vcc
	v_sub_f32_e32 v104, v104, v105

; __device__ __forceinline__ float silu_f(float v) { return v * __builtin_amdgcn_rcpf(1.f + __expf(-v)); }
;     __device__ __forceinline__ void operator()(const f32x4 (&acc)[2][2][4][2], const Unit& u, int wr, int wc, int fr, int fq, int ui, PG8_LAS unsigned char* lds) const {
;     ...
;                     f32x4 v[2] = {acc[ai][bj][m][0] * rs, acc[ai][bj][m][1] * rs};
;                     if (ksum) { csum[bj][0] += v[0]; csum[bj][1] += v[1]; }
; #pragma unroll
;                     for (int n = 0; n < 2; ++n) {
;                         f32x4 lbv = (f32x4){0.f, 0.f, 0.f, 0.f};
;                         if (act == 2) lbv = *(const f32x4*)(lb + (col0 - 1024) + bj * HALF + 4 * n);
; #pragma unroll
;                         for (int e = 0; e < 4; ++e) {
;                             float x = v[n][e];
;                             if (act == 1) x = silu_f(x);
;                             else if (act == 2) { const float l = lbv[e]; x = __logf(l + (1.f - l) * __builtin_amdgcn_rcpf(1.f + __expf(-x))); }
.LBB0_368:
	v_mov_b32_e32 v114, v156
	v_mov_b32_e32 v115, v156
	v_mul_f32_e32 v114, v106, v114
	v_mul_f32_e32 v115, v107, v115
	s_and_b64 vcc, exec, s[48:49]
	s_mov_b64 s[0:1], -1
	s_cbranch_vccnz .LBB0_380
	s_and_b64 vcc, exec, s[46:47]
	v_mov_b32_e32 v105, v113
	s_cbranch_vccnz .LBB0_371
	v_mul_f32_e32 v105, 0xbfb8aa3b, v113
	v_exp_f32_e32 v105, v105
	v_sub_f32_e32 v106, 1.0, v109
	v_add_f32_e32 v105, 1.0, v105
	v_rcp_f32_e32 v105, v105
	s_nop 0
	v_fmac_f32_e32 v109, v105, v106
	v_cmp_gt_f32_e32 vcc, s35, v109
	s_nop 1
	v_cndmask_b32_e64 v105, 0, 32, vcc
	v_ldexp_f32 v105, v109, v105
	v_log_f32_e32 v105, v105
	s_nop 0
	v_mul_f32_e32 v106, 0x3f317217, v105
	v_fma_f32 v106, v105, s13, -v106
	v_fmac_f32_e32 v106, 0x3377d1cf, v105
	v_fmac_f32_e32 v106, 0x3f317217, v105
	v_cmp_lt_f32_e64 s[52:53], |v105|, s36
	s_nop 1
	v_cndmask_b32_e64 v105, v105, v106, s[52:53]
	v_cndmask_b32_e32 v106, 0, v214, vcc
	v_sub_f32_e32 v105, v105, v106

; __device__ __forceinline__ float silu_f(float v) { return v * __builtin_amdgcn_rcpf(1.f + __expf(-v)); }
;     __device__ __forceinline__ void operator()(const f32x4 (&acc)[2][2][4][2], const Unit& u, int wr, int wc, int fr, int fq, int ui, PG8_LAS unsigned char* lds) const {
;     ...
;                     f32x4 v[2] = {acc[ai][bj][m][0] * rs, acc[ai][bj][m][1] * rs};
;                     if (ksum) { csum[bj][0] += v[0]; csum[bj][1] += v[1]; }
; #pragma unroll
;                     for (int n = 0; n < 2; ++n) {
;                         f32x4 lbv = (f32x4){0.f, 0.f, 0.f, 0.f};
;                         if (act == 2) lbv = *(const f32x4*)(lb + (col0 - 1024) + bj * HALF + 4 * n);
; #pragma unroll
;                         for (int e = 0; e < 4; ++e) {
;                             float x = v[n][e];
;                             if (act == 1) x = silu_f(x);
;                             else if (act == 2) { const float l = lbv[e]; x = __logf(l + (1.f - l) * __builtin_amdgcn_rcpf(1.f + __expf(-x))); }
.LBB0_388:
	s_nop 0
	v_mul_f32_e32 v110, v100, v156
	v_mul_f32_e32 v111, v101, v157
	s_and_b64 vcc, exec, s[48:49]
	s_mov_b64 s[0:1], -1
	s_cbranch_vccnz .LBB0_392
	s_and_b64 vcc, exec, s[46:47]
	v_mov_b32_e32 v154, v110
	s_cbranch_vccnz .LBB0_391
	v_mul_f32_e32 v100, 0xbfb8aa3b, v110
	v_exp_f32_e32 v100, v100
	s_waitcnt vmcnt(0)
	v_sub_f32_e32 v101, 1.0, v104
	v_add_f32_e32 v100, 1.0, v100
	v_rcp_f32_e32 v100, v100
	s_nop 0
	v_fmac_f32_e32 v104, v100, v101
	v_cmp_gt_f32_e32 vcc, s35, v104
	s_nop 1
	v_cndmask_b32_e64 v100, 0, 32, vcc
	v_ldexp_f32 v100, v104, v100
	v_log_f32_e32 v100, v100
	s_nop 0
	v_mul_f32_e32 v101, 0x3f317217, v100
	v_fma_f32 v101, v100, s13, -v101
	v_fmac_f32_e32 v101, 0x3377d1cf, v100
	v_fmac_f32_e32 v101, 0x3f317217, v100
	v_cmp_lt_f32_e64 s[52:53], |v100|, s36
	s_nop 1
	v_cndmask_b32_e64 v100, v100, v101, s[52:53]
	v_cndmask_b32_e32 v101, 0, v214, vcc
	v_sub_f32_e32 v154, v100, v101

; __device__ __forceinline__ float silu_f(float v) { return v * __builtin_amdgcn_rcpf(1.f + __expf(-v)); }
;     __device__ __forceinline__ void operator()(const f32x4 (&acc)[2][2][4][2], const Unit& u, int wr, int wc, int fr, int fq, int ui, PG8_LAS unsigned char* lds) const {
;     ...
;                     f32x4 v[2] = {acc[ai][bj][m][0] * rs, acc[ai][bj][m][1] * rs};
;                     if (ksum) { csum[bj][0] += v[0]; csum[bj][1] += v[1]; }
; #pragma unroll
;                     for (int n = 0; n < 2; ++n) {
;                         f32x4 lbv = (f32x4){0.f, 0.f, 0.f, 0.f};
;                         if (act == 2) lbv = *(const f32x4*)(lb + (col0 - 1024) + bj * HALF + 4 * n);
; #pragma unroll
;                         for (int e = 0; e < 4; ++e) {
;                             float x = v[n][e];
;                             if (act == 1) x = silu_f(x);
;                             else if (act == 2) { const float l = lbv[e]; x = __logf(l + (1.f - l) * __builtin_amdgcn_rcpf(1.f + __expf(-x))); }
.LBB0_394:
	v_mov_b32_e32 v100, v156
	v_mov_b32_e32 v101, v156
	v_mul_f32_e32 v108, v102, v100
	v_mul_f32_e32 v109, v103, v101
	s_and_b64 vcc, exec, s[48:49]
	s_mov_b64 s[0:1], -1
	s_cbranch_vccnz .LBB0_406
	s_and_b64 vcc, exec, s[46:47]
	v_mov_b32_e32 v160, v111
	s_cbranch_vccnz .LBB0_397
	v_mul_f32_e32 v100, 0xbfb8aa3b, v111
	v_exp_f32_e32 v100, v100
	s_waitcnt vmcnt(0)
	v_sub_f32_e32 v101, 1.0, v105
	v_add_f32_e32 v100, 1.0, v100
	v_rcp_f32_e32 v100, v100
	s_nop 0
	v_fmac_f32_e32 v105, v100, v101
	v_cmp_gt_f32_e32 vcc, s35, v105
	s_nop 1
	v_cndmask_b32_e64 v100, 0, 32, vcc
	v_ldexp_f32 v100, v105, v100
	v_log_f32_e32 v100, v100
	s_nop 0
	v_mul_f32_e32 v101, 0x3f317217, v100
	v_fma_f32 v101, v100, s13, -v101
	v_fmac_f32_e32 v101, 0x3377d1cf, v100
	v_fmac_f32_e32 v101, 0x3f317217, v100
	v_cmp_lt_f32_e64 s[52:53], |v100|, s36
	s_nop 1
	v_cndmask_b32_e64 v100, v100, v101, s[52:53]
	v_cndmask_b32_e32 v101, 0, v214, vcc
	v_sub_f32_e32 v160, v100, v101

; __device__ __forceinline__ float silu_f(float v) { return v * __builtin_amdgcn_rcpf(1.f + __expf(-v)); }
;     __device__ __forceinline__ void operator()(const f32x4 (&acc)[2][2][4][2], const Unit& u, int wr, int wc, int fr, int fq, int ui, PG8_LAS unsigned char* lds) const {
;     ...
;                     f32x4 v[2] = {acc[ai][bj][m][0] * rs, acc[ai][bj][m][1] * rs};
;                     if (ksum) { csum[bj][0] += v[0]; csum[bj][1] += v[1]; }
; #pragma unroll
;                     for (int n = 0; n < 2; ++n) {
;                         f32x4 lbv = (f32x4){0.f, 0.f, 0.f, 0.f};
;                         if (act == 2) lbv = *(const f32x4*)(lb + (col0 - 1024) + bj * HALF + 4 * n);
; #pragma unroll
;                         for (int e = 0; e < 4; ++e) {
;                             float x = v[n][e];
;                             if (act == 1) x = silu_f(x);
;                             else if (act == 2) { const float l = lbv[e]; x = __logf(l + (1.f - l) * __builtin_amdgcn_rcpf(1.f + __expf(-x))); }
.LBB0_414:
	s_waitcnt vmcnt(0)
	v_mul_f32_e32 v104, v96, v156
	v_mul_f32_e32 v105, v97, v157
	s_and_b64 vcc, exec, s[48:49]
	s_mov_b64 s[0:1], -1
	s_cbranch_vccnz .LBB0_418
	s_and_b64 vcc, exec, s[46:47]
	v_mov_b32_e32 v96, v104
	s_cbranch_vccnz .LBB0_417
	v_mul_f32_e32 v96, 0xbfb8aa3b, v104
	v_exp_f32_e32 v96, v96
	v_sub_f32_e32 v97, 1.0, v100
	v_add_f32_e32 v96, 1.0, v96
	v_rcp_f32_e32 v96, v96
	s_nop 0
	v_fmac_f32_e32 v100, v96, v97
	v_cmp_gt_f32_e32 vcc, s35, v100
	s_nop 1
	v_cndmask_b32_e64 v96, 0, 32, vcc
	v_ldexp_f32 v96, v100, v96
	v_log_f32_e32 v96, v96
	s_nop 0
	v_mul_f32_e32 v97, 0x3f317217, v96
	v_fma_f32 v97, v96, s13, -v97
	v_fmac_f32_e32 v97, 0x3377d1cf, v96
	v_fmac_f32_e32 v97, 0x3f317217, v96
	v_cmp_lt_f32_e64 s[52:53], |v96|, s36
	s_nop 1
	v_cndmask_b32_e64 v96, v96, v97, s[52:53]
	v_cndmask_b32_e32 v97, 0, v214, vcc
	v_sub_f32_e32 v96, v96, v97

; __device__ __forceinline__ float silu_f(float v) { return v * __builtin_amdgcn_rcpf(1.f + __expf(-v)); }
;     __device__ __forceinline__ void operator()(const f32x4 (&acc)[2][2][4][2], const Unit& u, int wr, int wc, int fr, int fq, int ui, PG8_LAS unsigned char* lds) const {
;     ...
;                     f32x4 v[2] = {acc[ai][bj][m][0] * rs, acc[ai][bj][m][1] * rs};
;                     if (ksum) { csum[bj][0] += v[0]; csum[bj][1] += v[1]; }
; #pragma unroll
;                     for (int n = 0; n < 2; ++n) {
;                         f32x4 lbv = (f32x4){0.f, 0.f, 0.f, 0.f};
;                         if (act == 2) lbv = *(const f32x4*)(lb + (col0 - 1024) + bj * HALF + 4 * n);
; #pragma unroll
;                         for (int e = 0; e < 4; ++e) {
;                             float x = v[n][e];
;                             if (act == 1) x = silu_f(x);
;                             else if (act == 2) { const float l = lbv[e]; x = __logf(l + (1.f - l) * __builtin_amdgcn_rcpf(1.f + __expf(-x))); }
.LBB0_420:
	v_mov_b32_e32 v157, v156
	v_mul_f32_e32 v106, v98, v156
	v_mul_f32_e32 v107, v99, v157
	s_and_b64 vcc, exec, s[48:49]
	s_mov_b64 s[0:1], -1
	s_cbranch_vccnz .LBB0_432
	s_and_b64 vcc, exec, s[46:47]
	v_mov_b32_e32 v97, v105
	s_cbranch_vccnz .LBB0_423
	v_mul_f32_e32 v97, 0xbfb8aa3b, v105
	v_exp_f32_e32 v97, v97
	v_sub_f32_e32 v98, 1.0, v101
	v_add_f32_e32 v97, 1.0, v97
	v_rcp_f32_e32 v97, v97
	s_nop 0
	v_fmac_f32_e32 v101, v97, v98
	v_cmp_gt_f32_e32 vcc, s35, v101
	s_nop 1
	v_cndmask_b32_e64 v97, 0, 32, vcc
	v_ldexp_f32 v97, v101, v97
	v_log_f32_e32 v97, v97
	s_nop 0
	v_mul_f32_e32 v98, 0x3f317217, v97
	v_fma_f32 v98, v97, s13, -v98
	v_fmac_f32_e32 v98, 0x3377d1cf, v97
	v_fmac_f32_e32 v98, 0x3f317217, v97
	v_cmp_lt_f32_e64 s[52:53], |v97|, s36
	s_nop 1
	v_cndmask_b32_e64 v97, v97, v98, s[52:53]
	v_cndmask_b32_e32 v98, 0, v214, vcc
	v_sub_f32_e32 v97, v97, v98

; __device__ __forceinline__ float ssq_row(const float* part, int row) {
;     const f32x4* p = (const f32x4*)(part + (size_t)row * 16);
;     const f32x4 a = p[0], b = p[1], c = p[2], d = p[3];
;     return (((a[0] + a[1]) + (a[2] + a[3])) + ((b[0] + b[1]) + (b[2] + b[3]))) + (((c[0] + c[1]) + (c[2] + c[3])) + ((d[0] + d[1]) + (d[2] + d[3])));
; }
;     __device__ __forceinline__ void operator()(const f32x4 (&acc)[2][2][4][2], const Unit& u, int wr, int wc, int fr, int fq, int ui, PG8_LAS unsigned char* lds) const {
;     ...
;                     if (use_tab) { rs4[m] = tab[ai * HALF + m * 16] * sc; rs4[m + 1] = tab[ai * HALF + (m + 1) * 16] * sc; }
;                     else {
;                         asm volatile("" ::: "memory");
;                         rs4[m] = __builtin_amdgcn_rsqf(ssq_row(ssq, row0 + ai * HALF + m * 16) * (1.0f / 1024.0f) + RMS_EPS) * sc;
;                         rs4[m + 1] = __builtin_amdgcn_rsqf(ssq_row(ssq, row0 + ai * HALF + (m + 1) * 16) * (1.0f / 1024.0f) + RMS_EPS) * sc;
.LBB0_440:
	s_andn2_b64 vcc, exec, s[0:1]
	v_or_b32_e32 v156, 48, v150
	s_cbranch_vccnz .LBB0_442
	v_lshlrev_b64 v[96:97], 6, v[160:161]
	v_lshl_add_u64 v[158:159], s[24:25], 0, v[96:97]
	global_load_dwordx4 v[96:99], v[158:159], off offset:16
	global_load_dwordx4 v[100:103], v[158:159], off offset:48
	global_load_dwordx4 v[180:183], v[158:159], off
	global_load_dwordx4 v[184:187], v[158:159], off offset:32
	v_ashrrev_i32_e32 v157, 31, v156
	s_waitcnt vmcnt(1)
	v_mov_b32_e32 v158, v180
	s_waitcnt vmcnt(0)
	v_mov_b32_e32 v159, v184
	v_mov_b32_e32 v184, v181
	v_mov_b32_e32 v162, v182
	v_mov_b32_e32 v163, v186
	v_mov_b32_e32 v186, v183
	v_add_f32_e32 v158, v158, v184
	v_add_f32_e32 v159, v159, v185
	v_add_f32_e32 v162, v162, v186
	v_add_f32_e32 v163, v163, v187
	s_nop 0
	v_add_f32_e32 v158, v158, v162
	v_add_f32_e32 v159, v159, v163
	v_mov_b32_e32 v162, v96
	v_mov_b32_e32 v163, v100
	v_mov_b32_e32 v100, v97
	v_add_f32_e32 v96, v162, v100
	v_add_f32_e32 v97, v163, v101
	v_mov_b32_e32 v100, v98
	v_mov_b32_e32 v101, v102
	v_mov_b32_e32 v102, v99
	v_add_f32_e32 v98, v100, v102
	v_add_f32_e32 v99, v101, v103
	s_nop 0
	v_add_f32_e32 v96, v96, v98
	v_add_f32_e32 v97, v97, v99
	s_nop 0
	v_add_f32_e32 v96, v158, v96
	v_add_f32_e32 v97, v159, v97
	s_nop 0
	v_add_f32_e32 v96, v96, v97
	v_fmamk_f32 v96, v96, 0x3a800000, v211
	v_rsq_f32_e32 v96, v96
	s_nop 0
	v_mul_f32_e32 v158, v169, v96
	v_lshlrev_b64 v[96:97], 6, v[156:157]
	v_lshl_add_u64 v[162:163], s[24:25], 0, v[96:97]
	global_load_dwordx4 v[96:99], v[162:163], off offset:16
	global_load_dwordx4 v[100:103], v[162:163], off offset:48
	global_load_dwordx4 v[180:183], v[162:163], off
	global_load_dwordx4 v[184:187], v[162:163], off offset:32
	s_waitcnt vmcnt(1)
	v_mov_b32_e32 v162, v180
	s_waitcnt vmcnt(0)
	v_mov_b32_e32 v163, v184
	v_mov_b32_e32 v184, v181
	v_mov_b32_e32 v172, v182
	v_mov_b32_e32 v173, v186
	v_mov_b32_e32 v186, v183
	v_add_f32_e32 v162, v162, v184
	v_add_f32_e32 v163, v163, v185
	v_add_f32_e32 v172, v172, v186
	v_add_f32_e32 v173, v173, v187
	s_nop 0
	v_add_f32_e32 v162, v162, v172
	v_add_f32_e32 v163, v163, v173
	v_mov_b32_e32 v172, v96
	v_mov_b32_e32 v173, v100
	v_mov_b32_e32 v100, v97
	v_add_f32_e32 v96, v172, v100
	v_add_f32_e32 v97, v173, v101
	v_mov_b32_e32 v100, v98
	v_mov_b32_e32 v101, v102
	v_mov_b32_e32 v102, v99
	v_add_f32_e32 v98, v100, v102
	v_add_f32_e32 v99, v101, v103
	s_nop 0
	v_add_f32_e32 v96, v96, v98
	v_add_f32_e32 v97, v97, v99
	s_nop 0
	v_add_f32_e32 v96, v162, v96
	v_add_f32_e32 v97, v163, v97
	s_nop 0
	v_add_f32_e32 v96, v96, v97
	v_fmamk_f32 v96, v96, 0x3a800000, v211
	v_rsq_f32_e32 v157, v96

; __device__ __forceinline__ float silu_f(float v) { return v * __builtin_amdgcn_rcpf(1.f + __expf(-v)); }
;     __device__ __forceinline__ void operator()(const f32x4 (&acc)[2][2][4][2], const Unit& u, int wr, int wc, int fr, int fq, int ui, PG8_LAS unsigned char* lds) const {
;     ...
;                     f32x4 v[2] = {acc[ai][bj][m][0] * rs, acc[ai][bj][m][1] * rs};
;                     if (ksum) { csum[bj][0] += v[0]; csum[bj][1] += v[1]; }
; #pragma unroll
;                     for (int n = 0; n < 2; ++n) {
;                         f32x4 lbv = (f32x4){0.f, 0.f, 0.f, 0.f};
;                         if (act == 2) lbv = *(const f32x4*)(lb + (col0 - 1024) + bj * HALF + 4 * n);
; #pragma unroll
;                         for (int e = 0; e < 4; ++e) {
;                             float x = v[n][e];
;                             if (act == 1) x = silu_f(x);
;                             else if (act == 2) { const float l = lbv[e]; x = __logf(l + (1.f - l) * __builtin_amdgcn_rcpf(1.f + __expf(-x))); }
.LBB0_444:
	v_mul_f32_e32 v102, v92, v158
	v_mul_f32_e32 v103, v93, v158
	s_and_b64 vcc, exec, s[48:49]
	s_mov_b64 s[0:1], -1
	s_cbranch_vccnz .LBB0_448
	s_and_b64 vcc, exec, s[46:47]
	v_mov_b32_e32 v171, v102
	s_cbranch_vccnz .LBB0_447
	v_mul_f32_e32 v92, 0xbfb8aa3b, v102
	v_exp_f32_e32 v92, v92
	s_waitcnt vmcnt(0)
	v_sub_f32_e32 v93, 1.0, v96
	v_add_f32_e32 v92, 1.0, v92
	v_rcp_f32_e32 v92, v92
	s_nop 0
	v_fmac_f32_e32 v96, v92, v93
	v_cmp_gt_f32_e32 vcc, s35, v96
	s_nop 1
	v_cndmask_b32_e64 v92, 0, 32, vcc
	v_ldexp_f32 v92, v96, v92
	v_log_f32_e32 v92, v92
	s_nop 0
	v_mul_f32_e32 v93, 0x3f317217, v92
	v_fma_f32 v93, v92, s13, -v93
	v_fmac_f32_e32 v93, 0x3377d1cf, v92
	v_fmac_f32_e32 v93, 0x3f317217, v92
	v_cmp_lt_f32_e64 s[52:53], |v92|, s36
	s_nop 1
	v_cndmask_b32_e64 v92, v92, v93, s[52:53]
	v_cndmask_b32_e32 v93, 0, v214, vcc
	v_sub_f32_e32 v171, v92, v93

; __device__ __forceinline__ float silu_f(float v) { return v * __builtin_amdgcn_rcpf(1.f + __expf(-v)); }
;     __device__ __forceinline__ void operator()(const f32x4 (&acc)[2][2][4][2], const Unit& u, int wr, int wc, int fr, int fq, int ui, PG8_LAS unsigned char* lds) const {
;     ...
;                     f32x4 v[2] = {acc[ai][bj][m][0] * rs, acc[ai][bj][m][1] * rs};
;                     if (ksum) { csum[bj][0] += v[0]; csum[bj][1] += v[1]; }
; #pragma unroll
;                     for (int n = 0; n < 2; ++n) {
;                         f32x4 lbv = (f32x4){0.f, 0.f, 0.f, 0.f};
;                         if (act == 2) lbv = *(const f32x4*)(lb + (col0 - 1024) + bj * HALF + 4 * n);
; #pragma unroll
;                         for (int e = 0; e < 4; ++e) {
;                             float x = v[n][e];
;                             if (act == 1) x = silu_f(x);
;                             else if (act == 2) { const float l = lbv[e]; x = __logf(l + (1.f - l) * __builtin_amdgcn_rcpf(1.f + __expf(-x))); }
.LBB0_450:
	v_mul_f32_e32 v100, v94, v158
	v_mul_f32_e32 v101, v95, v158
	s_and_b64 vcc, exec, s[48:49]
	s_mov_b64 s[0:1], -1
	s_cbranch_vccnz .LBB0_462
	s_and_b64 vcc, exec, s[46:47]
	v_mov_b32_e32 v172, v103
	s_cbranch_vccnz .LBB0_453
	v_mul_f32_e32 v92, 0xbfb8aa3b, v103
	v_exp_f32_e32 v92, v92
	s_waitcnt vmcnt(0)
	v_sub_f32_e32 v93, 1.0, v97
	v_add_f32_e32 v92, 1.0, v92
	v_rcp_f32_e32 v92, v92
	s_nop 0
	v_fmac_f32_e32 v97, v92, v93
	v_cmp_gt_f32_e32 vcc, s35, v97
	s_nop 1
	v_cndmask_b32_e64 v92, 0, 32, vcc
	v_ldexp_f32 v92, v97, v92
	v_log_f32_e32 v92, v92
	s_nop 0
	v_mul_f32_e32 v93, 0x3f317217, v92
	v_fma_f32 v93, v92, s13, -v93
	v_fmac_f32_e32 v93, 0x3377d1cf, v92
	v_fmac_f32_e32 v93, 0x3f317217, v92
	v_cmp_lt_f32_e64 s[52:53], |v92|, s36
	s_nop 1
	v_cndmask_b32_e64 v92, v92, v93, s[52:53]
	v_cndmask_b32_e32 v93, 0, v214, vcc
	v_sub_f32_e32 v172, v92, v93

; __device__ __forceinline__ float silu_f(float v) { return v * __builtin_amdgcn_rcpf(1.f + __expf(-v)); }
;     __device__ __forceinline__ void operator()(const f32x4 (&acc)[2][2][4][2], const Unit& u, int wr, int wc, int fr, int fq, int ui, PG8_LAS unsigned char* lds) const {
;     ...
;                     f32x4 v[2] = {acc[ai][bj][m][0] * rs, acc[ai][bj][m][1] * rs};
;                     if (ksum) { csum[bj][0] += v[0]; csum[bj][1] += v[1]; }
; #pragma unroll
;                     for (int n = 0; n < 2; ++n) {
;                         f32x4 lbv = (f32x4){0.f, 0.f, 0.f, 0.f};
;                         if (act == 2) lbv = *(const f32x4*)(lb + (col0 - 1024) + bj * HALF + 4 * n);
; #pragma unroll
;                         for (int e = 0; e < 4; ++e) {
;                             float x = v[n][e];
;                             if (act == 1) x = silu_f(x);
;                             else if (act == 2) { const float l = lbv[e]; x = __logf(l + (1.f - l) * __builtin_amdgcn_rcpf(1.f + __expf(-x))); }
.LBB0_470:
	v_mov_b32_e32 v162, v158
	v_mov_b32_e32 v163, v158
	s_waitcnt vmcnt(0)
	v_mul_f32_e32 v98, v88, v162
	v_mul_f32_e32 v99, v89, v163
	s_and_b64 vcc, exec, s[48:49]
	s_mov_b64 s[0:1], -1
	s_cbranch_vccnz .LBB0_474
	s_and_b64 vcc, exec, s[46:47]
	v_mov_b32_e32 v88, v98
	s_cbranch_vccnz .LBB0_473
	v_mul_f32_e32 v88, 0xbfb8aa3b, v98
	v_exp_f32_e32 v88, v88
	v_sub_f32_e32 v89, 1.0, v92
	v_add_f32_e32 v88, 1.0, v88
	v_rcp_f32_e32 v88, v88
	s_nop 0
	v_fmac_f32_e32 v92, v88, v89
	v_cmp_gt_f32_e32 vcc, s35, v92
	s_nop 1
	v_cndmask_b32_e64 v88, 0, 32, vcc
	v_ldexp_f32 v88, v92, v88
	v_log_f32_e32 v88, v88
	s_nop 0
	v_mul_f32_e32 v89, 0x3f317217, v88
	v_fma_f32 v89, v88, s13, -v89
	v_fmac_f32_e32 v89, 0x3377d1cf, v88
	v_fmac_f32_e32 v89, 0x3f317217, v88
	v_cmp_lt_f32_e64 s[52:53], |v88|, s36
	s_nop 1
	v_cndmask_b32_e64 v88, v88, v89, s[52:53]
	v_cndmask_b32_e32 v89, 0, v214, vcc
	v_sub_f32_e32 v88, v88, v89

; __device__ __forceinline__ float silu_f(float v) { return v * __builtin_amdgcn_rcpf(1.f + __expf(-v)); }
;     __device__ __forceinline__ void operator()(const f32x4 (&acc)[2][2][4][2], const Unit& u, int wr, int wc, int fr, int fq, int ui, PG8_LAS unsigned char* lds) const {
;     ...
;                     f32x4 v[2] = {acc[ai][bj][m][0] * rs, acc[ai][bj][m][1] * rs};
;                     if (ksum) { csum[bj][0] += v[0]; csum[bj][1] += v[1]; }
; #pragma unroll
;                     for (int n = 0; n < 2; ++n) {
;                         f32x4 lbv = (f32x4){0.f, 0.f, 0.f, 0.f};
;                         if (act == 2) lbv = *(const f32x4*)(lb + (col0 - 1024) + bj * HALF + 4 * n);
; #pragma unroll
;                         for (int e = 0; e < 4; ++e) {
;                             float x = v[n][e];
;                             if (act == 1) x = silu_f(x);
;                             else if (act == 2) { const float l = lbv[e]; x = __logf(l + (1.f - l) * __builtin_amdgcn_rcpf(1.f + __expf(-x))); }
.LBB0_476:
	v_mov_b32_e32 v159, v158
	v_mul_f32_e32 v96, v90, v158
	v_mul_f32_e32 v97, v91, v159
	s_and_b64 vcc, exec, s[48:49]
	s_mov_b64 s[0:1], -1
	s_cbranch_vccnz .LBB0_488
	s_and_b64 vcc, exec, s[46:47]
	v_mov_b32_e32 v89, v99
	s_cbranch_vccnz .LBB0_479
	v_mul_f32_e32 v89, 0xbfb8aa3b, v99
	v_exp_f32_e32 v89, v89
	v_sub_f32_e32 v90, 1.0, v93
	v_add_f32_e32 v89, 1.0, v89
	v_rcp_f32_e32 v89, v89
	s_nop 0
	v_fmac_f32_e32 v93, v89, v90
	v_cmp_gt_f32_e32 vcc, s35, v93
	s_nop 1
	v_cndmask_b32_e64 v89, 0, 32, vcc
	v_ldexp_f32 v89, v93, v89
	v_log_f32_e32 v89, v89
	s_nop 0
	v_mul_f32_e32 v90, 0x3f317217, v89
	v_fma_f32 v90, v89, s13, -v90
	v_fmac_f32_e32 v90, 0x3377d1cf, v89
	v_fmac_f32_e32 v90, 0x3f317217, v89
	v_cmp_lt_f32_e64 s[52:53], |v89|, s36
	s_nop 1
	v_cndmask_b32_e64 v89, v89, v90, s[52:53]
	v_cndmask_b32_e32 v90, 0, v214, vcc
	v_sub_f32_e32 v89, v89, v90

; __device__ __forceinline__ float silu_f(float v) { return v * __builtin_amdgcn_rcpf(1.f + __expf(-v)); }
;     __device__ __forceinline__ void operator()(const f32x4 (&acc)[2][2][4][2], const Unit& u, int wr, int wc, int fr, int fq, int ui, PG8_LAS unsigned char* lds) const {
;     ...
;                     f32x4 v[2] = {acc[ai][bj][m][0] * rs, acc[ai][bj][m][1] * rs};
;                     if (ksum) { csum[bj][0] += v[0]; csum[bj][1] += v[1]; }
; #pragma unroll
;                     for (int n = 0; n < 2; ++n) {
;                         f32x4 lbv = (f32x4){0.f, 0.f, 0.f, 0.f};
;                         if (act == 2) lbv = *(const f32x4*)(lb + (col0 - 1024) + bj * HALF + 4 * n);
; #pragma unroll
;                         for (int e = 0; e < 4; ++e) {
;                             float x = v[n][e];
;                             if (act == 1) x = silu_f(x);
;                             else if (act == 2) { const float l = lbv[e]; x = __logf(l + (1.f - l) * __builtin_amdgcn_rcpf(1.f + __expf(-x))); }
.LBB0_496:
	s_nop 0
	v_mul_f32_e32 v94, v84, v162
	v_mul_f32_e32 v95, v85, v163
	s_and_b64 vcc, exec, s[48:49]
	s_mov_b64 s[0:1], -1
	s_cbranch_vccnz .LBB0_500
	s_and_b64 vcc, exec, s[46:47]
	v_mov_b32_e32 v171, v94
	s_cbranch_vccnz .LBB0_499
	v_mul_f32_e32 v84, 0xbfb8aa3b, v94
	v_exp_f32_e32 v84, v84
	s_waitcnt vmcnt(0)
	v_sub_f32_e32 v85, 1.0, v88
	v_add_f32_e32 v84, 1.0, v84
	v_rcp_f32_e32 v84, v84
	s_nop 0
	v_fmac_f32_e32 v88, v84, v85
	v_cmp_gt_f32_e32 vcc, s35, v88
	s_nop 1
	v_cndmask_b32_e64 v84, 0, 32, vcc
	v_ldexp_f32 v84, v88, v84
	v_log_f32_e32 v84, v84
	s_nop 0
	v_mul_f32_e32 v85, 0x3f317217, v84
	v_fma_f32 v85, v84, s13, -v85
	v_fmac_f32_e32 v85, 0x3377d1cf, v84
	v_fmac_f32_e32 v85, 0x3f317217, v84
	v_cmp_lt_f32_e64 s[52:53], |v84|, s36
	s_nop 1
	v_cndmask_b32_e64 v84, v84, v85, s[52:53]
	v_cndmask_b32_e32 v85, 0, v214, vcc
	v_sub_f32_e32 v171, v84, v85

; __device__ __forceinline__ float silu_f(float v) { return v * __builtin_amdgcn_rcpf(1.f + __expf(-v)); }
;     __device__ __forceinline__ void operator()(const f32x4 (&acc)[2][2][4][2], const Unit& u, int wr, int wc, int fr, int fq, int ui, PG8_LAS unsigned char* lds) const {
;     ...
;                     f32x4 v[2] = {acc[ai][bj][m][0] * rs, acc[ai][bj][m][1] * rs};
;                     if (ksum) { csum[bj][0] += v[0]; csum[bj][1] += v[1]; }
; #pragma unroll
;                     for (int n = 0; n < 2; ++n) {
;                         f32x4 lbv = (f32x4){0.f, 0.f, 0.f, 0.f};
;                         if (act == 2) lbv = *(const f32x4*)(lb + (col0 - 1024) + bj * HALF + 4 * n);
; #pragma unroll
;                         for (int e = 0; e < 4; ++e) {
;                             float x = v[n][e];
;                             if (act == 1) x = silu_f(x);
;                             else if (act == 2) { const float l = lbv[e]; x = __logf(l + (1.f - l) * __builtin_amdgcn_rcpf(1.f + __expf(-x))); }
.LBB0_502:
	v_mov_b32_e32 v159, v158
	v_mul_f32_e32 v92, v86, v158
	v_mul_f32_e32 v93, v87, v159
	s_and_b64 vcc, exec, s[48:49]
	s_mov_b64 s[0:1], -1
	s_cbranch_vccnz .LBB0_514
	s_and_b64 vcc, exec, s[46:47]
	v_mov_b32_e32 v172, v95
	s_cbranch_vccnz .LBB0_505
	v_mul_f32_e32 v84, 0xbfb8aa3b, v95
	v_exp_f32_e32 v84, v84
	s_waitcnt vmcnt(0)
	v_sub_f32_e32 v85, 1.0, v89
	v_add_f32_e32 v84, 1.0, v84
	v_rcp_f32_e32 v84, v84
	s_nop 0
	v_fmac_f32_e32 v89, v84, v85
	v_cmp_gt_f32_e32 vcc, s35, v89
	s_nop 1
	v_cndmask_b32_e64 v84, 0, 32, vcc
	v_ldexp_f32 v84, v89, v84
	v_log_f32_e32 v84, v84
	s_nop 0
	v_mul_f32_e32 v85, 0x3f317217, v84
	v_fma_f32 v85, v84, s13, -v85
	v_fmac_f32_e32 v85, 0x3377d1cf, v84
	v_fmac_f32_e32 v85, 0x3f317217, v84
	v_cmp_lt_f32_e64 s[52:53], |v84|, s36
	s_nop 1
	v_cndmask_b32_e64 v84, v84, v85, s[52:53]
	v_cndmask_b32_e32 v85, 0, v214, vcc
	v_sub_f32_e32 v172, v84, v85

; __device__ __forceinline__ float silu_f(float v) { return v * __builtin_amdgcn_rcpf(1.f + __expf(-v)); }
;     __device__ __forceinline__ void operator()(const f32x4 (&acc)[2][2][4][2], const Unit& u, int wr, int wc, int fr, int fq, int ui, PG8_LAS unsigned char* lds) const {
;     ...
;                     f32x4 v[2] = {acc[ai][bj][m][0] * rs, acc[ai][bj][m][1] * rs};
;                     if (ksum) { csum[bj][0] += v[0]; csum[bj][1] += v[1]; }
; #pragma unroll
;                     for (int n = 0; n < 2; ++n) {
;                         f32x4 lbv = (f32x4){0.f, 0.f, 0.f, 0.f};
;                         if (act == 2) lbv = *(const f32x4*)(lb + (col0 - 1024) + bj * HALF + 4 * n);
; #pragma unroll
;                         for (int e = 0; e < 4; ++e) {
;                             float x = v[n][e];
;                             if (act == 1) x = silu_f(x);
;                             else if (act == 2) { const float l = lbv[e]; x = __logf(l + (1.f - l) * __builtin_amdgcn_rcpf(1.f + __expf(-x))); }
.LBB0_522:
	s_waitcnt vmcnt(0)
	v_mul_f32_e32 v90, v80, v162
	v_mul_f32_e32 v91, v81, v163
	s_and_b64 vcc, exec, s[48:49]
	s_mov_b64 s[0:1], -1
	s_cbranch_vccnz .LBB0_526
	s_and_b64 vcc, exec, s[46:47]
	v_mov_b32_e32 v80, v90
	s_cbranch_vccnz .LBB0_525
	v_mul_f32_e32 v80, 0xbfb8aa3b, v90
	v_exp_f32_e32 v80, v80
	v_sub_f32_e32 v81, 1.0, v84
	v_add_f32_e32 v80, 1.0, v80
	v_rcp_f32_e32 v80, v80
	s_nop 0
	v_fmac_f32_e32 v84, v80, v81
	v_cmp_gt_f32_e32 vcc, s35, v84
	s_nop 1
	v_cndmask_b32_e64 v80, 0, 32, vcc
	v_ldexp_f32 v80, v84, v80
	v_log_f32_e32 v80, v80
	s_nop 0
	v_mul_f32_e32 v81, 0x3f317217, v80
	v_fma_f32 v81, v80, s13, -v81
	v_fmac_f32_e32 v81, 0x3377d1cf, v80
	v_fmac_f32_e32 v81, 0x3f317217, v80
	v_cmp_lt_f32_e64 s[52:53], |v80|, s36
	s_nop 1
	v_cndmask_b32_e64 v80, v80, v81, s[52:53]
	v_cndmask_b32_e32 v81, 0, v214, vcc
	v_sub_f32_e32 v80, v80, v81

; __device__ __forceinline__ float silu_f(float v) { return v * __builtin_amdgcn_rcpf(1.f + __expf(-v)); }
;     __device__ __forceinline__ void operator()(const f32x4 (&acc)[2][2][4][2], const Unit& u, int wr, int wc, int fr, int fq, int ui, PG8_LAS unsigned char* lds) const {
;     ...
;                     f32x4 v[2] = {acc[ai][bj][m][0] * rs, acc[ai][bj][m][1] * rs};
;                     if (ksum) { csum[bj][0] += v[0]; csum[bj][1] += v[1]; }
; #pragma unroll
;                     for (int n = 0; n < 2; ++n) {
;                         f32x4 lbv = (f32x4){0.f, 0.f, 0.f, 0.f};
;                         if (act == 2) lbv = *(const f32x4*)(lb + (col0 - 1024) + bj * HALF + 4 * n);
; #pragma unroll
;                         for (int e = 0; e < 4; ++e) {
;                             float x = v[n][e];
;                             if (act == 1) x = silu_f(x);
;                             else if (act == 2) { const float l = lbv[e]; x = __logf(l + (1.f - l) * __builtin_amdgcn_rcpf(1.f + __expf(-x))); }
.LBB0_528:
	v_mov_b32_e32 v159, v158
	v_mul_f32_e32 v88, v82, v158
	v_mul_f32_e32 v89, v83, v159
	s_and_b64 vcc, exec, s[48:49]
	s_mov_b64 s[0:1], -1
	s_cbranch_vccnz .LBB0_540
	s_and_b64 vcc, exec, s[46:47]
	v_mov_b32_e32 v81, v91
	s_cbranch_vccnz .LBB0_531
	v_mul_f32_e32 v81, 0xbfb8aa3b, v91
	v_exp_f32_e32 v81, v81
	v_sub_f32_e32 v82, 1.0, v85
	v_add_f32_e32 v81, 1.0, v81
	v_rcp_f32_e32 v81, v81
	s_nop 0
	v_fmac_f32_e32 v85, v81, v82
	v_cmp_gt_f32_e32 vcc, s35, v85
	s_nop 1
	v_cndmask_b32_e64 v81, 0, 32, vcc
	v_ldexp_f32 v81, v85, v81
	v_log_f32_e32 v81, v81
	s_nop 0
	v_mul_f32_e32 v82, 0x3f317217, v81
	v_fma_f32 v82, v81, s13, -v82
	v_fmac_f32_e32 v82, 0x3377d1cf, v81
	v_fmac_f32_e32 v82, 0x3f317217, v81
	v_cmp_lt_f32_e64 s[52:53], |v81|, s36
	s_nop 1
	v_cndmask_b32_e64 v81, v81, v82, s[52:53]
	v_cndmask_b32_e32 v82, 0, v214, vcc
	v_sub_f32_e32 v81, v81, v82

; __device__ __forceinline__ float silu_f(float v) { return v * __builtin_amdgcn_rcpf(1.f + __expf(-v)); }
;     __device__ __forceinline__ void operator()(const f32x4 (&acc)[2][2][4][2], const Unit& u, int wr, int wc, int fr, int fq, int ui, PG8_LAS unsigned char* lds) const {
;     ...
;                         rs4[m] = __builtin_amdgcn_rsqf(ssq_row(ssq, row0 + ai * HALF + m * 16) * (1.0f / 1024.0f) + RMS_EPS) * sc;
;                         rs4[m + 1] = __builtin_amdgcn_rsqf(ssq_row(ssq, row0 + ai * HALF + (m + 1) * 16) * (1.0f / 1024.0f) + RMS_EPS) * sc;
;                     }
;                 }
;                 const int row = row0 + ai * HALF + m * 16;
;                 const float rs = rs4[m];
;                 bf16_t* rowp = O + (size_t)row * ldc + col0;
; #pragma unroll
;                 for (int bj = 0; bj < 2; ++bj) {
;                     f32x4 v[2] = {acc[ai][bj][m][0] * rs, acc[ai][bj][m][1] * rs};
;                     if (ksum) { csum[bj][0] += v[0]; csum[bj][1] += v[1]; }
; #pragma unroll
;                     for (int n = 0; n < 2; ++n) {
;                         f32x4 lbv = (f32x4){0.f, 0.f, 0.f, 0.f};
;                         if (act == 2) lbv = *(const f32x4*)(lb + (col0 - 1024) + bj * HALF + 4 * n);
; #pragma unroll
;                         for (int e = 0; e < 4; ++e) {
;                             float x = v[n][e];
;                             if (act == 1) x = silu_f(x);
;                             else if (act == 2) { const float l = lbv[e]; x = __logf(l + (1.f - l) * __builtin_amdgcn_rcpf(1.f + __expf(-x))); }
.LBB0_548:
	v_mul_f32_e32 v158, v169, v157
	v_mul_f32_e32 v86, v76, v158
	v_mul_f32_e32 v87, v77, v158
	s_and_b64 vcc, exec, s[48:49]
	s_mov_b64 s[0:1], -1
	s_cbranch_vccnz .LBB0_552
	s_and_b64 vcc, exec, s[46:47]
	v_mov_b32_e32 v160, v86
	s_cbranch_vccnz .LBB0_551
	v_mul_f32_e32 v76, 0xbfb8aa3b, v86
	v_exp_f32_e32 v76, v76
	s_waitcnt vmcnt(0)
	v_sub_f32_e32 v77, 1.0, v80
	v_add_f32_e32 v76, 1.0, v76
	v_rcp_f32_e32 v76, v76
	s_nop 0
	v_fmac_f32_e32 v80, v76, v77
	v_cmp_gt_f32_e32 vcc, s35, v80
	s_nop 1
	v_cndmask_b32_e64 v76, 0, 32, vcc
	v_ldexp_f32 v76, v80, v76
	v_log_f32_e32 v76, v76
	s_nop 0
	v_mul_f32_e32 v77, 0x3f317217, v76
	v_fma_f32 v77, v76, s13, -v77
	v_fmac_f32_e32 v77, 0x3377d1cf, v76
	v_fmac_f32_e32 v77, 0x3f317217, v76
	v_cmp_lt_f32_e64 s[52:53], |v76|, s36
	s_nop 1
	v_cndmask_b32_e64 v76, v76, v77, s[52:53]
	v_cndmask_b32_e32 v77, 0, v214, vcc
	v_sub_f32_e32 v160, v76, v77

; __device__ __forceinline__ float silu_f(float v) { return v * __builtin_amdgcn_rcpf(1.f + __expf(-v)); }
;     __device__ __forceinline__ void operator()(const f32x4 (&acc)[2][2][4][2], const Unit& u, int wr, int wc, int fr, int fq, int ui, PG8_LAS unsigned char* lds) const {
;     ...
;                     f32x4 v[2] = {acc[ai][bj][m][0] * rs, acc[ai][bj][m][1] * rs};
;                     if (ksum) { csum[bj][0] += v[0]; csum[bj][1] += v[1]; }
; #pragma unroll
;                     for (int n = 0; n < 2; ++n) {
;                         f32x4 lbv = (f32x4){0.f, 0.f, 0.f, 0.f};
;                         if (act == 2) lbv = *(const f32x4*)(lb + (col0 - 1024) + bj * HALF + 4 * n);
; #pragma unroll
;                         for (int e = 0; e < 4; ++e) {
;                             float x = v[n][e];
;                             if (act == 1) x = silu_f(x);
;                             else if (act == 2) { const float l = lbv[e]; x = __logf(l + (1.f - l) * __builtin_amdgcn_rcpf(1.f + __expf(-x))); }
.LBB0_554:
	v_mul_f32_e32 v84, v78, v158
	v_mul_f32_e32 v85, v79, v158
	s_and_b64 vcc, exec, s[48:49]
	s_mov_b64 s[0:1], -1
	s_cbranch_vccnz .LBB0_566
	s_and_b64 vcc, exec, s[46:47]
	v_mov_b32_e32 v161, v87
	s_cbranch_vccnz .LBB0_557
	v_mul_f32_e32 v76, 0xbfb8aa3b, v87
	v_exp_f32_e32 v76, v76
	s_waitcnt vmcnt(0)
	v_sub_f32_e32 v77, 1.0, v81
	v_add_f32_e32 v76, 1.0, v76
	v_rcp_f32_e32 v76, v76
	s_nop 0
	v_fmac_f32_e32 v81, v76, v77
	v_cmp_gt_f32_e32 vcc, s35, v81
	s_nop 1
	v_cndmask_b32_e64 v76, 0, 32, vcc
	v_ldexp_f32 v76, v81, v76
	v_log_f32_e32 v76, v76
	s_nop 0
	v_mul_f32_e32 v77, 0x3f317217, v76
	v_fma_f32 v77, v76, s13, -v77
	v_fmac_f32_e32 v77, 0x3377d1cf, v76
	v_fmac_f32_e32 v77, 0x3f317217, v76
	v_cmp_lt_f32_e64 s[52:53], |v76|, s36
	s_nop 1
	v_cndmask_b32_e64 v76, v76, v77, s[52:53]
	v_cndmask_b32_e32 v77, 0, v214, vcc
	v_sub_f32_e32 v161, v76, v77

; __device__ __forceinline__ float silu_f(float v) { return v * __builtin_amdgcn_rcpf(1.f + __expf(-v)); }
;     __device__ __forceinline__ void operator()(const f32x4 (&acc)[2][2][4][2], const Unit& u, int wr, int wc, int fr, int fq, int ui, PG8_LAS unsigned char* lds) const {
;     ...
;                     f32x4 v[2] = {acc[ai][bj][m][0] * rs, acc[ai][bj][m][1] * rs};
;                     if (ksum) { csum[bj][0] += v[0]; csum[bj][1] += v[1]; }
; #pragma unroll
;                     for (int n = 0; n < 2; ++n) {
;                         f32x4 lbv = (f32x4){0.f, 0.f, 0.f, 0.f};
;                         if (act == 2) lbv = *(const f32x4*)(lb + (col0 - 1024) + bj * HALF + 4 * n);
; #pragma unroll
;                         for (int e = 0; e < 4; ++e) {
;                             float x = v[n][e];
;                             if (act == 1) x = silu_f(x);
;                             else if (act == 2) { const float l = lbv[e]; x = __logf(l + (1.f - l) * __builtin_amdgcn_rcpf(1.f + __expf(-x))); }
.LBB0_574:
	v_mov_b32_e32 v159, v158
	s_waitcnt vmcnt(0)
	v_mul_f32_e32 v82, v72, v158
	v_mul_f32_e32 v83, v73, v159
	s_and_b64 vcc, exec, s[48:49]
	s_mov_b64 s[0:1], -1
	s_cbranch_vccnz .LBB0_578
	s_and_b64 vcc, exec, s[46:47]
	v_mov_b32_e32 v72, v82
	s_cbranch_vccnz .LBB0_577
	v_mul_f32_e32 v72, 0xbfb8aa3b, v82
	v_exp_f32_e32 v72, v72
	v_sub_f32_e32 v73, 1.0, v76
	v_add_f32_e32 v72, 1.0, v72
	v_rcp_f32_e32 v72, v72
	s_nop 0
	v_fmac_f32_e32 v76, v72, v73
	v_cmp_gt_f32_e32 vcc, s35, v76
	s_nop 1
	v_cndmask_b32_e64 v72, 0, 32, vcc
	v_ldexp_f32 v72, v76, v72
	v_log_f32_e32 v72, v72
	s_nop 0
	v_mul_f32_e32 v73, 0x3f317217, v72
	v_fma_f32 v73, v72, s13, -v73
	v_fmac_f32_e32 v73, 0x3377d1cf, v72
	v_fmac_f32_e32 v73, 0x3f317217, v72
	v_cmp_lt_f32_e64 s[52:53], |v72|, s36
	s_nop 1
	v_cndmask_b32_e64 v72, v72, v73, s[52:53]
	v_cndmask_b32_e32 v73, 0, v214, vcc
	v_sub_f32_e32 v72, v72, v73

; __device__ __forceinline__ float silu_f(float v) { return v * __builtin_amdgcn_rcpf(1.f + __expf(-v)); }
;     __device__ __forceinline__ void operator()(const f32x4 (&acc)[2][2][4][2], const Unit& u, int wr, int wc, int fr, int fq, int ui, PG8_LAS unsigned char* lds) const {
;     ...
;                     f32x4 v[2] = {acc[ai][bj][m][0] * rs, acc[ai][bj][m][1] * rs};
;                     if (ksum) { csum[bj][0] += v[0]; csum[bj][1] += v[1]; }
; #pragma unroll
;                     for (int n = 0; n < 2; ++n) {
;                         f32x4 lbv = (f32x4){0.f, 0.f, 0.f, 0.f};
;                         if (act == 2) lbv = *(const f32x4*)(lb + (col0 - 1024) + bj * HALF + 4 * n);
; #pragma unroll
;                         for (int e = 0; e < 4; ++e) {
;                             float x = v[n][e];
;                             if (act == 1) x = silu_f(x);
;                             else if (act == 2) { const float l = lbv[e]; x = __logf(l + (1.f - l) * __builtin_amdgcn_rcpf(1.f + __expf(-x))); }
.LBB0_580:
	v_mov_b32_e32 v80, v158
	v_mov_b32_e32 v81, v158
	v_mul_f32_e32 v80, v74, v80
	v_mul_f32_e32 v81, v75, v81
	s_and_b64 vcc, exec, s[48:49]
	s_mov_b64 s[0:1], -1
	s_cbranch_vccnz .LBB0_592
	s_and_b64 vcc, exec, s[46:47]
	v_mov_b32_e32 v73, v83
	s_cbranch_vccnz .LBB0_583
	v_mul_f32_e32 v73, 0xbfb8aa3b, v83
	v_exp_f32_e32 v73, v73
	v_sub_f32_e32 v74, 1.0, v77
	v_add_f32_e32 v73, 1.0, v73
	v_rcp_f32_e32 v73, v73
	s_nop 0
	v_fmac_f32_e32 v77, v73, v74
	v_cmp_gt_f32_e32 vcc, s35, v77
	s_nop 1
	v_cndmask_b32_e64 v73, 0, 32, vcc
	v_ldexp_f32 v73, v77, v73
	v_log_f32_e32 v73, v73
	s_nop 0
	v_mul_f32_e32 v74, 0x3f317217, v73
	v_fma_f32 v74, v73, s13, -v74
	v_fmac_f32_e32 v74, 0x3377d1cf, v73
	v_fmac_f32_e32 v74, 0x3f317217, v73
	v_cmp_lt_f32_e64 s[52:53], |v73|, s36
	s_nop 1
	v_cndmask_b32_e64 v73, v73, v74, s[52:53]
	v_cndmask_b32_e32 v74, 0, v214, vcc
	v_sub_f32_e32 v73, v73, v74

; __device__ __forceinline__ float silu_f(float v) { return v * __builtin_amdgcn_rcpf(1.f + __expf(-v)); }
;     __device__ __forceinline__ void operator()(const f32x4 (&acc)[2][2][4][2], const Unit& u, int wr, int wc, int fr, int fq, int ui, PG8_LAS unsigned char* lds) const {
;     ...
;                     f32x4 v[2] = {acc[ai][bj][m][0] * rs, acc[ai][bj][m][1] * rs};
;                     if (ksum) { csum[bj][0] += v[0]; csum[bj][1] += v[1]; }
; #pragma unroll
;                     for (int n = 0; n < 2; ++n) {
;                         f32x4 lbv = (f32x4){0.f, 0.f, 0.f, 0.f};
;                         if (act == 2) lbv = *(const f32x4*)(lb + (col0 - 1024) + bj * HALF + 4 * n);
; #pragma unroll
;                         for (int e = 0; e < 4; ++e) {
;                             float x = v[n][e];
;                             if (act == 1) x = silu_f(x);
;                             else if (act == 2) { const float l = lbv[e]; x = __logf(l + (1.f - l) * __builtin_amdgcn_rcpf(1.f + __expf(-x))); }
.LBB0_600:
	s_nop 0
	v_mul_f32_e32 v78, v68, v158
	v_mul_f32_e32 v79, v69, v159
	s_and_b64 vcc, exec, s[48:49]
	s_mov_b64 s[0:1], -1
	s_cbranch_vccnz .LBB0_604
	s_and_b64 vcc, exec, s[46:47]
	v_mov_b32_e32 v160, v78
	s_cbranch_vccnz .LBB0_603
	v_mul_f32_e32 v68, 0xbfb8aa3b, v78
	v_exp_f32_e32 v68, v68
	s_waitcnt vmcnt(0)
	v_sub_f32_e32 v69, 1.0, v72
	v_add_f32_e32 v68, 1.0, v68
	v_rcp_f32_e32 v68, v68
	s_nop 0
	v_fmac_f32_e32 v72, v68, v69
	v_cmp_gt_f32_e32 vcc, s35, v72
	s_nop 1
	v_cndmask_b32_e64 v68, 0, 32, vcc
	v_ldexp_f32 v68, v72, v68
	v_log_f32_e32 v68, v68
	s_nop 0
	v_mul_f32_e32 v69, 0x3f317217, v68
	v_fma_f32 v69, v68, s13, -v69
	v_fmac_f32_e32 v69, 0x3377d1cf, v68
	v_fmac_f32_e32 v69, 0x3f317217, v68
	v_cmp_lt_f32_e64 s[52:53], |v68|, s36
	s_nop 1
	v_cndmask_b32_e64 v68, v68, v69, s[52:53]
	v_cndmask_b32_e32 v69, 0, v214, vcc
	v_sub_f32_e32 v160, v68, v69

; __device__ __forceinline__ float silu_f(float v) { return v * __builtin_amdgcn_rcpf(1.f + __expf(-v)); }
;     __device__ __forceinline__ void operator()(const f32x4 (&acc)[2][2][4][2], const Unit& u, int wr, int wc, int fr, int fq, int ui, PG8_LAS unsigned char* lds) const {
;     ...
;                     f32x4 v[2] = {acc[ai][bj][m][0] * rs, acc[ai][bj][m][1] * rs};
;                     if (ksum) { csum[bj][0] += v[0]; csum[bj][1] += v[1]; }
; #pragma unroll
;                     for (int n = 0; n < 2; ++n) {
;                         f32x4 lbv = (f32x4){0.f, 0.f, 0.f, 0.f};
;                         if (act == 2) lbv = *(const f32x4*)(lb + (col0 - 1024) + bj * HALF + 4 * n);
; #pragma unroll
;                         for (int e = 0; e < 4; ++e) {
;                             float x = v[n][e];
;                             if (act == 1) x = silu_f(x);
;                             else if (act == 2) { const float l = lbv[e]; x = __logf(l + (1.f - l) * __builtin_amdgcn_rcpf(1.f + __expf(-x))); }
.LBB0_606:
	v_mov_b32_e32 v68, v158
	v_mov_b32_e32 v69, v158
	v_mul_f32_e32 v76, v70, v68
	v_mul_f32_e32 v77, v71, v69
	s_and_b64 vcc, exec, s[48:49]
	s_mov_b64 s[0:1], -1
	s_cbranch_vccnz .LBB0_618
	s_and_b64 vcc, exec, s[46:47]
	v_mov_b32_e32 v161, v79
	s_cbranch_vccnz .LBB0_609
	v_mul_f32_e32 v68, 0xbfb8aa3b, v79
	v_exp_f32_e32 v68, v68
	s_waitcnt vmcnt(0)
	v_sub_f32_e32 v69, 1.0, v73
	v_add_f32_e32 v68, 1.0, v68
	v_rcp_f32_e32 v68, v68
	s_nop 0
	v_fmac_f32_e32 v73, v68, v69
	v_cmp_gt_f32_e32 vcc, s35, v73
	s_nop 1
	v_cndmask_b32_e64 v68, 0, 32, vcc
	v_ldexp_f32 v68, v73, v68
	v_log_f32_e32 v68, v68
	s_nop 0
	v_mul_f32_e32 v69, 0x3f317217, v68
	v_fma_f32 v69, v68, s13, -v69
	v_fmac_f32_e32 v69, 0x3377d1cf, v68
	v_fmac_f32_e32 v69, 0x3f317217, v68
	v_cmp_lt_f32_e64 s[52:53], |v68|, s36
	s_nop 1
	v_cndmask_b32_e64 v68, v68, v69, s[52:53]
	v_cndmask_b32_e32 v69, 0, v214, vcc
	v_sub_f32_e32 v161, v68, v69

; __device__ __forceinline__ float silu_f(float v) { return v * __builtin_amdgcn_rcpf(1.f + __expf(-v)); }
;     __device__ __forceinline__ void operator()(const f32x4 (&acc)[2][2][4][2], const Unit& u, int wr, int wc, int fr, int fq, int ui, PG8_LAS unsigned char* lds) const {
;     ...
;                     f32x4 v[2] = {acc[ai][bj][m][0] * rs, acc[ai][bj][m][1] * rs};
;                     if (ksum) { csum[bj][0] += v[0]; csum[bj][1] += v[1]; }
; #pragma unroll
;                     for (int n = 0; n < 2; ++n) {
;                         f32x4 lbv = (f32x4){0.f, 0.f, 0.f, 0.f};
;                         if (act == 2) lbv = *(const f32x4*)(lb + (col0 - 1024) + bj * HALF + 4 * n);
; #pragma unroll
;                         for (int e = 0; e < 4; ++e) {
;                             float x = v[n][e];
;                             if (act == 1) x = silu_f(x);
;                             else if (act == 2) { const float l = lbv[e]; x = __logf(l + (1.f - l) * __builtin_amdgcn_rcpf(1.f + __expf(-x))); }
.LBB0_626:
	s_waitcnt vmcnt(0)
	v_mul_f32_e32 v74, v64, v158
	v_mul_f32_e32 v75, v65, v159
	s_and_b64 vcc, exec, s[48:49]
	s_mov_b64 s[0:1], -1
	s_cbranch_vccnz .LBB0_630
	s_and_b64 vcc, exec, s[46:47]
	v_mov_b32_e32 v64, v74
	s_cbranch_vccnz .LBB0_629
	v_mul_f32_e32 v64, 0xbfb8aa3b, v74
	v_exp_f32_e32 v64, v64
	v_sub_f32_e32 v65, 1.0, v68
	v_add_f32_e32 v64, 1.0, v64
	v_rcp_f32_e32 v64, v64
	s_nop 0
	v_fmac_f32_e32 v68, v64, v65
	v_cmp_gt_f32_e32 vcc, s35, v68
	s_nop 1
	v_cndmask_b32_e64 v64, 0, 32, vcc
	v_ldexp_f32 v64, v68, v64
	v_log_f32_e32 v64, v64
	s_nop 0
	v_mul_f32_e32 v65, 0x3f317217, v64
	v_fma_f32 v65, v64, s13, -v65
	v_fmac_f32_e32 v65, 0x3377d1cf, v64
	v_fmac_f32_e32 v65, 0x3f317217, v64
	v_cmp_lt_f32_e64 s[52:53], |v64|, s36
	s_nop 1
	v_cndmask_b32_e64 v64, v64, v65, s[52:53]
	v_cndmask_b32_e32 v65, 0, v214, vcc
	v_sub_f32_e32 v64, v64, v65

; __device__ __forceinline__ float silu_f(float v) { return v * __builtin_amdgcn_rcpf(1.f + __expf(-v)); }
;     __device__ __forceinline__ void operator()(const f32x4 (&acc)[2][2][4][2], const Unit& u, int wr, int wc, int fr, int fq, int ui, PG8_LAS unsigned char* lds) const {
;     ...
;                     f32x4 v[2] = {acc[ai][bj][m][0] * rs, acc[ai][bj][m][1] * rs};
;                     if (ksum) { csum[bj][0] += v[0]; csum[bj][1] += v[1]; }
; #pragma unroll
;                     for (int n = 0; n < 2; ++n) {
;                         f32x4 lbv = (f32x4){0.f, 0.f, 0.f, 0.f};
;                         if (act == 2) lbv = *(const f32x4*)(lb + (col0 - 1024) + bj * HALF + 4 * n);
; #pragma unroll
;                         for (int e = 0; e < 4; ++e) {
;                             float x = v[n][e];
;                             if (act == 1) x = silu_f(x);
;                             else if (act == 2) { const float l = lbv[e]; x = __logf(l + (1.f - l) * __builtin_amdgcn_rcpf(1.f + __expf(-x))); }
.LBB0_632:
	v_mov_b32_e32 v159, v158
	v_mul_f32_e32 v72, v66, v158
	v_mul_f32_e32 v73, v67, v159
	s_and_b64 vcc, exec, s[48:49]
	s_mov_b64 s[0:1], -1
	s_cbranch_vccnz .LBB0_644
	s_and_b64 vcc, exec, s[46:47]
	v_mov_b32_e32 v65, v75
	s_cbranch_vccnz .LBB0_635
	v_mul_f32_e32 v65, 0xbfb8aa3b, v75
	v_exp_f32_e32 v65, v65
	v_sub_f32_e32 v66, 1.0, v69
	v_add_f32_e32 v65, 1.0, v65
	v_rcp_f32_e32 v65, v65
	s_nop 0
	v_fmac_f32_e32 v69, v65, v66
	v_cmp_gt_f32_e32 vcc, s35, v69
	s_nop 1
	v_cndmask_b32_e64 v65, 0, 32, vcc
	v_ldexp_f32 v65, v69, v65
	v_log_f32_e32 v65, v65
	s_nop 0
	v_mul_f32_e32 v66, 0x3f317217, v65
	v_fma_f32 v66, v65, s13, -v66
	v_fmac_f32_e32 v66, 0x3377d1cf, v65
	v_fmac_f32_e32 v66, 0x3f317217, v65
	v_cmp_lt_f32_e64 s[52:53], |v65|, s36
	s_nop 1
	v_cndmask_b32_e64 v65, v65, v66, s[52:53]
	v_cndmask_b32_e32 v66, 0, v214, vcc
	v_sub_f32_e32 v65, v65, v66

; __device__ __forceinline__ float ssq_row(const float* part, int row) {
;     const f32x4* p = (const f32x4*)(part + (size_t)row * 16);
;     const f32x4 a = p[0], b = p[1], c = p[2], d = p[3];
;     return (((a[0] + a[1]) + (a[2] + a[3])) + ((b[0] + b[1]) + (b[2] + b[3]))) + (((c[0] + c[1]) + (c[2] + c[3])) + ((d[0] + d[1]) + (d[2] + d[3])));
; }
;     __device__ __forceinline__ void operator()(const f32x4 (&acc)[2][2][4][2], const Unit& u, int wr, int wc, int fr, int fq, int ui, PG8_LAS unsigned char* lds) const {
;     ...
;                     if (use_tab) { rs4[m] = tab[ai * HALF + m * 16] * sc; rs4[m + 1] = tab[ai * HALF + (m + 1) * 16] * sc; }
;                     else {
;                         asm volatile("" ::: "memory");
;                         rs4[m] = __builtin_amdgcn_rsqf(ssq_row(ssq, row0 + ai * HALF + m * 16) * (1.0f / 1024.0f) + RMS_EPS) * sc;
;                         rs4[m + 1] = __builtin_amdgcn_rsqf(ssq_row(ssq, row0 + ai * HALF + (m + 1) * 16) * (1.0f / 1024.0f) + RMS_EPS) * sc;
.LBB0_652:
	s_andn2_b64 vcc, exec, s[0:1]
	s_cbranch_vccnz .LBB0_654
	v_lshlrev_b64 v[64:65], 6, v[158:159]
	v_lshl_add_u64 v[156:157], s[24:25], 0, v[64:65]
	global_load_dwordx4 v[64:67], v[156:157], off offset:16
	global_load_dwordx4 v[68:71], v[156:157], off offset:48
	global_load_dwordx4 v[160:163], v[156:157], off
	global_load_dwordx4 v[180:183], v[156:157], off offset:32
	s_mov_b64 s[0:1], 0x2400
	s_waitcnt vmcnt(1)
	v_mov_b32_e32 v156, v160
	s_waitcnt vmcnt(0)
	v_mov_b32_e32 v157, v180
	v_mov_b32_e32 v180, v161
	v_mov_b32_e32 v160, v162
	v_mov_b32_e32 v161, v182
	v_mov_b32_e32 v182, v163
	v_add_f32_e32 v156, v156, v180
	v_add_f32_e32 v157, v157, v181
	v_add_f32_e32 v160, v160, v182
	v_add_f32_e32 v161, v161, v183
	s_nop 0
	v_add_f32_e32 v156, v156, v160
	v_add_f32_e32 v157, v157, v161
	v_mov_b32_e32 v160, v64
	v_mov_b32_e32 v161, v68
	v_mov_b32_e32 v68, v65
	v_add_f32_e32 v64, v160, v68
	v_add_f32_e32 v65, v161, v69
	v_mov_b32_e32 v68, v66
	v_mov_b32_e32 v69, v70
	v_mov_b32_e32 v70, v67
	v_add_f32_e32 v66, v68, v70
	v_add_f32_e32 v67, v69, v71
	s_nop 0
	v_add_f32_e32 v64, v64, v66
	v_add_f32_e32 v65, v65, v67
	s_nop 0
	v_add_f32_e32 v64, v156, v64
	v_add_f32_e32 v65, v157, v65
	s_nop 0
	v_add_f32_e32 v64, v64, v65
	v_fmamk_f32 v64, v64, 0x3a800000, v211
	v_rsq_f32_e32 v64, v64
	s_nop 0
	v_mul_f32_e32 v154, v169, v64
	v_lshlrev_b64 v[64:65], 6, v[150:151]
	v_lshl_add_u64 v[64:65], s[24:25], 0, v[64:65]
	v_lshl_add_u64 v[156:157], v[64:65], 0, s[0:1]
	v_add_co_u32_e32 v64, vcc, s23, v64
	s_nop 1
	v_addc_co_u32_e32 v65, vcc, 0, v65, vcc
	global_load_dwordx4 v[64:67], v[64:65], off offset:1024
	s_nop 0
	global_load_dwordx4 v[68:71], v[156:157], off offset:16
	global_load_dwordx4 v[160:163], v[156:157], off offset:48
	global_load_dwordx4 v[180:183], v[156:157], off offset:32
	s_waitcnt vmcnt(3)
	v_mov_b32_e32 v156, v64
	s_waitcnt vmcnt(0)
	v_mov_b32_e32 v157, v180
	v_mov_b32_e32 v180, v65
	v_add_f32_e32 v64, v156, v180
	v_add_f32_e32 v65, v157, v181
	v_mov_b32_e32 v156, v66
	v_mov_b32_e32 v157, v182
	v_mov_b32_e32 v182, v67
	v_add_f32_e32 v66, v156, v182
	v_add_f32_e32 v67, v157, v183
	s_nop 0
	v_add_f32_e32 v64, v64, v66
	v_add_f32_e32 v65, v65, v67
	v_mov_b32_e32 v66, v68
	v_mov_b32_e32 v67, v160
	v_mov_b32_e32 v160, v69
	v_mov_b32_e32 v68, v70
	v_mov_b32_e32 v69, v162
	v_mov_b32_e32 v162, v71
	v_add_f32_e32 v66, v66, v160
	v_add_f32_e32 v67, v67, v161
	v_add_f32_e32 v68, v68, v162
	v_add_f32_e32 v69, v69, v163
	s_nop 0
	v_add_f32_e32 v66, v66, v68
	v_add_f32_e32 v67, v67, v69
	s_nop 0
	v_add_f32_e32 v64, v64, v66
	v_add_f32_e32 v65, v65, v67
	s_nop 0
	v_add_f32_e32 v64, v64, v65
	v_fmamk_f32 v64, v64, 0x3a800000, v211
	v_rsq_f32_e32 v157, v64

; __device__ __forceinline__ float silu_f(float v) { return v * __builtin_amdgcn_rcpf(1.f + __expf(-v)); }
;     __device__ __forceinline__ void operator()(const f32x4 (&acc)[2][2][4][2], const Unit& u, int wr, int wc, int fr, int fq, int ui, PG8_LAS unsigned char* lds) const {
;     ...
;                     f32x4 v[2] = {acc[ai][bj][m][0] * rs, acc[ai][bj][m][1] * rs};
;                     if (ksum) { csum[bj][0] += v[0]; csum[bj][1] += v[1]; }
; #pragma unroll
;                     for (int n = 0; n < 2; ++n) {
;                         f32x4 lbv = (f32x4){0.f, 0.f, 0.f, 0.f};
;                         if (act == 2) lbv = *(const f32x4*)(lb + (col0 - 1024) + bj * HALF + 4 * n);
; #pragma unroll
;                         for (int e = 0; e < 4; ++e) {
;                             float x = v[n][e];
;                             if (act == 1) x = silu_f(x);
;                             else if (act == 2) { const float l = lbv[e]; x = __logf(l + (1.f - l) * __builtin_amdgcn_rcpf(1.f + __expf(-x))); }
.LBB0_656:
	v_mul_f32_e32 v70, v60, v154
	v_mul_f32_e32 v71, v61, v154
	s_and_b64 vcc, exec, s[48:49]
	s_mov_b64 s[0:1], -1
	s_cbranch_vccnz .LBB0_660
	s_and_b64 vcc, exec, s[46:47]
	v_mov_b32_e32 v156, v70
	s_cbranch_vccnz .LBB0_659
	v_mul_f32_e32 v60, 0xbfb8aa3b, v70
	v_exp_f32_e32 v60, v60
	s_waitcnt vmcnt(0)
	v_sub_f32_e32 v61, 1.0, v64
	v_add_f32_e32 v60, 1.0, v60
	v_rcp_f32_e32 v60, v60
	s_nop 0
	v_fmac_f32_e32 v64, v60, v61
	v_cmp_gt_f32_e32 vcc, s35, v64
	s_nop 1
	v_cndmask_b32_e64 v60, 0, 32, vcc
	v_ldexp_f32 v60, v64, v60
	v_log_f32_e32 v60, v60
	s_nop 0
	v_mul_f32_e32 v61, 0x3f317217, v60
	v_fma_f32 v61, v60, s13, -v61
	v_fmac_f32_e32 v61, 0x3377d1cf, v60
	v_fmac_f32_e32 v61, 0x3f317217, v60
	v_cmp_lt_f32_e64 s[52:53], |v60|, s36
	s_nop 1
	v_cndmask_b32_e64 v60, v60, v61, s[52:53]
	v_cndmask_b32_e32 v61, 0, v214, vcc
	v_sub_f32_e32 v156, v60, v61

; __device__ __forceinline__ float silu_f(float v) { return v * __builtin_amdgcn_rcpf(1.f + __expf(-v)); }
;     __device__ __forceinline__ void operator()(const f32x4 (&acc)[2][2][4][2], const Unit& u, int wr, int wc, int fr, int fq, int ui, PG8_LAS unsigned char* lds) const {
;     ...
;                     f32x4 v[2] = {acc[ai][bj][m][0] * rs, acc[ai][bj][m][1] * rs};
;                     if (ksum) { csum[bj][0] += v[0]; csum[bj][1] += v[1]; }
; #pragma unroll
;                     for (int n = 0; n < 2; ++n) {
;                         f32x4 lbv = (f32x4){0.f, 0.f, 0.f, 0.f};
;                         if (act == 2) lbv = *(const f32x4*)(lb + (col0 - 1024) + bj * HALF + 4 * n);
; #pragma unroll
;                         for (int e = 0; e < 4; ++e) {
;                             float x = v[n][e];
;                             if (act == 1) x = silu_f(x);
;                             else if (act == 2) { const float l = lbv[e]; x = __logf(l + (1.f - l) * __builtin_amdgcn_rcpf(1.f + __expf(-x))); }
.LBB0_662:
	v_mul_f32_e32 v68, v62, v154
	v_mul_f32_e32 v69, v63, v154
	s_and_b64 vcc, exec, s[48:49]
	s_mov_b64 s[0:1], -1
	s_cbranch_vccnz .LBB0_674
	s_and_b64 vcc, exec, s[46:47]
	v_mov_b32_e32 v160, v71
	s_cbranch_vccnz .LBB0_665
	v_mul_f32_e32 v60, 0xbfb8aa3b, v71
	v_exp_f32_e32 v60, v60
	s_waitcnt vmcnt(0)
	v_sub_f32_e32 v61, 1.0, v65
	v_add_f32_e32 v60, 1.0, v60
	v_rcp_f32_e32 v60, v60
	s_nop 0
	v_fmac_f32_e32 v65, v60, v61
	v_cmp_gt_f32_e32 vcc, s35, v65
	s_nop 1
	v_cndmask_b32_e64 v60, 0, 32, vcc
	v_ldexp_f32 v60, v65, v60
	v_log_f32_e32 v60, v60
	s_nop 0
	v_mul_f32_e32 v61, 0x3f317217, v60
	v_fma_f32 v61, v60, s13, -v61
	v_fmac_f32_e32 v61, 0x3377d1cf, v60
	v_fmac_f32_e32 v61, 0x3f317217, v60
	v_cmp_lt_f32_e64 s[52:53], |v60|, s36
	s_nop 1
	v_cndmask_b32_e64 v60, v60, v61, s[52:53]
	v_cndmask_b32_e32 v61, 0, v214, vcc
	v_sub_f32_e32 v160, v60, v61

; __device__ __forceinline__ float silu_f(float v) { return v * __builtin_amdgcn_rcpf(1.f + __expf(-v)); }
;     __device__ __forceinline__ void operator()(const f32x4 (&acc)[2][2][4][2], const Unit& u, int wr, int wc, int fr, int fq, int ui, PG8_LAS unsigned char* lds) const {
;     ...
;                     f32x4 v[2] = {acc[ai][bj][m][0] * rs, acc[ai][bj][m][1] * rs};
;                     if (ksum) { csum[bj][0] += v[0]; csum[bj][1] += v[1]; }
; #pragma unroll
;                     for (int n = 0; n < 2; ++n) {
;                         f32x4 lbv = (f32x4){0.f, 0.f, 0.f, 0.f};
;                         if (act == 2) lbv = *(const f32x4*)(lb + (col0 - 1024) + bj * HALF + 4 * n);
; #pragma unroll
;                         for (int e = 0; e < 4; ++e) {
;                             float x = v[n][e];
;                             if (act == 1) x = silu_f(x);
;                             else if (act == 2) { const float l = lbv[e]; x = __logf(l + (1.f - l) * __builtin_amdgcn_rcpf(1.f + __expf(-x))); }
.LBB0_682:
	v_mov_b32_e32 v155, v154
	s_waitcnt vmcnt(0)
	v_mul_f32_e32 v66, v56, v154
	v_mul_f32_e32 v67, v57, v155
	s_and_b64 vcc, exec, s[48:49]
	s_mov_b64 s[0:1], -1
	s_cbranch_vccnz .LBB0_686
	s_and_b64 vcc, exec, s[46:47]
	v_mov_b32_e32 v56, v66
	s_cbranch_vccnz .LBB0_685
	v_mul_f32_e32 v56, 0xbfb8aa3b, v66
	v_exp_f32_e32 v56, v56
	v_sub_f32_e32 v57, 1.0, v60
	v_add_f32_e32 v56, 1.0, v56
	v_rcp_f32_e32 v56, v56
	s_nop 0
	v_fmac_f32_e32 v60, v56, v57
	v_cmp_gt_f32_e32 vcc, s35, v60
	s_nop 1
	v_cndmask_b32_e64 v56, 0, 32, vcc
	v_ldexp_f32 v56, v60, v56
	v_log_f32_e32 v56, v56
	s_nop 0
	v_mul_f32_e32 v57, 0x3f317217, v56
	v_fma_f32 v57, v56, s13, -v57
	v_fmac_f32_e32 v57, 0x3377d1cf, v56
	v_fmac_f32_e32 v57, 0x3f317217, v56
	v_cmp_lt_f32_e64 s[52:53], |v56|, s36
	s_nop 1
	v_cndmask_b32_e64 v56, v56, v57, s[52:53]
	v_cndmask_b32_e32 v57, 0, v214, vcc
	v_sub_f32_e32 v56, v56, v57

; __device__ __forceinline__ float silu_f(float v) { return v * __builtin_amdgcn_rcpf(1.f + __expf(-v)); }
;     __device__ __forceinline__ void operator()(const f32x4 (&acc)[2][2][4][2], const Unit& u, int wr, int wc, int fr, int fq, int ui, PG8_LAS unsigned char* lds) const {
;     ...
;                     f32x4 v[2] = {acc[ai][bj][m][0] * rs, acc[ai][bj][m][1] * rs};
;                     if (ksum) { csum[bj][0] += v[0]; csum[bj][1] += v[1]; }
; #pragma unroll
;                     for (int n = 0; n < 2; ++n) {
;                         f32x4 lbv = (f32x4){0.f, 0.f, 0.f, 0.f};
;                         if (act == 2) lbv = *(const f32x4*)(lb + (col0 - 1024) + bj * HALF + 4 * n);
; #pragma unroll
;                         for (int e = 0; e < 4; ++e) {
;                             float x = v[n][e];
;                             if (act == 1) x = silu_f(x);
;                             else if (act == 2) { const float l = lbv[e]; x = __logf(l + (1.f - l) * __builtin_amdgcn_rcpf(1.f + __expf(-x))); }
.LBB0_688:
	v_mov_b32_e32 v64, v154
	v_mov_b32_e32 v65, v154
	v_mul_f32_e32 v64, v58, v64
	v_mul_f32_e32 v65, v59, v65
	s_and_b64 vcc, exec, s[48:49]
	s_mov_b64 s[0:1], -1
	s_cbranch_vccnz .LBB0_700
	s_and_b64 vcc, exec, s[46:47]
	v_mov_b32_e32 v57, v67
	s_cbranch_vccnz .LBB0_691
	v_mul_f32_e32 v57, 0xbfb8aa3b, v67
	v_exp_f32_e32 v57, v57
	v_sub_f32_e32 v58, 1.0, v61
	v_add_f32_e32 v57, 1.0, v57
	v_rcp_f32_e32 v57, v57
	s_nop 0
	v_fmac_f32_e32 v61, v57, v58
	v_cmp_gt_f32_e32 vcc, s35, v61
	s_nop 1
	v_cndmask_b32_e64 v57, 0, 32, vcc
	v_ldexp_f32 v57, v61, v57
	v_log_f32_e32 v57, v57
	s_nop 0
	v_mul_f32_e32 v58, 0x3f317217, v57
	v_fma_f32 v58, v57, s13, -v58
	v_fmac_f32_e32 v58, 0x3377d1cf, v57
	v_fmac_f32_e32 v58, 0x3f317217, v57
	v_cmp_lt_f32_e64 s[52:53], |v57|, s36
	s_nop 1
	v_cndmask_b32_e64 v57, v57, v58, s[52:53]
	v_cndmask_b32_e32 v58, 0, v214, vcc
	v_sub_f32_e32 v57, v57, v58

; __device__ __forceinline__ float silu_f(float v) { return v * __builtin_amdgcn_rcpf(1.f + __expf(-v)); }
;     __device__ __forceinline__ void operator()(const f32x4 (&acc)[2][2][4][2], const Unit& u, int wr, int wc, int fr, int fq, int ui, PG8_LAS unsigned char* lds) const {
;     ...
;                     f32x4 v[2] = {acc[ai][bj][m][0] * rs, acc[ai][bj][m][1] * rs};
;                     if (ksum) { csum[bj][0] += v[0]; csum[bj][1] += v[1]; }
; #pragma unroll
;                     for (int n = 0; n < 2; ++n) {
;                         f32x4 lbv = (f32x4){0.f, 0.f, 0.f, 0.f};
;                         if (act == 2) lbv = *(const f32x4*)(lb + (col0 - 1024) + bj * HALF + 4 * n);
; #pragma unroll
;                         for (int e = 0; e < 4; ++e) {
;                             float x = v[n][e];
;                             if (act == 1) x = silu_f(x);
;                             else if (act == 2) { const float l = lbv[e]; x = __logf(l + (1.f - l) * __builtin_amdgcn_rcpf(1.f + __expf(-x))); }
.LBB0_708:
	s_nop 0
	v_mul_f32_e32 v62, v52, v154
	v_mul_f32_e32 v63, v53, v155
	s_and_b64 vcc, exec, s[48:49]
	s_mov_b64 s[0:1], -1
	s_cbranch_vccnz .LBB0_712
	s_and_b64 vcc, exec, s[46:47]
	v_mov_b32_e32 v156, v62
	s_cbranch_vccnz .LBB0_711
	v_mul_f32_e32 v52, 0xbfb8aa3b, v62
	v_exp_f32_e32 v52, v52
	s_waitcnt vmcnt(0)
	v_sub_f32_e32 v53, 1.0, v56
	v_add_f32_e32 v52, 1.0, v52
	v_rcp_f32_e32 v52, v52
	s_nop 0
	v_fmac_f32_e32 v56, v52, v53
	v_cmp_gt_f32_e32 vcc, s35, v56
	s_nop 1
	v_cndmask_b32_e64 v52, 0, 32, vcc
	v_ldexp_f32 v52, v56, v52
	v_log_f32_e32 v52, v52
	s_nop 0
	v_mul_f32_e32 v53, 0x3f317217, v52
	v_fma_f32 v53, v52, s13, -v53
	v_fmac_f32_e32 v53, 0x3377d1cf, v52
	v_fmac_f32_e32 v53, 0x3f317217, v52
	v_cmp_lt_f32_e64 s[52:53], |v52|, s36
	s_nop 1
	v_cndmask_b32_e64 v52, v52, v53, s[52:53]
	v_cndmask_b32_e32 v53, 0, v214, vcc
	v_sub_f32_e32 v156, v52, v53

; __device__ __forceinline__ float silu_f(float v) { return v * __builtin_amdgcn_rcpf(1.f + __expf(-v)); }
;     __device__ __forceinline__ void operator()(const f32x4 (&acc)[2][2][4][2], const Unit& u, int wr, int wc, int fr, int fq, int ui, PG8_LAS unsigned char* lds) const {
;     ...
;                     f32x4 v[2] = {acc[ai][bj][m][0] * rs, acc[ai][bj][m][1] * rs};
;                     if (ksum) { csum[bj][0] += v[0]; csum[bj][1] += v[1]; }
; #pragma unroll
;                     for (int n = 0; n < 2; ++n) {
;                         f32x4 lbv = (f32x4){0.f, 0.f, 0.f, 0.f};
;                         if (act == 2) lbv = *(const f32x4*)(lb + (col0 - 1024) + bj * HALF + 4 * n);
; #pragma unroll
;                         for (int e = 0; e < 4; ++e) {
;                             float x = v[n][e];
;                             if (act == 1) x = silu_f(x);
;                             else if (act == 2) { const float l = lbv[e]; x = __logf(l + (1.f - l) * __builtin_amdgcn_rcpf(1.f + __expf(-x))); }
.LBB0_714:
	v_mov_b32_e32 v52, v154
	v_mov_b32_e32 v53, v154
	v_mul_f32_e32 v60, v54, v52
	v_mul_f32_e32 v61, v55, v53
	s_and_b64 vcc, exec, s[48:49]
	s_mov_b64 s[0:1], -1
	s_cbranch_vccnz .LBB0_726
	s_and_b64 vcc, exec, s[46:47]
	v_mov_b32_e32 v160, v63
	s_cbranch_vccnz .LBB0_717
	v_mul_f32_e32 v52, 0xbfb8aa3b, v63
	v_exp_f32_e32 v52, v52
	s_waitcnt vmcnt(0)
	v_sub_f32_e32 v53, 1.0, v57
	v_add_f32_e32 v52, 1.0, v52
	v_rcp_f32_e32 v52, v52
	s_nop 0
	v_fmac_f32_e32 v57, v52, v53
	v_cmp_gt_f32_e32 vcc, s35, v57
	s_nop 1
	v_cndmask_b32_e64 v52, 0, 32, vcc
	v_ldexp_f32 v52, v57, v52
	v_log_f32_e32 v52, v52
	s_nop 0
	v_mul_f32_e32 v53, 0x3f317217, v52
	v_fma_f32 v53, v52, s13, -v53
	v_fmac_f32_e32 v53, 0x3377d1cf, v52
	v_fmac_f32_e32 v53, 0x3f317217, v52
	v_cmp_lt_f32_e64 s[52:53], |v52|, s36
	s_nop 1
	v_cndmask_b32_e64 v52, v52, v53, s[52:53]
	v_cndmask_b32_e32 v53, 0, v214, vcc
	v_sub_f32_e32 v160, v52, v53

; __device__ __forceinline__ float silu_f(float v) { return v * __builtin_amdgcn_rcpf(1.f + __expf(-v)); }
;     __device__ __forceinline__ void operator()(const f32x4 (&acc)[2][2][4][2], const Unit& u, int wr, int wc, int fr, int fq, int ui, PG8_LAS unsigned char* lds) const {
;     ...
;                     f32x4 v[2] = {acc[ai][bj][m][0] * rs, acc[ai][bj][m][1] * rs};
;                     if (ksum) { csum[bj][0] += v[0]; csum[bj][1] += v[1]; }
; #pragma unroll
;                     for (int n = 0; n < 2; ++n) {
;                         f32x4 lbv = (f32x4){0.f, 0.f, 0.f, 0.f};
;                         if (act == 2) lbv = *(const f32x4*)(lb + (col0 - 1024) + bj * HALF + 4 * n);
; #pragma unroll
;                         for (int e = 0; e < 4; ++e) {
;                             float x = v[n][e];
;                             if (act == 1) x = silu_f(x);
;                             else if (act == 2) { const float l = lbv[e]; x = __logf(l + (1.f - l) * __builtin_amdgcn_rcpf(1.f + __expf(-x))); }
.LBB0_734:
	s_waitcnt vmcnt(0)
	v_mul_f32_e32 v58, v48, v154
	v_mul_f32_e32 v59, v49, v155
	s_and_b64 vcc, exec, s[48:49]
	s_mov_b64 s[0:1], -1
	s_cbranch_vccnz .LBB0_738
	s_and_b64 vcc, exec, s[46:47]
	v_mov_b32_e32 v48, v58
	s_cbranch_vccnz .LBB0_737
	v_mul_f32_e32 v48, 0xbfb8aa3b, v58
	v_exp_f32_e32 v48, v48
	v_sub_f32_e32 v49, 1.0, v52
	v_add_f32_e32 v48, 1.0, v48
	v_rcp_f32_e32 v48, v48
	s_nop 0
	v_fmac_f32_e32 v52, v48, v49
	v_cmp_gt_f32_e32 vcc, s35, v52
	s_nop 1
	v_cndmask_b32_e64 v48, 0, 32, vcc
	v_ldexp_f32 v48, v52, v48
	v_log_f32_e32 v48, v48
	s_nop 0
	v_mul_f32_e32 v49, 0x3f317217, v48
	v_fma_f32 v49, v48, s13, -v49
	v_fmac_f32_e32 v49, 0x3377d1cf, v48
	v_fmac_f32_e32 v49, 0x3f317217, v48
	v_cmp_lt_f32_e64 s[52:53], |v48|, s36
	s_nop 1
	v_cndmask_b32_e64 v48, v48, v49, s[52:53]
	v_cndmask_b32_e32 v49, 0, v214, vcc
	v_sub_f32_e32 v48, v48, v49

; __device__ __forceinline__ float silu_f(float v) { return v * __builtin_amdgcn_rcpf(1.f + __expf(-v)); }
;     __device__ __forceinline__ void operator()(const f32x4 (&acc)[2][2][4][2], const Unit& u, int wr, int wc, int fr, int fq, int ui, PG8_LAS unsigned char* lds) const {
;     ...
;                     f32x4 v[2] = {acc[ai][bj][m][0] * rs, acc[ai][bj][m][1] * rs};
;                     if (ksum) { csum[bj][0] += v[0]; csum[bj][1] += v[1]; }
; #pragma unroll
;                     for (int n = 0; n < 2; ++n) {
;                         f32x4 lbv = (f32x4){0.f, 0.f, 0.f, 0.f};
;                         if (act == 2) lbv = *(const f32x4*)(lb + (col0 - 1024) + bj * HALF + 4 * n);
; #pragma unroll
;                         for (int e = 0; e < 4; ++e) {
;                             float x = v[n][e];
;                             if (act == 1) x = silu_f(x);
;                             else if (act == 2) { const float l = lbv[e]; x = __logf(l + (1.f - l) * __builtin_amdgcn_rcpf(1.f + __expf(-x))); }
.LBB0_740:
	v_mov_b32_e32 v155, v154
	v_mul_f32_e32 v56, v50, v154
	v_mul_f32_e32 v57, v51, v155
	s_and_b64 vcc, exec, s[48:49]
	s_mov_b64 s[0:1], -1
	s_cbranch_vccnz .LBB0_752
	s_and_b64 vcc, exec, s[46:47]
	v_mov_b32_e32 v49, v59
	s_cbranch_vccnz .LBB0_743
	v_mul_f32_e32 v49, 0xbfb8aa3b, v59
	v_exp_f32_e32 v49, v49
	v_sub_f32_e32 v50, 1.0, v53
	v_add_f32_e32 v49, 1.0, v49
	v_rcp_f32_e32 v49, v49
	s_nop 0
	v_fmac_f32_e32 v53, v49, v50
	v_cmp_gt_f32_e32 vcc, s35, v53
	s_nop 1
	v_cndmask_b32_e64 v49, 0, 32, vcc
	v_ldexp_f32 v49, v53, v49
	v_log_f32_e32 v49, v49
	s_nop 0
	v_mul_f32_e32 v50, 0x3f317217, v49
	v_fma_f32 v50, v49, s13, -v50
	v_fmac_f32_e32 v50, 0x3377d1cf, v49
	v_fmac_f32_e32 v50, 0x3f317217, v49
	v_cmp_lt_f32_e64 s[52:53], |v49|, s36
	s_nop 1
	v_cndmask_b32_e64 v49, v49, v50, s[52:53]
	v_cndmask_b32_e32 v50, 0, v214, vcc
	v_sub_f32_e32 v49, v49, v50

; __device__ __forceinline__ float silu_f(float v) { return v * __builtin_amdgcn_rcpf(1.f + __expf(-v)); }
;     __device__ __forceinline__ void operator()(const f32x4 (&acc)[2][2][4][2], const Unit& u, int wr, int wc, int fr, int fq, int ui, PG8_LAS unsigned char* lds) const {
;     ...
;                         rs4[m] = __builtin_amdgcn_rsqf(ssq_row(ssq, row0 + ai * HALF + m * 16) * (1.0f / 1024.0f) + RMS_EPS) * sc;
;                         rs4[m + 1] = __builtin_amdgcn_rsqf(ssq_row(ssq, row0 + ai * HALF + (m + 1) * 16) * (1.0f / 1024.0f) + RMS_EPS) * sc;
;                     }
;                 }
;                 const int row = row0 + ai * HALF + m * 16;
;                 const float rs = rs4[m];
;                 bf16_t* rowp = O + (size_t)row * ldc + col0;
; #pragma unroll
;                 for (int bj = 0; bj < 2; ++bj) {
;                     f32x4 v[2] = {acc[ai][bj][m][0] * rs, acc[ai][bj][m][1] * rs};
;                     if (ksum) { csum[bj][0] += v[0]; csum[bj][1] += v[1]; }
; #pragma unroll
;                     for (int n = 0; n < 2; ++n) {
;                         f32x4 lbv = (f32x4){0.f, 0.f, 0.f, 0.f};
;                         if (act == 2) lbv = *(const f32x4*)(lb + (col0 - 1024) + bj * HALF + 4 * n);
; #pragma unroll
;                         for (int e = 0; e < 4; ++e) {
;                             float x = v[n][e];
;                             if (act == 1) x = silu_f(x);
;                             else if (act == 2) { const float l = lbv[e]; x = __logf(l + (1.f - l) * __builtin_amdgcn_rcpf(1.f + __expf(-x))); }
.LBB0_760:
	v_mul_f32_e32 v154, v169, v157
	v_mul_f32_e32 v54, v44, v154
	v_mul_f32_e32 v55, v45, v154
	s_and_b64 vcc, exec, s[48:49]
	s_mov_b64 s[0:1], -1
	s_cbranch_vccnz .LBB0_764
	s_and_b64 vcc, exec, s[46:47]
	v_mov_b32_e32 v158, v54
	s_cbranch_vccnz .LBB0_763
	v_mul_f32_e32 v44, 0xbfb8aa3b, v54
	v_exp_f32_e32 v44, v44
	s_waitcnt vmcnt(0)
	v_sub_f32_e32 v45, 1.0, v48
	v_add_f32_e32 v44, 1.0, v44
	v_rcp_f32_e32 v44, v44
	s_nop 0
	v_fmac_f32_e32 v48, v44, v45
	v_cmp_gt_f32_e32 vcc, s35, v48
	s_nop 1
	v_cndmask_b32_e64 v44, 0, 32, vcc
	v_ldexp_f32 v44, v48, v44
	v_log_f32_e32 v44, v44
	s_nop 0
	v_mul_f32_e32 v45, 0x3f317217, v44
	v_fma_f32 v45, v44, s13, -v45
	v_fmac_f32_e32 v45, 0x3377d1cf, v44
	v_fmac_f32_e32 v45, 0x3f317217, v44
	v_cmp_lt_f32_e64 s[52:53], |v44|, s36
	s_nop 1
	v_cndmask_b32_e64 v44, v44, v45, s[52:53]
	v_cndmask_b32_e32 v45, 0, v214, vcc
	v_sub_f32_e32 v158, v44, v45

; __device__ __forceinline__ float silu_f(float v) { return v * __builtin_amdgcn_rcpf(1.f + __expf(-v)); }
;     __device__ __forceinline__ void operator()(const f32x4 (&acc)[2][2][4][2], const Unit& u, int wr, int wc, int fr, int fq, int ui, PG8_LAS unsigned char* lds) const {
;     ...
;                     f32x4 v[2] = {acc[ai][bj][m][0] * rs, acc[ai][bj][m][1] * rs};
;                     if (ksum) { csum[bj][0] += v[0]; csum[bj][1] += v[1]; }
; #pragma unroll
;                     for (int n = 0; n < 2; ++n) {
;                         f32x4 lbv = (f32x4){0.f, 0.f, 0.f, 0.f};
;                         if (act == 2) lbv = *(const f32x4*)(lb + (col0 - 1024) + bj * HALF + 4 * n);
; #pragma unroll
;                         for (int e = 0; e < 4; ++e) {
;                             float x = v[n][e];
;                             if (act == 1) x = silu_f(x);
;                             else if (act == 2) { const float l = lbv[e]; x = __logf(l + (1.f - l) * __builtin_amdgcn_rcpf(1.f + __expf(-x))); }
.LBB0_766:
	v_mul_f32_e32 v52, v46, v154
	v_mul_f32_e32 v53, v47, v154
	s_and_b64 vcc, exec, s[48:49]
	s_mov_b64 s[0:1], -1
	s_cbranch_vccnz .LBB0_778
	s_and_b64 vcc, exec, s[46:47]
	v_mov_b32_e32 v159, v55
	s_cbranch_vccnz .LBB0_769
	v_mul_f32_e32 v44, 0xbfb8aa3b, v55
	v_exp_f32_e32 v44, v44
	s_waitcnt vmcnt(0)
	v_sub_f32_e32 v45, 1.0, v49
	v_add_f32_e32 v44, 1.0, v44
	v_rcp_f32_e32 v44, v44
	s_nop 0
	v_fmac_f32_e32 v49, v44, v45
	v_cmp_gt_f32_e32 vcc, s35, v49
	s_nop 1
	v_cndmask_b32_e64 v44, 0, 32, vcc
	v_ldexp_f32 v44, v49, v44
	v_log_f32_e32 v44, v44
	s_nop 0
	v_mul_f32_e32 v45, 0x3f317217, v44
	v_fma_f32 v45, v44, s13, -v45
	v_fmac_f32_e32 v45, 0x3377d1cf, v44
	v_fmac_f32_e32 v45, 0x3f317217, v44
	v_cmp_lt_f32_e64 s[52:53], |v44|, s36
	s_nop 1
	v_cndmask_b32_e64 v44, v44, v45, s[52:53]
	v_cndmask_b32_e32 v45, 0, v214, vcc
	v_sub_f32_e32 v159, v44, v45

; __device__ __forceinline__ float silu_f(float v) { return v * __builtin_amdgcn_rcpf(1.f + __expf(-v)); }
;     __device__ __forceinline__ void operator()(const f32x4 (&acc)[2][2][4][2], const Unit& u, int wr, int wc, int fr, int fq, int ui, PG8_LAS unsigned char* lds) const {
;     ...
;                     f32x4 v[2] = {acc[ai][bj][m][0] * rs, acc[ai][bj][m][1] * rs};
;                     if (ksum) { csum[bj][0] += v[0]; csum[bj][1] += v[1]; }
; #pragma unroll
;                     for (int n = 0; n < 2; ++n) {
;                         f32x4 lbv = (f32x4){0.f, 0.f, 0.f, 0.f};
;                         if (act == 2) lbv = *(const f32x4*)(lb + (col0 - 1024) + bj * HALF + 4 * n);
; #pragma unroll
;                         for (int e = 0; e < 4; ++e) {
;                             float x = v[n][e];
;                             if (act == 1) x = silu_f(x);
;                             else if (act == 2) { const float l = lbv[e]; x = __logf(l + (1.f - l) * __builtin_amdgcn_rcpf(1.f + __expf(-x))); }
.LBB0_786:
	v_mov_b32_e32 v155, v154
	s_waitcnt vmcnt(0)
	v_mul_f32_e32 v50, v40, v154
	v_mul_f32_e32 v51, v41, v155
	s_and_b64 vcc, exec, s[48:49]
	s_mov_b64 s[0:1], -1
	s_cbranch_vccnz .LBB0_790
	s_and_b64 vcc, exec, s[46:47]
	v_mov_b32_e32 v40, v50
	s_cbranch_vccnz .LBB0_789
	v_mul_f32_e32 v40, 0xbfb8aa3b, v50
	v_exp_f32_e32 v40, v40
	v_sub_f32_e32 v41, 1.0, v44
	v_add_f32_e32 v40, 1.0, v40
	v_rcp_f32_e32 v40, v40
	s_nop 0
	v_fmac_f32_e32 v44, v40, v41
	v_cmp_gt_f32_e32 vcc, s35, v44
	s_nop 1
	v_cndmask_b32_e64 v40, 0, 32, vcc
	v_ldexp_f32 v40, v44, v40
	v_log_f32_e32 v40, v40
	s_nop 0
	v_mul_f32_e32 v41, 0x3f317217, v40
	v_fma_f32 v41, v40, s13, -v41
	v_fmac_f32_e32 v41, 0x3377d1cf, v40
	v_fmac_f32_e32 v41, 0x3f317217, v40
	v_cmp_lt_f32_e64 s[52:53], |v40|, s36
	s_nop 1
	v_cndmask_b32_e64 v40, v40, v41, s[52:53]
	v_cndmask_b32_e32 v41, 0, v214, vcc
	v_sub_f32_e32 v40, v40, v41

; __device__ __forceinline__ float silu_f(float v) { return v * __builtin_amdgcn_rcpf(1.f + __expf(-v)); }
;     __device__ __forceinline__ void operator()(const f32x4 (&acc)[2][2][4][2], const Unit& u, int wr, int wc, int fr, int fq, int ui, PG8_LAS unsigned char* lds) const {
;     ...
;                     f32x4 v[2] = {acc[ai][bj][m][0] * rs, acc[ai][bj][m][1] * rs};
;                     if (ksum) { csum[bj][0] += v[0]; csum[bj][1] += v[1]; }
; #pragma unroll
;                     for (int n = 0; n < 2; ++n) {
;                         f32x4 lbv = (f32x4){0.f, 0.f, 0.f, 0.f};
;                         if (act == 2) lbv = *(const f32x4*)(lb + (col0 - 1024) + bj * HALF + 4 * n);
; #pragma unroll
;                         for (int e = 0; e < 4; ++e) {
;                             float x = v[n][e];
;                             if (act == 1) x = silu_f(x);
;                             else if (act == 2) { const float l = lbv[e]; x = __logf(l + (1.f - l) * __builtin_amdgcn_rcpf(1.f + __expf(-x))); }
.LBB0_792:
	v_mov_b32_e32 v48, v154
	v_mov_b32_e32 v49, v154
	v_mul_f32_e32 v48, v42, v48
	v_mul_f32_e32 v49, v43, v49
	s_and_b64 vcc, exec, s[48:49]
	s_mov_b64 s[0:1], -1
	s_cbranch_vccnz .LBB0_804
	s_and_b64 vcc, exec, s[46:47]
	v_mov_b32_e32 v41, v51
	s_cbranch_vccnz .LBB0_795
	v_mul_f32_e32 v41, 0xbfb8aa3b, v51
	v_exp_f32_e32 v41, v41
	v_sub_f32_e32 v42, 1.0, v45
	v_add_f32_e32 v41, 1.0, v41
	v_rcp_f32_e32 v41, v41
	s_nop 0
	v_fmac_f32_e32 v45, v41, v42
	v_cmp_gt_f32_e32 vcc, s35, v45
	s_nop 1
	v_cndmask_b32_e64 v41, 0, 32, vcc
	v_ldexp_f32 v41, v45, v41
	v_log_f32_e32 v41, v41
	s_nop 0
	v_mul_f32_e32 v42, 0x3f317217, v41
	v_fma_f32 v42, v41, s13, -v42
	v_fmac_f32_e32 v42, 0x3377d1cf, v41
	v_fmac_f32_e32 v42, 0x3f317217, v41
	v_cmp_lt_f32_e64 s[52:53], |v41|, s36
	s_nop 1
	v_cndmask_b32_e64 v41, v41, v42, s[52:53]
	v_cndmask_b32_e32 v42, 0, v214, vcc
	v_sub_f32_e32 v41, v41, v42

; __device__ __forceinline__ float silu_f(float v) { return v * __builtin_amdgcn_rcpf(1.f + __expf(-v)); }
;     __device__ __forceinline__ void operator()(const f32x4 (&acc)[2][2][4][2], const Unit& u, int wr, int wc, int fr, int fq, int ui, PG8_LAS unsigned char* lds) const {
;     ...
;                     f32x4 v[2] = {acc[ai][bj][m][0] * rs, acc[ai][bj][m][1] * rs};
;                     if (ksum) { csum[bj][0] += v[0]; csum[bj][1] += v[1]; }
; #pragma unroll
;                     for (int n = 0; n < 2; ++n) {
;                         f32x4 lbv = (f32x4){0.f, 0.f, 0.f, 0.f};
;                         if (act == 2) lbv = *(const f32x4*)(lb + (col0 - 1024) + bj * HALF + 4 * n);
; #pragma unroll
;                         for (int e = 0; e < 4; ++e) {
;                             float x = v[n][e];
;                             if (act == 1) x = silu_f(x);
;                             else if (act == 2) { const float l = lbv[e]; x = __logf(l + (1.f - l) * __builtin_amdgcn_rcpf(1.f + __expf(-x))); }
.LBB0_812:
	s_nop 0
	v_mul_f32_e32 v46, v36, v154
	v_mul_f32_e32 v47, v37, v155
	s_and_b64 vcc, exec, s[48:49]
	s_mov_b64 s[0:1], -1
	s_cbranch_vccnz .LBB0_816
	s_and_b64 vcc, exec, s[46:47]
	v_mov_b32_e32 v158, v46
	s_cbranch_vccnz .LBB0_815
	v_mul_f32_e32 v36, 0xbfb8aa3b, v46
	v_exp_f32_e32 v36, v36
	s_waitcnt vmcnt(0)
	v_sub_f32_e32 v37, 1.0, v40
	v_add_f32_e32 v36, 1.0, v36
	v_rcp_f32_e32 v36, v36
	s_nop 0
	v_fmac_f32_e32 v40, v36, v37
	v_cmp_gt_f32_e32 vcc, s35, v40
	s_nop 1
	v_cndmask_b32_e64 v36, 0, 32, vcc
	v_ldexp_f32 v36, v40, v36
	v_log_f32_e32 v36, v36
	s_nop 0
	v_mul_f32_e32 v37, 0x3f317217, v36
	v_fma_f32 v37, v36, s13, -v37
	v_fmac_f32_e32 v37, 0x3377d1cf, v36
	v_fmac_f32_e32 v37, 0x3f317217, v36
	v_cmp_lt_f32_e64 s[52:53], |v36|, s36
	s_nop 1
	v_cndmask_b32_e64 v36, v36, v37, s[52:53]
	v_cndmask_b32_e32 v37, 0, v214, vcc
	v_sub_f32_e32 v158, v36, v37

; __device__ __forceinline__ float silu_f(float v) { return v * __builtin_amdgcn_rcpf(1.f + __expf(-v)); }
;     __device__ __forceinline__ void operator()(const f32x4 (&acc)[2][2][4][2], const Unit& u, int wr, int wc, int fr, int fq, int ui, PG8_LAS unsigned char* lds) const {
;     ...
;                     f32x4 v[2] = {acc[ai][bj][m][0] * rs, acc[ai][bj][m][1] * rs};
;                     if (ksum) { csum[bj][0] += v[0]; csum[bj][1] += v[1]; }
; #pragma unroll
;                     for (int n = 0; n < 2; ++n) {
;                         f32x4 lbv = (f32x4){0.f, 0.f, 0.f, 0.f};
;                         if (act == 2) lbv = *(const f32x4*)(lb + (col0 - 1024) + bj * HALF + 4 * n);
; #pragma unroll
;                         for (int e = 0; e < 4; ++e) {
;                             float x = v[n][e];
;                             if (act == 1) x = silu_f(x);
;                             else if (act == 2) { const float l = lbv[e]; x = __logf(l + (1.f - l) * __builtin_amdgcn_rcpf(1.f + __expf(-x))); }
.LBB0_818:
	v_mov_b32_e32 v36, v154
	v_mov_b32_e32 v37, v154
	v_mul_f32_e32 v44, v38, v36
	v_mul_f32_e32 v45, v39, v37
	s_and_b64 vcc, exec, s[48:49]
	s_mov_b64 s[0:1], -1
	s_cbranch_vccnz .LBB0_830
	s_and_b64 vcc, exec, s[46:47]
	v_mov_b32_e32 v159, v47
	s_cbranch_vccnz .LBB0_821
	v_mul_f32_e32 v36, 0xbfb8aa3b, v47
	v_exp_f32_e32 v36, v36
	s_waitcnt vmcnt(0)
	v_sub_f32_e32 v37, 1.0, v41
	v_add_f32_e32 v36, 1.0, v36
	v_rcp_f32_e32 v36, v36
	s_nop 0
	v_fmac_f32_e32 v41, v36, v37
	v_cmp_gt_f32_e32 vcc, s35, v41
	s_nop 1
	v_cndmask_b32_e64 v36, 0, 32, vcc
	v_ldexp_f32 v36, v41, v36
	v_log_f32_e32 v36, v36
	s_nop 0
	v_mul_f32_e32 v37, 0x3f317217, v36
	v_fma_f32 v37, v36, s13, -v37
	v_fmac_f32_e32 v37, 0x3377d1cf, v36
	v_fmac_f32_e32 v37, 0x3f317217, v36
	v_cmp_lt_f32_e64 s[52:53], |v36|, s36
	s_nop 1
	v_cndmask_b32_e64 v36, v36, v37, s[52:53]
	v_cndmask_b32_e32 v37, 0, v214, vcc
	v_sub_f32_e32 v159, v36, v37

; __device__ __forceinline__ float silu_f(float v) { return v * __builtin_amdgcn_rcpf(1.f + __expf(-v)); }
;     __device__ __forceinline__ void operator()(const f32x4 (&acc)[2][2][4][2], const Unit& u, int wr, int wc, int fr, int fq, int ui, PG8_LAS unsigned char* lds) const {
;     ...
;                     f32x4 v[2] = {acc[ai][bj][m][0] * rs, acc[ai][bj][m][1] * rs};
;                     if (ksum) { csum[bj][0] += v[0]; csum[bj][1] += v[1]; }
; #pragma unroll
;                     for (int n = 0; n < 2; ++n) {
;                         f32x4 lbv = (f32x4){0.f, 0.f, 0.f, 0.f};
;                         if (act == 2) lbv = *(const f32x4*)(lb + (col0 - 1024) + bj * HALF + 4 * n);
; #pragma unroll
;                         for (int e = 0; e < 4; ++e) {
;                             float x = v[n][e];
;                             if (act == 1) x = silu_f(x);
;                             else if (act == 2) { const float l = lbv[e]; x = __logf(l + (1.f - l) * __builtin_amdgcn_rcpf(1.f + __expf(-x))); }
.LBB0_838:
	s_waitcnt vmcnt(0)
	v_mul_f32_e32 v42, v32, v154
	v_mul_f32_e32 v43, v33, v155
	s_and_b64 vcc, exec, s[48:49]
	s_mov_b64 s[0:1], -1
	s_cbranch_vccnz .LBB0_842
	s_and_b64 vcc, exec, s[46:47]
	v_mov_b32_e32 v32, v42
	s_cbranch_vccnz .LBB0_841
	v_mul_f32_e32 v32, 0xbfb8aa3b, v42
	v_exp_f32_e32 v32, v32
	v_sub_f32_e32 v33, 1.0, v36
	v_add_f32_e32 v32, 1.0, v32
	v_rcp_f32_e32 v32, v32
	s_nop 0
	v_fmac_f32_e32 v36, v32, v33
	v_cmp_gt_f32_e32 vcc, s35, v36
	s_nop 1
	v_cndmask_b32_e64 v32, 0, 32, vcc
	v_ldexp_f32 v32, v36, v32
	v_log_f32_e32 v32, v32
	s_nop 0
	v_mul_f32_e32 v33, 0x3f317217, v32
	v_fma_f32 v33, v32, s13, -v33
	v_fmac_f32_e32 v33, 0x3377d1cf, v32
	v_fmac_f32_e32 v33, 0x3f317217, v32
	v_cmp_lt_f32_e64 s[52:53], |v32|, s36
	s_nop 1
	v_cndmask_b32_e64 v32, v32, v33, s[52:53]
	v_cndmask_b32_e32 v33, 0, v214, vcc
	v_sub_f32_e32 v32, v32, v33

; __device__ __forceinline__ float silu_f(float v) { return v * __builtin_amdgcn_rcpf(1.f + __expf(-v)); }
;     __device__ __forceinline__ void operator()(const f32x4 (&acc)[2][2][4][2], const Unit& u, int wr, int wc, int fr, int fq, int ui, PG8_LAS unsigned char* lds) const {
;     ...
;                     f32x4 v[2] = {acc[ai][bj][m][0] * rs, acc[ai][bj][m][1] * rs};
;                     if (ksum) { csum[bj][0] += v[0]; csum[bj][1] += v[1]; }
; #pragma unroll
;                     for (int n = 0; n < 2; ++n) {
;                         f32x4 lbv = (f32x4){0.f, 0.f, 0.f, 0.f};
;                         if (act == 2) lbv = *(const f32x4*)(lb + (col0 - 1024) + bj * HALF + 4 * n);
; #pragma unroll
;                         for (int e = 0; e < 4; ++e) {
;                             float x = v[n][e];
;                             if (act == 1) x = silu_f(x);
;                             else if (act == 2) { const float l = lbv[e]; x = __logf(l + (1.f - l) * __builtin_amdgcn_rcpf(1.f + __expf(-x))); }
.LBB0_844:
	v_mov_b32_e32 v155, v154
	v_mul_f32_e32 v40, v34, v154
	v_mul_f32_e32 v41, v35, v155
	s_and_b64 vcc, exec, s[48:49]
	s_mov_b64 s[0:1], -1
	s_cbranch_vccnz .LBB0_856
	s_and_b64 vcc, exec, s[46:47]
	v_mov_b32_e32 v33, v43
	s_cbranch_vccnz .LBB0_847
	v_mul_f32_e32 v33, 0xbfb8aa3b, v43
	v_exp_f32_e32 v33, v33
	v_sub_f32_e32 v34, 1.0, v37
	v_add_f32_e32 v33, 1.0, v33
	v_rcp_f32_e32 v33, v33
	s_nop 0
	v_fmac_f32_e32 v37, v33, v34
	v_cmp_gt_f32_e32 vcc, s35, v37
	s_nop 1
	v_cndmask_b32_e64 v33, 0, 32, vcc
	v_ldexp_f32 v33, v37, v33
	v_log_f32_e32 v33, v33
	s_nop 0
	v_mul_f32_e32 v34, 0x3f317217, v33
	v_fma_f32 v34, v33, s13, -v34
	v_fmac_f32_e32 v34, 0x3377d1cf, v33
	v_fmac_f32_e32 v34, 0x3f317217, v33
	v_cmp_lt_f32_e64 s[52:53], |v33|, s36
	s_nop 1
	v_cndmask_b32_e64 v33, v33, v34, s[52:53]
	v_cndmask_b32_e32 v34, 0, v214, vcc
	v_sub_f32_e32 v33, v33, v34

; __device__ __forceinline__ float ssq_row(const float* part, int row) {
;     const f32x4* p = (const f32x4*)(part + (size_t)row * 16);
;     const f32x4 a = p[0], b = p[1], c = p[2], d = p[3];
;     return (((a[0] + a[1]) + (a[2] + a[3])) + ((b[0] + b[1]) + (b[2] + b[3]))) + (((c[0] + c[1]) + (c[2] + c[3])) + ((d[0] + d[1]) + (d[2] + d[3])));
; }
;     __device__ __forceinline__ void operator()(const f32x4 (&acc)[2][2][4][2], const Unit& u, int wr, int wc, int fr, int fq, int ui, PG8_LAS unsigned char* lds) const {
;     ...
;                     if (use_tab) { rs4[m] = tab[ai * HALF + m * 16] * sc; rs4[m + 1] = tab[ai * HALF + (m + 1) * 16] * sc; }
;                     else {
;                         asm volatile("" ::: "memory");
;                         rs4[m] = __builtin_amdgcn_rsqf(ssq_row(ssq, row0 + ai * HALF + m * 16) * (1.0f / 1024.0f) + RMS_EPS) * sc;
;                         rs4[m + 1] = __builtin_amdgcn_rsqf(ssq_row(ssq, row0 + ai * HALF + (m + 1) * 16) * (1.0f / 1024.0f) + RMS_EPS) * sc;
.LBB0_864:
	s_andn2_b64 vcc, exec, s[0:1]
	s_cbranch_vccnz .LBB0_866
	v_lshlrev_b64 v[32:33], 6, v[158:159]
	v_lshl_add_u64 v[160:161], s[24:25], 0, v[32:33]
	global_load_dwordx4 v[32:35], v[160:161], off offset:16
	global_load_dwordx4 v[36:39], v[160:161], off offset:48
	global_load_dwordx4 v[154:157], v[160:161], off
	s_nop 0
	global_load_dwordx4 v[160:163], v[160:161], off offset:32
	s_mov_b64 s[0:1], 0x2c00
	s_waitcnt vmcnt(1)
	v_mov_b32_e32 v170, v154
	s_waitcnt vmcnt(0)
	v_mov_b32_e32 v171, v160
	v_mov_b32_e32 v160, v155
	v_add_f32_e32 v154, v170, v160
	v_add_f32_e32 v155, v171, v161
	v_mov_b32_e32 v160, v156
	v_mov_b32_e32 v161, v162
	v_mov_b32_e32 v162, v157
	v_add_f32_e32 v156, v160, v162
	v_add_f32_e32 v157, v161, v163
	s_nop 0
	v_add_f32_e32 v154, v154, v156
	v_add_f32_e32 v155, v155, v157
	v_mov_b32_e32 v156, v32
	v_mov_b32_e32 v157, v36
	v_mov_b32_e32 v36, v33
	v_add_f32_e32 v32, v156, v36
	v_add_f32_e32 v33, v157, v37
	v_mov_b32_e32 v36, v34
	v_mov_b32_e32 v37, v38
	v_mov_b32_e32 v38, v35
	v_add_f32_e32 v34, v36, v38
	v_add_f32_e32 v35, v37, v39
	s_nop 0
	v_add_f32_e32 v32, v32, v34
	v_add_f32_e32 v33, v33, v35
	s_nop 0
	v_add_f32_e32 v32, v154, v32
	v_add_f32_e32 v33, v155, v33
	s_nop 0
	v_add_f32_e32 v32, v32, v33
	v_fmamk_f32 v32, v32, 0x3a800000, v211
	v_rsq_f32_e32 v32, v32
	s_nop 0
	v_mul_f32_e32 v34, v169, v32
	v_lshlrev_b64 v[32:33], 6, v[150:151]
	v_lshl_add_u64 v[32:33], s[24:25], 0, v[32:33]
	v_lshl_add_u64 v[170:171], v[32:33], 0, s[0:1]
	v_add_co_u32_e32 v32, vcc, s23, v32
	s_nop 1
	v_addc_co_u32_e32 v33, vcc, 0, v33, vcc
	global_load_dwordx4 v[36:39], v[32:33], off offset:3072
	global_load_dwordx4 v[154:157], v[170:171], off offset:16
	global_load_dwordx4 v[160:163], v[170:171], off offset:48
	s_nop 0
	global_load_dwordx4 v[170:173], v[170:171], off offset:32
	s_waitcnt vmcnt(3)
	v_mov_b32_e32 v32, v36
	v_mov_b32_e32 v36, v38
	s_waitcnt vmcnt(2)
	v_mov_b32_e32 v38, v156
	s_waitcnt vmcnt(0)
	v_mov_b32_e32 v33, v170
	v_mov_b32_e32 v170, v37
	v_mov_b32_e32 v37, v172
	v_mov_b32_e32 v172, v39
	v_add_f32_e32 v32, v32, v170
	v_add_f32_e32 v33, v33, v171
	v_add_f32_e32 v36, v36, v172
	v_add_f32_e32 v37, v37, v173
	v_mov_b32_e32 v39, v162
	v_add_f32_e32 v32, v32, v36
	v_add_f32_e32 v33, v33, v37
	v_mov_b32_e32 v36, v154
	v_mov_b32_e32 v37, v160
	v_mov_b32_e32 v160, v155
	v_mov_b32_e32 v162, v157
	v_add_f32_e32 v36, v36, v160
	v_add_f32_e32 v37, v37, v161
	v_add_f32_e32 v38, v38, v162
	v_add_f32_e32 v39, v39, v163
	s_nop 0
	v_add_f32_e32 v36, v36, v38
	v_add_f32_e32 v37, v37, v39
	s_nop 0
	v_add_f32_e32 v32, v32, v36
	v_add_f32_e32 v33, v33, v37
	s_nop 0
	v_add_f32_e32 v32, v32, v33
	v_fmamk_f32 v32, v32, 0x3a800000, v211
	v_rsq_f32_e32 v157, v32

; __device__ __forceinline__ float silu_f(float v) { return v * __builtin_amdgcn_rcpf(1.f + __expf(-v)); }
;     __device__ __forceinline__ void operator()(const f32x4 (&acc)[2][2][4][2], const Unit& u, int wr, int wc, int fr, int fq, int ui, PG8_LAS unsigned char* lds) const {
;     ...
;                     f32x4 v[2] = {acc[ai][bj][m][0] * rs, acc[ai][bj][m][1] * rs};
;                     if (ksum) { csum[bj][0] += v[0]; csum[bj][1] += v[1]; }
; #pragma unroll
;                     for (int n = 0; n < 2; ++n) {
;                         f32x4 lbv = (f32x4){0.f, 0.f, 0.f, 0.f};
;                         if (act == 2) lbv = *(const f32x4*)(lb + (col0 - 1024) + bj * HALF + 4 * n);
; #pragma unroll
;                         for (int e = 0; e < 4; ++e) {
;                             float x = v[n][e];
;                             if (act == 1) x = silu_f(x);
;                             else if (act == 2) { const float l = lbv[e]; x = __logf(l + (1.f - l) * __builtin_amdgcn_rcpf(1.f + __expf(-x))); }
.LBB0_868:
	v_mul_f32_e32 v154, v28, v34
	v_mul_f32_e32 v155, v29, v34
	s_and_b64 vcc, exec, s[48:49]
	s_mov_b64 s[0:1], -1
	s_cbranch_vccnz .LBB0_872
	s_and_b64 vcc, exec, s[46:47]
	v_mov_b32_e32 v151, v154
	s_cbranch_vccnz .LBB0_871
	v_mul_f32_e32 v28, 0xbfb8aa3b, v154
	v_exp_f32_e32 v28, v28
	s_waitcnt vmcnt(0)
	v_sub_f32_e32 v29, 1.0, v36
	v_add_f32_e32 v28, 1.0, v28
	v_rcp_f32_e32 v28, v28
	s_nop 0
	v_fmac_f32_e32 v36, v28, v29
	v_cmp_gt_f32_e32 vcc, s35, v36
	s_nop 1
	v_cndmask_b32_e64 v28, 0, 32, vcc
	v_ldexp_f32 v28, v36, v28
	v_log_f32_e32 v28, v28
	s_nop 0
	v_mul_f32_e32 v29, 0x3f317217, v28
	v_fma_f32 v29, v28, s13, -v29
	v_fmac_f32_e32 v29, 0x3377d1cf, v28
	v_fmac_f32_e32 v29, 0x3f317217, v28
	v_cmp_lt_f32_e64 s[50:51], |v28|, s36
	s_nop 1
	v_cndmask_b32_e64 v28, v28, v29, s[50:51]
	v_cndmask_b32_e32 v29, 0, v214, vcc
	v_sub_f32_e32 v151, v28, v29

; __device__ __forceinline__ float silu_f(float v) { return v * __builtin_amdgcn_rcpf(1.f + __expf(-v)); }
;     __device__ __forceinline__ void operator()(const f32x4 (&acc)[2][2][4][2], const Unit& u, int wr, int wc, int fr, int fq, int ui, PG8_LAS unsigned char* lds) const {
;     ...
;                     f32x4 v[2] = {acc[ai][bj][m][0] * rs, acc[ai][bj][m][1] * rs};
;                     if (ksum) { csum[bj][0] += v[0]; csum[bj][1] += v[1]; }
; #pragma unroll
;                     for (int n = 0; n < 2; ++n) {
;                         f32x4 lbv = (f32x4){0.f, 0.f, 0.f, 0.f};
;                         if (act == 2) lbv = *(const f32x4*)(lb + (col0 - 1024) + bj * HALF + 4 * n);
; #pragma unroll
;                         for (int e = 0; e < 4; ++e) {
;                             float x = v[n][e];
;                             if (act == 1) x = silu_f(x);
;                             else if (act == 2) { const float l = lbv[e]; x = __logf(l + (1.f - l) * __builtin_amdgcn_rcpf(1.f + __expf(-x))); }
.LBB0_874:
	v_mul_f32_e32 v32, v30, v34
	v_mul_f32_e32 v33, v31, v34
	s_and_b64 vcc, exec, s[48:49]
	s_mov_b64 s[0:1], -1
	s_cbranch_vccnz .LBB0_886
	s_and_b64 vcc, exec, s[46:47]
	v_mov_b32_e32 v156, v155
	s_cbranch_vccnz .LBB0_877
	v_mul_f32_e32 v28, 0xbfb8aa3b, v155
	v_exp_f32_e32 v28, v28
	s_waitcnt vmcnt(0)
	v_sub_f32_e32 v29, 1.0, v37
	v_add_f32_e32 v28, 1.0, v28
	v_rcp_f32_e32 v28, v28
	s_nop 0
	v_fmac_f32_e32 v37, v28, v29
	v_cmp_gt_f32_e32 vcc, s35, v37
	s_nop 1
	v_cndmask_b32_e64 v28, 0, 32, vcc
	v_ldexp_f32 v28, v37, v28
	v_log_f32_e32 v28, v28
	s_nop 0
	v_mul_f32_e32 v29, 0x3f317217, v28
	v_fma_f32 v29, v28, s13, -v29
	v_fmac_f32_e32 v29, 0x3377d1cf, v28
	v_fmac_f32_e32 v29, 0x3f317217, v28
	v_cmp_lt_f32_e64 s[50:51], |v28|, s36
	s_nop 1
	v_cndmask_b32_e64 v28, v28, v29, s[50:51]
	v_cndmask_b32_e32 v29, 0, v214, vcc
	v_sub_f32_e32 v156, v28, v29

; __device__ __forceinline__ float silu_f(float v) { return v * __builtin_amdgcn_rcpf(1.f + __expf(-v)); }
;     __device__ __forceinline__ void operator()(const f32x4 (&acc)[2][2][4][2], const Unit& u, int wr, int wc, int fr, int fq, int ui, PG8_LAS unsigned char* lds) const {
;     ...
;                     f32x4 v[2] = {acc[ai][bj][m][0] * rs, acc[ai][bj][m][1] * rs};
;                     if (ksum) { csum[bj][0] += v[0]; csum[bj][1] += v[1]; }
; #pragma unroll
;                     for (int n = 0; n < 2; ++n) {
;                         f32x4 lbv = (f32x4){0.f, 0.f, 0.f, 0.f};
;                         if (act == 2) lbv = *(const f32x4*)(lb + (col0 - 1024) + bj * HALF + 4 * n);
; #pragma unroll
;                         for (int e = 0; e < 4; ++e) {
;                             float x = v[n][e];
;                             if (act == 1) x = silu_f(x);
;                             else if (act == 2) { const float l = lbv[e]; x = __logf(l + (1.f - l) * __builtin_amdgcn_rcpf(1.f + __expf(-x))); }
.LBB0_894:
	v_mov_b32_e32 v160, v34
	v_mov_b32_e32 v161, v34
	s_waitcnt vmcnt(0)
	v_mul_f32_e32 v38, v24, v160
	v_mul_f32_e32 v39, v25, v161
	s_and_b64 vcc, exec, s[48:49]
	s_mov_b64 s[0:1], -1
	s_cbranch_vccnz .LBB0_898
	s_and_b64 vcc, exec, s[46:47]
	v_mov_b32_e32 v24, v38
	s_cbranch_vccnz .LBB0_897
	v_mul_f32_e32 v24, 0xbfb8aa3b, v38
	v_exp_f32_e32 v24, v24
	v_sub_f32_e32 v25, 1.0, v28
	v_add_f32_e32 v24, 1.0, v24
	v_rcp_f32_e32 v24, v24
	s_nop 0
	v_fmac_f32_e32 v28, v24, v25
	v_cmp_gt_f32_e32 vcc, s35, v28
	s_nop 1
	v_cndmask_b32_e64 v24, 0, 32, vcc
	v_ldexp_f32 v24, v28, v24
	v_log_f32_e32 v24, v24
	s_nop 0
	v_mul_f32_e32 v25, 0x3f317217, v24
	v_fma_f32 v25, v24, s13, -v25
	v_fmac_f32_e32 v25, 0x3377d1cf, v24
	v_fmac_f32_e32 v25, 0x3f317217, v24
	v_cmp_lt_f32_e64 s[50:51], |v24|, s36
	s_nop 1
	v_cndmask_b32_e64 v24, v24, v25, s[50:51]
	v_cndmask_b32_e32 v25, 0, v214, vcc
	v_sub_f32_e32 v24, v24, v25

; __device__ __forceinline__ float silu_f(float v) { return v * __builtin_amdgcn_rcpf(1.f + __expf(-v)); }
;     __device__ __forceinline__ void operator()(const f32x4 (&acc)[2][2][4][2], const Unit& u, int wr, int wc, int fr, int fq, int ui, PG8_LAS unsigned char* lds) const {
;     ...
;                     f32x4 v[2] = {acc[ai][bj][m][0] * rs, acc[ai][bj][m][1] * rs};
;                     if (ksum) { csum[bj][0] += v[0]; csum[bj][1] += v[1]; }
; #pragma unroll
;                     for (int n = 0; n < 2; ++n) {
;                         f32x4 lbv = (f32x4){0.f, 0.f, 0.f, 0.f};
;                         if (act == 2) lbv = *(const f32x4*)(lb + (col0 - 1024) + bj * HALF + 4 * n);
; #pragma unroll
;                         for (int e = 0; e < 4; ++e) {
;                             float x = v[n][e];
;                             if (act == 1) x = silu_f(x);
;                             else if (act == 2) { const float l = lbv[e]; x = __logf(l + (1.f - l) * __builtin_amdgcn_rcpf(1.f + __expf(-x))); }
.LBB0_900:
	v_mov_b32_e32 v35, v34
	v_mul_f32_e32 v36, v26, v34
	v_mul_f32_e32 v37, v27, v35
	s_and_b64 vcc, exec, s[48:49]
	s_mov_b64 s[0:1], -1
	s_cbranch_vccnz .LBB0_912
	s_and_b64 vcc, exec, s[46:47]
	v_mov_b32_e32 v25, v39
	s_cbranch_vccnz .LBB0_903
	v_mul_f32_e32 v25, 0xbfb8aa3b, v39
	v_exp_f32_e32 v25, v25
	v_sub_f32_e32 v26, 1.0, v29
	v_add_f32_e32 v25, 1.0, v25
	v_rcp_f32_e32 v25, v25
	s_nop 0
	v_fmac_f32_e32 v29, v25, v26
	v_cmp_gt_f32_e32 vcc, s35, v29
	s_nop 1
	v_cndmask_b32_e64 v25, 0, 32, vcc
	v_ldexp_f32 v25, v29, v25
	v_log_f32_e32 v25, v25
	s_nop 0
	v_mul_f32_e32 v26, 0x3f317217, v25
	v_fma_f32 v26, v25, s13, -v26
	v_fmac_f32_e32 v26, 0x3377d1cf, v25
	v_fmac_f32_e32 v26, 0x3f317217, v25
	v_cmp_lt_f32_e64 s[50:51], |v25|, s36
	s_nop 1
	v_cndmask_b32_e64 v25, v25, v26, s[50:51]
	v_cndmask_b32_e32 v26, 0, v214, vcc
	v_sub_f32_e32 v25, v25, v26

; __device__ __forceinline__ float silu_f(float v) { return v * __builtin_amdgcn_rcpf(1.f + __expf(-v)); }
;     __device__ __forceinline__ void operator()(const f32x4 (&acc)[2][2][4][2], const Unit& u, int wr, int wc, int fr, int fq, int ui, PG8_LAS unsigned char* lds) const {
;     ...
;                     f32x4 v[2] = {acc[ai][bj][m][0] * rs, acc[ai][bj][m][1] * rs};
;                     if (ksum) { csum[bj][0] += v[0]; csum[bj][1] += v[1]; }
; #pragma unroll
;                     for (int n = 0; n < 2; ++n) {
;                         f32x4 lbv = (f32x4){0.f, 0.f, 0.f, 0.f};
;                         if (act == 2) lbv = *(const f32x4*)(lb + (col0 - 1024) + bj * HALF + 4 * n);
; #pragma unroll
;                         for (int e = 0; e < 4; ++e) {
;                             float x = v[n][e];
;                             if (act == 1) x = silu_f(x);
;                             else if (act == 2) { const float l = lbv[e]; x = __logf(l + (1.f - l) * __builtin_amdgcn_rcpf(1.f + __expf(-x))); }
.LBB0_920:
	s_nop 0
	v_mul_f32_e32 v30, v20, v160
	v_mul_f32_e32 v31, v21, v161
	s_and_b64 vcc, exec, s[48:49]
	s_mov_b64 s[0:1], -1
	s_cbranch_vccnz .LBB0_924
	s_and_b64 vcc, exec, s[46:47]
	v_mov_b32_e32 v151, v30
	s_cbranch_vccnz .LBB0_923
	v_mul_f32_e32 v20, 0xbfb8aa3b, v30
	v_exp_f32_e32 v20, v20
	s_waitcnt vmcnt(0)
	v_sub_f32_e32 v21, 1.0, v24
	v_add_f32_e32 v20, 1.0, v20
	v_rcp_f32_e32 v20, v20
	s_nop 0
	v_fmac_f32_e32 v24, v20, v21
	v_cmp_gt_f32_e32 vcc, s35, v24
	s_nop 1
	v_cndmask_b32_e64 v20, 0, 32, vcc
	v_ldexp_f32 v20, v24, v20
	v_log_f32_e32 v20, v20
	s_nop 0
	v_mul_f32_e32 v21, 0x3f317217, v20
	v_fma_f32 v21, v20, s13, -v21
	v_fmac_f32_e32 v21, 0x3377d1cf, v20
	v_fmac_f32_e32 v21, 0x3f317217, v20
	v_cmp_lt_f32_e64 s[50:51], |v20|, s36
	s_nop 1
	v_cndmask_b32_e64 v20, v20, v21, s[50:51]
	v_cndmask_b32_e32 v21, 0, v214, vcc
	v_sub_f32_e32 v151, v20, v21

; __device__ __forceinline__ float silu_f(float v) { return v * __builtin_amdgcn_rcpf(1.f + __expf(-v)); }
;     __device__ __forceinline__ void operator()(const f32x4 (&acc)[2][2][4][2], const Unit& u, int wr, int wc, int fr, int fq, int ui, PG8_LAS unsigned char* lds) const {
;     ...
;                     f32x4 v[2] = {acc[ai][bj][m][0] * rs, acc[ai][bj][m][1] * rs};
;                     if (ksum) { csum[bj][0] += v[0]; csum[bj][1] += v[1]; }
; #pragma unroll
;                     for (int n = 0; n < 2; ++n) {
;                         f32x4 lbv = (f32x4){0.f, 0.f, 0.f, 0.f};
;                         if (act == 2) lbv = *(const f32x4*)(lb + (col0 - 1024) + bj * HALF + 4 * n);
; #pragma unroll
;                         for (int e = 0; e < 4; ++e) {
;                             float x = v[n][e];
;                             if (act == 1) x = silu_f(x);
;                             else if (act == 2) { const float l = lbv[e]; x = __logf(l + (1.f - l) * __builtin_amdgcn_rcpf(1.f + __expf(-x))); }
.LBB0_926:
	v_mov_b32_e32 v35, v34
	v_mul_f32_e32 v28, v22, v34
	v_mul_f32_e32 v29, v23, v35
	s_and_b64 vcc, exec, s[48:49]
	s_mov_b64 s[0:1], -1
	s_cbranch_vccnz .LBB0_938
	s_and_b64 vcc, exec, s[46:47]
	v_mov_b32_e32 v156, v31
	s_cbranch_vccnz .LBB0_929
	v_mul_f32_e32 v20, 0xbfb8aa3b, v31
	v_exp_f32_e32 v20, v20
	s_waitcnt vmcnt(0)
	v_sub_f32_e32 v21, 1.0, v25
	v_add_f32_e32 v20, 1.0, v20
	v_rcp_f32_e32 v20, v20
	s_nop 0
	v_fmac_f32_e32 v25, v20, v21
	v_cmp_gt_f32_e32 vcc, s35, v25
	s_nop 1
	v_cndmask_b32_e64 v20, 0, 32, vcc
	v_ldexp_f32 v20, v25, v20
	v_log_f32_e32 v20, v20
	s_nop 0
	v_mul_f32_e32 v21, 0x3f317217, v20
	v_fma_f32 v21, v20, s13, -v21
	v_fmac_f32_e32 v21, 0x3377d1cf, v20
	v_fmac_f32_e32 v21, 0x3f317217, v20
	v_cmp_lt_f32_e64 s[50:51], |v20|, s36
	s_nop 1
	v_cndmask_b32_e64 v20, v20, v21, s[50:51]
	v_cndmask_b32_e32 v21, 0, v214, vcc
	v_sub_f32_e32 v156, v20, v21

; __device__ __forceinline__ float silu_f(float v) { return v * __builtin_amdgcn_rcpf(1.f + __expf(-v)); }
;     __device__ __forceinline__ void operator()(const f32x4 (&acc)[2][2][4][2], const Unit& u, int wr, int wc, int fr, int fq, int ui, PG8_LAS unsigned char* lds) const {
;     ...
;                     f32x4 v[2] = {acc[ai][bj][m][0] * rs, acc[ai][bj][m][1] * rs};
;                     if (ksum) { csum[bj][0] += v[0]; csum[bj][1] += v[1]; }
; #pragma unroll
;                     for (int n = 0; n < 2; ++n) {
;                         f32x4 lbv = (f32x4){0.f, 0.f, 0.f, 0.f};
;                         if (act == 2) lbv = *(const f32x4*)(lb + (col0 - 1024) + bj * HALF + 4 * n);
; #pragma unroll
;                         for (int e = 0; e < 4; ++e) {
;                             float x = v[n][e];
;                             if (act == 1) x = silu_f(x);
;                             else if (act == 2) { const float l = lbv[e]; x = __logf(l + (1.f - l) * __builtin_amdgcn_rcpf(1.f + __expf(-x))); }
.LBB0_946:
	s_waitcnt vmcnt(0)
	v_mul_f32_e32 v26, v16, v160
	v_mul_f32_e32 v27, v17, v161
	s_and_b64 vcc, exec, s[48:49]
	s_mov_b64 s[0:1], -1
	s_cbranch_vccnz .LBB0_950
	s_and_b64 vcc, exec, s[46:47]
	v_mov_b32_e32 v16, v26
	s_cbranch_vccnz .LBB0_949
	v_mul_f32_e32 v16, 0xbfb8aa3b, v26
	v_exp_f32_e32 v16, v16
	v_sub_f32_e32 v17, 1.0, v20
	v_add_f32_e32 v16, 1.0, v16
	v_rcp_f32_e32 v16, v16
	s_nop 0
	v_fmac_f32_e32 v20, v16, v17
	v_cmp_gt_f32_e32 vcc, s35, v20
	s_nop 1
	v_cndmask_b32_e64 v16, 0, 32, vcc
	v_ldexp_f32 v16, v20, v16
	v_log_f32_e32 v16, v16
	s_nop 0
	v_mul_f32_e32 v17, 0x3f317217, v16
	v_fma_f32 v17, v16, s13, -v17
	v_fmac_f32_e32 v17, 0x3377d1cf, v16
	v_fmac_f32_e32 v17, 0x3f317217, v16
	v_cmp_lt_f32_e64 s[50:51], |v16|, s36
	s_nop 1
	v_cndmask_b32_e64 v16, v16, v17, s[50:51]
	v_cndmask_b32_e32 v17, 0, v214, vcc
	v_sub_f32_e32 v16, v16, v17

; __device__ __forceinline__ float silu_f(float v) { return v * __builtin_amdgcn_rcpf(1.f + __expf(-v)); }
;     __device__ __forceinline__ void operator()(const f32x4 (&acc)[2][2][4][2], const Unit& u, int wr, int wc, int fr, int fq, int ui, PG8_LAS unsigned char* lds) const {
;     ...
;                     f32x4 v[2] = {acc[ai][bj][m][0] * rs, acc[ai][bj][m][1] * rs};
;                     if (ksum) { csum[bj][0] += v[0]; csum[bj][1] += v[1]; }
; #pragma unroll
;                     for (int n = 0; n < 2; ++n) {
;                         f32x4 lbv = (f32x4){0.f, 0.f, 0.f, 0.f};
;                         if (act == 2) lbv = *(const f32x4*)(lb + (col0 - 1024) + bj * HALF + 4 * n);
; #pragma unroll
;                         for (int e = 0; e < 4; ++e) {
;                             float x = v[n][e];
;                             if (act == 1) x = silu_f(x);
;                             else if (act == 2) { const float l = lbv[e]; x = __logf(l + (1.f - l) * __builtin_amdgcn_rcpf(1.f + __expf(-x))); }
.LBB0_952:
	v_mov_b32_e32 v35, v34
	v_mul_f32_e32 v24, v18, v34
	v_mul_f32_e32 v25, v19, v35
	s_and_b64 vcc, exec, s[48:49]
	s_mov_b64 s[0:1], -1
	s_cbranch_vccnz .LBB0_964
	s_and_b64 vcc, exec, s[46:47]
	v_mov_b32_e32 v17, v27
	s_cbranch_vccnz .LBB0_955
	v_mul_f32_e32 v17, 0xbfb8aa3b, v27
	v_exp_f32_e32 v17, v17
	v_sub_f32_e32 v18, 1.0, v21
	v_add_f32_e32 v17, 1.0, v17
	v_rcp_f32_e32 v17, v17
	s_nop 0
	v_fmac_f32_e32 v21, v17, v18
	v_cmp_gt_f32_e32 vcc, s35, v21
	s_nop 1
	v_cndmask_b32_e64 v17, 0, 32, vcc
	v_ldexp_f32 v17, v21, v17
	v_log_f32_e32 v17, v17
	s_nop 0
	v_mul_f32_e32 v18, 0x3f317217, v17
	v_fma_f32 v18, v17, s13, -v18
	v_fmac_f32_e32 v18, 0x3377d1cf, v17
	v_fmac_f32_e32 v18, 0x3f317217, v17
	v_cmp_lt_f32_e64 s[50:51], |v17|, s36
	s_nop 1
	v_cndmask_b32_e64 v17, v17, v18, s[50:51]
	v_cndmask_b32_e32 v18, 0, v214, vcc
	v_sub_f32_e32 v17, v17, v18

; __device__ __forceinline__ float silu_f(float v) { return v * __builtin_amdgcn_rcpf(1.f + __expf(-v)); }
;     __device__ __forceinline__ void operator()(const f32x4 (&acc)[2][2][4][2], const Unit& u, int wr, int wc, int fr, int fq, int ui, PG8_LAS unsigned char* lds) const {
;     ...
;                     if (use_tab) { rs4[m] = tab[ai * HALF + m * 16] * sc; rs4[m + 1] = tab[ai * HALF + (m + 1) * 16] * sc; }
;                     else {
;                         asm volatile("" ::: "memory");
;                         rs4[m] = __builtin_amdgcn_rsqf(ssq_row(ssq, row0 + ai * HALF + m * 16) * (1.0f / 1024.0f) + RMS_EPS) * sc;
;                         rs4[m + 1] = __builtin_amdgcn_rsqf(ssq_row(ssq, row0 + ai * HALF + (m + 1) * 16) * (1.0f / 1024.0f) + RMS_EPS) * sc;
;                     }
;                 }
;                 const int row = row0 + ai * HALF + m * 16;
;                 const float rs = rs4[m];
;                 bf16_t* rowp = O + (size_t)row * ldc + col0;
; #pragma unroll
;                 for (int bj = 0; bj < 2; ++bj) {
;                     f32x4 v[2] = {acc[ai][bj][m][0] * rs, acc[ai][bj][m][1] * rs};
;                     if (ksum) { csum[bj][0] += v[0]; csum[bj][1] += v[1]; }
; #pragma unroll
;                     for (int n = 0; n < 2; ++n) {
;                         f32x4 lbv = (f32x4){0.f, 0.f, 0.f, 0.f};
;                         if (act == 2) lbv = *(const f32x4*)(lb + (col0 - 1024) + bj * HALF + 4 * n);
; #pragma unroll
;                         for (int e = 0; e < 4; ++e) {
;                             float x = v[n][e];
;                             if (act == 1) x = silu_f(x);
;                             else if (act == 2) { const float l = lbv[e]; x = __logf(l + (1.f - l) * __builtin_amdgcn_rcpf(1.f + __expf(-x))); }
.LBB0_972:
	v_mul_f32_e32 v34, v169, v157
	v_mul_f32_e32 v22, v12, v34
	v_mul_f32_e32 v23, v13, v34
	s_and_b64 vcc, exec, s[48:49]
	s_mov_b64 s[0:1], -1
	s_cbranch_vccnz .LBB0_976
	s_and_b64 vcc, exec, s[46:47]
	v_mov_b32_e32 v156, v22
	s_cbranch_vccnz .LBB0_975
	v_mul_f32_e32 v12, 0xbfb8aa3b, v22
	v_exp_f32_e32 v12, v12
	s_waitcnt vmcnt(0)
	v_sub_f32_e32 v13, 1.0, v16
	v_add_f32_e32 v12, 1.0, v12
	v_rcp_f32_e32 v12, v12
	s_nop 0
	v_fmac_f32_e32 v16, v12, v13
	v_cmp_gt_f32_e32 vcc, s35, v16
	s_nop 1
	v_cndmask_b32_e64 v12, 0, 32, vcc
	v_ldexp_f32 v12, v16, v12
	v_log_f32_e32 v12, v12
	s_nop 0
	v_mul_f32_e32 v13, 0x3f317217, v12
	v_fma_f32 v13, v12, s13, -v13
	v_fmac_f32_e32 v13, 0x3377d1cf, v12
	v_fmac_f32_e32 v13, 0x3f317217, v12
	v_cmp_lt_f32_e64 s[50:51], |v12|, s36
	s_nop 1
	v_cndmask_b32_e64 v12, v12, v13, s[50:51]
	v_cndmask_b32_e32 v13, 0, v214, vcc
	v_sub_f32_e32 v156, v12, v13

; __device__ __forceinline__ float silu_f(float v) { return v * __builtin_amdgcn_rcpf(1.f + __expf(-v)); }
;     __device__ __forceinline__ void operator()(const f32x4 (&acc)[2][2][4][2], const Unit& u, int wr, int wc, int fr, int fq, int ui, PG8_LAS unsigned char* lds) const {
;     ...
;                     f32x4 v[2] = {acc[ai][bj][m][0] * rs, acc[ai][bj][m][1] * rs};
;                     if (ksum) { csum[bj][0] += v[0]; csum[bj][1] += v[1]; }
; #pragma unroll
;                     for (int n = 0; n < 2; ++n) {
;                         f32x4 lbv = (f32x4){0.f, 0.f, 0.f, 0.f};
;                         if (act == 2) lbv = *(const f32x4*)(lb + (col0 - 1024) + bj * HALF + 4 * n);
; #pragma unroll
;                         for (int e = 0; e < 4; ++e) {
;                             float x = v[n][e];
;                             if (act == 1) x = silu_f(x);
;                             else if (act == 2) { const float l = lbv[e]; x = __logf(l + (1.f - l) * __builtin_amdgcn_rcpf(1.f + __expf(-x))); }
.LBB0_978:
	v_mul_f32_e32 v20, v14, v34
	v_mul_f32_e32 v21, v15, v34
	s_and_b64 vcc, exec, s[48:49]
	s_mov_b64 s[0:1], -1
	s_cbranch_vccnz .LBB0_990
	s_and_b64 vcc, exec, s[46:47]
	v_mov_b32_e32 v157, v23
	s_cbranch_vccnz .LBB0_981
	v_mul_f32_e32 v12, 0xbfb8aa3b, v23
	v_exp_f32_e32 v12, v12
	s_waitcnt vmcnt(0)
	v_sub_f32_e32 v13, 1.0, v17
	v_add_f32_e32 v12, 1.0, v12
	v_rcp_f32_e32 v12, v12
	s_nop 0
	v_fmac_f32_e32 v17, v12, v13
	v_cmp_gt_f32_e32 vcc, s35, v17
	s_nop 1
	v_cndmask_b32_e64 v12, 0, 32, vcc
	v_ldexp_f32 v12, v17, v12
	v_log_f32_e32 v12, v12
	s_nop 0
	v_mul_f32_e32 v13, 0x3f317217, v12
	v_fma_f32 v13, v12, s13, -v13
	v_fmac_f32_e32 v13, 0x3377d1cf, v12
	v_fmac_f32_e32 v13, 0x3f317217, v12
	v_cmp_lt_f32_e64 s[50:51], |v12|, s36
	s_nop 1
	v_cndmask_b32_e64 v12, v12, v13, s[50:51]
	v_cndmask_b32_e32 v13, 0, v214, vcc
	v_sub_f32_e32 v157, v12, v13

; __device__ __forceinline__ float silu_f(float v) { return v * __builtin_amdgcn_rcpf(1.f + __expf(-v)); }
;     __device__ __forceinline__ void operator()(const f32x4 (&acc)[2][2][4][2], const Unit& u, int wr, int wc, int fr, int fq, int ui, PG8_LAS unsigned char* lds) const {
;     ...
;                     f32x4 v[2] = {acc[ai][bj][m][0] * rs, acc[ai][bj][m][1] * rs};
;                     if (ksum) { csum[bj][0] += v[0]; csum[bj][1] += v[1]; }
; #pragma unroll
;                     for (int n = 0; n < 2; ++n) {
;                         f32x4 lbv = (f32x4){0.f, 0.f, 0.f, 0.f};
;                         if (act == 2) lbv = *(const f32x4*)(lb + (col0 - 1024) + bj * HALF + 4 * n);
; #pragma unroll
;                         for (int e = 0; e < 4; ++e) {
;                             float x = v[n][e];
;                             if (act == 1) x = silu_f(x);
;                             else if (act == 2) { const float l = lbv[e]; x = __logf(l + (1.f - l) * __builtin_amdgcn_rcpf(1.f + __expf(-x))); }
.LBB0_998:
	v_mov_b32_e32 v35, v34
	s_waitcnt vmcnt(0)
	v_mul_f32_e32 v18, v8, v34
	v_mul_f32_e32 v19, v9, v35
	s_and_b64 vcc, exec, s[48:49]
	s_mov_b64 s[0:1], -1
	s_cbranch_vccnz .LBB0_1002
	s_and_b64 vcc, exec, s[46:47]
	v_mov_b32_e32 v8, v18
	s_cbranch_vccnz .LBB0_1001
	v_mul_f32_e32 v8, 0xbfb8aa3b, v18
	v_exp_f32_e32 v8, v8
	v_sub_f32_e32 v9, 1.0, v12
	v_add_f32_e32 v8, 1.0, v8
	v_rcp_f32_e32 v8, v8
	s_nop 0
	v_fmac_f32_e32 v12, v8, v9
	v_cmp_gt_f32_e32 vcc, s35, v12
	s_nop 1
	v_cndmask_b32_e64 v8, 0, 32, vcc
	v_ldexp_f32 v8, v12, v8
	v_log_f32_e32 v8, v8
	s_nop 0
	v_mul_f32_e32 v9, 0x3f317217, v8
	v_fma_f32 v9, v8, s13, -v9
	v_fmac_f32_e32 v9, 0x3377d1cf, v8
	v_fmac_f32_e32 v9, 0x3f317217, v8
	v_cmp_lt_f32_e64 s[50:51], |v8|, s36
	s_nop 1
	v_cndmask_b32_e64 v8, v8, v9, s[50:51]
	v_cndmask_b32_e32 v9, 0, v214, vcc
	v_sub_f32_e32 v8, v8, v9

; __device__ __forceinline__ float silu_f(float v) { return v * __builtin_amdgcn_rcpf(1.f + __expf(-v)); }
;     __device__ __forceinline__ void operator()(const f32x4 (&acc)[2][2][4][2], const Unit& u, int wr, int wc, int fr, int fq, int ui, PG8_LAS unsigned char* lds) const {
;     ...
;                     f32x4 v[2] = {acc[ai][bj][m][0] * rs, acc[ai][bj][m][1] * rs};
;                     if (ksum) { csum[bj][0] += v[0]; csum[bj][1] += v[1]; }
; #pragma unroll
;                     for (int n = 0; n < 2; ++n) {
;                         f32x4 lbv = (f32x4){0.f, 0.f, 0.f, 0.f};
;                         if (act == 2) lbv = *(const f32x4*)(lb + (col0 - 1024) + bj * HALF + 4 * n);
; #pragma unroll
;                         for (int e = 0; e < 4; ++e) {
;                             float x = v[n][e];
;                             if (act == 1) x = silu_f(x);
;                             else if (act == 2) { const float l = lbv[e]; x = __logf(l + (1.f - l) * __builtin_amdgcn_rcpf(1.f + __expf(-x))); }
.LBB0_1004:
	v_mov_b32_e32 v16, v34
	v_mov_b32_e32 v17, v34
	v_mul_f32_e32 v16, v10, v16
	v_mul_f32_e32 v17, v11, v17
	s_and_b64 vcc, exec, s[48:49]
	s_mov_b64 s[0:1], -1
	s_cbranch_vccnz .LBB0_1016
	s_and_b64 vcc, exec, s[46:47]
	v_mov_b32_e32 v9, v19
	s_cbranch_vccnz .LBB0_1007
	v_mul_f32_e32 v9, 0xbfb8aa3b, v19
	v_exp_f32_e32 v9, v9
	v_sub_f32_e32 v10, 1.0, v13
	v_add_f32_e32 v9, 1.0, v9
	v_rcp_f32_e32 v9, v9
	s_nop 0
	v_fmac_f32_e32 v13, v9, v10
	v_cmp_gt_f32_e32 vcc, s35, v13
	s_nop 1
	v_cndmask_b32_e64 v9, 0, 32, vcc
	v_ldexp_f32 v9, v13, v9
	v_log_f32_e32 v9, v9
	s_nop 0
	v_mul_f32_e32 v10, 0x3f317217, v9
	v_fma_f32 v10, v9, s13, -v10
	v_fmac_f32_e32 v10, 0x3377d1cf, v9
	v_fmac_f32_e32 v10, 0x3f317217, v9
	v_cmp_lt_f32_e64 s[50:51], |v9|, s36
	s_nop 1
	v_cndmask_b32_e64 v9, v9, v10, s[50:51]
	v_cndmask_b32_e32 v10, 0, v214, vcc
	v_sub_f32_e32 v9, v9, v10

; __device__ __forceinline__ float silu_f(float v) { return v * __builtin_amdgcn_rcpf(1.f + __expf(-v)); }
;     __device__ __forceinline__ void operator()(const f32x4 (&acc)[2][2][4][2], const Unit& u, int wr, int wc, int fr, int fq, int ui, PG8_LAS unsigned char* lds) const {
;     ...
;                     f32x4 v[2] = {acc[ai][bj][m][0] * rs, acc[ai][bj][m][1] * rs};
;                     if (ksum) { csum[bj][0] += v[0]; csum[bj][1] += v[1]; }
; #pragma unroll
;                     for (int n = 0; n < 2; ++n) {
;                         f32x4 lbv = (f32x4){0.f, 0.f, 0.f, 0.f};
;                         if (act == 2) lbv = *(const f32x4*)(lb + (col0 - 1024) + bj * HALF + 4 * n);
; #pragma unroll
;                         for (int e = 0; e < 4; ++e) {
;                             float x = v[n][e];
;                             if (act == 1) x = silu_f(x);
;                             else if (act == 2) { const float l = lbv[e]; x = __logf(l + (1.f - l) * __builtin_amdgcn_rcpf(1.f + __expf(-x))); }
.LBB0_1024:
	s_nop 0
	v_mul_f32_e32 v14, v4, v34
	v_mul_f32_e32 v15, v5, v35
	s_and_b64 vcc, exec, s[48:49]
	s_mov_b64 s[0:1], -1
	s_cbranch_vccnz .LBB0_1028
	s_and_b64 vcc, exec, s[46:47]
	v_mov_b32_e32 v145, v14
	s_cbranch_vccnz .LBB0_1027
	v_mul_f32_e32 v4, 0xbfb8aa3b, v14
	v_exp_f32_e32 v4, v4
	s_waitcnt vmcnt(0)
	v_sub_f32_e32 v5, 1.0, v8
	v_add_f32_e32 v4, 1.0, v4
	v_rcp_f32_e32 v4, v4
	s_nop 0
	v_fmac_f32_e32 v8, v4, v5
	v_cmp_gt_f32_e32 vcc, s35, v8
	s_nop 1
	v_cndmask_b32_e64 v4, 0, 32, vcc
	v_ldexp_f32 v4, v8, v4
	v_log_f32_e32 v4, v4
	s_nop 0
	v_mul_f32_e32 v5, 0x3f317217, v4
	v_fma_f32 v5, v4, s13, -v5
	v_fmac_f32_e32 v5, 0x3377d1cf, v4
	v_fmac_f32_e32 v5, 0x3f317217, v4
	v_cmp_lt_f32_e64 s[50:51], |v4|, s36
	s_nop 1
	v_cndmask_b32_e64 v4, v4, v5, s[50:51]
	v_cndmask_b32_e32 v5, 0, v214, vcc
	v_sub_f32_e32 v145, v4, v5

; __device__ __forceinline__ float silu_f(float v) { return v * __builtin_amdgcn_rcpf(1.f + __expf(-v)); }
;     __device__ __forceinline__ void operator()(const f32x4 (&acc)[2][2][4][2], const Unit& u, int wr, int wc, int fr, int fq, int ui, PG8_LAS unsigned char* lds) const {
;     ...
;                     f32x4 v[2] = {acc[ai][bj][m][0] * rs, acc[ai][bj][m][1] * rs};
;                     if (ksum) { csum[bj][0] += v[0]; csum[bj][1] += v[1]; }
; #pragma unroll
;                     for (int n = 0; n < 2; ++n) {
;                         f32x4 lbv = (f32x4){0.f, 0.f, 0.f, 0.f};
;                         if (act == 2) lbv = *(const f32x4*)(lb + (col0 - 1024) + bj * HALF + 4 * n);
; #pragma unroll
;                         for (int e = 0; e < 4; ++e) {
;                             float x = v[n][e];
;                             if (act == 1) x = silu_f(x);
;                             else if (act == 2) { const float l = lbv[e]; x = __logf(l + (1.f - l) * __builtin_amdgcn_rcpf(1.f + __expf(-x))); }
.LBB0_1030:
	v_mov_b32_e32 v4, v34
	v_mov_b32_e32 v5, v34
	v_mul_f32_e32 v12, v6, v4
	v_mul_f32_e32 v13, v7, v5
	s_and_b64 vcc, exec, s[48:49]
	s_mov_b64 s[0:1], -1
	s_cbranch_vccnz .LBB0_1042
	s_and_b64 vcc, exec, s[46:47]
	v_mov_b32_e32 v156, v15
	s_cbranch_vccnz .LBB0_1033
	v_mul_f32_e32 v4, 0xbfb8aa3b, v15
	v_exp_f32_e32 v4, v4
	s_waitcnt vmcnt(0)
	v_sub_f32_e32 v5, 1.0, v9
	v_add_f32_e32 v4, 1.0, v4
	v_rcp_f32_e32 v4, v4
	s_nop 0
	v_fmac_f32_e32 v9, v4, v5
	v_cmp_gt_f32_e32 vcc, s35, v9
	s_nop 1
	v_cndmask_b32_e64 v4, 0, 32, vcc
	v_ldexp_f32 v4, v9, v4
	v_log_f32_e32 v4, v4
	s_nop 0
	v_mul_f32_e32 v5, 0x3f317217, v4
	v_fma_f32 v5, v4, s13, -v5
	v_fmac_f32_e32 v5, 0x3377d1cf, v4
	v_fmac_f32_e32 v5, 0x3f317217, v4
	v_cmp_lt_f32_e64 s[50:51], |v4|, s36
	s_nop 1
	v_cndmask_b32_e64 v4, v4, v5, s[50:51]
	v_cndmask_b32_e32 v5, 0, v214, vcc
	v_sub_f32_e32 v156, v4, v5

; __device__ __forceinline__ float silu_f(float v) { return v * __builtin_amdgcn_rcpf(1.f + __expf(-v)); }
;     __device__ __forceinline__ void operator()(const f32x4 (&acc)[2][2][4][2], const Unit& u, int wr, int wc, int fr, int fq, int ui, PG8_LAS unsigned char* lds) const {
;     ...
;                     f32x4 v[2] = {acc[ai][bj][m][0] * rs, acc[ai][bj][m][1] * rs};
;                     if (ksum) { csum[bj][0] += v[0]; csum[bj][1] += v[1]; }
; #pragma unroll
;                     for (int n = 0; n < 2; ++n) {
;                         f32x4 lbv = (f32x4){0.f, 0.f, 0.f, 0.f};
;                         if (act == 2) lbv = *(const f32x4*)(lb + (col0 - 1024) + bj * HALF + 4 * n);
; #pragma unroll
;                         for (int e = 0; e < 4; ++e) {
;                             float x = v[n][e];
;                             if (act == 1) x = silu_f(x);
;                             else if (act == 2) { const float l = lbv[e]; x = __logf(l + (1.f - l) * __builtin_amdgcn_rcpf(1.f + __expf(-x))); }
.LBB0_1050:
	s_waitcnt vmcnt(0)
	v_mul_f32_e32 v8, v0, v34
	v_mul_f32_e32 v9, v1, v35
	s_and_b64 vcc, exec, s[48:49]
	s_mov_b64 s[0:1], -1
	s_cbranch_vccnz .LBB0_1054
	s_and_b64 vcc, exec, s[46:47]
	v_mov_b32_e32 v11, v8
	s_cbranch_vccnz .LBB0_1053
	v_mul_f32_e32 v0, 0xbfb8aa3b, v8
	v_exp_f32_e32 v0, v0
	v_sub_f32_e32 v1, 1.0, v4
	v_add_f32_e32 v0, 1.0, v0
	v_rcp_f32_e32 v0, v0
	s_nop 0
	v_fmac_f32_e32 v4, v0, v1
	v_cmp_gt_f32_e32 vcc, s35, v4
	s_nop 1
	v_cndmask_b32_e64 v0, 0, 32, vcc
	v_ldexp_f32 v0, v4, v0
	v_log_f32_e32 v0, v0
	s_nop 0
	v_mul_f32_e32 v1, 0x3f317217, v0
	v_fma_f32 v1, v0, s13, -v1
	v_fmac_f32_e32 v1, 0x3377d1cf, v0
	v_fmac_f32_e32 v1, 0x3f317217, v0
	v_cmp_lt_f32_e64 s[50:51], |v0|, s36
	s_nop 1
	v_cndmask_b32_e64 v0, v0, v1, s[50:51]
	v_cndmask_b32_e32 v1, 0, v214, vcc
	v_sub_f32_e32 v11, v0, v1

; __device__ __forceinline__ float silu_f(float v) { return v * __builtin_amdgcn_rcpf(1.f + __expf(-v)); }
;     __device__ __forceinline__ void operator()(const f32x4 (&acc)[2][2][4][2], const Unit& u, int wr, int wc, int fr, int fq, int ui, PG8_LAS unsigned char* lds) const {
;     ...
;                     f32x4 v[2] = {acc[ai][bj][m][0] * rs, acc[ai][bj][m][1] * rs};
;                     if (ksum) { csum[bj][0] += v[0]; csum[bj][1] += v[1]; }
; #pragma unroll
;                     for (int n = 0; n < 2; ++n) {
;                         f32x4 lbv = (f32x4){0.f, 0.f, 0.f, 0.f};
;                         if (act == 2) lbv = *(const f32x4*)(lb + (col0 - 1024) + bj * HALF + 4 * n);
; #pragma unroll
;                         for (int e = 0; e < 4; ++e) {
;                             float x = v[n][e];
;                             if (act == 1) x = silu_f(x);
;                             else if (act == 2) { const float l = lbv[e]; x = __logf(l + (1.f - l) * __builtin_amdgcn_rcpf(1.f + __expf(-x))); }
.LBB0_1056:
	v_mov_b32_e32 v35, v34
	v_mul_f32_e32 v0, v2, v34
	v_mul_f32_e32 v1, v3, v35
	s_and_b64 vcc, exec, s[48:49]
	s_mov_b64 s[0:1], -1
	s_cbranch_vccnz .LBB0_1068
	s_and_b64 vcc, exec, s[46:47]
	v_mov_b32_e32 v2, v9
	s_cbranch_vccnz .LBB0_1059
	v_mul_f32_e32 v2, 0xbfb8aa3b, v9
	v_exp_f32_e32 v2, v2
	v_sub_f32_e32 v3, 1.0, v5
	v_add_f32_e32 v2, 1.0, v2
	v_rcp_f32_e32 v2, v2
	s_nop 0
	v_fmac_f32_e32 v5, v2, v3
	v_cmp_gt_f32_e32 vcc, s35, v5
	s_nop 1
	v_cndmask_b32_e64 v2, 0, 32, vcc
	v_ldexp_f32 v2, v5, v2
	v_log_f32_e32 v2, v2
	s_nop 0
	v_mul_f32_e32 v3, 0x3f317217, v2
	v_fma_f32 v3, v2, s13, -v3
	v_fmac_f32_e32 v3, 0x3377d1cf, v2
	v_fmac_f32_e32 v3, 0x3f317217, v2
	v_cmp_lt_f32_e64 s[50:51], |v2|, s36
	s_nop 1
	v_cndmask_b32_e64 v2, v2, v3, s[50:51]
	v_cndmask_b32_e32 v3, 0, v214, vcc
	v_sub_f32_e32 v2, v2, v3

;     __device__ __forceinline__ void operator()(const f32x4 (&acc)[2][2][4][2], const Unit& u, int wr, int wc, int fr, int fq, int ui, PG8_LAS unsigned char* lds) const {
;     ...
;                     f32x4 v[2] = {acc[ai][bj][m][0] * rs, acc[ai][bj][m][1] * rs};
;                     if (ksum) { csum[bj][0] += v[0]; csum[bj][1] += v[1]; }
;     ...
;         if (ksum) {
;             const int b = u.pm >> 3, nblk = u.pm & 7;
; #pragma unroll
;             for (int bj = 0; bj < 2; ++bj)
; #pragma unroll
;                 for (int n = 0; n < 2; ++n)
; #pragma unroll
;                     for (int e = 0; e < 4; ++e) {
;                         float t = csum[bj][n][e];
;                         t += __shfl_xor(t, 1); t += __shfl_xor(t, 2); t += __shfl_xor(t, 4); t += __shfl_xor(t, 8);
;                         if (fr == 0) { const int kc = col0 + bj * HALF + 4 * n + e - 1024, h = kc >> 7, d = kc & 127;
;                             atomicAdd(kmean + ((size_t)((b * 8 + h) * 8 + nblk)) * 128 + d, t * (1.0f / 256.0f)); }
;                     }
.LBB0_1074:
	s_cmp_eq_u32 s71, 1
	s_cselect_b64 s[0:1], -1, 0
	s_and_b64 s[46:47], s[58:59], s[0:1]
	s_andn2_b64 vcc, exec, s[46:47]
	v_cvt_pk_bf16_f32 v156, v145, v156
	v_cvt_pk_bf16_f32 v157, v157, v10
	v_cvt_pk_bf16_f32 v158, v11, v2
	v_cvt_pk_bf16_f32 v159, v3, v4
	global_store_dwordx4 v[150:151], v[156:159], off offset:256
	s_cbranch_vccnz .LBB0_1108
	v_add_f32_e32 v2, 0, v148
	v_add_f32_e32 v3, 0, v149
	s_add_i32 s0, s73, 0xfffffc00
	v_add_f32_e32 v2, v2, v118
	v_add_f32_e32 v3, v3, v119
	s_and_b32 s39, s78, -8
	v_add_f32_e32 v2, v2, v102
	v_add_f32_e32 v3, v3, v103
	s_lshr_b32 s0, s0, 7
	v_add_f32_e32 v2, v2, v86
	v_add_f32_e32 v3, v3, v87
	s_or_b32 s0, s0, s39
	v_add_f32_e32 v2, v2, v70
	v_add_f32_e32 v3, v3, v71
	s_and_b32 s38, s78, 7
	v_add_f32_e32 v2, v2, v54
	v_add_f32_e32 v3, v3, v55
	s_lshl_b32 s0, s0, 3
	v_add_f32_e32 v2, v2, v154
	v_add_f32_e32 v3, v3, v155
	s_or_b32 s0, s0, s38
	v_add_f32_e32 v4, v2, v22
	v_add_f32_e32 v5, v3, v23
	v_xor_b32_e32 v3, 1, v213
	v_cndmask_b32_e64 v2, 0, v4, s[46:47]
	v_and_b32_e32 v4, 64, v213
	v_add_u32_e32 v4, 64, v4
	v_cmp_lt_i32_e32 vcc, v3, v4
	s_ashr_i32 s1, s0, 31
	s_lshl_b64 s[0:1], s[0:1], 9
	v_cndmask_b32_e32 v3, v213, v3, vcc
	v_lshlrev_b32_e32 v6, 2, v3
	ds_bpermute_b32 v11, v6, v2
	v_xor_b32_e32 v3, 2, v213
	v_cmp_lt_i32_e32 vcc, v3, v4
	s_waitcnt lgkmcnt(0)
	v_add_f32_e32 v2, v2, v11
	v_cndmask_b32_e32 v3, v213, v3, vcc
	v_lshlrev_b32_e32 v7, 2, v3
	v_xor_b32_e32 v3, 4, v213
	ds_bpermute_b32 v22, v7, v2
	v_cmp_lt_i32_e32 vcc, v3, v4
	s_waitcnt lgkmcnt(0)
	v_add_f32_e32 v2, v2, v22
	v_cndmask_b32_e32 v3, v213, v3, vcc
	v_lshlrev_b32_e32 v10, 2, v3
	v_xor_b32_e32 v3, 8, v213
	v_cmp_lt_i32_e32 vcc, v3, v4
	s_nop 1
	v_cndmask_b32_e32 v3, v213, v3, vcc
	v_lshlrev_b32_e32 v11, 2, v3
	ds_bpermute_b32 v3, v10, v2
	s_waitcnt lgkmcnt(0)
	v_add_f32_e32 v4, v2, v3
	ds_bpermute_b32 v22, v11, v4
	v_lshl_add_u64 v[2:3], v[138:139], 0, s[0:1]
	s_and_saveexec_b64 s[0:1], s[42:43]
	s_cbranch_execz .LBB0_1077
	s_waitcnt lgkmcnt(0)
	v_add_f32_e32 v4, v4, v22
	v_mul_f32_e32 v4, 0x3b800000, v4
	global_atomic_add_f32 v[2:3], v4, off
.LBB0_1077:
	s_or_b64 exec, exec, s[0:1]
	v_cndmask_b32_e64 v4, 0, v5, s[46:47]
	ds_bpermute_b32 v5, v6, v4
	s_waitcnt lgkmcnt(0)
	v_add_f32_e32 v22, v4, v5
	ds_bpermute_b32 v23, v7, v22
	v_add_f32_e32 v4, 0, v146
	v_add_f32_e32 v5, 0, v147
	s_waitcnt lgkmcnt(0)
	v_add_f32_e32 v22, v22, v23
	ds_bpermute_b32 v23, v10, v22
	v_add_f32_e32 v4, v4, v116
	v_add_f32_e32 v5, v5, v117
	s_waitcnt lgkmcnt(0)
	v_add_f32_e32 v22, v22, v23
	v_add_f32_e32 v4, v4, v100
	v_add_f32_e32 v5, v5, v101
	ds_bpermute_b32 v23, v11, v22
	v_add_f32_e32 v4, v4, v84
	v_add_f32_e32 v5, v5, v85
	s_nop 0
	v_add_f32_e32 v4, v4, v68
	v_add_f32_e32 v5, v5, v69
	s_nop 0
	v_add_f32_e32 v4, v4, v52
	v_add_f32_e32 v5, v5, v53
	s_nop 0
	v_add_f32_e32 v4, v4, v32
	v_add_f32_e32 v5, v5, v33
	s_nop 0
	v_add_f32_e32 v20, v4, v20
	v_add_f32_e32 v21, v5, v21
	s_nop 0
	v_cndmask_b32_e64 v4, 0, v21, s[46:47]
	v_cndmask_b32_e64 v5, 0, v20, s[46:47]
	s_and_saveexec_b64 s[0:1], s[42:43]
	s_cbranch_execz .LBB0_1079
	s_waitcnt lgkmcnt(0)
	v_add_f32_e32 v20, v22, v23
	v_mul_f32_e32 v20, 0x3b800000, v20
	global_atomic_add_f32 v[2:3], v20, off offset:4

;     __device__ __forceinline__ void operator()(const f32x4 (&acc)[2][2][4][2], const Unit& u, int wr, int wc, int fr, int fq, int ui, PG8_LAS unsigned char* lds) const {
;     ...
;                     f32x4 v[2] = {acc[ai][bj][m][0] * rs, acc[ai][bj][m][1] * rs};
;                     if (ksum) { csum[bj][0] += v[0]; csum[bj][1] += v[1]; }
;     ...
;         if (ksum) {
;             const int b = u.pm >> 3, nblk = u.pm & 7;
; #pragma unroll
;             for (int bj = 0; bj < 2; ++bj)
; #pragma unroll
;                 for (int n = 0; n < 2; ++n)
; #pragma unroll
;                     for (int e = 0; e < 4; ++e) {
;                         float t = csum[bj][n][e];
;                         t += __shfl_xor(t, 1); t += __shfl_xor(t, 2); t += __shfl_xor(t, 4); t += __shfl_xor(t, 8);
;                         if (fr == 0) { const int kc = col0 + bj * HALF + 4 * n + e - 1024, h = kc >> 7, d = kc & 127;
;                             atomicAdd(kmean + ((size_t)((b * 8 + h) * 8 + nblk)) * 128 + d, t * (1.0f / 256.0f)); }
;                     }
.LBB0_1083:
	s_or_b64 exec, exec, s[0:1]
	v_add_f32_e32 v2, 0, v128
	v_add_f32_e32 v3, 0, v129
	s_nop 0
	v_add_f32_e32 v2, v2, v112
	v_add_f32_e32 v3, v3, v113
	s_nop 0
	v_add_f32_e32 v2, v2, v98
	v_add_f32_e32 v3, v3, v99
	s_nop 0
	v_add_f32_e32 v2, v2, v82
	v_add_f32_e32 v3, v3, v83
	s_nop 0
	v_add_f32_e32 v2, v2, v66
	v_add_f32_e32 v3, v3, v67
	s_nop 0
	v_add_f32_e32 v2, v2, v50
	v_add_f32_e32 v3, v3, v51
	s_nop 0
	v_add_f32_e32 v2, v2, v38
	v_add_f32_e32 v3, v3, v39
	s_waitcnt lgkmcnt(0)
	v_add_f32_e32 v4, v2, v18
	v_add_f32_e32 v5, v3, v19
	s_nop 0
	v_cndmask_b32_e64 v2, 0, v4, s[46:47]
	ds_bpermute_b32 v3, v6, v2
	v_add_u32_e32 v4, 0xfffffc04, v144
	v_lshrrev_b32_e32 v4, 7, v4
	v_or_b32_e32 v19, s39, v4
	s_waitcnt lgkmcnt(0)
	v_add_f32_e32 v2, v2, v3
	ds_bpermute_b32 v3, v7, v2
	s_waitcnt lgkmcnt(0)
	v_add_f32_e32 v2, v2, v3
	ds_bpermute_b32 v3, v10, v2
	s_waitcnt lgkmcnt(0)
	v_add_f32_e32 v4, v2, v3
	ds_bpermute_b32 v18, v11, v4
	v_lshl_or_b32 v2, v19, 3, s38
	v_ashrrev_i32_e32 v3, 31, v2
	v_lshlrev_b64 v[2:3], 9, v[2:3]
	v_lshl_add_u64 v[2:3], v[138:139], 0, v[2:3]
	s_and_saveexec_b64 s[0:1], s[42:43]
	s_cbranch_execz .LBB0_1085
	s_waitcnt lgkmcnt(0)
	v_add_f32_e32 v4, v4, v18
	v_mul_f32_e32 v4, 0x3b800000, v4
	global_atomic_add_f32 v[2:3], v4, off offset:16
.LBB0_1085:
	s_or_b64 exec, exec, s[0:1]
	v_cndmask_b32_e64 v4, 0, v5, s[46:47]
	ds_bpermute_b32 v5, v6, v4
	s_waitcnt lgkmcnt(0)
	v_add_f32_e32 v18, v4, v5
	ds_bpermute_b32 v19, v7, v18
	v_add_f32_e32 v4, 0, v130
	v_add_f32_e32 v5, 0, v131
	s_waitcnt lgkmcnt(0)
	v_add_f32_e32 v18, v18, v19
	ds_bpermute_b32 v19, v10, v18
	v_add_f32_e32 v4, v4, v114
	v_add_f32_e32 v5, v5, v115
	s_waitcnt lgkmcnt(0)
	v_add_f32_e32 v18, v18, v19
	v_add_f32_e32 v4, v4, v96
	v_add_f32_e32 v5, v5, v97
	ds_bpermute_b32 v19, v11, v18
	v_add_f32_e32 v4, v4, v80
	v_add_f32_e32 v5, v5, v81
	s_nop 0
	v_add_f32_e32 v4, v4, v64
	v_add_f32_e32 v5, v5, v65
	s_nop 0
	v_add_f32_e32 v4, v4, v48
	v_add_f32_e32 v5, v5, v49
	s_nop 0
	v_add_f32_e32 v4, v4, v36
	v_add_f32_e32 v5, v5, v37
	s_nop 0
	v_add_f32_e32 v16, v4, v16
	v_add_f32_e32 v17, v5, v17
	s_nop 0
	v_cndmask_b32_e64 v4, 0, v17, s[46:47]
	v_cndmask_b32_e64 v5, 0, v16, s[46:47]
	s_and_saveexec_b64 s[0:1], s[42:43]
	s_cbranch_execz .LBB0_1087
	s_waitcnt lgkmcnt(0)
	v_add_f32_e32 v16, v18, v19
	v_mul_f32_e32 v16, 0x3b800000, v16
	global_atomic_add_f32 v[2:3], v16, off offset:20

;     __device__ __forceinline__ void operator()(const f32x4 (&acc)[2][2][4][2], const Unit& u, int wr, int wc, int fr, int fq, int ui, PG8_LAS unsigned char* lds) const {
;     ...
;                     f32x4 v[2] = {acc[ai][bj][m][0] * rs, acc[ai][bj][m][1] * rs};
;                     if (ksum) { csum[bj][0] += v[0]; csum[bj][1] += v[1]; }
;     ...
;         if (ksum) {
;             const int b = u.pm >> 3, nblk = u.pm & 7;
; #pragma unroll
;             for (int bj = 0; bj < 2; ++bj)
; #pragma unroll
;                 for (int n = 0; n < 2; ++n)
; #pragma unroll
;                     for (int e = 0; e < 4; ++e) {
;                         float t = csum[bj][n][e];
;                         t += __shfl_xor(t, 1); t += __shfl_xor(t, 2); t += __shfl_xor(t, 4); t += __shfl_xor(t, 8);
;                         if (fr == 0) { const int kc = col0 + bj * HALF + 4 * n + e - 1024, h = kc >> 7, d = kc & 127;
;                             atomicAdd(kmean + ((size_t)((b * 8 + h) * 8 + nblk)) * 128 + d, t * (1.0f / 256.0f)); }
;                     }
.LBB0_1091:
	s_or_b64 exec, exec, s[0:1]
	v_add_f32_e32 v2, 0, v126
	v_add_f32_e32 v3, 0, v127
	s_addk_i32 s73, 0xfc80
	v_add_f32_e32 v2, v2, v110
	v_add_f32_e32 v3, v3, v111
	s_lshr_b32 s0, s73, 7
	v_add_f32_e32 v2, v2, v94
	v_add_f32_e32 v3, v3, v95
	s_or_b32 s0, s0, s39
	v_add_f32_e32 v2, v2, v78
	v_add_f32_e32 v3, v3, v79
	s_lshl_b32 s0, s0, 3
	v_add_f32_e32 v2, v2, v62
	v_add_f32_e32 v3, v3, v63
	s_or_b32 s0, s0, s38
	v_add_f32_e32 v2, v2, v46
	v_add_f32_e32 v3, v3, v47
	s_ashr_i32 s1, s0, 31
	v_add_f32_e32 v2, v2, v30
	v_add_f32_e32 v3, v3, v31
	s_lshl_b64 s[0:1], s[0:1], 9
	s_waitcnt lgkmcnt(0)
	v_add_f32_e32 v4, v2, v14
	v_add_f32_e32 v5, v3, v15
	s_nop 0
	v_cndmask_b32_e64 v2, 0, v4, s[46:47]
	ds_bpermute_b32 v3, v6, v2
	s_waitcnt lgkmcnt(0)
	v_add_f32_e32 v2, v2, v3
	ds_bpermute_b32 v3, v7, v2
	s_waitcnt lgkmcnt(0)
	v_add_f32_e32 v2, v2, v3
	ds_bpermute_b32 v3, v10, v2
	s_waitcnt lgkmcnt(0)
	v_add_f32_e32 v4, v2, v3
	ds_bpermute_b32 v14, v11, v4
	v_lshl_add_u64 v[2:3], v[138:139], 0, s[0:1]
	s_and_saveexec_b64 s[0:1], s[42:43]
	s_cbranch_execz .LBB0_1093
	s_waitcnt lgkmcnt(0)
	v_add_f32_e32 v4, v4, v14
	v_mul_f32_e32 v4, 0x3b800000, v4
	global_atomic_add_f32 v[2:3], v4, off
.LBB0_1093:
	s_or_b64 exec, exec, s[0:1]
	v_cndmask_b32_e64 v4, 0, v5, s[46:47]
	ds_bpermute_b32 v5, v6, v4
	s_waitcnt lgkmcnt(0)
	v_add_f32_e32 v14, v4, v5
	ds_bpermute_b32 v15, v7, v14
	v_add_f32_e32 v4, 0, v124
	v_add_f32_e32 v5, 0, v125
	s_waitcnt lgkmcnt(0)
	v_add_f32_e32 v14, v14, v15
	ds_bpermute_b32 v15, v10, v14
	v_add_f32_e32 v4, v4, v108
	v_add_f32_e32 v5, v5, v109
	s_waitcnt lgkmcnt(0)
	v_add_f32_e32 v14, v14, v15
	v_add_f32_e32 v4, v4, v92
	v_add_f32_e32 v5, v5, v93
	ds_bpermute_b32 v15, v11, v14
	v_add_f32_e32 v4, v4, v76
	v_add_f32_e32 v5, v5, v77
	s_nop 0
	v_add_f32_e32 v4, v4, v60
	v_add_f32_e32 v5, v5, v61
	s_nop 0
	v_add_f32_e32 v4, v4, v44
	v_add_f32_e32 v5, v5, v45
	s_nop 0
	v_add_f32_e32 v4, v4, v28
	v_add_f32_e32 v5, v5, v29
	s_nop 0
	v_add_f32_e32 v12, v4, v12
	v_add_f32_e32 v13, v5, v13
	s_nop 0
	v_cndmask_b32_e64 v4, 0, v13, s[46:47]
	v_cndmask_b32_e64 v5, 0, v12, s[46:47]
	s_and_saveexec_b64 s[0:1], s[42:43]
	s_cbranch_execz .LBB0_1095
	s_waitcnt lgkmcnt(0)
	v_add_f32_e32 v12, v14, v15
	v_mul_f32_e32 v12, 0x3b800000, v12
	global_atomic_add_f32 v[2:3], v12, off offset:4

;     __device__ __forceinline__ void operator()(const f32x4 (&acc)[2][2][4][2], const Unit& u, int wr, int wc, int fr, int fq, int ui, PG8_LAS unsigned char* lds) const {
;     ...
;                     f32x4 v[2] = {acc[ai][bj][m][0] * rs, acc[ai][bj][m][1] * rs};
;                     if (ksum) { csum[bj][0] += v[0]; csum[bj][1] += v[1]; }
;     ...
;         if (ksum) {
;             const int b = u.pm >> 3, nblk = u.pm & 7;
; #pragma unroll
;             for (int bj = 0; bj < 2; ++bj)
; #pragma unroll
;                 for (int n = 0; n < 2; ++n)
; #pragma unroll
;                     for (int e = 0; e < 4; ++e) {
;                         float t = csum[bj][n][e];
;                         t += __shfl_xor(t, 1); t += __shfl_xor(t, 2); t += __shfl_xor(t, 4); t += __shfl_xor(t, 8);
;                         if (fr == 0) { const int kc = col0 + bj * HALF + 4 * n + e - 1024, h = kc >> 7, d = kc & 127;
;                             atomicAdd(kmean + ((size_t)((b * 8 + h) * 8 + nblk)) * 128 + d, t * (1.0f / 256.0f)); }
;                     }
.LBB0_1099:
	s_or_b64 exec, exec, s[0:1]
	v_add_f32_e32 v2, 0, v120
	v_add_f32_e32 v3, 0, v121
	s_nop 0
	v_add_f32_e32 v2, v2, v104
	v_add_f32_e32 v3, v3, v105
	s_nop 0
	v_add_f32_e32 v2, v2, v90
	v_add_f32_e32 v3, v3, v91
	s_nop 0
	v_add_f32_e32 v2, v2, v74
	v_add_f32_e32 v3, v3, v75
	s_nop 0
	v_add_f32_e32 v2, v2, v58
	v_add_f32_e32 v3, v3, v59
	s_nop 0
	v_add_f32_e32 v2, v2, v42
	v_add_f32_e32 v3, v3, v43
	s_nop 0
	v_add_f32_e32 v2, v2, v26
	v_add_f32_e32 v3, v3, v27
	s_waitcnt lgkmcnt(0)
	v_add_f32_e32 v4, v2, v8
	v_add_f32_e32 v5, v3, v9
	s_nop 0
	v_cndmask_b32_e64 v2, 0, v4, s[46:47]
	ds_bpermute_b32 v3, v6, v2
	v_add_u32_e32 v4, 0xfffffc84, v144
	v_lshrrev_b32_e32 v4, 7, v4
	v_or_b32_e32 v9, s39, v4
	s_waitcnt lgkmcnt(0)
	v_add_f32_e32 v2, v2, v3
	ds_bpermute_b32 v3, v7, v2
	s_waitcnt lgkmcnt(0)
	v_add_f32_e32 v2, v2, v3
	ds_bpermute_b32 v3, v10, v2
	s_waitcnt lgkmcnt(0)
	v_add_f32_e32 v4, v2, v3
	ds_bpermute_b32 v8, v11, v4
	v_lshl_or_b32 v2, v9, 3, s38
	v_ashrrev_i32_e32 v3, 31, v2
	v_lshlrev_b64 v[2:3], 9, v[2:3]
	v_lshl_add_u64 v[2:3], v[138:139], 0, v[2:3]
	s_and_saveexec_b64 s[0:1], s[42:43]
	s_cbranch_execz .LBB0_1101
	s_waitcnt lgkmcnt(0)
	v_add_f32_e32 v4, v4, v8
	v_mul_f32_e32 v4, 0x3b800000, v4
	global_atomic_add_f32 v[2:3], v4, off offset:16
.LBB0_1101:
	s_or_b64 exec, exec, s[0:1]
	v_cndmask_b32_e64 v4, 0, v5, s[46:47]
	ds_bpermute_b32 v5, v6, v4
	s_waitcnt lgkmcnt(0)
	v_add_f32_e32 v8, v4, v5
	ds_bpermute_b32 v9, v7, v8
	v_add_f32_e32 v4, 0, v122
	v_add_f32_e32 v5, 0, v123
	s_waitcnt lgkmcnt(0)
	v_add_f32_e32 v12, v8, v9
	ds_bpermute_b32 v13, v10, v12
	v_add_f32_e32 v4, v4, v106
	v_add_f32_e32 v5, v5, v107
	s_nop 0
	v_add_f32_e32 v4, v4, v88
	v_add_f32_e32 v5, v5, v89
	s_nop 0
	v_add_f32_e32 v4, v4, v72
	v_add_f32_e32 v5, v5, v73
	s_nop 0
	v_add_f32_e32 v4, v4, v56
	v_add_f32_e32 v5, v5, v57
	s_nop 0
	v_add_f32_e32 v8, v4, v40
	v_add_f32_e32 v9, v5, v41
	s_waitcnt lgkmcnt(0)
	v_add_f32_e32 v4, v12, v13
	ds_bpermute_b32 v5, v11, v4
	v_add_f32_e32 v8, v8, v24
	v_add_f32_e32 v9, v9, v25
	s_nop 0
	v_add_f32_e32 v8, v8, v0
	v_add_f32_e32 v9, v9, v1
	s_nop 0
	v_cndmask_b32_e64 v0, 0, v9, s[46:47]
	v_cndmask_b32_e64 v1, 0, v8, s[46:47]
	s_and_saveexec_b64 s[0:1], s[42:43]
	s_cbranch_execz .LBB0_1103
	s_waitcnt lgkmcnt(0)
	v_add_f32_e32 v4, v4, v5
	v_mul_f32_e32 v4, 0x3b800000, v4
	global_atomic_add_f32 v[2:3], v4, off offset:20

; __device__ __forceinline__ unsigned cvt_pk_bf16(float lo, float hi) { unsigned r; asm volatile("v_cvt_pk_bf16_f32 %0, %1, %2" : "=v"(r) : "v"(lo), "v"(hi)); return r; }
;     __device__ __forceinline__ void operator()(const f32x4 (&acc)[2][2][4][2], const Unit& u, int wr, int wc, int fr, int fq, int, PG8_LAS unsigned char*) const {
;     ...
;                 for (int bj = 0; bj < 2; ++bj) xw[m][bj] = *(const u32x4*)(xb + (size_t)(row0 + ai * HALF + m * 16) * 1024 + col0 + bj * HALF);
; #pragma unroll
;             for (int m = 0; m < 4; ++m) {
;                 const int row = row0 + ai * HALF + m * 16; const size_t off = (size_t)row * 1024 + col0;
;                 float s = 0.f;
; #pragma unroll
;                 for (int bj = 0; bj < 2; ++bj) {
;                     const u32x4 xv = xw[m][bj];
;                     const f32x4 xo0 = {__builtin_bit_cast(float, xv.x << 16), __builtin_bit_cast(float, xv.x & 0xffff0000u), __builtin_bit_cast(float, xv.y << 16), __builtin_bit_cast(float, xv.y & 0xffff0000u)};
;                     const f32x4 xo1 = {__builtin_bit_cast(float, xv.z << 16), __builtin_bit_cast(float, xv.z & 0xffff0000u), __builtin_bit_cast(float, xv.w << 16), __builtin_bit_cast(float, xv.w & 0xffff0000u)};
;                     const f32x4 o0 = xo0 + acc[ai][bj][m][0] * csv[bj][0], o1 = xo1 + acc[ai][bj][m][1] * csv[bj][1];
;                     u32x4 w; w.x = cvt_pk_bf16(o0[0], o0[1]); w.y = cvt_pk_bf16(o0[2], o0[3]); w.z = cvt_pk_bf16(o1[0], o1[1]); w.w = cvt_pk_bf16(o1[2], o1[3]);
;                     if (!dry) *(u32x4*)(xb + off + bj * HALF) = w;
; #pragma unroll
;                     for (int q = 0; q < 4; ++q) { const unsigned ww = w[q]; const float ra = __builtin_bit_cast(float, ww << 16), rb = __builtin_bit_cast(float, ww & 0xffff0000u); s += ra * ra + rb * rb; }
;                 }
;                 s += __shfl_xor(s, 16); s += __shfl_xor(s, 32);
;                 if (fq == 0 && !dry) ssq_next[(size_t)row * 16 + u.pn * 4 + wc] = s;
;             }
.Lal2_skip:
	s_waitcnt vmcnt(0)
	v_lshlrev_b32_e32 v172, 16, v176
	v_and_b32_e32 v173, 0xffff0000, v176
	v_lshlrev_b32_e32 v176, 16, v177
	v_and_b32_e32 v177, 0xffff0000, v177
	v_lshlrev_b32_e32 v222, 16, v178
	v_and_b32_e32 v223, 0xffff0000, v178
	v_lshlrev_b32_e32 v224, 16, v168
	v_and_b32_e32 v225, 0xffff0000, v168
	v_lshlrev_b32_e32 v168, 16, v169
	v_and_b32_e32 v169, 0xffff0000, v169
	v_lshlrev_b32_e32 v226, 16, v170
	v_and_b32_e32 v227, 0xffff0000, v170
	v_lshlrev_b32_e32 v170, 16, v171
	v_and_b32_e32 v171, 0xffff0000, v171
	v_lshlrev_b32_e32 v178, 16, v179
	v_and_b32_e32 v179, 0xffff0000, v179
	v_fma_f32 v142, v142, v70, v176
	v_fma_f32 v143, v143, v71, v177
	v_fma_f32 v140, v140, v68, v172
	v_fma_f32 v141, v141, v69, v173
	v_fma_f32 v136, v136, v64, v222
	v_fma_f32 v137, v137, v65, v223
	v_fma_f32 v134, v134, v62, v168
	v_fma_f32 v135, v135, v63, v169
	v_fma_f32 v168, v130, v58, v170
	v_fma_f32 v169, v131, v59, v171
	v_fma_f32 v170, v128, v56, v226
	v_fma_f32 v171, v129, v57, v227
	v_cvt_pk_bf16_f32 v128, v140, v141
	v_cvt_pk_bf16_f32 v129, v142, v143
	v_fma_f32 v138, v138, v66, v178
	v_fma_f32 v139, v139, v67, v179
	v_cvt_pk_bf16_f32 v130, v136, v137
	v_lshlrev_b32_e32 v136, 16, v128
	v_cvt_pk_bf16_f32 v131, v138, v139
	global_store_dwordx4 v[208:209], v[128:131], off
	v_lshlrev_b32_e32 v137, 16, v129
	v_lshlrev_b32_e32 v138, 16, v130
	v_and_b32_e32 v128, 0xffff0000, v128
	v_and_b32_e32 v129, 0xffff0000, v129
	v_and_b32_e32 v130, 0xffff0000, v130
	v_mul_f32_e32 v128, v128, v128
	v_mul_f32_e32 v129, v129, v129
	v_fma_f32 v132, v132, v60, v224
	v_fma_f32 v133, v133, v61, v225
	v_lshlrev_b32_e32 v139, 16, v131
	v_and_b32_e32 v131, 0xffff0000, v131
	v_mul_f32_e32 v130, v130, v130
	v_fmac_f32_e32 v128, v136, v136
	v_fmac_f32_e32 v129, v137, v137
	v_cvt_pk_bf16_f32 v132, v132, v133
	v_mul_f32_e32 v131, v131, v131
	v_and_b32_e32 v141, 0xffff0000, v132
	v_fmac_f32_e32 v130, v138, v138
	v_add_f32_e32 v128, v128, v129
	v_cvt_pk_bf16_f32 v133, v134, v135
	v_lshlrev_b32_e32 v140, 16, v132
	v_and_b32_e32 v143, 0xffff0000, v133
	v_fmac_f32_e32 v131, v139, v139
	v_mul_f32_e32 v136, v141, v141
	v_add_f32_e32 v128, v128, v130
	v_cvt_pk_bf16_f32 v134, v170, v171
	v_cvt_pk_bf16_f32 v135, v168, v169
	v_lshlrev_b32_e32 v142, 16, v133
	v_and_b32_e32 v169, 0xffff0000, v134
	v_mul_f32_e32 v137, v143, v143
	v_fmac_f32_e32 v136, v140, v140
	v_add_f32_e32 v128, v128, v131
	v_lshlrev_b32_e32 v168, 16, v134
	v_mul_f32_e32 v138, v169, v169
	v_fmac_f32_e32 v137, v142, v142
	v_add_f32_e32 v128, v128, v136
	v_and_b32_e32 v129, 0xffff0000, v135
	v_lshlrev_b32_e32 v170, 16, v135
	v_fmac_f32_e32 v138, v168, v168
	v_add_f32_e32 v128, v128, v137
	v_mul_f32_e32 v129, v129, v129
	v_add_f32_e32 v128, v128, v138
	v_fmac_f32_e32 v129, v170, v170
	v_and_b32_e32 v130, 64, v213
	v_add_f32_e32 v129, v128, v129
	v_xor_b32_e32 v128, 16, v213
	v_add_u32_e32 v131, 64, v130
	v_cmp_lt_i32_e32 vcc, v128, v131
	global_store_dwordx4 v[208:209], v[132:135], off offset:256
	s_nop 0
	v_cndmask_b32_e32 v128, v213, v128, vcc
	v_lshlrev_b32_e32 v128, 2, v128
	ds_bpermute_b32 v130, v128, v129
	s_waitcnt lgkmcnt(0)
	v_add_f32_e32 v130, v129, v130
	v_xor_b32_e32 v129, 32, v213
	v_cmp_lt_i32_e32 vcc, v129, v131
	s_nop 1
	v_cndmask_b32_e32 v129, v213, v129, vcc
	v_lshlrev_b32_e32 v129, 2, v129
	ds_bpermute_b32 v131, v129, v130
	s_and_saveexec_b64 s[38:39], s[40:41]
	s_cbranch_execz .LBB0_1654
	v_lshlrev_b64 v[132:133], 6, v[194:195]
	v_lshl_add_u64 v[132:133], s[6:7], 0, v[132:133]
	v_lshl_add_u64 v[132:133], s[0:1], 2, v[132:133]
	s_lshl_b32 s16, s71, 2
	v_lshl_add_u64 v[132:133], v[132:133], 0, s[16:17]
	s_waitcnt lgkmcnt(0)
	v_add_f32_e32 v130, v130, v131
	global_store_dword v[132:133], v130, off
.LBB0_1654:
	s_or_b64 exec, exec, s[38:39]
	v_lshlrev_b32_e32 v130, 16, v164
	s_waitcnt lgkmcnt(0)
	v_and_b32_e32 v131, 0xffff0000, v164
	v_lshlrev_b32_e32 v134, 16, v166
	v_and_b32_e32 v135, 0xffff0000, v166
	v_lshlrev_b32_e32 v136, 16, v167
	v_and_b32_e32 v137, 0xffff0000, v167
	v_fma_f32 v124, v124, v68, v130
	v_fma_f32 v125, v125, v69, v131
	v_lshlrev_b32_e32 v132, 16, v165
	v_and_b32_e32 v133, 0xffff0000, v165
	v_fma_f32 v130, v122, v66, v136
	v_fma_f32 v131, v123, v67, v137
	v_fma_f32 v122, v120, v64, v134
	v_fma_f32 v123, v121, v65, v135
	v_cvt_pk_bf16_f32 v120, v124, v125
	v_lshl_add_u64 v[124:125], s[10:11], 0, v[206:207]
	v_fma_f32 v126, v126, v70, v132
	v_fma_f32 v127, v127, v71, v133
	v_lshl_add_u64 v[124:125], v[190:191], 1, v[124:125]
	v_cvt_pk_bf16_f32 v121, v126, v127
	v_cvt_pk_bf16_f32 v122, v122, v123
	v_cvt_pk_bf16_f32 v123, v130, v131
	global_store_dwordx4 v[124:125], v[120:123], off
	v_lshlrev_b32_e32 v126, 16, v120
	v_and_b32_e32 v127, 0xffff0000, v162
	v_and_b32_e32 v120, 0xffff0000, v120
	v_mul_f32_e32 v120, v120, v120
	v_fmac_f32_e32 v120, v126, v126
	v_lshlrev_b32_e32 v126, 16, v121
	v_and_b32_e32 v121, 0xffff0000, v121
	v_mul_f32_e32 v121, v121, v121
	v_fmac_f32_e32 v121, v126, v126
	v_add_f32_e32 v120, v120, v121
	v_lshlrev_b32_e32 v121, 16, v122
	v_and_b32_e32 v122, 0xffff0000, v122
	v_mul_f32_e32 v122, v122, v122
	v_fmac_f32_e32 v122, v121, v121
	v_add_f32_e32 v120, v120, v122
	v_and_b32_e32 v122, 0xffff0000, v123
	v_lshlrev_b32_e32 v121, 16, v123
	v_mul_f32_e32 v122, v122, v122
	v_fmac_f32_e32 v122, v121, v121
	v_add_f32_e32 v132, v120, v122
	v_lshlrev_b32_e32 v120, 16, v160
	v_and_b32_e32 v121, 0xffff0000, v160
	v_lshlrev_b32_e32 v126, 16, v162
	v_lshlrev_b32_e32 v122, 16, v161
	v_and_b32_e32 v123, 0xffff0000, v161
	v_lshlrev_b32_e32 v130, 16, v163
	v_and_b32_e32 v131, 0xffff0000, v163
	v_fma_f32 v116, v116, v60, v120
	v_fma_f32 v117, v117, v61, v121
	v_fma_f32 v112, v112, v56, v126
	v_fma_f32 v113, v113, v57, v127
	v_fma_f32 v118, v118, v62, v122
	v_fma_f32 v119, v119, v63, v123
	v_fma_f32 v120, v114, v58, v130
	v_fma_f32 v121, v115, v59, v131
	v_cvt_pk_bf16_f32 v114, v116, v117
	v_cvt_pk_bf16_f32 v115, v118, v119
	v_cvt_pk_bf16_f32 v116, v112, v113
	s_nop 0
	v_and_b32_e32 v113, 0xffff0000, v114
	v_lshlrev_b32_e32 v112, 16, v114
	v_mul_f32_e32 v113, v113, v113
	v_fmac_f32_e32 v113, v112, v112
	v_and_b32_e32 v118, 0xffff0000, v115
	v_add_f32_e32 v112, v132, v113
	v_lshlrev_b32_e32 v113, 16, v115
	v_mul_f32_e32 v118, v118, v118
	v_fmac_f32_e32 v118, v113, v113
	v_add_f32_e32 v112, v112, v118
	v_and_b32_e32 v118, 0xffff0000, v116
	v_lshlrev_b32_e32 v113, 16, v116
	v_mul_f32_e32 v118, v118, v118
	v_fmac_f32_e32 v118, v113, v113
	v_cvt_pk_bf16_f32 v117, v120, v121
	v_add_f32_e32 v112, v112, v118
	v_and_b32_e32 v118, 0xffff0000, v117
	v_lshlrev_b32_e32 v113, 16, v117
	v_mul_f32_e32 v118, v118, v118
	v_fmac_f32_e32 v118, v113, v113
	v_add_f32_e32 v112, v112, v118
	ds_bpermute_b32 v113, v128, v112
	global_store_dwordx4 v[124:125], v[114:117], off offset:256
	s_waitcnt lgkmcnt(0)
	v_add_f32_e32 v112, v112, v113
	ds_bpermute_b32 v113, v129, v112
	s_and_saveexec_b64 s[38:39], s[40:41]
	s_cbranch_execz .LBB0_1656
; __device__ __forceinline__ unsigned cvt_pk_bf16(float lo, float hi) { unsigned r; asm volatile("v_cvt_pk_bf16_f32 %0, %1, %2" : "=v"(r) : "v"(lo), "v"(hi)); return r; }
;     __device__ __forceinline__ void operator()(const f32x4 (&acc)[2][2][4][2], const Unit& u, int wr, int wc, int fr, int fq, int, PG8_LAS unsigned char*) const {
;     ...
;                 for (int bj = 0; bj < 2; ++bj) xw[m][bj] = *(const u32x4*)(xb + (size_t)(row0 + ai * HALF + m * 16) * 1024 + col0 + bj * HALF);
; #pragma unroll
;             for (int m = 0; m < 4; ++m) {
;                 const int row = row0 + ai * HALF + m * 16; const size_t off = (size_t)row * 1024 + col0;
;                 float s = 0.f;
; #pragma unroll
;                 for (int bj = 0; bj < 2; ++bj) {
;                     const u32x4 xv = xw[m][bj];
;                     const f32x4 xo0 = {__builtin_bit_cast(float, xv.x << 16), __builtin_bit_cast(float, xv.x & 0xffff0000u), __builtin_bit_cast(float, xv.y << 16), __builtin_bit_cast(float, xv.y & 0xffff0000u)};
;                     const f32x4 xo1 = {__builtin_bit_cast(float, xv.z << 16), __builtin_bit_cast(float, xv.z & 0xffff0000u), __builtin_bit_cast(float, xv.w << 16), __builtin_bit_cast(float, xv.w & 0xffff0000u)};
;                     const f32x4 o0 = xo0 + acc[ai][bj][m][0] * csv[bj][0], o1 = xo1 + acc[ai][bj][m][1] * csv[bj][1];
;                     u32x4 w; w.x = cvt_pk_bf16(o0[0], o0[1]); w.y = cvt_pk_bf16(o0[2], o0[3]); w.z = cvt_pk_bf16(o1[0], o1[1]); w.w = cvt_pk_bf16(o1[2], o1[3]);
;                     if (!dry) *(u32x4*)(xb + off + bj * HALF) = w;
; #pragma unroll
;                     for (int q = 0; q < 4; ++q) { const unsigned ww = w[q]; const float ra = __builtin_bit_cast(float, ww << 16), rb = __builtin_bit_cast(float, ww & 0xffff0000u); s += ra * ra + rb * rb; }
;                 }
;                 s += __shfl_xor(s, 16); s += __shfl_xor(s, 32);
;                 if (fq == 0 && !dry) ssq_next[(size_t)row * 16 + u.pn * 4 + wc] = s;
;             }
	v_lshlrev_b64 v[114:115], 6, v[202:203]
	v_lshl_add_u64 v[114:115], s[6:7], 0, v[114:115]
	v_lshl_add_u64 v[114:115], s[0:1], 2, v[114:115]
	s_lshl_b32 s16, s71, 2
	v_lshl_add_u64 v[114:115], v[114:115], 0, s[16:17]
	s_waitcnt lgkmcnt(0)
	v_add_f32_e32 v112, v112, v113
	global_store_dword v[114:115], v112, off
.LBB0_1656:
	s_or_b64 exec, exec, s[38:39]
	v_lshlrev_b32_e32 v112, 16, v156
	s_waitcnt lgkmcnt(0)
	v_and_b32_e32 v113, 0xffff0000, v156
	v_lshlrev_b32_e32 v116, 16, v158
	v_and_b32_e32 v117, 0xffff0000, v158
	v_lshlrev_b32_e32 v118, 16, v159
	v_and_b32_e32 v119, 0xffff0000, v159
	v_fma_f32 v108, v108, v68, v112
	v_fma_f32 v109, v109, v69, v113
	v_lshlrev_b32_e32 v114, 16, v157
	v_and_b32_e32 v115, 0xffff0000, v157
	v_fma_f32 v112, v106, v66, v118
	v_fma_f32 v113, v107, v67, v119
	v_fma_f32 v106, v104, v64, v116
	v_fma_f32 v107, v105, v65, v117
	v_cvt_pk_bf16_f32 v104, v108, v109
	v_lshl_add_u64 v[108:109], s[10:11], 0, v[204:205]
	v_fma_f32 v110, v110, v70, v114
	v_fma_f32 v111, v111, v71, v115
	v_lshl_add_u64 v[108:109], v[190:191], 1, v[108:109]
	v_cvt_pk_bf16_f32 v105, v110, v111
	v_cvt_pk_bf16_f32 v106, v106, v107
	v_cvt_pk_bf16_f32 v107, v112, v113
	global_store_dwordx4 v[108:109], v[104:107], off
	v_lshlrev_b32_e32 v110, 16, v104
	v_and_b32_e32 v111, 0xffff0000, v154
	v_and_b32_e32 v104, 0xffff0000, v104
	v_mul_f32_e32 v104, v104, v104
	v_fmac_f32_e32 v104, v110, v110
	v_lshlrev_b32_e32 v110, 16, v105
	v_and_b32_e32 v105, 0xffff0000, v105
	v_mul_f32_e32 v105, v105, v105
	v_fmac_f32_e32 v105, v110, v110
	v_add_f32_e32 v104, v104, v105
	v_lshlrev_b32_e32 v105, 16, v106
	v_and_b32_e32 v106, 0xffff0000, v106
	v_mul_f32_e32 v106, v106, v106
	v_fmac_f32_e32 v106, v105, v105
	v_add_f32_e32 v104, v104, v106
	v_and_b32_e32 v106, 0xffff0000, v107
	v_lshlrev_b32_e32 v105, 16, v107
	v_mul_f32_e32 v106, v106, v106
	v_fmac_f32_e32 v106, v105, v105
	v_add_f32_e32 v114, v104, v106
	v_lshlrev_b32_e32 v104, 16, v152
	v_and_b32_e32 v105, 0xffff0000, v152
	v_lshlrev_b32_e32 v110, 16, v154
	v_lshlrev_b32_e32 v106, 16, v153
	v_and_b32_e32 v107, 0xffff0000, v153
	v_lshlrev_b32_e32 v112, 16, v155
	v_and_b32_e32 v113, 0xffff0000, v155
	v_fma_f32 v100, v100, v60, v104
	v_fma_f32 v101, v101, v61, v105
	v_fma_f32 v96, v96, v56, v110
	v_fma_f32 v97, v97, v57, v111
	v_fma_f32 v102, v102, v62, v106
	v_fma_f32 v103, v103, v63, v107
	v_fma_f32 v104, v98, v58, v112
	v_fma_f32 v105, v99, v59, v113
	v_cvt_pk_bf16_f32 v98, v100, v101
	v_cvt_pk_bf16_f32 v99, v102, v103
	v_cvt_pk_bf16_f32 v100, v96, v97
	s_nop 0
	v_and_b32_e32 v97, 0xffff0000, v98
	v_lshlrev_b32_e32 v96, 16, v98
	v_mul_f32_e32 v97, v97, v97
	v_fmac_f32_e32 v97, v96, v96
	v_and_b32_e32 v102, 0xffff0000, v99
	v_add_f32_e32 v96, v114, v97
	v_lshlrev_b32_e32 v97, 16, v99
	v_mul_f32_e32 v102, v102, v102
	v_fmac_f32_e32 v102, v97, v97
	v_add_f32_e32 v96, v96, v102
	v_and_b32_e32 v102, 0xffff0000, v100
	v_lshlrev_b32_e32 v97, 16, v100
	v_mul_f32_e32 v102, v102, v102
	v_fmac_f32_e32 v102, v97, v97
	v_cvt_pk_bf16_f32 v101, v104, v105
	v_add_f32_e32 v96, v96, v102
	v_and_b32_e32 v102, 0xffff0000, v101
	v_lshlrev_b32_e32 v97, 16, v101
	v_mul_f32_e32 v102, v102, v102
	v_fmac_f32_e32 v102, v97, v97
	v_add_f32_e32 v96, v96, v102
	ds_bpermute_b32 v97, v128, v96
	global_store_dwordx4 v[108:109], v[98:101], off offset:256
	s_waitcnt lgkmcnt(0)
	v_add_f32_e32 v96, v96, v97
	ds_bpermute_b32 v97, v129, v96
	s_and_saveexec_b64 s[38:39], s[40:41]
	s_cbranch_execz .LBB0_1658
	v_lshlrev_b64 v[98:99], 6, v[200:201]
	v_lshl_add_u64 v[98:99], s[6:7], 0, v[98:99]
	v_lshl_add_u64 v[98:99], s[0:1], 2, v[98:99]
	s_lshl_b32 s16, s71, 2
	v_lshl_add_u64 v[98:99], v[98:99], 0, s[16:17]
	s_waitcnt lgkmcnt(0)
	v_add_f32_e32 v96, v96, v97
	global_store_dword v[98:99], v96, off
.LBB0_1658:
	s_or_b64 exec, exec, s[38:39]
	v_lshlrev_b32_e32 v96, 16, v148
	s_waitcnt lgkmcnt(0)
	v_and_b32_e32 v97, 0xffff0000, v148
	v_lshlrev_b32_e32 v100, 16, v150
	v_and_b32_e32 v101, 0xffff0000, v150
	v_lshlrev_b32_e32 v102, 16, v151
	v_and_b32_e32 v103, 0xffff0000, v151
	v_fma_f32 v92, v92, v68, v96
	v_fma_f32 v93, v93, v69, v97
	v_lshlrev_b32_e32 v98, 16, v149
	v_and_b32_e32 v99, 0xffff0000, v149
	v_fma_f32 v96, v90, v66, v102
	v_fma_f32 v97, v91, v67, v103
	v_fma_f32 v90, v88, v64, v100
	v_fma_f32 v91, v89, v65, v101
	v_cvt_pk_bf16_f32 v88, v92, v93
	v_lshl_add_u64 v[92:93], s[10:11], 0, v[198:199]
	v_fma_f32 v94, v94, v70, v98
	v_fma_f32 v95, v95, v71, v99
	v_lshl_add_u64 v[92:93], v[190:191], 1, v[92:93]
	v_cvt_pk_bf16_f32 v89, v94, v95
	v_cvt_pk_bf16_f32 v90, v90, v91
	v_cvt_pk_bf16_f32 v91, v96, v97
	global_store_dwordx4 v[92:93], v[88:91], off
	v_lshlrev_b32_e32 v94, 16, v88
	v_and_b32_e32 v95, 0xffff0000, v146
	v_and_b32_e32 v88, 0xffff0000, v88
	v_mul_f32_e32 v88, v88, v88
	v_fmac_f32_e32 v88, v94, v94
	v_lshlrev_b32_e32 v94, 16, v89
	v_and_b32_e32 v89, 0xffff0000, v89
	v_mul_f32_e32 v89, v89, v89
	v_fmac_f32_e32 v89, v94, v94
	v_add_f32_e32 v88, v88, v89
	v_lshlrev_b32_e32 v89, 16, v90
	v_and_b32_e32 v90, 0xffff0000, v90
	v_mul_f32_e32 v90, v90, v90
	v_fmac_f32_e32 v90, v89, v89
	v_add_f32_e32 v88, v88, v90
	v_and_b32_e32 v90, 0xffff0000, v91
	v_lshlrev_b32_e32 v89, 16, v91
	v_mul_f32_e32 v90, v90, v90
	v_fmac_f32_e32 v90, v89, v89
	v_add_f32_e32 v98, v88, v90
	v_lshlrev_b32_e32 v88, 16, v144
	v_and_b32_e32 v89, 0xffff0000, v144
	v_lshlrev_b32_e32 v94, 16, v146
	v_lshlrev_b32_e32 v90, 16, v145
	v_and_b32_e32 v91, 0xffff0000, v145
	v_lshlrev_b32_e32 v96, 16, v147
	v_and_b32_e32 v97, 0xffff0000, v147
	v_fma_f32 v84, v84, v60, v88
	v_fma_f32 v85, v85, v61, v89
	v_fma_f32 v80, v80, v56, v94
	v_fma_f32 v81, v81, v57, v95
	v_fma_f32 v86, v86, v62, v90
	v_fma_f32 v87, v87, v63, v91
	v_fma_f32 v88, v82, v58, v96
	v_fma_f32 v89, v83, v59, v97
	v_cvt_pk_bf16_f32 v82, v84, v85
	v_cvt_pk_bf16_f32 v83, v86, v87
	v_cvt_pk_bf16_f32 v84, v80, v81
	s_nop 0
	v_and_b32_e32 v81, 0xffff0000, v82
	v_lshlrev_b32_e32 v80, 16, v82
	v_mul_f32_e32 v81, v81, v81
	v_fmac_f32_e32 v81, v80, v80
	v_and_b32_e32 v86, 0xffff0000, v83
	v_add_f32_e32 v80, v98, v81
	v_lshlrev_b32_e32 v81, 16, v83
	v_mul_f32_e32 v86, v86, v86
	v_fmac_f32_e32 v86, v81, v81
	v_add_f32_e32 v80, v80, v86
	v_and_b32_e32 v86, 0xffff0000, v84
	v_lshlrev_b32_e32 v81, 16, v84
	v_mul_f32_e32 v86, v86, v86
	v_fmac_f32_e32 v86, v81, v81
	v_cvt_pk_bf16_f32 v85, v88, v89
	v_add_f32_e32 v80, v80, v86
	v_and_b32_e32 v86, 0xffff0000, v85
	v_lshlrev_b32_e32 v81, 16, v85
	v_mul_f32_e32 v86, v86, v86
	v_fmac_f32_e32 v86, v81, v81
	v_add_f32_e32 v80, v80, v86
	ds_bpermute_b32 v81, v128, v80
	global_store_dwordx4 v[92:93], v[82:85], off offset:256
	s_waitcnt lgkmcnt(0)
	v_add_f32_e32 v80, v80, v81
	ds_bpermute_b32 v81, v129, v80
	s_and_saveexec_b64 s[38:39], s[40:41]
	s_cbranch_execz .LBB0_1660
	v_lshlrev_b64 v[82:83], 6, v[196:197]
	v_lshl_add_u64 v[82:83], s[6:7], 0, v[82:83]
	v_lshl_add_u64 v[82:83], s[0:1], 2, v[82:83]
	s_lshl_b32 s16, s71, 2
	v_lshl_add_u64 v[82:83], v[82:83], 0, s[16:17]
	s_waitcnt lgkmcnt(0)
	v_add_f32_e32 v80, v80, v81
	global_store_dword v[82:83], v80, off
; __device__ __forceinline__ unsigned cvt_pk_bf16(float lo, float hi) { unsigned r; asm volatile("v_cvt_pk_bf16_f32 %0, %1, %2" : "=v"(r) : "v"(lo), "v"(hi)); return r; }
;     __device__ __forceinline__ void operator()(const f32x4 (&acc)[2][2][4][2], const Unit& u, int wr, int wc, int fr, int fq, int, PG8_LAS unsigned char*) const {
;     ...
;         for (int ai = 0; ai < 2; ++ai) {
;             u32x4 xw[4][2];
; #pragma unroll
;             for (int m = 0; m < 4; ++m)
; #pragma unroll
;                 for (int bj = 0; bj < 2; ++bj) xw[m][bj] = *(const u32x4*)(xb + (size_t)(row0 + ai * HALF + m * 16) * 1024 + col0 + bj * HALF);
; #pragma unroll
;             for (int m = 0; m < 4; ++m) {
;                 const int row = row0 + ai * HALF + m * 16; const size_t off = (size_t)row * 1024 + col0;
;                 float s = 0.f;
; #pragma unroll
;                 for (int bj = 0; bj < 2; ++bj) {
;                     const u32x4 xv = xw[m][bj];
;                     const f32x4 xo0 = {__builtin_bit_cast(float, xv.x << 16), __builtin_bit_cast(float, xv.x & 0xffff0000u), __builtin_bit_cast(float, xv.y << 16), __builtin_bit_cast(float, xv.y & 0xffff0000u)};
;                     const f32x4 xo1 = {__builtin_bit_cast(float, xv.z << 16), __builtin_bit_cast(float, xv.z & 0xffff0000u), __builtin_bit_cast(float, xv.w << 16), __builtin_bit_cast(float, xv.w & 0xffff0000u)};
;                     const f32x4 o0 = xo0 + acc[ai][bj][m][0] * csv[bj][0], o1 = xo1 + acc[ai][bj][m][1] * csv[bj][1];
;                     u32x4 w; w.x = cvt_pk_bf16(o0[0], o0[1]); w.y = cvt_pk_bf16(o0[2], o0[3]); w.z = cvt_pk_bf16(o1[0], o1[1]); w.w = cvt_pk_bf16(o1[2], o1[3]);
;                     if (!dry) *(u32x4*)(xb + off + bj * HALF) = w;
; #pragma unroll
;                     for (int q = 0; q < 4; ++q) { const unsigned ww = w[q]; const float ra = __builtin_bit_cast(float, ww << 16), rb = __builtin_bit_cast(float, ww & 0xffff0000u); s += ra * ra + rb * rb; }
;                 }
;                 s += __shfl_xor(s, 16); s += __shfl_xor(s, 32);
;                 if (fq == 0 && !dry) ssq_next[(size_t)row * 16 + u.pn * 4 + wc] = s;
;             }
.LBB0_1660:
	s_or_b64 exec, exec, s[38:39]
	v_add_u32_e32 v120, 0x80, v194
	v_ashrrev_i32_e32 v121, 31, v120
	v_lshlrev_b64 v[126:127], 11, v[120:121]
	s_waitcnt lgkmcnt(0)
	v_lshl_add_u64 v[80:81], v[192:193], 0, v[126:127]
	global_load_dwordx4 v[122:125], v[80:81], off
	global_load_dwordx4 v[104:107], v[80:81], off offset:256
	v_add_u32_e32 v116, 0x90, v194
	v_ashrrev_i32_e32 v117, 31, v116
	v_add_u32_e32 v112, 0xa0, v194
	v_lshlrev_b64 v[118:119], 11, v[116:117]
	v_ashrrev_i32_e32 v113, 31, v112
	v_add_u32_e32 v108, 0xb0, v194
	v_lshl_add_u64 v[80:81], v[192:193], 0, v[118:119]
	v_lshlrev_b64 v[114:115], 11, v[112:113]
	v_ashrrev_i32_e32 v109, 31, v108
	global_load_dwordx4 v[100:103], v[80:81], off
	global_load_dwordx4 v[96:99], v[80:81], off offset:256
	v_lshl_add_u64 v[80:81], v[192:193], 0, v[114:115]
	v_lshlrev_b64 v[110:111], 11, v[108:109]
	global_load_dwordx4 v[92:95], v[80:81], off
	global_load_dwordx4 v[88:91], v[80:81], off offset:256
	v_lshl_add_u64 v[80:81], v[192:193], 0, v[110:111]
	global_load_dwordx4 v[84:87], v[80:81], off
	s_nop 0
	global_load_dwordx4 v[80:83], v[80:81], off offset:256
	s_waitcnt vmcnt(7)
	v_lshlrev_b32_e32 v130, 16, v122
	v_and_b32_e32 v131, 0xffff0000, v122
	v_lshlrev_b32_e32 v122, 16, v123
	v_and_b32_e32 v123, 0xffff0000, v123
	v_lshlrev_b32_e32 v132, 16, v124
	v_and_b32_e32 v133, 0xffff0000, v124
	v_lshlrev_b32_e32 v124, 16, v125
	v_and_b32_e32 v125, 0xffff0000, v125
	v_fma_f32 v76, v76, v68, v130
	v_fma_f32 v77, v77, v69, v131
	v_fma_f32 v78, v78, v70, v122
	v_fma_f32 v79, v79, v71, v123
	v_fma_f32 v122, v74, v66, v124
	v_fma_f32 v123, v75, v67, v125
	v_fma_f32 v74, v72, v64, v132
	v_fma_f32 v75, v73, v65, v133
	v_cvt_pk_bf16_f32 v72, v76, v77
	v_lshl_add_u64 v[76:77], s[10:11], 0, v[126:127]
	v_lshl_add_u64 v[76:77], v[190:191], 1, v[76:77]
	v_cvt_pk_bf16_f32 v73, v78, v79
	v_cvt_pk_bf16_f32 v74, v74, v75
	v_cvt_pk_bf16_f32 v75, v122, v123
	global_store_dwordx4 v[76:77], v[72:75], off
	v_lshlrev_b32_e32 v78, 16, v72
	s_waitcnt vmcnt(7)
	v_and_b32_e32 v79, 0xffff0000, v106
	v_and_b32_e32 v72, 0xffff0000, v72
	v_mul_f32_e32 v72, v72, v72
	v_fmac_f32_e32 v72, v78, v78
	v_lshlrev_b32_e32 v78, 16, v73
	v_and_b32_e32 v73, 0xffff0000, v73
	v_mul_f32_e32 v73, v73, v73
	v_fmac_f32_e32 v73, v78, v78
	v_add_f32_e32 v72, v72, v73
	v_lshlrev_b32_e32 v73, 16, v74
	v_and_b32_e32 v74, 0xffff0000, v74
	v_mul_f32_e32 v74, v74, v74
	v_fmac_f32_e32 v74, v73, v73
	v_add_f32_e32 v72, v72, v74
	v_and_b32_e32 v74, 0xffff0000, v75
	v_lshlrev_b32_e32 v73, 16, v75
	v_mul_f32_e32 v74, v74, v74
	v_fmac_f32_e32 v74, v73, v73
	v_add_f32_e32 v122, v72, v74
	v_lshlrev_b32_e32 v72, 16, v104
	v_and_b32_e32 v73, 0xffff0000, v104
	v_lshlrev_b32_e32 v74, 16, v105
	v_and_b32_e32 v75, 0xffff0000, v105
	v_lshlrev_b32_e32 v78, 16, v106
	v_lshlrev_b32_e32 v104, 16, v107
	v_and_b32_e32 v105, 0xffff0000, v107
	v_fma_f32 v52, v52, v60, v72
	v_fma_f32 v53, v53, v61, v73
	v_fma_f32 v72, v50, v58, v104
	v_fma_f32 v73, v51, v59, v105
	v_fma_f32 v50, v48, v56, v78
	v_fma_f32 v51, v49, v57, v79
	v_cvt_pk_bf16_f32 v48, v52, v53
	v_fma_f32 v54, v54, v62, v74
	v_fma_f32 v55, v55, v63, v75
	v_lshlrev_b32_e32 v52, 16, v48
	v_cvt_pk_bf16_f32 v49, v54, v55
	v_cvt_pk_bf16_f32 v50, v50, v51
	v_cvt_pk_bf16_f32 v51, v72, v73
	global_store_dwordx4 v[76:77], v[48:51], off offset:256
	s_nop 1
	v_and_b32_e32 v48, 0xffff0000, v48
	v_mul_f32_e32 v48, v48, v48
	v_fmac_f32_e32 v48, v52, v52
	v_lshlrev_b32_e32 v52, 16, v49
	v_and_b32_e32 v49, 0xffff0000, v49
	v_mul_f32_e32 v49, v49, v49
	v_add_f32_e32 v48, v122, v48
	v_fmac_f32_e32 v49, v52, v52
	v_add_f32_e32 v48, v48, v49
	v_lshlrev_b32_e32 v49, 16, v50
	v_and_b32_e32 v50, 0xffff0000, v50
	v_mul_f32_e32 v50, v50, v50
	v_fmac_f32_e32 v50, v49, v49
	v_add_f32_e32 v48, v48, v50
	v_and_b32_e32 v50, 0xffff0000, v51
	v_lshlrev_b32_e32 v49, 16, v51
	v_mul_f32_e32 v50, v50, v50
	v_fmac_f32_e32 v50, v49, v49
	v_add_f32_e32 v48, v48, v50
	ds_bpermute_b32 v49, v128, v48
	s_waitcnt lgkmcnt(0)
	v_add_f32_e32 v48, v48, v49
	ds_bpermute_b32 v49, v129, v48
	s_and_saveexec_b64 s[38:39], s[40:41]
	s_cbranch_execz .LBB0_1662
	v_lshlrev_b64 v[50:51], 6, v[120:121]
	v_lshl_add_u64 v[50:51], s[6:7], 0, v[50:51]
	v_lshl_add_u64 v[50:51], s[0:1], 2, v[50:51]
	s_lshl_b32 s16, s71, 2
	v_lshl_add_u64 v[50:51], v[50:51], 0, s[16:17]
	s_waitcnt lgkmcnt(0)
	v_add_f32_e32 v48, v48, v49
	global_store_dword v[50:51], v48, off
; __device__ __forceinline__ unsigned cvt_pk_bf16(float lo, float hi) { unsigned r; asm volatile("v_cvt_pk_bf16_f32 %0, %1, %2" : "=v"(r) : "v"(lo), "v"(hi)); return r; }
;     __device__ __forceinline__ void operator()(const f32x4 (&acc)[2][2][4][2], const Unit& u, int wr, int wc, int fr, int fq, int, PG8_LAS unsigned char*) const {
;     ...
;                 for (int bj = 0; bj < 2; ++bj) xw[m][bj] = *(const u32x4*)(xb + (size_t)(row0 + ai * HALF + m * 16) * 1024 + col0 + bj * HALF);
; #pragma unroll
;             for (int m = 0; m < 4; ++m) {
;                 const int row = row0 + ai * HALF + m * 16; const size_t off = (size_t)row * 1024 + col0;
;                 float s = 0.f;
; #pragma unroll
;                 for (int bj = 0; bj < 2; ++bj) {
;                     const u32x4 xv = xw[m][bj];
;                     const f32x4 xo0 = {__builtin_bit_cast(float, xv.x << 16), __builtin_bit_cast(float, xv.x & 0xffff0000u), __builtin_bit_cast(float, xv.y << 16), __builtin_bit_cast(float, xv.y & 0xffff0000u)};
;                     const f32x4 xo1 = {__builtin_bit_cast(float, xv.z << 16), __builtin_bit_cast(float, xv.z & 0xffff0000u), __builtin_bit_cast(float, xv.w << 16), __builtin_bit_cast(float, xv.w & 0xffff0000u)};
;                     const f32x4 o0 = xo0 + acc[ai][bj][m][0] * csv[bj][0], o1 = xo1 + acc[ai][bj][m][1] * csv[bj][1];
;                     u32x4 w; w.x = cvt_pk_bf16(o0[0], o0[1]); w.y = cvt_pk_bf16(o0[2], o0[3]); w.z = cvt_pk_bf16(o1[0], o1[1]); w.w = cvt_pk_bf16(o1[2], o1[3]);
;                     if (!dry) *(u32x4*)(xb + off + bj * HALF) = w;
; #pragma unroll
;                     for (int q = 0; q < 4; ++q) { const unsigned ww = w[q]; const float ra = __builtin_bit_cast(float, ww << 16), rb = __builtin_bit_cast(float, ww & 0xffff0000u); s += ra * ra + rb * rb; }
;                 }
;                 s += __shfl_xor(s, 16); s += __shfl_xor(s, 32);
;                 if (fq == 0 && !dry) ssq_next[(size_t)row * 16 + u.pn * 4 + wc] = s;
;             }
.LBB0_1662:
	s_or_b64 exec, exec, s[38:39]
	s_waitcnt vmcnt(7)
	v_lshlrev_b32_e32 v48, 16, v100
	s_waitcnt lgkmcnt(0)
	v_and_b32_e32 v49, 0xffff0000, v100
	v_lshlrev_b32_e32 v52, 16, v102
	v_and_b32_e32 v53, 0xffff0000, v102
	v_lshlrev_b32_e32 v54, 16, v103
	v_and_b32_e32 v55, 0xffff0000, v103
	v_fma_f32 v44, v44, v68, v48
	v_fma_f32 v45, v45, v69, v49
	v_lshlrev_b32_e32 v50, 16, v101
	v_and_b32_e32 v51, 0xffff0000, v101
	v_fma_f32 v48, v42, v66, v54
	v_fma_f32 v49, v43, v67, v55
	v_fma_f32 v42, v40, v64, v52
	v_fma_f32 v43, v41, v65, v53
	v_cvt_pk_bf16_f32 v40, v44, v45
	v_lshl_add_u64 v[44:45], s[10:11], 0, v[118:119]
	v_fma_f32 v46, v46, v70, v50
	v_fma_f32 v47, v47, v71, v51
	v_lshl_add_u64 v[44:45], v[190:191], 1, v[44:45]
	v_cvt_pk_bf16_f32 v41, v46, v47
	v_cvt_pk_bf16_f32 v42, v42, v43
	v_cvt_pk_bf16_f32 v43, v48, v49
	global_store_dwordx4 v[44:45], v[40:43], off
	v_lshlrev_b32_e32 v46, 16, v40
	s_waitcnt vmcnt(7)
	v_and_b32_e32 v47, 0xffff0000, v98
	v_and_b32_e32 v40, 0xffff0000, v40
	v_mul_f32_e32 v40, v40, v40
	v_fmac_f32_e32 v40, v46, v46
	v_lshlrev_b32_e32 v46, 16, v41
	v_and_b32_e32 v41, 0xffff0000, v41
	v_mul_f32_e32 v41, v41, v41
	v_fmac_f32_e32 v41, v46, v46
	v_add_f32_e32 v40, v40, v41
	v_lshlrev_b32_e32 v41, 16, v42
	v_and_b32_e32 v42, 0xffff0000, v42
	v_mul_f32_e32 v42, v42, v42
	v_fmac_f32_e32 v42, v41, v41
	v_add_f32_e32 v40, v40, v42
	v_and_b32_e32 v42, 0xffff0000, v43
	v_lshlrev_b32_e32 v41, 16, v43
	v_mul_f32_e32 v42, v42, v42
	v_fmac_f32_e32 v42, v41, v41
	v_add_f32_e32 v50, v40, v42
	v_lshlrev_b32_e32 v40, 16, v96
	v_and_b32_e32 v41, 0xffff0000, v96
	v_lshlrev_b32_e32 v46, 16, v98
	v_lshlrev_b32_e32 v42, 16, v97
	v_and_b32_e32 v43, 0xffff0000, v97
	v_lshlrev_b32_e32 v48, 16, v99
	v_and_b32_e32 v49, 0xffff0000, v99
	v_fma_f32 v36, v36, v60, v40
	v_fma_f32 v37, v37, v61, v41
	v_fma_f32 v32, v32, v56, v46
	v_fma_f32 v33, v33, v57, v47
	v_fma_f32 v38, v38, v62, v42
	v_fma_f32 v39, v39, v63, v43
	v_fma_f32 v40, v34, v58, v48
	v_fma_f32 v41, v35, v59, v49
	v_cvt_pk_bf16_f32 v34, v36, v37
	v_cvt_pk_bf16_f32 v35, v38, v39
	v_cvt_pk_bf16_f32 v36, v32, v33
	s_nop 0
	v_and_b32_e32 v33, 0xffff0000, v34
	v_lshlrev_b32_e32 v32, 16, v34
	v_mul_f32_e32 v33, v33, v33
	v_fmac_f32_e32 v33, v32, v32
	v_and_b32_e32 v38, 0xffff0000, v35
	v_add_f32_e32 v32, v50, v33
	v_lshlrev_b32_e32 v33, 16, v35
	v_mul_f32_e32 v38, v38, v38
	v_fmac_f32_e32 v38, v33, v33
	v_add_f32_e32 v32, v32, v38
	v_and_b32_e32 v38, 0xffff0000, v36
	v_lshlrev_b32_e32 v33, 16, v36
	v_mul_f32_e32 v38, v38, v38
	v_fmac_f32_e32 v38, v33, v33
	v_cvt_pk_bf16_f32 v37, v40, v41
	v_add_f32_e32 v32, v32, v38
	v_and_b32_e32 v38, 0xffff0000, v37
	v_lshlrev_b32_e32 v33, 16, v37
	v_mul_f32_e32 v38, v38, v38
	v_fmac_f32_e32 v38, v33, v33
	v_add_f32_e32 v32, v32, v38
	ds_bpermute_b32 v33, v128, v32
	global_store_dwordx4 v[44:45], v[34:37], off offset:256
	s_waitcnt lgkmcnt(0)
	v_add_f32_e32 v32, v32, v33
	ds_bpermute_b32 v33, v129, v32
	s_and_saveexec_b64 s[38:39], s[40:41]
	s_cbranch_execz .LBB0_1664
	v_lshlrev_b64 v[34:35], 6, v[116:117]
	v_lshl_add_u64 v[34:35], s[6:7], 0, v[34:35]
	v_lshl_add_u64 v[34:35], s[0:1], 2, v[34:35]
	s_lshl_b32 s16, s71, 2
	v_lshl_add_u64 v[34:35], v[34:35], 0, s[16:17]
	s_waitcnt lgkmcnt(0)
	v_add_f32_e32 v32, v32, v33
	global_store_dword v[34:35], v32, off
; __device__ __forceinline__ unsigned cvt_pk_bf16(float lo, float hi) { unsigned r; asm volatile("v_cvt_pk_bf16_f32 %0, %1, %2" : "=v"(r) : "v"(lo), "v"(hi)); return r; }
;     __device__ __forceinline__ void operator()(const f32x4 (&acc)[2][2][4][2], const Unit& u, int wr, int wc, int fr, int fq, int, PG8_LAS unsigned char*) const {
;     ...
;                 for (int bj = 0; bj < 2; ++bj) xw[m][bj] = *(const u32x4*)(xb + (size_t)(row0 + ai * HALF + m * 16) * 1024 + col0 + bj * HALF);
; #pragma unroll
;             for (int m = 0; m < 4; ++m) {
;                 const int row = row0 + ai * HALF + m * 16; const size_t off = (size_t)row * 1024 + col0;
;                 float s = 0.f;
; #pragma unroll
;                 for (int bj = 0; bj < 2; ++bj) {
;                     const u32x4 xv = xw[m][bj];
;                     const f32x4 xo0 = {__builtin_bit_cast(float, xv.x << 16), __builtin_bit_cast(float, xv.x & 0xffff0000u), __builtin_bit_cast(float, xv.y << 16), __builtin_bit_cast(float, xv.y & 0xffff0000u)};
;                     const f32x4 xo1 = {__builtin_bit_cast(float, xv.z << 16), __builtin_bit_cast(float, xv.z & 0xffff0000u), __builtin_bit_cast(float, xv.w << 16), __builtin_bit_cast(float, xv.w & 0xffff0000u)};
;                     const f32x4 o0 = xo0 + acc[ai][bj][m][0] * csv[bj][0], o1 = xo1 + acc[ai][bj][m][1] * csv[bj][1];
;                     u32x4 w; w.x = cvt_pk_bf16(o0[0], o0[1]); w.y = cvt_pk_bf16(o0[2], o0[3]); w.z = cvt_pk_bf16(o1[0], o1[1]); w.w = cvt_pk_bf16(o1[2], o1[3]);
;                     if (!dry) *(u32x4*)(xb + off + bj * HALF) = w;
; #pragma unroll
;                     for (int q = 0; q < 4; ++q) { const unsigned ww = w[q]; const float ra = __builtin_bit_cast(float, ww << 16), rb = __builtin_bit_cast(float, ww & 0xffff0000u); s += ra * ra + rb * rb; }
;                 }
;                 s += __shfl_xor(s, 16); s += __shfl_xor(s, 32);
;                 if (fq == 0 && !dry) ssq_next[(size_t)row * 16 + u.pn * 4 + wc] = s;
;             }
.LBB0_1664:
	s_or_b64 exec, exec, s[38:39]
	s_waitcnt vmcnt(7)
	v_lshlrev_b32_e32 v32, 16, v92
	s_waitcnt lgkmcnt(0)
	v_and_b32_e32 v33, 0xffff0000, v92
	v_lshlrev_b32_e32 v36, 16, v94
	v_and_b32_e32 v37, 0xffff0000, v94
	v_lshlrev_b32_e32 v38, 16, v95
	v_and_b32_e32 v39, 0xffff0000, v95
	v_fma_f32 v28, v28, v68, v32
	v_fma_f32 v29, v29, v69, v33
	v_lshlrev_b32_e32 v34, 16, v93
	v_and_b32_e32 v35, 0xffff0000, v93
	v_fma_f32 v32, v26, v66, v38
	v_fma_f32 v33, v27, v67, v39
	v_fma_f32 v26, v24, v64, v36
	v_fma_f32 v27, v25, v65, v37
	v_cvt_pk_bf16_f32 v24, v28, v29
	v_lshl_add_u64 v[28:29], s[10:11], 0, v[114:115]
	v_fma_f32 v30, v30, v70, v34
	v_fma_f32 v31, v31, v71, v35
	v_lshl_add_u64 v[28:29], v[190:191], 1, v[28:29]
	v_cvt_pk_bf16_f32 v25, v30, v31
	v_cvt_pk_bf16_f32 v26, v26, v27
	v_cvt_pk_bf16_f32 v27, v32, v33
	global_store_dwordx4 v[28:29], v[24:27], off
	v_lshlrev_b32_e32 v30, 16, v24
	s_waitcnt vmcnt(7)
	v_and_b32_e32 v31, 0xffff0000, v90
	v_and_b32_e32 v24, 0xffff0000, v24
	v_mul_f32_e32 v24, v24, v24
	v_fmac_f32_e32 v24, v30, v30
	v_lshlrev_b32_e32 v30, 16, v25
	v_and_b32_e32 v25, 0xffff0000, v25
	v_mul_f32_e32 v25, v25, v25
	v_fmac_f32_e32 v25, v30, v30
	v_add_f32_e32 v24, v24, v25
	v_lshlrev_b32_e32 v25, 16, v26
	v_and_b32_e32 v26, 0xffff0000, v26
	v_mul_f32_e32 v26, v26, v26
	v_fmac_f32_e32 v26, v25, v25
	v_add_f32_e32 v24, v24, v26
	v_and_b32_e32 v26, 0xffff0000, v27
	v_lshlrev_b32_e32 v25, 16, v27
	v_mul_f32_e32 v26, v26, v26
	v_fmac_f32_e32 v26, v25, v25
	v_add_f32_e32 v34, v24, v26
	v_lshlrev_b32_e32 v24, 16, v88
	v_and_b32_e32 v25, 0xffff0000, v88
	v_lshlrev_b32_e32 v30, 16, v90
	v_lshlrev_b32_e32 v26, 16, v89
	v_and_b32_e32 v27, 0xffff0000, v89
	v_lshlrev_b32_e32 v32, 16, v91
	v_and_b32_e32 v33, 0xffff0000, v91
	v_fma_f32 v20, v20, v60, v24
	v_fma_f32 v21, v21, v61, v25
	v_fma_f32 v16, v16, v56, v30
	v_fma_f32 v17, v17, v57, v31
	v_fma_f32 v22, v22, v62, v26
	v_fma_f32 v23, v23, v63, v27
	v_fma_f32 v24, v18, v58, v32
	v_fma_f32 v25, v19, v59, v33
	v_cvt_pk_bf16_f32 v18, v20, v21
	v_cvt_pk_bf16_f32 v19, v22, v23
	v_cvt_pk_bf16_f32 v20, v16, v17
	s_nop 0
	v_and_b32_e32 v17, 0xffff0000, v18
	v_lshlrev_b32_e32 v16, 16, v18
	v_mul_f32_e32 v17, v17, v17
	v_fmac_f32_e32 v17, v16, v16
	v_and_b32_e32 v22, 0xffff0000, v19
	v_add_f32_e32 v16, v34, v17
	v_lshlrev_b32_e32 v17, 16, v19
	v_mul_f32_e32 v22, v22, v22
	v_fmac_f32_e32 v22, v17, v17
	v_add_f32_e32 v16, v16, v22
	v_and_b32_e32 v22, 0xffff0000, v20
	v_lshlrev_b32_e32 v17, 16, v20
	v_mul_f32_e32 v22, v22, v22
	v_fmac_f32_e32 v22, v17, v17
	v_cvt_pk_bf16_f32 v21, v24, v25
	v_add_f32_e32 v16, v16, v22
	v_and_b32_e32 v22, 0xffff0000, v21
	v_lshlrev_b32_e32 v17, 16, v21
	v_mul_f32_e32 v22, v22, v22
	v_fmac_f32_e32 v22, v17, v17
	v_add_f32_e32 v16, v16, v22
	ds_bpermute_b32 v17, v128, v16
	global_store_dwordx4 v[28:29], v[18:21], off offset:256
	s_waitcnt lgkmcnt(0)
	v_add_f32_e32 v16, v16, v17
	ds_bpermute_b32 v17, v129, v16
	s_and_saveexec_b64 s[38:39], s[40:41]
	s_cbranch_execz .LBB0_1666
	v_lshlrev_b64 v[18:19], 6, v[112:113]
	v_lshl_add_u64 v[18:19], s[6:7], 0, v[18:19]
	v_lshl_add_u64 v[18:19], s[0:1], 2, v[18:19]
	s_lshl_b32 s16, s71, 2
	v_lshl_add_u64 v[18:19], v[18:19], 0, s[16:17]
	s_waitcnt lgkmcnt(0)
	v_add_f32_e32 v16, v16, v17
	global_store_dword v[18:19], v16, off
.LBB0_1666:
	s_or_b64 exec, exec, s[38:39]
	s_waitcnt vmcnt(7)
	v_lshlrev_b32_e32 v16, 16, v84
	s_waitcnt lgkmcnt(0)
	v_and_b32_e32 v17, 0xffff0000, v84
	v_lshlrev_b32_e32 v20, 16, v86
	v_and_b32_e32 v21, 0xffff0000, v86
	v_lshlrev_b32_e32 v22, 16, v87
	v_and_b32_e32 v23, 0xffff0000, v87
	v_fma_f32 v12, v12, v68, v16
	v_fma_f32 v13, v13, v69, v17
	v_lshlrev_b32_e32 v18, 16, v85
	v_and_b32_e32 v19, 0xffff0000, v85
	v_fma_f32 v16, v10, v66, v22
	v_fma_f32 v17, v11, v67, v23
	v_fma_f32 v10, v8, v64, v20
	v_fma_f32 v11, v9, v65, v21
	v_cvt_pk_bf16_f32 v8, v12, v13
	v_lshl_add_u64 v[12:13], s[10:11], 0, v[110:111]
	v_fma_f32 v14, v14, v70, v18
	v_fma_f32 v15, v15, v71, v19
	v_lshl_add_u64 v[12:13], v[190:191], 1, v[12:13]
	v_cvt_pk_bf16_f32 v9, v14, v15
	v_cvt_pk_bf16_f32 v10, v10, v11
	v_cvt_pk_bf16_f32 v11, v16, v17
	global_store_dwordx4 v[12:13], v[8:11], off
	v_lshlrev_b32_e32 v14, 16, v8
	s_waitcnt vmcnt(7)
	v_and_b32_e32 v15, 0xffff0000, v82
	v_and_b32_e32 v8, 0xffff0000, v8
	v_mul_f32_e32 v8, v8, v8
	v_fmac_f32_e32 v8, v14, v14
	v_lshlrev_b32_e32 v14, 16, v9
	v_and_b32_e32 v9, 0xffff0000, v9
	v_mul_f32_e32 v9, v9, v9
	v_fmac_f32_e32 v9, v14, v14
	v_add_f32_e32 v8, v8, v9
	v_lshlrev_b32_e32 v9, 16, v10
	v_and_b32_e32 v10, 0xffff0000, v10
	v_mul_f32_e32 v10, v10, v10
	v_fmac_f32_e32 v10, v9, v9
	v_add_f32_e32 v8, v8, v10
	v_and_b32_e32 v10, 0xffff0000, v11
	v_lshlrev_b32_e32 v9, 16, v11
	v_mul_f32_e32 v10, v10, v10
	v_fmac_f32_e32 v10, v9, v9
	v_add_f32_e32 v18, v8, v10
	v_lshlrev_b32_e32 v8, 16, v80
	v_and_b32_e32 v9, 0xffff0000, v80
	v_lshlrev_b32_e32 v14, 16, v82
	v_lshlrev_b32_e32 v10, 16, v81
	v_and_b32_e32 v11, 0xffff0000, v81
	v_lshlrev_b32_e32 v16, 16, v83
	v_and_b32_e32 v17, 0xffff0000, v83
	v_fma_f32 v4, v4, v60, v8
	v_fma_f32 v5, v5, v61, v9
	v_fma_f32 v0, v0, v56, v14
	v_fma_f32 v1, v1, v57, v15
	v_fma_f32 v6, v6, v62, v10
	v_fma_f32 v7, v7, v63, v11
	v_fma_f32 v8, v2, v58, v16
	v_fma_f32 v9, v3, v59, v17
	v_cvt_pk_bf16_f32 v2, v4, v5
	v_cvt_pk_bf16_f32 v3, v6, v7
	v_cvt_pk_bf16_f32 v4, v0, v1
	s_nop 0
	v_and_b32_e32 v1, 0xffff0000, v2
	v_lshlrev_b32_e32 v0, 16, v2
	v_mul_f32_e32 v1, v1, v1
	v_fmac_f32_e32 v1, v0, v0
	v_and_b32_e32 v6, 0xffff0000, v3
	v_add_f32_e32 v0, v18, v1
	v_lshlrev_b32_e32 v1, 16, v3
	v_mul_f32_e32 v6, v6, v6
	v_fmac_f32_e32 v6, v1, v1
	v_add_f32_e32 v0, v0, v6
	v_and_b32_e32 v6, 0xffff0000, v4
	v_lshlrev_b32_e32 v1, 16, v4
	v_mul_f32_e32 v6, v6, v6
	v_fmac_f32_e32 v6, v1, v1
	v_cvt_pk_bf16_f32 v5, v8, v9
	v_add_f32_e32 v0, v0, v6
	v_and_b32_e32 v6, 0xffff0000, v5
	v_lshlrev_b32_e32 v1, 16, v5
	v_mul_f32_e32 v6, v6, v6
	v_fmac_f32_e32 v6, v1, v1
	v_add_f32_e32 v0, v0, v6
	ds_bpermute_b32 v1, v128, v0
	global_store_dwordx4 v[12:13], v[2:5], off offset:256
	s_waitcnt lgkmcnt(0)
	v_add_f32_e32 v0, v0, v1
	ds_bpermute_b32 v1, v129, v0
	s_and_saveexec_b64 s[38:39], s[40:41]
	s_cbranch_execz .LBB0_1668
	v_lshlrev_b64 v[2:3], 6, v[108:109]
	v_lshl_add_u64 v[2:3], s[6:7], 0, v[2:3]
	v_lshl_add_u64 v[2:3], s[0:1], 2, v[2:3]
	s_lshl_b32 s16, s71, 2
	v_lshl_add_u64 v[2:3], v[2:3], 0, s[16:17]
	s_waitcnt lgkmcnt(0)
	v_add_f32_e32 v0, v0, v1
	global_store_dword v[2:3], v0, off

; __device__ __forceinline__ float silu_f(float v) { return v * __builtin_amdgcn_rcpf(1.f + __expf(-v)); }
; __device__ __forceinline__ float ssq_row(const float* part, int row) {
;     const f32x4* p = (const f32x4*)(part + (size_t)row * 16);
;     const f32x4 a = p[0], b = p[1], c = p[2], d = p[3];
;     __device__ __forceinline__ void operator()(const f32x4 (&acc)[2][2][4][2], const Unit& u, int wr, int wc, int fr, int fq, int ui, PG8_LAS unsigned char* lds) const {
;     ...
;                     if (use_tab) { rs4[m] = tab[ai * HALF + m * 16] * sc; rs4[m + 1] = tab[ai * HALF + (m + 1) * 16] * sc; }
;                     else {
;                         asm volatile("" ::: "memory");
;                         rs4[m] = __builtin_amdgcn_rsqf(ssq_row(ssq, row0 + ai * HALF + m * 16) * (1.0f / 1024.0f) + RMS_EPS) * sc;
;                         rs4[m + 1] = __builtin_amdgcn_rsqf(ssq_row(ssq, row0 + ai * HALF + (m + 1) * 16) * (1.0f / 1024.0f) + RMS_EPS) * sc;
;                     }
;                 }
;                 const int row = row0 + ai * HALF + m * 16;
;                 const float rs = rs4[m];
;                 bf16_t* rowp = O + (size_t)row * ldc + col0;
; #pragma unroll
;                 for (int bj = 0; bj < 2; ++bj) {
;                     f32x4 v[2] = {acc[ai][bj][m][0] * rs, acc[ai][bj][m][1] * rs};
;                     if (ksum) { csum[bj][0] += v[0]; csum[bj][1] += v[1]; }
; #pragma unroll
;                     for (int n = 0; n < 2; ++n) {
;                         f32x4 lbv = (f32x4){0.f, 0.f, 0.f, 0.f};
;                         if (act == 2) lbv = *(const f32x4*)(lb + (col0 - 1024) + bj * HALF + 4 * n);
; #pragma unroll
;                         for (int e = 0; e < 4; ++e) {
;                             float x = v[n][e];
;                             if (act == 1) x = silu_f(x);
;                             else if (act == 2) { const float l = lbv[e]; x = __logf(l + (1.f - l) * __builtin_amdgcn_rcpf(1.f + __expf(-x))); }
;                             else if (act == 3) { x = fmaxf(x, 0.f); x = x * x; }
;                             v[n][e] = x;
;                         }
;                     }
;                     u32x4 w; w.x = cvt_pk_bf16(v[0][0], v[0][1]); w.y = cvt_pk_bf16(v[0][2], v[0][3]); w.z = cvt_pk_bf16(v[1][0], v[1][1]); w.w = cvt_pk_bf16(v[1][2], v[1][3]);
;                     *(u32x4*)(rowp + bj * HALF) = w;
.LBB0_1757:
	s_andn2_b64 vcc, exec, s[0:1]
	s_cbranch_vccnz .LBB0_1759
	v_lshlrev_b64 v[138:139], 6, v[140:141]
	v_lshl_add_u64 v[138:139], s[6:7], 0, v[138:139]
	global_load_dwordx4 v[152:155], v[138:139], off offset:16
	global_load_dwordx4 v[156:159], v[138:139], off offset:48
	global_load_dwordx4 v[160:163], v[138:139], off
	global_load_dwordx4 v[164:167], v[138:139], off offset:32
	s_waitcnt vmcnt(0)
	v_mov_b32_e32 v138, v160
	v_mov_b32_e32 v139, v164
	v_mov_b32_e32 v164, v161
	s_waitcnt lgkmcnt(0)
	v_mov_b32_e32 v142, v162
	v_mov_b32_e32 v143, v166
	v_mov_b32_e32 v166, v163
	v_add_f32_e32 v138, v138, v164
	v_add_f32_e32 v139, v139, v165
	v_add_f32_e32 v142, v142, v166
	v_add_f32_e32 v143, v143, v167
	s_nop 0
	v_add_f32_e32 v138, v138, v142
	v_add_f32_e32 v139, v139, v143
	v_mov_b32_e32 v142, v152
	v_mov_b32_e32 v143, v156
	v_mov_b32_e32 v156, v153
	v_mov_b32_e32 v152, v154
	v_mov_b32_e32 v153, v158
	v_mov_b32_e32 v158, v155
	v_add_f32_e32 v142, v142, v156
	v_add_f32_e32 v143, v143, v157
	v_add_f32_e32 v152, v152, v158
	v_add_f32_e32 v153, v153, v159
	s_nop 0
	v_add_f32_e32 v142, v142, v152
	v_add_f32_e32 v143, v143, v153
	s_nop 0
	v_add_f32_e32 v138, v138, v142
	v_add_f32_e32 v139, v139, v143
	s_nop 0
	v_add_f32_e32 v138, v138, v139
	v_fmamk_f32 v138, v138, 0x3a800000, v211
	v_rsq_f32_e32 v142, v138
	v_lshlrev_b64 v[138:139], 6, v[144:145]
	v_lshl_add_u64 v[138:139], s[6:7], 0, v[138:139]
	global_load_dwordx4 v[152:155], v[138:139], off offset:16
	global_load_dwordx4 v[156:159], v[138:139], off offset:48
	global_load_dwordx4 v[160:163], v[138:139], off
	global_load_dwordx4 v[164:167], v[138:139], off offset:32
	s_waitcnt vmcnt(1)
	v_mov_b32_e32 v138, v160
	s_waitcnt vmcnt(0)
	v_mov_b32_e32 v139, v164
	v_mov_b32_e32 v164, v161
	v_mov_b32_e32 v160, v162
	v_mov_b32_e32 v161, v166
	v_mov_b32_e32 v166, v163
	v_add_f32_e32 v138, v138, v164
	v_add_f32_e32 v139, v139, v165
	v_add_f32_e32 v160, v160, v166
	v_add_f32_e32 v161, v161, v167
	s_nop 0
	v_add_f32_e32 v138, v138, v160
	v_add_f32_e32 v139, v139, v161
	v_mov_b32_e32 v160, v152
	v_mov_b32_e32 v161, v156
	v_mov_b32_e32 v156, v153
	v_add_f32_e32 v152, v160, v156
	v_add_f32_e32 v153, v161, v157
	v_mov_b32_e32 v156, v154
	v_mov_b32_e32 v157, v158
	v_mov_b32_e32 v158, v155
	v_add_f32_e32 v154, v156, v158
	v_add_f32_e32 v155, v157, v159
	s_nop 0
	v_add_f32_e32 v152, v152, v154
	v_add_f32_e32 v153, v153, v155
	s_nop 0
	v_add_f32_e32 v138, v138, v152
	v_add_f32_e32 v139, v139, v153
	s_nop 0
	v_add_f32_e32 v138, v138, v139
	v_fmamk_f32 v138, v138, 0x3a800000, v211
	v_rsq_f32_e32 v143, v138
.LBB0_1759:
	s_waitcnt lgkmcnt(0)
	v_mul_f32_e32 v120, v120, v142
	v_mul_f32_e32 v121, v121, v142
	v_lshl_or_b32 v138, s65, 8, v149
	v_max_f32_e32 v120, 0, v120
	v_lshlrev_b64 v[152:153], 13, v[140:141]
	v_mul_f32_e32 v122, v122, v142
	v_mul_f32_e32 v123, v123, v142
	v_mul_f32_e32 v141, v120, v120
	v_max_f32_e32 v120, 0, v121
	v_ashrrev_i32_e32 v139, 31, v138
	v_mul_f32_e32 v124, v124, v142
	v_mul_f32_e32 v125, v125, v142
	v_mul_f32_e32 v154, v120, v120
	v_max_f32_e32 v120, 0, v122
	v_lshl_add_u64 v[152:153], s[14:15], 0, v[152:153]
	v_lshlrev_b64 v[138:139], 1, v[138:139]
	v_mul_f32_e32 v126, v126, v142
	v_mul_f32_e32 v127, v127, v142
	v_max_f32_e32 v124, 0, v124
	v_max_f32_e32 v125, 0, v125
	v_mul_f32_e32 v155, v120, v120
	v_max_f32_e32 v120, 0, v123
	v_mul_f32_e32 v112, v112, v142
	v_mul_f32_e32 v113, v113, v142
	v_lshl_add_u64 v[152:153], v[152:153], 0, v[138:139]
	v_mul_f32_e32 v124, v124, v124
	v_mul_f32_e32 v125, v125, v125
	v_max_f32_e32 v126, 0, v126
	v_max_f32_e32 v127, 0, v127
	v_mul_f32_e32 v123, v120, v120
	v_cvt_pk_bf16_f32 v120, v124, v125
	v_max_f32_e32 v112, 0, v112
	v_mul_f32_e32 v126, v126, v126
	v_mul_f32_e32 v127, v127, v127
	v_cvt_pk_bf16_f32 v121, v126, v127
	v_cvt_pk_bf16_f32 v122, v141, v154
	v_cvt_pk_bf16_f32 v123, v155, v123
	global_store_dwordx4 v[152:153], v[120:123], off
	v_mul_f32_e32 v114, v114, v142
	v_mul_f32_e32 v115, v115, v142
	v_mul_f32_e32 v118, v118, v142
	v_mul_f32_e32 v119, v119, v142
	v_mul_f32_e32 v120, v112, v112
	v_max_f32_e32 v112, 0, v113
	v_mul_f32_e32 v116, v116, v142
	v_mul_f32_e32 v117, v117, v142
	v_mul_f32_e32 v121, v112, v112
	v_max_f32_e32 v112, 0, v114
	v_max_f32_e32 v116, 0, v116
	v_max_f32_e32 v117, 0, v117
	v_max_f32_e32 v118, 0, v118
	v_max_f32_e32 v119, 0, v119
	v_mul_f32_e32 v122, v112, v112
	v_max_f32_e32 v112, 0, v115
	v_mul_f32_e32 v116, v116, v116
	v_mul_f32_e32 v117, v117, v117
	v_mul_f32_e32 v118, v118, v118
	v_mul_f32_e32 v119, v119, v119
	v_mul_f32_e32 v115, v112, v112
	v_cvt_pk_bf16_f32 v112, v116, v117
	v_cvt_pk_bf16_f32 v113, v118, v119
	v_cvt_pk_bf16_f32 v114, v120, v121
	v_cvt_pk_bf16_f32 v115, v122, v115
	global_store_dwordx4 v[152:153], v[112:115], off offset:256
	s_and_b64 vcc, exec, s[46:47]
	s_cbranch_vccz .Lal3_skip
	s_barrier
; __device__ __forceinline__ float silu_f(float v) { return v * __builtin_amdgcn_rcpf(1.f + __expf(-v)); }
; __device__ __forceinline__ float ssq_row(const float* part, int row) {
;     const f32x4* p = (const f32x4*)(part + (size_t)row * 16);
;     const f32x4 a = p[0], b = p[1], c = p[2], d = p[3];
;     __device__ __forceinline__ void operator()(const f32x4 (&acc)[2][2][4][2], const Unit& u, int wr, int wc, int fr, int fq, int ui, PG8_LAS unsigned char* lds) const {
;     ...
;                     if (use_tab) { rs4[m] = tab[ai * HALF + m * 16] * sc; rs4[m + 1] = tab[ai * HALF + (m + 1) * 16] * sc; }
;                     else {
;                         asm volatile("" ::: "memory");
;                         rs4[m] = __builtin_amdgcn_rsqf(ssq_row(ssq, row0 + ai * HALF + m * 16) * (1.0f / 1024.0f) + RMS_EPS) * sc;
;                         rs4[m + 1] = __builtin_amdgcn_rsqf(ssq_row(ssq, row0 + ai * HALF + (m + 1) * 16) * (1.0f / 1024.0f) + RMS_EPS) * sc;
;                     }
;                 }
;                 const int row = row0 + ai * HALF + m * 16;
;                 const float rs = rs4[m];
;                 bf16_t* rowp = O + (size_t)row * ldc + col0;
; #pragma unroll
;                 for (int bj = 0; bj < 2; ++bj) {
;                     f32x4 v[2] = {acc[ai][bj][m][0] * rs, acc[ai][bj][m][1] * rs};
;                     if (ksum) { csum[bj][0] += v[0]; csum[bj][1] += v[1]; }
; #pragma unroll
;                     for (int n = 0; n < 2; ++n) {
;                         f32x4 lbv = (f32x4){0.f, 0.f, 0.f, 0.f};
;                         if (act == 2) lbv = *(const f32x4*)(lb + (col0 - 1024) + bj * HALF + 4 * n);
; #pragma unroll
;                         for (int e = 0; e < 4; ++e) {
;                             float x = v[n][e];
;                             if (act == 1) x = silu_f(x);
;                             else if (act == 2) { const float l = lbv[e]; x = __logf(l + (1.f - l) * __builtin_amdgcn_rcpf(1.f + __expf(-x))); }
;                             else if (act == 3) { x = fmaxf(x, 0.f); x = x * x; }
;                             v[n][e] = x;
;                         }
;                     }
;                     u32x4 w; w.x = cvt_pk_bf16(v[0][0], v[0][1]); w.y = cvt_pk_bf16(v[0][2], v[0][3]); w.z = cvt_pk_bf16(v[1][0], v[1][1]); w.w = cvt_pk_bf16(v[1][2], v[1][3]);
;                     *(u32x4*)(rowp + bj * HALF) = w;
.Lal3_skip:
	s_mov_b64 s[0:1], -1
	s_and_b64 vcc, exec, s[40:41]
	v_mov_b32_e32 v114, v143
	v_mul_f32_e32 v104, v104, v114
	v_mul_f32_e32 v105, v105, v114
	v_mul_f32_e32 v110, v110, v114
	v_mul_f32_e32 v111, v111, v114
	v_max_f32_e32 v104, 0, v104
	v_mul_f32_e32 v108, v108, v114
	v_mul_f32_e32 v109, v109, v114
	v_mul_f32_e32 v106, v106, v114
	v_mul_f32_e32 v107, v107, v114
	v_mul_f32_e32 v115, v104, v104
	v_max_f32_e32 v104, 0, v105
	v_lshlrev_b64 v[112:113], 13, v[144:145]
	v_mul_f32_e32 v116, v104, v104
	v_max_f32_e32 v104, 0, v106
	v_lshl_add_u64 v[112:113], s[14:15], 0, v[112:113]
	v_max_f32_e32 v108, 0, v108
	v_max_f32_e32 v109, 0, v109
	v_mul_f32_e32 v117, v104, v104
	v_max_f32_e32 v104, 0, v107
	v_mul_f32_e32 v96, v96, v114
	v_mul_f32_e32 v97, v97, v114
	v_lshl_add_u64 v[112:113], v[112:113], 0, v[138:139]
	v_mul_f32_e32 v108, v108, v108
	v_mul_f32_e32 v109, v109, v109
	v_max_f32_e32 v110, 0, v110
	v_max_f32_e32 v111, 0, v111
	v_mul_f32_e32 v107, v104, v104
	v_cvt_pk_bf16_f32 v104, v108, v109
	v_max_f32_e32 v96, 0, v96
	v_mul_f32_e32 v110, v110, v110
	v_mul_f32_e32 v111, v111, v111
	v_cvt_pk_bf16_f32 v105, v110, v111
	v_cvt_pk_bf16_f32 v106, v115, v116
	v_cvt_pk_bf16_f32 v107, v117, v107
	global_store_dwordx4 v[112:113], v[104:107], off
	v_mul_f32_e32 v98, v98, v114
	v_mul_f32_e32 v99, v99, v114
	v_mul_f32_e32 v102, v102, v114
	v_mul_f32_e32 v103, v103, v114
	v_mul_f32_e32 v104, v96, v96
	v_max_f32_e32 v96, 0, v97
	v_mul_f32_e32 v100, v100, v114
	v_mul_f32_e32 v101, v101, v114
	v_mul_f32_e32 v105, v96, v96
	v_max_f32_e32 v96, 0, v98
	v_max_f32_e32 v100, 0, v100
	v_max_f32_e32 v101, 0, v101
	v_max_f32_e32 v102, 0, v102
	v_max_f32_e32 v103, 0, v103
	v_mul_f32_e32 v106, v96, v96
	v_max_f32_e32 v96, 0, v99
	v_mul_f32_e32 v100, v100, v100
	v_mul_f32_e32 v101, v101, v101
	v_mul_f32_e32 v102, v102, v102
	v_mul_f32_e32 v103, v103, v103
	v_mul_f32_e32 v99, v96, v96
	v_cvt_pk_bf16_f32 v96, v100, v101
	v_cvt_pk_bf16_f32 v97, v102, v103
	v_cvt_pk_bf16_f32 v98, v104, v105
	v_cvt_pk_bf16_f32 v99, v106, v99
	global_store_dwordx4 v[112:113], v[96:99], off offset:256
	s_nop 1
	v_or_b32_e32 v98, 32, v140
	v_or_b32_e32 v96, 48, v140
	v_ashrrev_i32_e32 v99, 31, v98
	v_ashrrev_i32_e32 v97, 31, v96
	s_cbranch_vccnz .LBB0_1761
	ds_read2_b32 v[100:101], v151 offset0:32 offset1:48
	s_mov_b64 s[0:1], 0
	s_waitcnt lgkmcnt(0)
	v_mov_b32_e32 v102, v101
.LBB0_1761:
	s_andn2_b64 vcc, exec, s[0:1]
	s_cbranch_vccnz .LBB0_1763
	v_lshlrev_b64 v[100:101], 6, v[98:99]
	v_lshl_add_u64 v[112:113], s[6:7], 0, v[100:101]
	global_load_dwordx4 v[100:103], v[112:113], off offset:16
	global_load_dwordx4 v[104:107], v[112:113], off offset:48
	global_load_dwordx4 v[108:111], v[112:113], off
	s_nop 0
	global_load_dwordx4 v[112:115], v[112:113], off offset:32
	s_waitcnt vmcnt(0)
	v_mov_b32_e32 v116, v108
	v_mov_b32_e32 v117, v112
	v_mov_b32_e32 v112, v109
	v_add_f32_e32 v108, v116, v112
	v_add_f32_e32 v109, v117, v113
	v_mov_b32_e32 v112, v110
	v_mov_b32_e32 v113, v114
	v_mov_b32_e32 v114, v111
	v_add_f32_e32 v110, v112, v114
	v_add_f32_e32 v111, v113, v115
	s_nop 0
	v_add_f32_e32 v108, v108, v110
	v_add_f32_e32 v109, v109, v111
	v_mov_b32_e32 v110, v100
	v_mov_b32_e32 v111, v104
	v_mov_b32_e32 v104, v101
	v_add_f32_e32 v100, v110, v104
	v_add_f32_e32 v101, v111, v105
	v_mov_b32_e32 v104, v102
	v_mov_b32_e32 v105, v106
	v_mov_b32_e32 v106, v103
	v_add_f32_e32 v102, v104, v106
	v_add_f32_e32 v103, v105, v107
	s_nop 0
	v_add_f32_e32 v100, v100, v102
	v_add_f32_e32 v101, v101, v103
	v_lshlrev_b64 v[102:103], 6, v[96:97]
	v_lshl_add_u64 v[114:115], s[6:7], 0, v[102:103]
	v_add_f32_e32 v100, v108, v100
	v_add_f32_e32 v101, v109, v101
	global_load_dwordx4 v[102:105], v[114:115], off offset:16
	global_load_dwordx4 v[106:109], v[114:115], off offset:48
	global_load_dwordx4 v[110:113], v[114:115], off
	s_nop 0
	global_load_dwordx4 v[114:117], v[114:115], off offset:32
	v_add_f32_e32 v100, v100, v101
	v_fmamk_f32 v100, v100, 0x3a800000, v211
	v_rsq_f32_e32 v100, v100
	s_waitcnt vmcnt(1)
	v_mov_b32_e32 v118, v110
	s_waitcnt vmcnt(0)
	v_mov_b32_e32 v119, v114
	v_mov_b32_e32 v114, v111
	v_add_f32_e32 v110, v118, v114
	v_add_f32_e32 v111, v119, v115
	v_mov_b32_e32 v114, v112
	v_mov_b32_e32 v115, v116
	v_mov_b32_e32 v116, v113
	v_add_f32_e32 v112, v114, v116
	v_add_f32_e32 v113, v115, v117
	s_nop 0
	v_add_f32_e32 v110, v110, v112
	v_add_f32_e32 v111, v111, v113
	v_mov_b32_e32 v112, v102
	v_mov_b32_e32 v113, v106
	v_mov_b32_e32 v106, v103
	v_add_f32_e32 v102, v112, v106
	v_add_f32_e32 v103, v113, v107
	v_mov_b32_e32 v106, v104
	v_mov_b32_e32 v107, v108
	v_mov_b32_e32 v108, v105
	v_add_f32_e32 v104, v106, v108
	v_add_f32_e32 v105, v107, v109
	s_nop 0
	v_add_f32_e32 v102, v102, v104
	v_add_f32_e32 v103, v103, v105
	s_nop 0
	v_add_f32_e32 v102, v110, v102
	v_add_f32_e32 v103, v111, v103
	s_nop 0
	v_add_f32_e32 v101, v102, v103
	v_fmamk_f32 v101, v101, 0x3a800000, v211
	v_rsq_f32_e32 v102, v101
; __device__ __forceinline__ float silu_f(float v) { return v * __builtin_amdgcn_rcpf(1.f + __expf(-v)); }
; __device__ __forceinline__ float ssq_row(const float* part, int row) {
;     const f32x4* p = (const f32x4*)(part + (size_t)row * 16);
;     const f32x4 a = p[0], b = p[1], c = p[2], d = p[3];
;     __device__ __forceinline__ void operator()(const f32x4 (&acc)[2][2][4][2], const Unit& u, int wr, int wc, int fr, int fq, int ui, PG8_LAS unsigned char* lds) const {
;     ...
;                     if (use_tab) { rs4[m] = tab[ai * HALF + m * 16] * sc; rs4[m + 1] = tab[ai * HALF + (m + 1) * 16] * sc; }
;                     else {
;                         asm volatile("" ::: "memory");
;                         rs4[m] = __builtin_amdgcn_rsqf(ssq_row(ssq, row0 + ai * HALF + m * 16) * (1.0f / 1024.0f) + RMS_EPS) * sc;
;                         rs4[m + 1] = __builtin_amdgcn_rsqf(ssq_row(ssq, row0 + ai * HALF + (m + 1) * 16) * (1.0f / 1024.0f) + RMS_EPS) * sc;
;                     }
;                 }
;                 const int row = row0 + ai * HALF + m * 16;
;                 const float rs = rs4[m];
;                 bf16_t* rowp = O + (size_t)row * ldc + col0;
; #pragma unroll
;                 for (int bj = 0; bj < 2; ++bj) {
;                     f32x4 v[2] = {acc[ai][bj][m][0] * rs, acc[ai][bj][m][1] * rs};
;                     if (ksum) { csum[bj][0] += v[0]; csum[bj][1] += v[1]; }
; #pragma unroll
;                     for (int n = 0; n < 2; ++n) {
;                         f32x4 lbv = (f32x4){0.f, 0.f, 0.f, 0.f};
;                         if (act == 2) lbv = *(const f32x4*)(lb + (col0 - 1024) + bj * HALF + 4 * n);
; #pragma unroll
;                         for (int e = 0; e < 4; ++e) {
;                             float x = v[n][e];
;                             if (act == 1) x = silu_f(x);
;                             else if (act == 2) { const float l = lbv[e]; x = __logf(l + (1.f - l) * __builtin_amdgcn_rcpf(1.f + __expf(-x))); }
;                             else if (act == 3) { x = fmaxf(x, 0.f); x = x * x; }
;                             v[n][e] = x;
;                         }
;                     }
;                     u32x4 w; w.x = cvt_pk_bf16(v[0][0], v[0][1]); w.y = cvt_pk_bf16(v[0][2], v[0][3]); w.z = cvt_pk_bf16(v[1][0], v[1][1]); w.w = cvt_pk_bf16(v[1][2], v[1][3]);
;                     *(u32x4*)(rowp + bj * HALF) = w;
.LBB0_1763:
	v_mul_f32_e32 v88, v88, v100
	v_mul_f32_e32 v89, v89, v100
	v_mul_f32_e32 v90, v90, v100
	v_mul_f32_e32 v91, v91, v100
	v_max_f32_e32 v88, 0, v88
	v_mul_f32_e32 v103, v88, v88
	v_max_f32_e32 v88, 0, v89
	v_lshlrev_b64 v[98:99], 13, v[98:99]
	v_mul_f32_e32 v92, v92, v100
	v_mul_f32_e32 v93, v93, v100
	v_mul_f32_e32 v104, v88, v88
	v_max_f32_e32 v88, 0, v90
	v_lshl_add_u64 v[98:99], s[14:15], 0, v[98:99]
	v_mul_f32_e32 v94, v94, v100
	v_mul_f32_e32 v95, v95, v100
	v_max_f32_e32 v92, 0, v92
	v_max_f32_e32 v93, 0, v93
	v_mul_f32_e32 v105, v88, v88
	v_max_f32_e32 v88, 0, v91
	v_mul_f32_e32 v80, v80, v100
	v_mul_f32_e32 v81, v81, v100
	v_lshl_add_u64 v[98:99], v[98:99], 0, v[138:139]
	v_mul_f32_e32 v92, v92, v92
	v_mul_f32_e32 v93, v93, v93
	v_max_f32_e32 v94, 0, v94
	v_max_f32_e32 v95, 0, v95
	v_mul_f32_e32 v91, v88, v88
	v_cvt_pk_bf16_f32 v88, v92, v93
	v_max_f32_e32 v80, 0, v80
	v_mul_f32_e32 v94, v94, v94
	v_mul_f32_e32 v95, v95, v95
	v_cvt_pk_bf16_f32 v89, v94, v95
	v_cvt_pk_bf16_f32 v90, v103, v104
	v_cvt_pk_bf16_f32 v91, v105, v91
	global_store_dwordx4 v[98:99], v[88:91], off
	v_mul_f32_e32 v82, v82, v100
	v_mul_f32_e32 v83, v83, v100
	v_mul_f32_e32 v86, v86, v100
	v_mul_f32_e32 v87, v87, v100
	v_mul_f32_e32 v88, v80, v80
	v_max_f32_e32 v80, 0, v81
	v_mul_f32_e32 v84, v84, v100
	v_mul_f32_e32 v85, v85, v100
	v_mul_f32_e32 v89, v80, v80
	v_max_f32_e32 v80, 0, v82
	v_max_f32_e32 v84, 0, v84
	v_max_f32_e32 v85, 0, v85
	v_max_f32_e32 v86, 0, v86
	v_max_f32_e32 v87, 0, v87
	v_mul_f32_e32 v90, v80, v80
	v_max_f32_e32 v80, 0, v83
	v_mul_f32_e32 v72, v72, v102
	v_mul_f32_e32 v73, v73, v102
	v_mul_f32_e32 v84, v84, v84
	v_mul_f32_e32 v85, v85, v85
	v_mul_f32_e32 v86, v86, v86
	v_mul_f32_e32 v87, v87, v87
	v_mul_f32_e32 v83, v80, v80
	v_cvt_pk_bf16_f32 v80, v84, v85
	v_cvt_pk_bf16_f32 v81, v86, v87
	v_cvt_pk_bf16_f32 v82, v88, v89
	v_max_f32_e32 v72, 0, v72
	v_cvt_pk_bf16_f32 v83, v90, v83
	global_store_dwordx4 v[98:99], v[80:83], off offset:256
	v_mul_f32_e32 v74, v74, v102
	v_mul_f32_e32 v75, v75, v102
	v_mul_f32_e32 v76, v76, v102
	v_mul_f32_e32 v77, v77, v102
	v_mul_f32_e32 v82, v72, v72
	v_max_f32_e32 v72, 0, v73
	v_lshlrev_b64 v[80:81], 13, v[96:97]
	v_mul_f32_e32 v83, v72, v72
	v_max_f32_e32 v72, 0, v74
	v_lshl_add_u64 v[80:81], s[14:15], 0, v[80:81]
	v_mul_f32_e32 v78, v78, v102
	v_mul_f32_e32 v79, v79, v102
	v_max_f32_e32 v76, 0, v76
	v_max_f32_e32 v77, 0, v77
	v_mul_f32_e32 v84, v72, v72
	v_max_f32_e32 v72, 0, v75
	v_mul_f32_e32 v64, v64, v102
	v_mul_f32_e32 v65, v65, v102
	v_lshl_add_u64 v[80:81], v[80:81], 0, v[138:139]
	v_mul_f32_e32 v76, v76, v76
	v_mul_f32_e32 v77, v77, v77
	v_max_f32_e32 v78, 0, v78
	v_max_f32_e32 v79, 0, v79
	v_mul_f32_e32 v75, v72, v72
	v_cvt_pk_bf16_f32 v72, v76, v77
	v_max_f32_e32 v64, 0, v64
	v_mul_f32_e32 v78, v78, v78
	v_mul_f32_e32 v79, v79, v79
	v_cvt_pk_bf16_f32 v73, v78, v79
	v_cvt_pk_bf16_f32 v74, v82, v83
	v_cvt_pk_bf16_f32 v75, v84, v75
	global_store_dwordx4 v[80:81], v[72:75], off
	v_mul_f32_e32 v66, v66, v102
	v_mul_f32_e32 v67, v67, v102
	v_mul_f32_e32 v70, v70, v102
	v_mul_f32_e32 v71, v71, v102
	v_mul_f32_e32 v72, v64, v64
	v_max_f32_e32 v64, 0, v65
	v_mul_f32_e32 v68, v68, v102
	v_mul_f32_e32 v69, v69, v102
	v_mul_f32_e32 v73, v64, v64
	v_max_f32_e32 v64, 0, v66
	v_max_f32_e32 v68, 0, v68
	v_max_f32_e32 v69, 0, v69
	v_max_f32_e32 v70, 0, v70
	v_max_f32_e32 v71, 0, v71
	v_mul_f32_e32 v74, v64, v64
	v_max_f32_e32 v64, 0, v67
	v_mul_f32_e32 v68, v68, v68
	v_mul_f32_e32 v69, v69, v69
	v_mul_f32_e32 v70, v70, v70
	v_mul_f32_e32 v71, v71, v71
	v_mul_f32_e32 v67, v64, v64
	v_cvt_pk_bf16_f32 v64, v68, v69
	v_cvt_pk_bf16_f32 v65, v70, v71
	v_cvt_pk_bf16_f32 v66, v72, v73
	v_cvt_pk_bf16_f32 v67, v74, v67
	global_store_dwordx4 v[80:81], v[64:67], off offset:256
	s_mov_b64 s[0:1], -1
	s_and_b64 vcc, exec, s[40:41]
	v_add_u32_e32 v66, 0x80, v140
	v_add_u32_e32 v64, 0x90, v140
	v_ashrrev_i32_e32 v67, 31, v66
	v_ashrrev_i32_e32 v65, 31, v64
	s_cbranch_vccnz .LBB0_1765
	ds_read2_b32 v[68:69], v151 offset0:128 offset1:144
	s_mov_b64 s[0:1], 0
	s_waitcnt lgkmcnt(0)
	v_mov_b32_e32 v142, v68
	v_mov_b32_e32 v68, v69
.LBB0_1765:
	s_andn2_b64 vcc, exec, s[0:1]
	s_cbranch_vccnz .LBB0_1767
	v_lshlrev_b64 v[68:69], 6, v[66:67]
	v_lshl_add_u64 v[80:81], s[6:7], 0, v[68:69]
	global_load_dwordx4 v[68:71], v[80:81], off offset:16
	global_load_dwordx4 v[72:75], v[80:81], off offset:48
	global_load_dwordx4 v[76:79], v[80:81], off
	s_nop 0
	global_load_dwordx4 v[80:83], v[80:81], off offset:32
	s_waitcnt vmcnt(0)
	v_mov_b32_e32 v84, v76
	v_mov_b32_e32 v85, v80
	v_mov_b32_e32 v80, v77
	v_add_f32_e32 v76, v84, v80
	v_add_f32_e32 v77, v85, v81
	v_mov_b32_e32 v80, v78
	v_mov_b32_e32 v81, v82
	v_mov_b32_e32 v82, v79
	v_add_f32_e32 v78, v80, v82
	v_add_f32_e32 v79, v81, v83
	s_nop 0
	v_add_f32_e32 v76, v76, v78
	v_add_f32_e32 v77, v77, v79
	v_mov_b32_e32 v78, v68
	v_mov_b32_e32 v79, v72
	v_mov_b32_e32 v72, v69
	v_add_f32_e32 v68, v78, v72
	v_add_f32_e32 v69, v79, v73
	v_mov_b32_e32 v72, v70
	v_mov_b32_e32 v73, v74
	v_mov_b32_e32 v74, v71
	v_add_f32_e32 v70, v72, v74
	v_add_f32_e32 v71, v73, v75
	s_nop 0
	v_add_f32_e32 v68, v68, v70
	v_add_f32_e32 v69, v69, v71
	s_nop 0
	v_add_f32_e32 v68, v76, v68
	v_add_f32_e32 v69, v77, v69
	s_nop 0
	v_add_f32_e32 v68, v68, v69
	v_fmamk_f32 v68, v68, 0x3a800000, v211
	v_rsq_f32_e32 v142, v68
	v_lshlrev_b64 v[68:69], 6, v[64:65]
	v_lshl_add_u64 v[80:81], s[6:7], 0, v[68:69]
	global_load_dwordx4 v[68:71], v[80:81], off offset:16
	global_load_dwordx4 v[72:75], v[80:81], off offset:48
	global_load_dwordx4 v[76:79], v[80:81], off
	s_nop 0
	global_load_dwordx4 v[80:83], v[80:81], off offset:32
	s_waitcnt vmcnt(1)
	v_mov_b32_e32 v84, v76
	s_waitcnt vmcnt(0)
	v_mov_b32_e32 v85, v80
	v_mov_b32_e32 v80, v77
	v_add_f32_e32 v76, v84, v80
	v_add_f32_e32 v77, v85, v81
	v_mov_b32_e32 v80, v78
	v_mov_b32_e32 v81, v82
	v_mov_b32_e32 v82, v79
	v_add_f32_e32 v78, v80, v82
	v_add_f32_e32 v79, v81, v83
	s_nop 0
	v_add_f32_e32 v76, v76, v78
	v_add_f32_e32 v77, v77, v79
	v_mov_b32_e32 v78, v68
	v_mov_b32_e32 v79, v72
	v_mov_b32_e32 v72, v69
	v_add_f32_e32 v68, v78, v72
	v_add_f32_e32 v69, v79, v73
	v_mov_b32_e32 v72, v70
	v_mov_b32_e32 v73, v74
	v_mov_b32_e32 v74, v71
	v_add_f32_e32 v70, v72, v74
	v_add_f32_e32 v71, v73, v75
	s_nop 0
	v_add_f32_e32 v68, v68, v70
	v_add_f32_e32 v69, v69, v71
	s_nop 0
	v_add_f32_e32 v68, v76, v68
	v_add_f32_e32 v69, v77, v69
	s_nop 0
	v_add_f32_e32 v68, v68, v69
	v_fmamk_f32 v68, v68, 0x3a800000, v211
	v_rsq_f32_e32 v68, v68
; __device__ __forceinline__ unsigned cvt_pk_bf16(float lo, float hi) { unsigned r; asm volatile("v_cvt_pk_bf16_f32 %0, %1, %2" : "=v"(r) : "v"(lo), "v"(hi)); return r; }
; __device__ __forceinline__ float silu_f(float v) { return v * __builtin_amdgcn_rcpf(1.f + __expf(-v)); }
;     __device__ __forceinline__ void operator()(const f32x4 (&acc)[2][2][4][2], const Unit& u, int wr, int wc, int fr, int fq, int ui, PG8_LAS unsigned char* lds) const {
;     ...
;                     if (use_tab) { rs4[m] = tab[ai * HALF + m * 16] * sc; rs4[m + 1] = tab[ai * HALF + (m + 1) * 16] * sc; }
;                     else {
;                         asm volatile("" ::: "memory");
;                         rs4[m] = __builtin_amdgcn_rsqf(ssq_row(ssq, row0 + ai * HALF + m * 16) * (1.0f / 1024.0f) + RMS_EPS) * sc;
;                         rs4[m + 1] = __builtin_amdgcn_rsqf(ssq_row(ssq, row0 + ai * HALF + (m + 1) * 16) * (1.0f / 1024.0f) + RMS_EPS) * sc;
;                     }
;                 }
;                 const int row = row0 + ai * HALF + m * 16;
;                 const float rs = rs4[m];
;                 bf16_t* rowp = O + (size_t)row * ldc + col0;
; #pragma unroll
;                 for (int bj = 0; bj < 2; ++bj) {
;                     f32x4 v[2] = {acc[ai][bj][m][0] * rs, acc[ai][bj][m][1] * rs};
;                     if (ksum) { csum[bj][0] += v[0]; csum[bj][1] += v[1]; }
; #pragma unroll
;                     for (int n = 0; n < 2; ++n) {
;                         f32x4 lbv = (f32x4){0.f, 0.f, 0.f, 0.f};
;                         if (act == 2) lbv = *(const f32x4*)(lb + (col0 - 1024) + bj * HALF + 4 * n);
; #pragma unroll
;                         for (int e = 0; e < 4; ++e) {
;                             float x = v[n][e];
;                             if (act == 1) x = silu_f(x);
;                             else if (act == 2) { const float l = lbv[e]; x = __logf(l + (1.f - l) * __builtin_amdgcn_rcpf(1.f + __expf(-x))); }
;                             else if (act == 3) { x = fmaxf(x, 0.f); x = x * x; }
;                             v[n][e] = x;
;                         }
;                     }
;                     u32x4 w; w.x = cvt_pk_bf16(v[0][0], v[0][1]); w.y = cvt_pk_bf16(v[0][2], v[0][3]); w.z = cvt_pk_bf16(v[1][0], v[1][1]); w.w = cvt_pk_bf16(v[1][2], v[1][3]);
;                     *(u32x4*)(rowp + bj * HALF) = w;
.LBB0_1767:
	v_mul_f32_e32 v56, v56, v142
	v_mul_f32_e32 v57, v57, v142
	v_mul_f32_e32 v58, v58, v142
	v_mul_f32_e32 v59, v59, v142
	v_max_f32_e32 v56, 0, v56
	v_mul_f32_e32 v69, v56, v56
	v_max_f32_e32 v56, 0, v57
	v_lshlrev_b64 v[66:67], 13, v[66:67]
	v_mul_f32_e32 v60, v60, v142
	v_mul_f32_e32 v61, v61, v142
	v_mul_f32_e32 v70, v56, v56
	v_max_f32_e32 v56, 0, v58
	v_lshl_add_u64 v[66:67], s[14:15], 0, v[66:67]
	v_mul_f32_e32 v62, v62, v142
	v_mul_f32_e32 v63, v63, v142
	v_max_f32_e32 v60, 0, v60
	v_max_f32_e32 v61, 0, v61
	v_mul_f32_e32 v71, v56, v56
	v_max_f32_e32 v56, 0, v59
	v_mul_f32_e32 v48, v48, v142
	v_mul_f32_e32 v49, v49, v142
	v_lshl_add_u64 v[66:67], v[66:67], 0, v[138:139]
	v_mul_f32_e32 v60, v60, v60
	v_mul_f32_e32 v61, v61, v61
	v_max_f32_e32 v62, 0, v62
	v_max_f32_e32 v63, 0, v63
	v_mul_f32_e32 v59, v56, v56
	v_cvt_pk_bf16_f32 v56, v60, v61
	v_max_f32_e32 v48, 0, v48
	v_mul_f32_e32 v62, v62, v62
	v_mul_f32_e32 v63, v63, v63
	v_cvt_pk_bf16_f32 v57, v62, v63
	v_cvt_pk_bf16_f32 v58, v69, v70
	v_cvt_pk_bf16_f32 v59, v71, v59
	global_store_dwordx4 v[66:67], v[56:59], off
	v_mul_f32_e32 v50, v50, v142
	v_mul_f32_e32 v51, v51, v142
	v_mul_f32_e32 v54, v54, v142
	v_mul_f32_e32 v55, v55, v142
	v_mul_f32_e32 v56, v48, v48
	v_max_f32_e32 v48, 0, v49
	v_mul_f32_e32 v52, v52, v142
	v_mul_f32_e32 v53, v53, v142
	v_mul_f32_e32 v57, v48, v48
	v_max_f32_e32 v48, 0, v50
	v_max_f32_e32 v52, 0, v52
	v_max_f32_e32 v53, 0, v53
	v_max_f32_e32 v54, 0, v54
	v_max_f32_e32 v55, 0, v55
	v_mul_f32_e32 v58, v48, v48
	v_max_f32_e32 v48, 0, v51
	v_mul_f32_e32 v40, v40, v68
	v_mul_f32_e32 v41, v41, v68
	v_mul_f32_e32 v52, v52, v52
	v_mul_f32_e32 v53, v53, v53
	v_mul_f32_e32 v54, v54, v54
	v_mul_f32_e32 v55, v55, v55
	v_mul_f32_e32 v51, v48, v48
	v_cvt_pk_bf16_f32 v48, v52, v53
	v_cvt_pk_bf16_f32 v49, v54, v55
	v_cvt_pk_bf16_f32 v50, v56, v57
	v_max_f32_e32 v40, 0, v40
	v_cvt_pk_bf16_f32 v51, v58, v51
	global_store_dwordx4 v[66:67], v[48:51], off offset:256
	v_mul_f32_e32 v42, v42, v68
	v_mul_f32_e32 v43, v43, v68
	v_mul_f32_e32 v44, v44, v68
	v_mul_f32_e32 v45, v45, v68
	v_mul_f32_e32 v50, v40, v40
	v_max_f32_e32 v40, 0, v41
	v_lshlrev_b64 v[48:49], 13, v[64:65]
	v_mul_f32_e32 v51, v40, v40
	v_max_f32_e32 v40, 0, v42
	v_lshl_add_u64 v[48:49], s[14:15], 0, v[48:49]
	v_mul_f32_e32 v46, v46, v68
	v_mul_f32_e32 v47, v47, v68
	v_max_f32_e32 v44, 0, v44
	v_max_f32_e32 v45, 0, v45
	v_mul_f32_e32 v52, v40, v40
	v_max_f32_e32 v40, 0, v43
	v_mul_f32_e32 v32, v32, v68
	v_mul_f32_e32 v33, v33, v68
	v_lshl_add_u64 v[48:49], v[48:49], 0, v[138:139]
	v_mul_f32_e32 v44, v44, v44
	v_mul_f32_e32 v45, v45, v45
	v_max_f32_e32 v46, 0, v46
	v_max_f32_e32 v47, 0, v47
	v_mul_f32_e32 v43, v40, v40
	v_cvt_pk_bf16_f32 v40, v44, v45
	v_max_f32_e32 v32, 0, v32
	v_mul_f32_e32 v46, v46, v46
	v_mul_f32_e32 v47, v47, v47
	v_cvt_pk_bf16_f32 v41, v46, v47
	v_cvt_pk_bf16_f32 v42, v50, v51
	v_cvt_pk_bf16_f32 v43, v52, v43
	global_store_dwordx4 v[48:49], v[40:43], off
	v_mul_f32_e32 v34, v34, v68
	v_mul_f32_e32 v35, v35, v68
	v_mul_f32_e32 v38, v38, v68
	v_mul_f32_e32 v39, v39, v68
	v_mul_f32_e32 v40, v32, v32
	v_max_f32_e32 v32, 0, v33
	v_mul_f32_e32 v36, v36, v68
	v_mul_f32_e32 v37, v37, v68
	v_mul_f32_e32 v41, v32, v32
	v_max_f32_e32 v32, 0, v34
	v_max_f32_e32 v36, 0, v36
	v_max_f32_e32 v38, 0, v38
	v_mul_f32_e32 v42, v32, v32
	v_max_f32_e32 v32, 0, v35
	v_mul_f32_e32 v36, v36, v36
	v_max_f32_e32 v37, 0, v37
	v_mul_f32_e32 v38, v38, v38
	v_max_f32_e32 v39, 0, v39
	v_mul_f32_e32 v35, v32, v32
	v_mul_f32_e32 v37, v37, v37
	v_mul_f32_e32 v39, v39, v39
	v_cvt_pk_bf16_f32 v32, v36, v37
	v_cvt_pk_bf16_f32 v33, v38, v39
	v_cvt_pk_bf16_f32 v34, v40, v41
	v_cvt_pk_bf16_f32 v35, v42, v35
	v_add_u32_e32 v38, 0xa0, v140
	v_add_u32_e32 v36, 0xb0, v140
	global_store_dwordx4 v[48:49], v[32:35], off offset:256
	s_mov_b64 s[0:1], -1
	s_and_b64 vcc, exec, s[40:41]
	v_ashrrev_i32_e32 v39, 31, v38
	v_ashrrev_i32_e32 v37, 31, v36
	s_cbranch_vccnz .LBB0_1769
	ds_read2_b32 v[34:35], v151 offset0:160 offset1:176
	s_mov_b64 s[0:1], 0
	s_waitcnt lgkmcnt(0)
	v_mov_b32_e32 v32, v35
; __device__ __forceinline__ float silu_f(float v) { return v * __builtin_amdgcn_rcpf(1.f + __expf(-v)); }
; __device__ __forceinline__ float ssq_row(const float* part, int row) {
;     const f32x4* p = (const f32x4*)(part + (size_t)row * 16);
;     const f32x4 a = p[0], b = p[1], c = p[2], d = p[3];
;     __device__ __forceinline__ void operator()(const f32x4 (&acc)[2][2][4][2], const Unit& u, int wr, int wc, int fr, int fq, int ui, PG8_LAS unsigned char* lds) const {
;     ...
;                     if (use_tab) { rs4[m] = tab[ai * HALF + m * 16] * sc; rs4[m + 1] = tab[ai * HALF + (m + 1) * 16] * sc; }
;                     else {
;                         asm volatile("" ::: "memory");
;                         rs4[m] = __builtin_amdgcn_rsqf(ssq_row(ssq, row0 + ai * HALF + m * 16) * (1.0f / 1024.0f) + RMS_EPS) * sc;
;                         rs4[m + 1] = __builtin_amdgcn_rsqf(ssq_row(ssq, row0 + ai * HALF + (m + 1) * 16) * (1.0f / 1024.0f) + RMS_EPS) * sc;
;                     }
;                 }
;                 const int row = row0 + ai * HALF + m * 16;
;                 const float rs = rs4[m];
;                 bf16_t* rowp = O + (size_t)row * ldc + col0;
; #pragma unroll
;                 for (int bj = 0; bj < 2; ++bj) {
;                     f32x4 v[2] = {acc[ai][bj][m][0] * rs, acc[ai][bj][m][1] * rs};
;                     if (ksum) { csum[bj][0] += v[0]; csum[bj][1] += v[1]; }
; #pragma unroll
;                     for (int n = 0; n < 2; ++n) {
;                         f32x4 lbv = (f32x4){0.f, 0.f, 0.f, 0.f};
;                         if (act == 2) lbv = *(const f32x4*)(lb + (col0 - 1024) + bj * HALF + 4 * n);
; #pragma unroll
;                         for (int e = 0; e < 4; ++e) {
;                             float x = v[n][e];
;                             if (act == 1) x = silu_f(x);
;                             else if (act == 2) { const float l = lbv[e]; x = __logf(l + (1.f - l) * __builtin_amdgcn_rcpf(1.f + __expf(-x))); }
;                             else if (act == 3) { x = fmaxf(x, 0.f); x = x * x; }
;                             v[n][e] = x;
;                         }
;                     }
;                     u32x4 w; w.x = cvt_pk_bf16(v[0][0], v[0][1]); w.y = cvt_pk_bf16(v[0][2], v[0][3]); w.z = cvt_pk_bf16(v[1][0], v[1][1]); w.w = cvt_pk_bf16(v[1][2], v[1][3]);
;                     *(u32x4*)(rowp + bj * HALF) = w;
.LBB0_1769:
	s_andn2_b64 vcc, exec, s[0:1]
	s_cbranch_vccnz .LBB0_1771
	v_lshlrev_b64 v[32:33], 6, v[38:39]
	v_lshl_add_u64 v[48:49], s[6:7], 0, v[32:33]
	global_load_dwordx4 v[32:35], v[48:49], off offset:16
	global_load_dwordx4 v[40:43], v[48:49], off offset:48
	global_load_dwordx4 v[44:47], v[48:49], off
	s_nop 0
	global_load_dwordx4 v[48:51], v[48:49], off offset:32
	s_waitcnt vmcnt(0)
	v_mov_b32_e32 v52, v44
	v_mov_b32_e32 v53, v48
	v_mov_b32_e32 v48, v45
	v_add_f32_e32 v44, v52, v48
	v_add_f32_e32 v45, v53, v49
	v_mov_b32_e32 v48, v46
	v_mov_b32_e32 v49, v50
	v_mov_b32_e32 v50, v47
	v_add_f32_e32 v46, v48, v50
	v_add_f32_e32 v47, v49, v51
	s_nop 0
	v_add_f32_e32 v44, v44, v46
	v_add_f32_e32 v45, v45, v47
	v_mov_b32_e32 v46, v32
	v_mov_b32_e32 v47, v40
	v_mov_b32_e32 v40, v33
	v_add_f32_e32 v32, v46, v40
	v_add_f32_e32 v33, v47, v41
	v_mov_b32_e32 v40, v34
	v_mov_b32_e32 v41, v42
	v_mov_b32_e32 v42, v35
	v_add_f32_e32 v34, v40, v42
	v_add_f32_e32 v35, v41, v43
	s_nop 0
	v_add_f32_e32 v32, v32, v34
	v_add_f32_e32 v33, v33, v35
	s_nop 0
	v_add_f32_e32 v32, v44, v32
	v_add_f32_e32 v33, v45, v33
	s_nop 0
	v_add_f32_e32 v32, v32, v33
	v_fmamk_f32 v32, v32, 0x3a800000, v211
	v_rsq_f32_e32 v34, v32
	v_lshlrev_b64 v[32:33], 6, v[36:37]
	v_lshl_add_u64 v[32:33], s[6:7], 0, v[32:33]
	global_load_dwordx4 v[40:43], v[32:33], off offset:16
	global_load_dwordx4 v[44:47], v[32:33], off offset:48
	global_load_dwordx4 v[48:51], v[32:33], off
	global_load_dwordx4 v[52:55], v[32:33], off offset:32
	s_waitcnt vmcnt(1)
	v_mov_b32_e32 v32, v48
	s_waitcnt vmcnt(0)
	v_mov_b32_e32 v33, v52
	v_mov_b32_e32 v52, v49
	v_mov_b32_e32 v48, v50
	v_mov_b32_e32 v49, v54
	v_mov_b32_e32 v54, v51
	v_add_f32_e32 v32, v32, v52
	v_add_f32_e32 v33, v33, v53
	v_add_f32_e32 v48, v48, v54
	v_add_f32_e32 v49, v49, v55
	s_nop 0
	v_add_f32_e32 v32, v32, v48
	v_add_f32_e32 v33, v33, v49
	v_mov_b32_e32 v48, v40
	v_mov_b32_e32 v49, v44
	v_mov_b32_e32 v44, v41
	v_add_f32_e32 v40, v48, v44
	v_add_f32_e32 v41, v49, v45
	v_mov_b32_e32 v44, v42
	v_mov_b32_e32 v45, v46
	v_mov_b32_e32 v46, v43
	v_add_f32_e32 v42, v44, v46
	v_add_f32_e32 v43, v45, v47
	s_nop 0
	v_add_f32_e32 v40, v40, v42
	v_add_f32_e32 v41, v41, v43
	s_nop 0
	v_add_f32_e32 v32, v32, v40
	v_add_f32_e32 v33, v33, v41
	s_nop 0
	v_add_f32_e32 v32, v32, v33
	v_fmamk_f32 v32, v32, 0x3a800000, v211
	v_rsq_f32_e32 v32, v32
.LBB0_1771:
	v_mul_f32_e32 v24, v24, v34
	v_mul_f32_e32 v25, v25, v34
	v_mul_f32_e32 v26, v26, v34
	v_mul_f32_e32 v27, v27, v34
	v_max_f32_e32 v24, 0, v24
	v_mul_f32_e32 v33, v24, v24
	v_max_f32_e32 v24, 0, v25
	v_lshlrev_b64 v[38:39], 13, v[38:39]
	v_mul_f32_e32 v30, v30, v34
	v_mul_f32_e32 v31, v31, v34
	v_mul_f32_e32 v28, v28, v34
	v_mul_f32_e32 v29, v29, v34
	v_mul_f32_e32 v35, v24, v24
	v_max_f32_e32 v24, 0, v26
	v_lshl_add_u64 v[38:39], s[14:15], 0, v[38:39]
	v_max_f32_e32 v28, 0, v28
	v_max_f32_e32 v29, 0, v29
	v_mul_f32_e32 v40, v24, v24
	v_max_f32_e32 v24, 0, v27
	v_mul_f32_e32 v16, v16, v34
	v_mul_f32_e32 v17, v17, v34
	v_lshl_add_u64 v[38:39], v[38:39], 0, v[138:139]
	v_mul_f32_e32 v28, v28, v28
	v_mul_f32_e32 v29, v29, v29
	v_max_f32_e32 v30, 0, v30
	v_max_f32_e32 v31, 0, v31
	v_mul_f32_e32 v27, v24, v24
	v_cvt_pk_bf16_f32 v24, v28, v29
	v_max_f32_e32 v16, 0, v16
	v_mul_f32_e32 v30, v30, v30
	v_mul_f32_e32 v31, v31, v31
	v_cvt_pk_bf16_f32 v25, v30, v31
	v_cvt_pk_bf16_f32 v26, v33, v35
	v_cvt_pk_bf16_f32 v27, v40, v27
	global_store_dwordx4 v[38:39], v[24:27], off
	v_mul_f32_e32 v18, v18, v34
	v_mul_f32_e32 v19, v19, v34
	v_mul_f32_e32 v22, v22, v34
	v_mul_f32_e32 v23, v23, v34
	v_mul_f32_e32 v24, v16, v16
	v_max_f32_e32 v16, 0, v17
	v_mul_f32_e32 v20, v20, v34
	v_mul_f32_e32 v21, v21, v34
	v_mul_f32_e32 v25, v16, v16
	v_max_f32_e32 v16, 0, v18
	v_max_f32_e32 v20, 0, v20
	v_max_f32_e32 v21, 0, v21
	v_max_f32_e32 v22, 0, v22
	v_max_f32_e32 v23, 0, v23
	v_mul_f32_e32 v26, v16, v16
	v_max_f32_e32 v16, 0, v19
	v_mul_f32_e32 v8, v8, v32
	v_mul_f32_e32 v9, v9, v32
	v_mul_f32_e32 v20, v20, v20
	v_mul_f32_e32 v21, v21, v21
	v_mul_f32_e32 v22, v22, v22
	v_mul_f32_e32 v23, v23, v23
	v_mul_f32_e32 v19, v16, v16
	v_cvt_pk_bf16_f32 v16, v20, v21
	v_cvt_pk_bf16_f32 v17, v22, v23
	v_cvt_pk_bf16_f32 v18, v24, v25
	v_max_f32_e32 v8, 0, v8
	v_cvt_pk_bf16_f32 v19, v26, v19
	global_store_dwordx4 v[38:39], v[16:19], off offset:256
	v_mul_f32_e32 v10, v10, v32
	v_mul_f32_e32 v11, v11, v32
	v_mul_f32_e32 v12, v12, v32
	v_mul_f32_e32 v13, v13, v32
	v_mul_f32_e32 v18, v8, v8
	v_max_f32_e32 v8, 0, v9
	v_lshlrev_b64 v[16:17], 13, v[36:37]
	v_mul_f32_e32 v19, v8, v8
	v_max_f32_e32 v8, 0, v10
	v_lshl_add_u64 v[16:17], s[14:15], 0, v[16:17]
	v_mul_f32_e32 v14, v14, v32
	v_mul_f32_e32 v15, v15, v32
	v_max_f32_e32 v12, 0, v12
	v_max_f32_e32 v13, 0, v13
	v_mul_f32_e32 v20, v8, v8
	v_max_f32_e32 v8, 0, v11
	v_mul_f32_e32 v0, v0, v32
	v_mul_f32_e32 v1, v1, v32
	v_lshl_add_u64 v[16:17], v[16:17], 0, v[138:139]
	v_mul_f32_e32 v12, v12, v12
	v_mul_f32_e32 v13, v13, v13
	v_max_f32_e32 v14, 0, v14
	v_max_f32_e32 v15, 0, v15
	v_mul_f32_e32 v11, v8, v8
	v_cvt_pk_bf16_f32 v8, v12, v13
	v_max_f32_e32 v0, 0, v0
	v_mul_f32_e32 v14, v14, v14
	v_mul_f32_e32 v15, v15, v15
	v_cvt_pk_bf16_f32 v9, v14, v15
	v_cvt_pk_bf16_f32 v10, v18, v19
	v_cvt_pk_bf16_f32 v11, v20, v11
	global_store_dwordx4 v[16:17], v[8:11], off
	v_mul_f32_e32 v2, v2, v32
	v_mul_f32_e32 v3, v3, v32
	v_mul_f32_e32 v6, v6, v32
	v_mul_f32_e32 v7, v7, v32
	v_mul_f32_e32 v8, v0, v0
	v_max_f32_e32 v0, 0, v1
	v_mul_f32_e32 v9, v0, v0
	v_max_f32_e32 v0, 0, v2
	v_mul_f32_e32 v4, v4, v32
	v_mul_f32_e32 v5, v5, v32
	v_mul_f32_e32 v10, v0, v0
	v_max_f32_e32 v0, 0, v3
	v_max_f32_e32 v4, 0, v4
	v_max_f32_e32 v5, 0, v5
	v_max_f32_e32 v6, 0, v6
	v_max_f32_e32 v7, 0, v7
	v_mul_f32_e32 v3, v0, v0
	s_andn2_b64 vcc, exec, s[42:43]
	s_mov_b64 s[0:1], -1
	v_mul_f32_e32 v4, v4, v4
	v_mul_f32_e32 v5, v5, v5
	v_mul_f32_e32 v6, v6, v6
	v_mul_f32_e32 v7, v7, v7
	v_cvt_pk_bf16_f32 v0, v4, v5
	v_cvt_pk_bf16_f32 v1, v6, v7
	v_cvt_pk_bf16_f32 v2, v8, v9
	v_cvt_pk_bf16_f32 v3, v10, v3
	global_store_dwordx4 v[16:17], v[0:3], off offset:256
	s_cbranch_vccnz .LBB0_1744
	s_andn2_b64 vcc, exec, s[44:45]
	s_cbranch_vccnz .LBB0_1743
	s_barrier
	s_branch .LBB0_1743

; __device__ __forceinline__ unsigned cvt_pk_bf16(float lo, float hi) { unsigned r; asm volatile("v_cvt_pk_bf16_f32 %0, %1, %2" : "=v"(r) : "v"(lo), "v"(hi)); return r; }
;     __device__ __forceinline__ void operator()(const f32x4 (&acc)[2][2][4][2], const Unit& u, int wr, int wc, int fr, int fq, int, PG8_LAS unsigned char*) const {
;     ...
;                 for (int bj = 0; bj < 2; ++bj) xw[m][bj] = *(const u32x4*)(xb + (size_t)(row0 + ai * HALF + m * 16) * 1024 + col0 + bj * HALF);
; #pragma unroll
;             for (int m = 0; m < 4; ++m) {
;                 const int row = row0 + ai * HALF + m * 16; const size_t off = (size_t)row * 1024 + col0;
;                 float s = 0.f;
; #pragma unroll
;                 for (int bj = 0; bj < 2; ++bj) {
;                     const u32x4 xv = xw[m][bj];
;                     const f32x4 xo0 = {__builtin_bit_cast(float, xv.x << 16), __builtin_bit_cast(float, xv.x & 0xffff0000u), __builtin_bit_cast(float, xv.y << 16), __builtin_bit_cast(float, xv.y & 0xffff0000u)};
;                     const f32x4 xo1 = {__builtin_bit_cast(float, xv.z << 16), __builtin_bit_cast(float, xv.z & 0xffff0000u), __builtin_bit_cast(float, xv.w << 16), __builtin_bit_cast(float, xv.w & 0xffff0000u)};
;                     const f32x4 o0 = xo0 + acc[ai][bj][m][0] * csv[bj][0], o1 = xo1 + acc[ai][bj][m][1] * csv[bj][1];
;                     u32x4 w; w.x = cvt_pk_bf16(o0[0], o0[1]); w.y = cvt_pk_bf16(o0[2], o0[3]); w.z = cvt_pk_bf16(o1[0], o1[1]); w.w = cvt_pk_bf16(o1[2], o1[3]);
;                     if (!dry) *(u32x4*)(xb + off + bj * HALF) = w;
; #pragma unroll
;                     for (int q = 0; q < 4; ++q) { const unsigned ww = w[q]; const float ra = __builtin_bit_cast(float, ww << 16), rb = __builtin_bit_cast(float, ww & 0xffff0000u); s += ra * ra + rb * rb; }
;                 }
;                 s += __shfl_xor(s, 16); s += __shfl_xor(s, 32);
;                 if (fq == 0 && !dry) ssq_next[(size_t)row * 16 + u.pn * 4 + wc] = s;
;             }
.Lal4_skip:
	s_waitcnt vmcnt(0)
	v_lshlrev_b32_e32 v172, 16, v176
	v_and_b32_e32 v173, 0xffff0000, v176
	v_lshlrev_b32_e32 v176, 16, v177
	v_and_b32_e32 v177, 0xffff0000, v177
	v_lshlrev_b32_e32 v198, 16, v178
	v_and_b32_e32 v199, 0xffff0000, v178
	v_lshlrev_b32_e32 v202, 16, v194
	v_and_b32_e32 v203, 0xffff0000, v194
	v_lshlrev_b32_e32 v178, 16, v179
	v_and_b32_e32 v179, 0xffff0000, v179
	v_lshlrev_b32_e32 v194, 16, v195
	v_and_b32_e32 v195, 0xffff0000, v195
	v_add_f32_e32 v126, v126, v176
	v_add_f32_e32 v127, v127, v177
	v_add_f32_e32 v124, v124, v172
	v_add_f32_e32 v125, v125, v173
	v_add_f32_e32 v120, v120, v198
	v_add_f32_e32 v121, v121, v199
	v_add_f32_e32 v176, v112, v202
	v_add_f32_e32 v177, v113, v203
	v_cvt_pk_bf16_f32 v112, v124, v125
	v_cvt_pk_bf16_f32 v113, v126, v127
	v_add_f32_e32 v122, v122, v178
	v_add_f32_e32 v123, v123, v179
	v_add_f32_e32 v172, v114, v194
	v_add_f32_e32 v173, v115, v195
	v_cvt_pk_bf16_f32 v114, v120, v121
	v_cvt_pk_bf16_f32 v115, v122, v123
	global_store_dwordx4 v[196:197], v[112:115], off
	v_lshlrev_b32_e32 v120, 16, v112
	v_lshlrev_b32_e32 v121, 16, v113
	v_and_b32_e32 v112, 0xffff0000, v112
	v_and_b32_e32 v113, 0xffff0000, v113
	v_lshlrev_b32_e32 v200, 16, v192
	v_and_b32_e32 v201, 0xffff0000, v192
	v_lshlrev_b32_e32 v122, 16, v114
	v_and_b32_e32 v114, 0xffff0000, v114
	v_mul_f32_e32 v112, v112, v112
	v_mul_f32_e32 v113, v113, v113
	v_add_f32_e32 v116, v116, v200
	v_add_f32_e32 v117, v117, v201
	v_lshlrev_b32_e32 v123, 16, v115
	v_and_b32_e32 v115, 0xffff0000, v115
	v_mul_f32_e32 v114, v114, v114
	v_fmac_f32_e32 v112, v120, v120
	v_fmac_f32_e32 v113, v121, v121
	v_lshlrev_b32_e32 v192, 16, v193
	v_and_b32_e32 v193, 0xffff0000, v193
	v_cvt_pk_bf16_f32 v116, v116, v117
	v_mul_f32_e32 v115, v115, v115
	v_and_b32_e32 v125, 0xffff0000, v116
	v_fmac_f32_e32 v114, v122, v122
	v_add_f32_e32 v112, v112, v113
	v_add_f32_e32 v118, v118, v192
	v_add_f32_e32 v119, v119, v193
	v_lshlrev_b32_e32 v124, 16, v116
	v_cvt_pk_bf16_f32 v117, v118, v119
	v_fmac_f32_e32 v115, v123, v123
	v_and_b32_e32 v127, 0xffff0000, v117
	v_mul_f32_e32 v120, v125, v125
	v_add_f32_e32 v112, v112, v114
	v_cvt_pk_bf16_f32 v118, v176, v177
	v_cvt_pk_bf16_f32 v119, v172, v173
	v_lshlrev_b32_e32 v126, 16, v117
	v_and_b32_e32 v173, 0xffff0000, v118
	v_mul_f32_e32 v121, v127, v127
	v_fmac_f32_e32 v120, v124, v124
	v_add_f32_e32 v112, v112, v115
	v_lshlrev_b32_e32 v172, 16, v118
	v_mul_f32_e32 v122, v173, v173
	v_fmac_f32_e32 v121, v126, v126
	v_add_f32_e32 v112, v112, v120
	v_and_b32_e32 v114, 0xffff0000, v119
	v_fmac_f32_e32 v122, v172, v172
	v_add_f32_e32 v112, v112, v121
	v_lshlrev_b32_e32 v113, 16, v119
	v_mul_f32_e32 v114, v114, v114
	v_add_f32_e32 v112, v112, v122
	v_fmac_f32_e32 v114, v113, v113
	v_add_f32_e32 v113, v112, v114
	v_and_b32_e32 v114, 64, v213
	v_xor_b32_e32 v112, 16, v213
	v_add_u32_e32 v115, 64, v114
	v_cmp_lt_i32_e32 vcc, v112, v115
	global_store_dwordx4 v[196:197], v[116:119], off offset:256
	s_nop 0
	v_cndmask_b32_e32 v112, v213, v112, vcc
	v_lshlrev_b32_e32 v112, 2, v112
	ds_bpermute_b32 v114, v112, v113
	s_waitcnt lgkmcnt(0)
	v_add_f32_e32 v114, v113, v114
	v_xor_b32_e32 v113, 32, v213
	v_cmp_lt_i32_e32 vcc, v113, v115
	s_nop 1
	v_cndmask_b32_e32 v113, v213, v113, vcc
	v_lshlrev_b32_e32 v113, 2, v113
	ds_bpermute_b32 v115, v113, v114
	s_and_saveexec_b64 s[54:55], s[40:41]
	s_cbranch_execz .LBB0_1850
	v_lshlrev_b64 v[116:117], 6, v[166:167]
	v_lshl_add_u64 v[116:117], s[24:25], 0, v[116:117]
	v_lshl_add_u64 v[116:117], s[0:1], 2, v[116:117]
	s_lshl_b32 s16, s63, 2
	v_lshl_add_u64 v[116:117], v[116:117], 0, s[16:17]
	s_waitcnt lgkmcnt(0)
	v_add_f32_e32 v114, v114, v115
	global_store_dword v[116:117], v114, off
.LBB0_1850:
	s_or_b64 exec, exec, s[54:55]
	v_lshlrev_b32_e32 v114, 16, v148
	s_waitcnt lgkmcnt(0)
	v_and_b32_e32 v115, 0xffff0000, v148
	v_lshlrev_b32_e32 v118, 16, v150
	v_and_b32_e32 v119, 0xffff0000, v150
	v_lshlrev_b32_e32 v120, 16, v151
	v_and_b32_e32 v121, 0xffff0000, v151
	v_add_f32_e32 v108, v108, v114
	v_add_f32_e32 v109, v109, v115
	v_lshlrev_b32_e32 v116, 16, v149
	v_and_b32_e32 v117, 0xffff0000, v149
	v_add_f32_e32 v114, v106, v120
	v_add_f32_e32 v115, v107, v121
	v_add_f32_e32 v106, v104, v118
	v_add_f32_e32 v107, v105, v119
	v_cvt_pk_bf16_f32 v104, v108, v109
	v_lshl_add_u64 v[108:109], s[10:11], 0, v[186:187]
	v_add_f32_e32 v110, v110, v116
	v_add_f32_e32 v111, v111, v117
	v_lshl_add_u64 v[108:109], v[162:163], 1, v[108:109]
	v_cvt_pk_bf16_f32 v105, v110, v111
	v_cvt_pk_bf16_f32 v106, v106, v107
	v_cvt_pk_bf16_f32 v107, v114, v115
	global_store_dwordx4 v[108:109], v[104:107], off
	v_lshlrev_b32_e32 v110, 16, v104
	v_and_b32_e32 v111, 0xffff0000, v146
	v_and_b32_e32 v104, 0xffff0000, v104
	v_mul_f32_e32 v104, v104, v104
	v_fmac_f32_e32 v104, v110, v110
	v_lshlrev_b32_e32 v110, 16, v105
	v_and_b32_e32 v105, 0xffff0000, v105
	v_mul_f32_e32 v105, v105, v105
	v_fmac_f32_e32 v105, v110, v110
	v_add_f32_e32 v104, v104, v105
	v_lshlrev_b32_e32 v105, 16, v106
	v_and_b32_e32 v106, 0xffff0000, v106
	v_mul_f32_e32 v106, v106, v106
	v_fmac_f32_e32 v106, v105, v105
	v_add_f32_e32 v104, v104, v106
	v_and_b32_e32 v106, 0xffff0000, v107
	v_lshlrev_b32_e32 v105, 16, v107
	v_mul_f32_e32 v106, v106, v106
	v_fmac_f32_e32 v106, v105, v105
	v_add_f32_e32 v116, v104, v106
	v_lshlrev_b32_e32 v104, 16, v144
	v_and_b32_e32 v105, 0xffff0000, v144
	v_lshlrev_b32_e32 v110, 16, v146
	v_lshlrev_b32_e32 v106, 16, v145
	v_and_b32_e32 v107, 0xffff0000, v145
	v_lshlrev_b32_e32 v114, 16, v147
	v_and_b32_e32 v115, 0xffff0000, v147
	v_add_f32_e32 v100, v100, v104
	v_add_f32_e32 v101, v101, v105
	v_add_f32_e32 v96, v96, v110
	v_add_f32_e32 v97, v97, v111
	v_add_f32_e32 v102, v102, v106
	v_add_f32_e32 v103, v103, v107
	v_add_f32_e32 v104, v98, v114
	v_add_f32_e32 v105, v99, v115
	v_cvt_pk_bf16_f32 v98, v100, v101
	v_cvt_pk_bf16_f32 v99, v102, v103
	v_cvt_pk_bf16_f32 v100, v96, v97
	s_nop 0
	v_and_b32_e32 v97, 0xffff0000, v98
	v_lshlrev_b32_e32 v96, 16, v98
	v_mul_f32_e32 v97, v97, v97
	v_fmac_f32_e32 v97, v96, v96
	v_and_b32_e32 v102, 0xffff0000, v99
	v_add_f32_e32 v96, v116, v97
	v_lshlrev_b32_e32 v97, 16, v99
	v_mul_f32_e32 v102, v102, v102
	v_fmac_f32_e32 v102, v97, v97
	v_add_f32_e32 v96, v96, v102
	v_and_b32_e32 v102, 0xffff0000, v100
	v_lshlrev_b32_e32 v97, 16, v100
	v_mul_f32_e32 v102, v102, v102
	v_fmac_f32_e32 v102, v97, v97
	v_cvt_pk_bf16_f32 v101, v104, v105
	v_add_f32_e32 v96, v96, v102
	v_and_b32_e32 v102, 0xffff0000, v101
	v_lshlrev_b32_e32 v97, 16, v101
	v_mul_f32_e32 v102, v102, v102
	v_fmac_f32_e32 v102, v97, v97
	v_add_f32_e32 v96, v96, v102
	ds_bpermute_b32 v97, v112, v96
	global_store_dwordx4 v[108:109], v[98:101], off offset:256
	s_waitcnt lgkmcnt(0)
	v_add_f32_e32 v96, v96, v97
	ds_bpermute_b32 v97, v113, v96
	s_and_saveexec_b64 s[54:55], s[40:41]
	s_cbranch_execz .LBB0_1852
; __device__ __forceinline__ unsigned cvt_pk_bf16(float lo, float hi) { unsigned r; asm volatile("v_cvt_pk_bf16_f32 %0, %1, %2" : "=v"(r) : "v"(lo), "v"(hi)); return r; }
;     __device__ __forceinline__ void operator()(const f32x4 (&acc)[2][2][4][2], const Unit& u, int wr, int wc, int fr, int fq, int, PG8_LAS unsigned char*) const {
;     ...
;                 for (int bj = 0; bj < 2; ++bj) xw[m][bj] = *(const u32x4*)(xb + (size_t)(row0 + ai * HALF + m * 16) * 1024 + col0 + bj * HALF);
; #pragma unroll
;             for (int m = 0; m < 4; ++m) {
;                 const int row = row0 + ai * HALF + m * 16; const size_t off = (size_t)row * 1024 + col0;
;                 float s = 0.f;
; #pragma unroll
;                 for (int bj = 0; bj < 2; ++bj) {
;                     const u32x4 xv = xw[m][bj];
;                     const f32x4 xo0 = {__builtin_bit_cast(float, xv.x << 16), __builtin_bit_cast(float, xv.x & 0xffff0000u), __builtin_bit_cast(float, xv.y << 16), __builtin_bit_cast(float, xv.y & 0xffff0000u)};
;                     const f32x4 xo1 = {__builtin_bit_cast(float, xv.z << 16), __builtin_bit_cast(float, xv.z & 0xffff0000u), __builtin_bit_cast(float, xv.w << 16), __builtin_bit_cast(float, xv.w & 0xffff0000u)};
;                     const f32x4 o0 = xo0 + acc[ai][bj][m][0] * csv[bj][0], o1 = xo1 + acc[ai][bj][m][1] * csv[bj][1];
;                     u32x4 w; w.x = cvt_pk_bf16(o0[0], o0[1]); w.y = cvt_pk_bf16(o0[2], o0[3]); w.z = cvt_pk_bf16(o1[0], o1[1]); w.w = cvt_pk_bf16(o1[2], o1[3]);
;                     if (!dry) *(u32x4*)(xb + off + bj * HALF) = w;
; #pragma unroll
;                     for (int q = 0; q < 4; ++q) { const unsigned ww = w[q]; const float ra = __builtin_bit_cast(float, ww << 16), rb = __builtin_bit_cast(float, ww & 0xffff0000u); s += ra * ra + rb * rb; }
;                 }
;                 s += __shfl_xor(s, 16); s += __shfl_xor(s, 32);
;                 if (fq == 0 && !dry) ssq_next[(size_t)row * 16 + u.pn * 4 + wc] = s;
;             }
	v_lshlrev_b64 v[98:99], 6, v[184:185]
	v_lshl_add_u64 v[98:99], s[24:25], 0, v[98:99]
	v_lshl_add_u64 v[98:99], s[0:1], 2, v[98:99]
	s_lshl_b32 s16, s63, 2
	v_lshl_add_u64 v[98:99], v[98:99], 0, s[16:17]
	s_waitcnt lgkmcnt(0)
	v_add_f32_e32 v96, v96, v97
	global_store_dword v[98:99], v96, off
.LBB0_1852:
	s_or_b64 exec, exec, s[54:55]
	v_lshlrev_b32_e32 v96, 16, v140
	s_waitcnt lgkmcnt(0)
	v_and_b32_e32 v97, 0xffff0000, v140
	v_lshlrev_b32_e32 v100, 16, v142
	v_and_b32_e32 v101, 0xffff0000, v142
	v_lshlrev_b32_e32 v102, 16, v143
	v_and_b32_e32 v103, 0xffff0000, v143
	v_add_f32_e32 v92, v92, v96
	v_add_f32_e32 v93, v93, v97
	v_lshlrev_b32_e32 v98, 16, v141
	v_and_b32_e32 v99, 0xffff0000, v141
	v_add_f32_e32 v96, v90, v102
	v_add_f32_e32 v97, v91, v103
	v_add_f32_e32 v90, v88, v100
	v_add_f32_e32 v91, v89, v101
	v_cvt_pk_bf16_f32 v88, v92, v93
	v_lshl_add_u64 v[92:93], s[10:11], 0, v[182:183]
	v_add_f32_e32 v94, v94, v98
	v_add_f32_e32 v95, v95, v99
	v_lshl_add_u64 v[92:93], v[162:163], 1, v[92:93]
	v_cvt_pk_bf16_f32 v89, v94, v95
	v_cvt_pk_bf16_f32 v90, v90, v91
	v_cvt_pk_bf16_f32 v91, v96, v97
	global_store_dwordx4 v[92:93], v[88:91], off
	v_lshlrev_b32_e32 v94, 16, v88
	v_and_b32_e32 v95, 0xffff0000, v138
	v_and_b32_e32 v88, 0xffff0000, v88
	v_mul_f32_e32 v88, v88, v88
	v_fmac_f32_e32 v88, v94, v94
	v_lshlrev_b32_e32 v94, 16, v89
	v_and_b32_e32 v89, 0xffff0000, v89
	v_mul_f32_e32 v89, v89, v89
	v_fmac_f32_e32 v89, v94, v94
	v_add_f32_e32 v88, v88, v89
	v_lshlrev_b32_e32 v89, 16, v90
	v_and_b32_e32 v90, 0xffff0000, v90
	v_mul_f32_e32 v90, v90, v90
	v_fmac_f32_e32 v90, v89, v89
	v_add_f32_e32 v88, v88, v90
	v_and_b32_e32 v90, 0xffff0000, v91
	v_lshlrev_b32_e32 v89, 16, v91
	v_mul_f32_e32 v90, v90, v90
	v_fmac_f32_e32 v90, v89, v89
	v_add_f32_e32 v98, v88, v90
	v_lshlrev_b32_e32 v88, 16, v136
	v_and_b32_e32 v89, 0xffff0000, v136
	v_lshlrev_b32_e32 v94, 16, v138
	v_lshlrev_b32_e32 v90, 16, v137
	v_and_b32_e32 v91, 0xffff0000, v137
	v_lshlrev_b32_e32 v96, 16, v139
	v_and_b32_e32 v97, 0xffff0000, v139
	v_add_f32_e32 v84, v84, v88
	v_add_f32_e32 v85, v85, v89
	v_add_f32_e32 v80, v80, v94
	v_add_f32_e32 v81, v81, v95
	v_add_f32_e32 v86, v86, v90
	v_add_f32_e32 v87, v87, v91
	v_add_f32_e32 v88, v82, v96
	v_add_f32_e32 v89, v83, v97
	v_cvt_pk_bf16_f32 v82, v84, v85
	v_cvt_pk_bf16_f32 v83, v86, v87
	v_cvt_pk_bf16_f32 v84, v80, v81
	s_nop 0
	v_and_b32_e32 v81, 0xffff0000, v82
	v_lshlrev_b32_e32 v80, 16, v82
	v_mul_f32_e32 v81, v81, v81
	v_fmac_f32_e32 v81, v80, v80
	v_and_b32_e32 v86, 0xffff0000, v83
	v_add_f32_e32 v80, v98, v81
	v_lshlrev_b32_e32 v81, 16, v83
	v_mul_f32_e32 v86, v86, v86
	v_fmac_f32_e32 v86, v81, v81
	v_add_f32_e32 v80, v80, v86
	v_and_b32_e32 v86, 0xffff0000, v84
	v_lshlrev_b32_e32 v81, 16, v84
	v_mul_f32_e32 v86, v86, v86
	v_fmac_f32_e32 v86, v81, v81
	v_cvt_pk_bf16_f32 v85, v88, v89
	v_add_f32_e32 v80, v80, v86
	v_and_b32_e32 v86, 0xffff0000, v85
	v_lshlrev_b32_e32 v81, 16, v85
	v_mul_f32_e32 v86, v86, v86
	v_fmac_f32_e32 v86, v81, v81
	v_add_f32_e32 v80, v80, v86
	ds_bpermute_b32 v81, v112, v80
	global_store_dwordx4 v[92:93], v[82:85], off offset:256
	s_waitcnt lgkmcnt(0)
	v_add_f32_e32 v80, v80, v81
	ds_bpermute_b32 v81, v113, v80
	s_and_saveexec_b64 s[54:55], s[40:41]
	s_cbranch_execz .LBB0_1854
	v_lshlrev_b64 v[82:83], 6, v[180:181]
	v_lshl_add_u64 v[82:83], s[24:25], 0, v[82:83]
	v_lshl_add_u64 v[82:83], s[0:1], 2, v[82:83]
	s_lshl_b32 s16, s63, 2
	v_lshl_add_u64 v[82:83], v[82:83], 0, s[16:17]
	s_waitcnt lgkmcnt(0)
	v_add_f32_e32 v80, v80, v81
	global_store_dword v[82:83], v80, off
.LBB0_1854:
	s_or_b64 exec, exec, s[54:55]
	v_lshlrev_b32_e32 v80, 16, v132
	s_waitcnt lgkmcnt(0)
	v_and_b32_e32 v81, 0xffff0000, v132
	v_lshlrev_b32_e32 v84, 16, v134
	v_and_b32_e32 v85, 0xffff0000, v134
	v_lshlrev_b32_e32 v86, 16, v135
	v_and_b32_e32 v87, 0xffff0000, v135
	v_add_f32_e32 v76, v76, v80
	v_add_f32_e32 v77, v77, v81
	v_lshlrev_b32_e32 v82, 16, v133
	v_and_b32_e32 v83, 0xffff0000, v133
	v_add_f32_e32 v80, v74, v86
	v_add_f32_e32 v81, v75, v87
	v_add_f32_e32 v74, v72, v84
	v_add_f32_e32 v75, v73, v85
	v_cvt_pk_bf16_f32 v72, v76, v77
	v_lshl_add_u64 v[76:77], s[10:11], 0, v[170:171]
	v_add_f32_e32 v78, v78, v82
	v_add_f32_e32 v79, v79, v83
	v_lshl_add_u64 v[76:77], v[162:163], 1, v[76:77]
	v_cvt_pk_bf16_f32 v73, v78, v79
	v_cvt_pk_bf16_f32 v74, v74, v75
	v_cvt_pk_bf16_f32 v75, v80, v81
	global_store_dwordx4 v[76:77], v[72:75], off
	v_lshlrev_b32_e32 v78, 16, v72
	v_and_b32_e32 v79, 0xffff0000, v130
	v_and_b32_e32 v72, 0xffff0000, v72
	v_mul_f32_e32 v72, v72, v72
	v_fmac_f32_e32 v72, v78, v78
	v_lshlrev_b32_e32 v78, 16, v73
	v_and_b32_e32 v73, 0xffff0000, v73
	v_mul_f32_e32 v73, v73, v73
	v_fmac_f32_e32 v73, v78, v78
	v_add_f32_e32 v72, v72, v73
	v_lshlrev_b32_e32 v73, 16, v74
	v_and_b32_e32 v74, 0xffff0000, v74
	v_mul_f32_e32 v74, v74, v74
	v_fmac_f32_e32 v74, v73, v73
	v_add_f32_e32 v72, v72, v74
	v_and_b32_e32 v74, 0xffff0000, v75
	v_lshlrev_b32_e32 v73, 16, v75
	v_mul_f32_e32 v74, v74, v74
	v_fmac_f32_e32 v74, v73, v73
	v_add_f32_e32 v82, v72, v74
	v_lshlrev_b32_e32 v72, 16, v128
	v_and_b32_e32 v73, 0xffff0000, v128
	v_lshlrev_b32_e32 v78, 16, v130
	v_lshlrev_b32_e32 v74, 16, v129
	v_and_b32_e32 v75, 0xffff0000, v129
	v_lshlrev_b32_e32 v80, 16, v131
	v_and_b32_e32 v81, 0xffff0000, v131
	v_add_f32_e32 v68, v68, v72
	v_add_f32_e32 v69, v69, v73
	v_add_f32_e32 v64, v64, v78
	v_add_f32_e32 v65, v65, v79
	v_add_f32_e32 v70, v70, v74
	v_add_f32_e32 v71, v71, v75
	v_add_f32_e32 v72, v66, v80
	v_add_f32_e32 v73, v67, v81
	v_cvt_pk_bf16_f32 v66, v68, v69
	v_cvt_pk_bf16_f32 v67, v70, v71
	v_cvt_pk_bf16_f32 v68, v64, v65
	s_nop 0
	v_and_b32_e32 v65, 0xffff0000, v66
	v_lshlrev_b32_e32 v64, 16, v66
	v_mul_f32_e32 v65, v65, v65
	v_fmac_f32_e32 v65, v64, v64
	v_and_b32_e32 v70, 0xffff0000, v67
	v_add_f32_e32 v64, v82, v65
	v_lshlrev_b32_e32 v65, 16, v67
	v_mul_f32_e32 v70, v70, v70
	v_fmac_f32_e32 v70, v65, v65
	v_add_f32_e32 v64, v64, v70
	v_and_b32_e32 v70, 0xffff0000, v68
	v_lshlrev_b32_e32 v65, 16, v68
	v_mul_f32_e32 v70, v70, v70
	v_fmac_f32_e32 v70, v65, v65
	v_cvt_pk_bf16_f32 v69, v72, v73
	v_add_f32_e32 v64, v64, v70
	v_and_b32_e32 v70, 0xffff0000, v69
	v_lshlrev_b32_e32 v65, 16, v69
	v_mul_f32_e32 v70, v70, v70
	v_fmac_f32_e32 v70, v65, v65
	v_add_f32_e32 v64, v64, v70
	ds_bpermute_b32 v65, v112, v64
	global_store_dwordx4 v[76:77], v[66:69], off offset:256
	s_waitcnt lgkmcnt(0)
	v_add_f32_e32 v64, v64, v65
	ds_bpermute_b32 v65, v113, v64
	s_and_saveexec_b64 s[54:55], s[40:41]
	s_cbranch_execz .LBB0_1856
	v_lshlrev_b64 v[66:67], 6, v[168:169]
	v_lshl_add_u64 v[66:67], s[24:25], 0, v[66:67]
	v_lshl_add_u64 v[66:67], s[0:1], 2, v[66:67]
	s_lshl_b32 s16, s63, 2
	v_lshl_add_u64 v[66:67], v[66:67], 0, s[16:17]
	s_waitcnt lgkmcnt(0)
	v_add_f32_e32 v64, v64, v65
	global_store_dword v[66:67], v64, off
; __device__ __forceinline__ unsigned cvt_pk_bf16(float lo, float hi) { unsigned r; asm volatile("v_cvt_pk_bf16_f32 %0, %1, %2" : "=v"(r) : "v"(lo), "v"(hi)); return r; }
;     __device__ __forceinline__ void operator()(const f32x4 (&acc)[2][2][4][2], const Unit& u, int wr, int wc, int fr, int fq, int, PG8_LAS unsigned char*) const {
;     ...
;         for (int ai = 0; ai < 2; ++ai) {
;             u32x4 xw[4][2];
; #pragma unroll
;             for (int m = 0; m < 4; ++m)
; #pragma unroll
;                 for (int bj = 0; bj < 2; ++bj) xw[m][bj] = *(const u32x4*)(xb + (size_t)(row0 + ai * HALF + m * 16) * 1024 + col0 + bj * HALF);
; #pragma unroll
;             for (int m = 0; m < 4; ++m) {
;                 const int row = row0 + ai * HALF + m * 16; const size_t off = (size_t)row * 1024 + col0;
;                 float s = 0.f;
; #pragma unroll
;                 for (int bj = 0; bj < 2; ++bj) {
;                     const u32x4 xv = xw[m][bj];
;                     const f32x4 xo0 = {__builtin_bit_cast(float, xv.x << 16), __builtin_bit_cast(float, xv.x & 0xffff0000u), __builtin_bit_cast(float, xv.y << 16), __builtin_bit_cast(float, xv.y & 0xffff0000u)};
;                     const f32x4 xo1 = {__builtin_bit_cast(float, xv.z << 16), __builtin_bit_cast(float, xv.z & 0xffff0000u), __builtin_bit_cast(float, xv.w << 16), __builtin_bit_cast(float, xv.w & 0xffff0000u)};
;                     const f32x4 o0 = xo0 + acc[ai][bj][m][0] * csv[bj][0], o1 = xo1 + acc[ai][bj][m][1] * csv[bj][1];
;                     u32x4 w; w.x = cvt_pk_bf16(o0[0], o0[1]); w.y = cvt_pk_bf16(o0[2], o0[3]); w.z = cvt_pk_bf16(o1[0], o1[1]); w.w = cvt_pk_bf16(o1[2], o1[3]);
;                     if (!dry) *(u32x4*)(xb + off + bj * HALF) = w;
; #pragma unroll
;                     for (int q = 0; q < 4; ++q) { const unsigned ww = w[q]; const float ra = __builtin_bit_cast(float, ww << 16), rb = __builtin_bit_cast(float, ww & 0xffff0000u); s += ra * ra + rb * rb; }
;                 }
;                 s += __shfl_xor(s, 16); s += __shfl_xor(s, 32);
;                 if (fq == 0 && !dry) ssq_next[(size_t)row * 16 + u.pn * 4 + wc] = s;
;             }
.LBB0_1856:
	s_or_b64 exec, exec, s[54:55]
	v_add_u32_e32 v104, 0x80, v166
	v_ashrrev_i32_e32 v105, 31, v104
	v_lshlrev_b64 v[110:111], 11, v[104:105]
	s_waitcnt lgkmcnt(0)
	v_lshl_add_u64 v[64:65], v[164:165], 0, v[110:111]
	global_load_dwordx4 v[106:109], v[64:65], off
	global_load_dwordx4 v[88:91], v[64:65], off offset:256
	v_add_u32_e32 v100, 0x90, v166
	v_ashrrev_i32_e32 v101, 31, v100
	v_add_u32_e32 v96, 0xa0, v166
	v_lshlrev_b64 v[102:103], 11, v[100:101]
	v_ashrrev_i32_e32 v97, 31, v96
	v_add_u32_e32 v92, 0xb0, v166
	v_lshl_add_u64 v[64:65], v[164:165], 0, v[102:103]
	v_lshlrev_b64 v[98:99], 11, v[96:97]
	v_ashrrev_i32_e32 v93, 31, v92
	global_load_dwordx4 v[84:87], v[64:65], off
	global_load_dwordx4 v[80:83], v[64:65], off offset:256
	v_lshl_add_u64 v[64:65], v[164:165], 0, v[98:99]
	v_lshlrev_b64 v[94:95], 11, v[92:93]
	global_load_dwordx4 v[76:79], v[64:65], off
	global_load_dwordx4 v[72:75], v[64:65], off offset:256
	v_lshl_add_u64 v[64:65], v[164:165], 0, v[94:95]
	global_load_dwordx4 v[68:71], v[64:65], off
	s_nop 0
	global_load_dwordx4 v[64:67], v[64:65], off offset:256
	s_waitcnt vmcnt(7)
	v_lshlrev_b32_e32 v114, 16, v106
	v_and_b32_e32 v115, 0xffff0000, v106
	v_lshlrev_b32_e32 v106, 16, v107
	v_and_b32_e32 v107, 0xffff0000, v107
	v_lshlrev_b32_e32 v116, 16, v108
	v_and_b32_e32 v117, 0xffff0000, v108
	v_lshlrev_b32_e32 v108, 16, v109
	v_and_b32_e32 v109, 0xffff0000, v109
	v_add_f32_e32 v60, v60, v114
	v_add_f32_e32 v61, v61, v115
	v_add_f32_e32 v62, v62, v106
	v_add_f32_e32 v63, v63, v107
	v_add_f32_e32 v106, v58, v108
	v_add_f32_e32 v107, v59, v109
	v_add_f32_e32 v58, v56, v116
	v_add_f32_e32 v59, v57, v117
	v_cvt_pk_bf16_f32 v56, v60, v61
	v_lshl_add_u64 v[60:61], s[10:11], 0, v[110:111]
	v_lshl_add_u64 v[60:61], v[162:163], 1, v[60:61]
	v_cvt_pk_bf16_f32 v57, v62, v63
	v_cvt_pk_bf16_f32 v58, v58, v59
	v_cvt_pk_bf16_f32 v59, v106, v107
	global_store_dwordx4 v[60:61], v[56:59], off
	v_lshlrev_b32_e32 v62, 16, v56
	s_waitcnt vmcnt(7)
	v_and_b32_e32 v63, 0xffff0000, v90
	v_and_b32_e32 v56, 0xffff0000, v56
	v_mul_f32_e32 v56, v56, v56
	v_fmac_f32_e32 v56, v62, v62
	v_lshlrev_b32_e32 v62, 16, v57
	v_and_b32_e32 v57, 0xffff0000, v57
	v_mul_f32_e32 v57, v57, v57
	v_fmac_f32_e32 v57, v62, v62
	v_add_f32_e32 v56, v56, v57
	v_lshlrev_b32_e32 v57, 16, v58
	v_and_b32_e32 v58, 0xffff0000, v58
	v_mul_f32_e32 v58, v58, v58
	v_fmac_f32_e32 v58, v57, v57
	v_add_f32_e32 v56, v56, v58
	v_and_b32_e32 v58, 0xffff0000, v59
	v_lshlrev_b32_e32 v57, 16, v59
	v_mul_f32_e32 v58, v58, v58
	v_fmac_f32_e32 v58, v57, v57
	v_add_f32_e32 v106, v56, v58
	v_lshlrev_b32_e32 v56, 16, v88
	v_and_b32_e32 v57, 0xffff0000, v88
	v_lshlrev_b32_e32 v58, 16, v89
	v_and_b32_e32 v59, 0xffff0000, v89
	v_lshlrev_b32_e32 v62, 16, v90
	v_lshlrev_b32_e32 v88, 16, v91
	v_and_b32_e32 v89, 0xffff0000, v91
	v_add_f32_e32 v52, v52, v56
	v_add_f32_e32 v53, v53, v57
	v_add_f32_e32 v56, v50, v88
	v_add_f32_e32 v57, v51, v89
	v_add_f32_e32 v50, v48, v62
	v_add_f32_e32 v51, v49, v63
	v_cvt_pk_bf16_f32 v48, v52, v53
	v_add_f32_e32 v54, v54, v58
	v_add_f32_e32 v55, v55, v59
	v_lshlrev_b32_e32 v52, 16, v48
	v_cvt_pk_bf16_f32 v49, v54, v55
	v_cvt_pk_bf16_f32 v50, v50, v51
	v_cvt_pk_bf16_f32 v51, v56, v57
	global_store_dwordx4 v[60:61], v[48:51], off offset:256
	s_nop 1
	v_and_b32_e32 v48, 0xffff0000, v48
	v_mul_f32_e32 v48, v48, v48
	v_fmac_f32_e32 v48, v52, v52
	v_lshlrev_b32_e32 v52, 16, v49
	v_and_b32_e32 v49, 0xffff0000, v49
	v_mul_f32_e32 v49, v49, v49
	v_add_f32_e32 v48, v106, v48
	v_fmac_f32_e32 v49, v52, v52
	v_add_f32_e32 v48, v48, v49
	v_lshlrev_b32_e32 v49, 16, v50
	v_and_b32_e32 v50, 0xffff0000, v50
	v_mul_f32_e32 v50, v50, v50
	v_fmac_f32_e32 v50, v49, v49
	v_add_f32_e32 v48, v48, v50
	v_and_b32_e32 v50, 0xffff0000, v51
	v_lshlrev_b32_e32 v49, 16, v51
	v_mul_f32_e32 v50, v50, v50
	v_fmac_f32_e32 v50, v49, v49
	v_add_f32_e32 v48, v48, v50
	ds_bpermute_b32 v49, v112, v48
	s_waitcnt lgkmcnt(0)
	v_add_f32_e32 v48, v48, v49
	ds_bpermute_b32 v49, v113, v48
	s_and_saveexec_b64 s[54:55], s[40:41]
	s_cbranch_execz .LBB0_1858
	v_lshlrev_b64 v[50:51], 6, v[104:105]
	v_lshl_add_u64 v[50:51], s[24:25], 0, v[50:51]
	v_lshl_add_u64 v[50:51], s[0:1], 2, v[50:51]
	s_lshl_b32 s16, s63, 2
	v_lshl_add_u64 v[50:51], v[50:51], 0, s[16:17]
	s_waitcnt lgkmcnt(0)
	v_add_f32_e32 v48, v48, v49
	global_store_dword v[50:51], v48, off
; __device__ __forceinline__ unsigned cvt_pk_bf16(float lo, float hi) { unsigned r; asm volatile("v_cvt_pk_bf16_f32 %0, %1, %2" : "=v"(r) : "v"(lo), "v"(hi)); return r; }
;     __device__ __forceinline__ void operator()(const f32x4 (&acc)[2][2][4][2], const Unit& u, int wr, int wc, int fr, int fq, int, PG8_LAS unsigned char*) const {
;     ...
;                 for (int bj = 0; bj < 2; ++bj) xw[m][bj] = *(const u32x4*)(xb + (size_t)(row0 + ai * HALF + m * 16) * 1024 + col0 + bj * HALF);
; #pragma unroll
;             for (int m = 0; m < 4; ++m) {
;                 const int row = row0 + ai * HALF + m * 16; const size_t off = (size_t)row * 1024 + col0;
;                 float s = 0.f;
; #pragma unroll
;                 for (int bj = 0; bj < 2; ++bj) {
;                     const u32x4 xv = xw[m][bj];
;                     const f32x4 xo0 = {__builtin_bit_cast(float, xv.x << 16), __builtin_bit_cast(float, xv.x & 0xffff0000u), __builtin_bit_cast(float, xv.y << 16), __builtin_bit_cast(float, xv.y & 0xffff0000u)};
;                     const f32x4 xo1 = {__builtin_bit_cast(float, xv.z << 16), __builtin_bit_cast(float, xv.z & 0xffff0000u), __builtin_bit_cast(float, xv.w << 16), __builtin_bit_cast(float, xv.w & 0xffff0000u)};
;                     const f32x4 o0 = xo0 + acc[ai][bj][m][0] * csv[bj][0], o1 = xo1 + acc[ai][bj][m][1] * csv[bj][1];
;                     u32x4 w; w.x = cvt_pk_bf16(o0[0], o0[1]); w.y = cvt_pk_bf16(o0[2], o0[3]); w.z = cvt_pk_bf16(o1[0], o1[1]); w.w = cvt_pk_bf16(o1[2], o1[3]);
;                     if (!dry) *(u32x4*)(xb + off + bj * HALF) = w;
; #pragma unroll
;                     for (int q = 0; q < 4; ++q) { const unsigned ww = w[q]; const float ra = __builtin_bit_cast(float, ww << 16), rb = __builtin_bit_cast(float, ww & 0xffff0000u); s += ra * ra + rb * rb; }
;                 }
;                 s += __shfl_xor(s, 16); s += __shfl_xor(s, 32);
;                 if (fq == 0 && !dry) ssq_next[(size_t)row * 16 + u.pn * 4 + wc] = s;
;             }
.LBB0_1858:
	s_or_b64 exec, exec, s[54:55]
	s_waitcnt vmcnt(7)
	v_lshlrev_b32_e32 v48, 16, v84
	s_waitcnt lgkmcnt(0)
	v_and_b32_e32 v49, 0xffff0000, v84
	v_lshlrev_b32_e32 v52, 16, v86
	v_and_b32_e32 v53, 0xffff0000, v86
	v_lshlrev_b32_e32 v54, 16, v87
	v_and_b32_e32 v55, 0xffff0000, v87
	v_add_f32_e32 v44, v44, v48
	v_add_f32_e32 v45, v45, v49
	v_lshlrev_b32_e32 v50, 16, v85
	v_and_b32_e32 v51, 0xffff0000, v85
	v_add_f32_e32 v48, v42, v54
	v_add_f32_e32 v49, v43, v55
	v_add_f32_e32 v42, v40, v52
	v_add_f32_e32 v43, v41, v53
	v_cvt_pk_bf16_f32 v40, v44, v45
	v_lshl_add_u64 v[44:45], s[10:11], 0, v[102:103]
	v_add_f32_e32 v46, v46, v50
	v_add_f32_e32 v47, v47, v51
	v_lshl_add_u64 v[44:45], v[162:163], 1, v[44:45]
	v_cvt_pk_bf16_f32 v41, v46, v47
	v_cvt_pk_bf16_f32 v42, v42, v43
	v_cvt_pk_bf16_f32 v43, v48, v49
	global_store_dwordx4 v[44:45], v[40:43], off
	v_lshlrev_b32_e32 v46, 16, v40
	s_waitcnt vmcnt(7)
	v_and_b32_e32 v47, 0xffff0000, v82
	v_and_b32_e32 v40, 0xffff0000, v40
	v_mul_f32_e32 v40, v40, v40
	v_fmac_f32_e32 v40, v46, v46
	v_lshlrev_b32_e32 v46, 16, v41
	v_and_b32_e32 v41, 0xffff0000, v41
	v_mul_f32_e32 v41, v41, v41
	v_fmac_f32_e32 v41, v46, v46
	v_add_f32_e32 v40, v40, v41
	v_lshlrev_b32_e32 v41, 16, v42
	v_and_b32_e32 v42, 0xffff0000, v42
	v_mul_f32_e32 v42, v42, v42
	v_fmac_f32_e32 v42, v41, v41
	v_add_f32_e32 v40, v40, v42
	v_and_b32_e32 v42, 0xffff0000, v43
	v_lshlrev_b32_e32 v41, 16, v43
	v_mul_f32_e32 v42, v42, v42
	v_fmac_f32_e32 v42, v41, v41
	v_add_f32_e32 v50, v40, v42
	v_lshlrev_b32_e32 v40, 16, v80
	v_and_b32_e32 v41, 0xffff0000, v80
	v_lshlrev_b32_e32 v46, 16, v82
	v_lshlrev_b32_e32 v42, 16, v81
	v_and_b32_e32 v43, 0xffff0000, v81
	v_lshlrev_b32_e32 v48, 16, v83
	v_and_b32_e32 v49, 0xffff0000, v83
	v_add_f32_e32 v36, v36, v40
	v_add_f32_e32 v37, v37, v41
	v_add_f32_e32 v32, v32, v46
	v_add_f32_e32 v33, v33, v47
	v_add_f32_e32 v38, v38, v42
	v_add_f32_e32 v39, v39, v43
	v_add_f32_e32 v40, v34, v48
	v_add_f32_e32 v41, v35, v49
	v_cvt_pk_bf16_f32 v34, v36, v37
	v_cvt_pk_bf16_f32 v35, v38, v39
	v_cvt_pk_bf16_f32 v36, v32, v33
	s_nop 0
	v_and_b32_e32 v33, 0xffff0000, v34
	v_lshlrev_b32_e32 v32, 16, v34
	v_mul_f32_e32 v33, v33, v33
	v_fmac_f32_e32 v33, v32, v32
	v_and_b32_e32 v38, 0xffff0000, v35
	v_add_f32_e32 v32, v50, v33
	v_lshlrev_b32_e32 v33, 16, v35
	v_mul_f32_e32 v38, v38, v38
	v_fmac_f32_e32 v38, v33, v33
	v_add_f32_e32 v32, v32, v38
	v_and_b32_e32 v38, 0xffff0000, v36
	v_lshlrev_b32_e32 v33, 16, v36
	v_mul_f32_e32 v38, v38, v38
	v_fmac_f32_e32 v38, v33, v33
	v_cvt_pk_bf16_f32 v37, v40, v41
	v_add_f32_e32 v32, v32, v38
	v_and_b32_e32 v38, 0xffff0000, v37
	v_lshlrev_b32_e32 v33, 16, v37
	v_mul_f32_e32 v38, v38, v38
	v_fmac_f32_e32 v38, v33, v33
	v_add_f32_e32 v32, v32, v38
	ds_bpermute_b32 v33, v112, v32
	global_store_dwordx4 v[44:45], v[34:37], off offset:256
	s_waitcnt lgkmcnt(0)
	v_add_f32_e32 v32, v32, v33
	ds_bpermute_b32 v33, v113, v32
	s_and_saveexec_b64 s[54:55], s[40:41]
	s_cbranch_execz .LBB0_1860
	v_lshlrev_b64 v[34:35], 6, v[100:101]
	v_lshl_add_u64 v[34:35], s[24:25], 0, v[34:35]
	v_lshl_add_u64 v[34:35], s[0:1], 2, v[34:35]
	s_lshl_b32 s16, s63, 2
	v_lshl_add_u64 v[34:35], v[34:35], 0, s[16:17]
	s_waitcnt lgkmcnt(0)
	v_add_f32_e32 v32, v32, v33
	global_store_dword v[34:35], v32, off
; __device__ __forceinline__ unsigned cvt_pk_bf16(float lo, float hi) { unsigned r; asm volatile("v_cvt_pk_bf16_f32 %0, %1, %2" : "=v"(r) : "v"(lo), "v"(hi)); return r; }
;     __device__ __forceinline__ void operator()(const f32x4 (&acc)[2][2][4][2], const Unit& u, int wr, int wc, int fr, int fq, int, PG8_LAS unsigned char*) const {
;     ...
;                 for (int bj = 0; bj < 2; ++bj) xw[m][bj] = *(const u32x4*)(xb + (size_t)(row0 + ai * HALF + m * 16) * 1024 + col0 + bj * HALF);
; #pragma unroll
;             for (int m = 0; m < 4; ++m) {
;                 const int row = row0 + ai * HALF + m * 16; const size_t off = (size_t)row * 1024 + col0;
;                 float s = 0.f;
; #pragma unroll
;                 for (int bj = 0; bj < 2; ++bj) {
;                     const u32x4 xv = xw[m][bj];
;                     const f32x4 xo0 = {__builtin_bit_cast(float, xv.x << 16), __builtin_bit_cast(float, xv.x & 0xffff0000u), __builtin_bit_cast(float, xv.y << 16), __builtin_bit_cast(float, xv.y & 0xffff0000u)};
;                     const f32x4 xo1 = {__builtin_bit_cast(float, xv.z << 16), __builtin_bit_cast(float, xv.z & 0xffff0000u), __builtin_bit_cast(float, xv.w << 16), __builtin_bit_cast(float, xv.w & 0xffff0000u)};
;                     const f32x4 o0 = xo0 + acc[ai][bj][m][0] * csv[bj][0], o1 = xo1 + acc[ai][bj][m][1] * csv[bj][1];
;                     u32x4 w; w.x = cvt_pk_bf16(o0[0], o0[1]); w.y = cvt_pk_bf16(o0[2], o0[3]); w.z = cvt_pk_bf16(o1[0], o1[1]); w.w = cvt_pk_bf16(o1[2], o1[3]);
;                     if (!dry) *(u32x4*)(xb + off + bj * HALF) = w;
; #pragma unroll
;                     for (int q = 0; q < 4; ++q) { const unsigned ww = w[q]; const float ra = __builtin_bit_cast(float, ww << 16), rb = __builtin_bit_cast(float, ww & 0xffff0000u); s += ra * ra + rb * rb; }
;                 }
;                 s += __shfl_xor(s, 16); s += __shfl_xor(s, 32);
;                 if (fq == 0 && !dry) ssq_next[(size_t)row * 16 + u.pn * 4 + wc] = s;
;             }
.LBB0_1860:
	s_or_b64 exec, exec, s[54:55]
	s_waitcnt vmcnt(7)
	v_lshlrev_b32_e32 v32, 16, v76
	s_waitcnt lgkmcnt(0)
	v_and_b32_e32 v33, 0xffff0000, v76
	v_lshlrev_b32_e32 v36, 16, v78
	v_and_b32_e32 v37, 0xffff0000, v78
	v_lshlrev_b32_e32 v38, 16, v79
	v_and_b32_e32 v39, 0xffff0000, v79
	v_add_f32_e32 v28, v28, v32
	v_add_f32_e32 v29, v29, v33
	v_lshlrev_b32_e32 v34, 16, v77
	v_and_b32_e32 v35, 0xffff0000, v77
	v_add_f32_e32 v32, v26, v38
	v_add_f32_e32 v33, v27, v39
	v_add_f32_e32 v26, v24, v36
	v_add_f32_e32 v27, v25, v37
	v_cvt_pk_bf16_f32 v24, v28, v29
	v_lshl_add_u64 v[28:29], s[10:11], 0, v[98:99]
	v_add_f32_e32 v30, v30, v34
	v_add_f32_e32 v31, v31, v35
	v_lshl_add_u64 v[28:29], v[162:163], 1, v[28:29]
	v_cvt_pk_bf16_f32 v25, v30, v31
	v_cvt_pk_bf16_f32 v26, v26, v27
	v_cvt_pk_bf16_f32 v27, v32, v33
	global_store_dwordx4 v[28:29], v[24:27], off
	v_lshlrev_b32_e32 v30, 16, v24
	s_waitcnt vmcnt(7)
	v_and_b32_e32 v31, 0xffff0000, v74
	v_and_b32_e32 v24, 0xffff0000, v24
	v_mul_f32_e32 v24, v24, v24
	v_fmac_f32_e32 v24, v30, v30
	v_lshlrev_b32_e32 v30, 16, v25
	v_and_b32_e32 v25, 0xffff0000, v25
	v_mul_f32_e32 v25, v25, v25
	v_fmac_f32_e32 v25, v30, v30
	v_add_f32_e32 v24, v24, v25
	v_lshlrev_b32_e32 v25, 16, v26
	v_and_b32_e32 v26, 0xffff0000, v26
	v_mul_f32_e32 v26, v26, v26
	v_fmac_f32_e32 v26, v25, v25
	v_add_f32_e32 v24, v24, v26
	v_and_b32_e32 v26, 0xffff0000, v27
	v_lshlrev_b32_e32 v25, 16, v27
	v_mul_f32_e32 v26, v26, v26
	v_fmac_f32_e32 v26, v25, v25
	v_add_f32_e32 v34, v24, v26
	v_lshlrev_b32_e32 v24, 16, v72
	v_and_b32_e32 v25, 0xffff0000, v72
	v_lshlrev_b32_e32 v30, 16, v74
	v_lshlrev_b32_e32 v26, 16, v73
	v_and_b32_e32 v27, 0xffff0000, v73
	v_lshlrev_b32_e32 v32, 16, v75
	v_and_b32_e32 v33, 0xffff0000, v75
	v_add_f32_e32 v20, v20, v24
	v_add_f32_e32 v21, v21, v25
	v_add_f32_e32 v16, v16, v30
	v_add_f32_e32 v17, v17, v31
	v_add_f32_e32 v22, v22, v26
	v_add_f32_e32 v23, v23, v27
	v_add_f32_e32 v24, v18, v32
	v_add_f32_e32 v25, v19, v33
	v_cvt_pk_bf16_f32 v18, v20, v21
	v_cvt_pk_bf16_f32 v19, v22, v23
	v_cvt_pk_bf16_f32 v20, v16, v17
	s_nop 0
	v_and_b32_e32 v17, 0xffff0000, v18
	v_lshlrev_b32_e32 v16, 16, v18
	v_mul_f32_e32 v17, v17, v17
	v_fmac_f32_e32 v17, v16, v16
	v_and_b32_e32 v22, 0xffff0000, v19
	v_add_f32_e32 v16, v34, v17
	v_lshlrev_b32_e32 v17, 16, v19
	v_mul_f32_e32 v22, v22, v22
	v_fmac_f32_e32 v22, v17, v17
	v_add_f32_e32 v16, v16, v22
	v_and_b32_e32 v22, 0xffff0000, v20
	v_lshlrev_b32_e32 v17, 16, v20
	v_mul_f32_e32 v22, v22, v22
	v_fmac_f32_e32 v22, v17, v17
	v_cvt_pk_bf16_f32 v21, v24, v25
	v_add_f32_e32 v16, v16, v22
	v_and_b32_e32 v22, 0xffff0000, v21
	v_lshlrev_b32_e32 v17, 16, v21
	v_mul_f32_e32 v22, v22, v22
	v_fmac_f32_e32 v22, v17, v17
	v_add_f32_e32 v16, v16, v22
	ds_bpermute_b32 v17, v112, v16
	global_store_dwordx4 v[28:29], v[18:21], off offset:256
	s_waitcnt lgkmcnt(0)
	v_add_f32_e32 v16, v16, v17
	ds_bpermute_b32 v17, v113, v16
	s_and_saveexec_b64 s[54:55], s[40:41]
	s_cbranch_execz .LBB0_1862
	v_lshlrev_b64 v[18:19], 6, v[96:97]
	v_lshl_add_u64 v[18:19], s[24:25], 0, v[18:19]
	v_lshl_add_u64 v[18:19], s[0:1], 2, v[18:19]
	s_lshl_b32 s16, s63, 2
	v_lshl_add_u64 v[18:19], v[18:19], 0, s[16:17]
	s_waitcnt lgkmcnt(0)
	v_add_f32_e32 v16, v16, v17
	global_store_dword v[18:19], v16, off
.LBB0_1862:
	s_or_b64 exec, exec, s[54:55]
	s_waitcnt vmcnt(7)
	v_lshlrev_b32_e32 v16, 16, v68
	s_waitcnt lgkmcnt(0)
	v_and_b32_e32 v17, 0xffff0000, v68
	v_lshlrev_b32_e32 v20, 16, v70
	v_and_b32_e32 v21, 0xffff0000, v70
	v_lshlrev_b32_e32 v22, 16, v71
	v_and_b32_e32 v23, 0xffff0000, v71
	v_add_f32_e32 v12, v12, v16
	v_add_f32_e32 v13, v13, v17
	v_lshlrev_b32_e32 v18, 16, v69
	v_and_b32_e32 v19, 0xffff0000, v69
	v_add_f32_e32 v16, v10, v22
	v_add_f32_e32 v17, v11, v23
	v_add_f32_e32 v10, v8, v20
	v_add_f32_e32 v11, v9, v21
	v_cvt_pk_bf16_f32 v8, v12, v13
	v_lshl_add_u64 v[12:13], s[10:11], 0, v[94:95]
	v_add_f32_e32 v14, v14, v18
	v_add_f32_e32 v15, v15, v19
	v_lshl_add_u64 v[12:13], v[162:163], 1, v[12:13]
	v_cvt_pk_bf16_f32 v9, v14, v15
	v_cvt_pk_bf16_f32 v10, v10, v11
	v_cvt_pk_bf16_f32 v11, v16, v17
	global_store_dwordx4 v[12:13], v[8:11], off
	v_lshlrev_b32_e32 v14, 16, v8
	s_waitcnt vmcnt(7)
	v_and_b32_e32 v15, 0xffff0000, v66
	v_and_b32_e32 v8, 0xffff0000, v8
	v_mul_f32_e32 v8, v8, v8
	v_fmac_f32_e32 v8, v14, v14
	v_lshlrev_b32_e32 v14, 16, v9
	v_and_b32_e32 v9, 0xffff0000, v9
	v_mul_f32_e32 v9, v9, v9
	v_fmac_f32_e32 v9, v14, v14
	v_add_f32_e32 v8, v8, v9
	v_lshlrev_b32_e32 v9, 16, v10
	v_and_b32_e32 v10, 0xffff0000, v10
	v_mul_f32_e32 v10, v10, v10
	v_fmac_f32_e32 v10, v9, v9
	v_add_f32_e32 v8, v8, v10
	v_and_b32_e32 v10, 0xffff0000, v11
	v_lshlrev_b32_e32 v9, 16, v11
	v_mul_f32_e32 v10, v10, v10
	v_fmac_f32_e32 v10, v9, v9
	v_add_f32_e32 v18, v8, v10
	v_lshlrev_b32_e32 v8, 16, v64
	v_and_b32_e32 v9, 0xffff0000, v64
	v_lshlrev_b32_e32 v14, 16, v66
	v_lshlrev_b32_e32 v10, 16, v65
	v_and_b32_e32 v11, 0xffff0000, v65
	v_lshlrev_b32_e32 v16, 16, v67
	v_and_b32_e32 v17, 0xffff0000, v67
	v_add_f32_e32 v4, v4, v8
	v_add_f32_e32 v5, v5, v9
	v_add_f32_e32 v0, v0, v14
	v_add_f32_e32 v1, v1, v15
	v_add_f32_e32 v6, v6, v10
	v_add_f32_e32 v7, v7, v11
	v_add_f32_e32 v8, v2, v16
	v_add_f32_e32 v9, v3, v17
	v_cvt_pk_bf16_f32 v2, v4, v5
	v_cvt_pk_bf16_f32 v3, v6, v7
	v_cvt_pk_bf16_f32 v4, v0, v1
	s_nop 0
	v_and_b32_e32 v1, 0xffff0000, v2
	v_lshlrev_b32_e32 v0, 16, v2
	v_mul_f32_e32 v1, v1, v1
	v_fmac_f32_e32 v1, v0, v0
	v_and_b32_e32 v6, 0xffff0000, v3
	v_add_f32_e32 v0, v18, v1
	v_lshlrev_b32_e32 v1, 16, v3
	v_mul_f32_e32 v6, v6, v6
	v_fmac_f32_e32 v6, v1, v1
	v_add_f32_e32 v0, v0, v6
	v_and_b32_e32 v6, 0xffff0000, v4
	v_lshlrev_b32_e32 v1, 16, v4
	v_mul_f32_e32 v6, v6, v6
	v_fmac_f32_e32 v6, v1, v1
	v_cvt_pk_bf16_f32 v5, v8, v9
	v_add_f32_e32 v0, v0, v6
	v_and_b32_e32 v6, 0xffff0000, v5
	v_lshlrev_b32_e32 v1, 16, v5
	v_mul_f32_e32 v6, v6, v6
	v_fmac_f32_e32 v6, v1, v1
	v_add_f32_e32 v0, v0, v6
	ds_bpermute_b32 v1, v112, v0
	global_store_dwordx4 v[12:13], v[2:5], off offset:256
	s_waitcnt lgkmcnt(0)
	v_add_f32_e32 v0, v0, v1
	ds_bpermute_b32 v1, v113, v0
	s_and_saveexec_b64 s[54:55], s[40:41]
	s_cbranch_execz .LBB0_1864
	v_lshlrev_b64 v[2:3], 6, v[92:93]
	v_lshl_add_u64 v[2:3], s[24:25], 0, v[2:3]
	v_lshl_add_u64 v[2:3], s[0:1], 2, v[2:3]
	s_lshl_b32 s16, s63, 2
	v_lshl_add_u64 v[2:3], v[2:3], 0, s[16:17]
	s_waitcnt lgkmcnt(0)
	v_add_f32_e32 v0, v0, v1
	global_store_dword v[2:3], v0, off
